# third pair-conversion pass (80 sites) plus 65 single-value f32->bf16 conversions feeding d16_hi LDS stores replaced by v_cvt_pk_bf16_f32
# speedup vs baseline: 1.0222x; 1.0081x over previous
; __device__ __forceinline__ unsigned pk2(float lo, float hi) { return f2bf(lo) | (f2bf(hi) << 16); }
; __device__ __forceinline__ void st16f(float* p, f32x4 v) { st16(p, __builtin_bit_cast(u32x4, v)); }
; __device__ __forceinline__ void st8bf(bf16_t* p, f32x4 a, f32x4 b) { u32x4 w; w.x = pk2(a[0], a[1]); w.y = pk2(a[2], a[3]); w.z = pk2(b[0], b[1]); w.w = pk2(b[2], b[3]); st16(p, w); }
;     __device__ __forceinline__ void st(int pn, int row, int c, f32x4 v0, f32x4 v1) const {
;     ...
;         else if (pn == 10) { float* o = nullptr;
;             if (!smp) { if (t >= SEQ - 512) o = out + O_WIN + ((size_t)b * 512 + (t - (SEQ - 512))) * 256 + c; } else o = out + O_WINS + ((size_t)b * 512 + 508 + t) * 256 + c;
;             st8bf(KW + (size_t)row * 256 + c, v0, v1); if (o) { st16f(o, v0); st16f(o + 4, v1); } }
.LBB0_297:
	s_andn2_saveexec_b64 s[10:11], s[10:11]
	v_lshl_add_u64 v[144:145], v[214:215], 0, v[140:141]
	s_or_b64 exec, exec, s[10:11]
	v_cvt_pk_bf16_f32 v146, v120, v121
	v_cvt_pk_bf16_f32 v147, v122, v123
	v_cvt_pk_bf16_f32 v148, v116, v117
	v_lshl_add_u64 v[150:151], v[208:209], 0, v[138:139]
	v_cvt_pk_bf16_f32 v149, v118, v119
	v_cmp_ne_u64_e32 vcc, 0, v[144:145]
	global_store_dwordx4 v[150:151], v[146:149], off
	s_and_saveexec_b64 s[10:11], vcc
	s_cbranch_execz .LBB0_301
	global_store_dwordx4 v[144:145], v[120:123], off
	global_store_dwordx4 v[144:145], v[116:119], off offset:16

; __device__ __forceinline__ unsigned pk2(float lo, float hi) { return f2bf(lo) | (f2bf(hi) << 16); }
; __device__ __forceinline__ void st16f(float* p, f32x4 v) { st16(p, __builtin_bit_cast(u32x4, v)); }
; __device__ __forceinline__ void st8bf(bf16_t* p, f32x4 a, f32x4 b) { u32x4 w; w.x = pk2(a[0], a[1]); w.y = pk2(a[2], a[3]); w.z = pk2(b[0], b[1]); w.w = pk2(b[2], b[3]); st16(p, w); }
;     __device__ __forceinline__ void st(int pn, int row, int c, f32x4 v0, f32x4 v1) const {
;     ...
;         else if (pn == 8) { float* o = (smp ? out + O_KCS + (size_t)(row - MP) * 256 : out + O_KC + (size_t)row * 256) + c; st16f(o, v0); st16f(o + 4, v1); }
;         else if (pn == 9) { float* o = (smp ? out + O_KSS + (size_t)(row - MP) * 256 : out + O_KSEL + (size_t)row * 256) + c; st16f(o, v0); st16f(o + 4, v1); st8bf(KS + (size_t)row * 256 + c, v0, v1); }
.LBB0_303:
	s_andn2_b64 vcc, exec, s[10:11]
	s_cbranch_vccnz .LBB0_305
	v_lshl_add_u64 v[144:145], s[36:37], 0, v[2:3]
	v_lshl_add_u64 v[146:147], s[38:39], 0, v[136:137]
	v_cndmask_b32_e64 v145, v145, v147, s[4:5]
	v_cndmask_b32_e64 v144, v144, v146, s[4:5]
	v_lshlrev_b32_e32 v146, 2, v206
	v_mov_b32_e32 v147, v1
	v_cndmask_b32_e64 v149, v133, 0, s[4:5]
	v_cndmask_b32_e64 v148, v132, v132, s[4:5]
	v_lshl_add_u64 v[144:145], v[144:145], 0, v[146:147]
	global_store_dwordx4 v[144:145], v[120:123], off
	global_store_dwordx4 v[144:145], v[116:119], off offset:16
	v_lshlrev_b64 v[144:145], 9, v[148:149]
	v_lshl_add_u64 v[148:149], v[210:211], 0, v[144:145]
	v_cvt_pk_bf16_f32 v144, v120, v121
	v_cvt_pk_bf16_f32 v145, v122, v123
	v_cvt_pk_bf16_f32 v146, v116, v117
	v_cvt_pk_bf16_f32 v147, v118, v119
	global_store_dwordx4 v[148:149], v[144:147], off

; __device__ __forceinline__ unsigned pk2(float lo, float hi) { return f2bf(lo) | (f2bf(hi) << 16); }
; __device__ __forceinline__ float sigmoidf_(float x) { return __builtin_amdgcn_rcpf(1.0f + __expf(-x)); }
; __device__ __forceinline__ void st8bf(bf16_t* p, f32x4 a, f32x4 b) { u32x4 w; w.x = pk2(a[0], a[1]); w.y = pk2(a[2], a[3]); w.z = pk2(b[0], b[1]); w.w = pk2(b[2], b[3]); st16(p, w); }
; __device__ __forceinline__ void stnt8(float* o, f32x4 a, f32x4 b) { __builtin_nontemporal_store(a, (f32x4*)o); __builtin_nontemporal_store(b, (f32x4*)(o + 4)); }
; __device__ __forceinline__ f32x4 sig4(f32x4 v) { f32x4 r; r[0] = sigmoidf_(v[0]); r[1] = sigmoidf_(v[1]); r[2] = sigmoidf_(v[2]); r[3] = sigmoidf_(v[3]); return r; }
;     __device__ __forceinline__ void st(int pn, int row, int c, f32x4 v0, f32x4 v1) const {
;         const bool smp = row >= MP; const int b = smp ? (row - MP) >> 2 : row >> 13, t = smp ? (row - MP) & 3 : row & (SEQ - 1);
;         if (pn < 6 || pn == 11 || pn == 12) st8bf((pn < 6 ? AG : BG) + (size_t)row * 512 + (pn < 6 ? pn - 4 : pn - 11) * 256 + c, v0 * sig4(v0), v1 * sig4(v1));
.LBB0_335:
	s_and_b64 s[10:11], s[66:67], exec
	s_cselect_b32 s11, s51, s79
	s_cselect_b32 s10, s33, s78
	v_lshl_add_u64 v[144:145], s[10:11], 0, v[2:3]
	v_mul_f32_e32 v146, 0xbfb8aa3b, v120
	v_lshl_add_u64 v[144:145], s[64:65], 1, v[144:145]
	v_exp_f32_e32 v150, v146
	v_lshlrev_b32_e32 v146, 1, v206
	v_mov_b32_e32 v147, v1
	v_lshl_add_u64 v[148:149], v[144:145], 0, v[146:147]
	v_mul_f32_e32 v145, 0xbfb8aa3b, v121
	v_exp_f32_e32 v145, v145
	v_mul_f32_e32 v146, 0xbfb8aa3b, v122
	v_mul_f32_e32 v147, 0xbfb8aa3b, v123
	v_exp_f32_e32 v146, v146
	v_exp_f32_e32 v147, v147
	v_add_f32_e32 v144, 1.0, v150
	v_add_f32_e32 v145, 1.0, v145
	v_rcp_f32_e32 v144, v144
	v_rcp_f32_e32 v145, v145
	v_mul_f32_e32 v150, 0xbfb8aa3b, v116
	v_mul_f32_e32 v151, 0xbfb8aa3b, v117
	v_exp_f32_e32 v150, v150
	v_exp_f32_e32 v151, v151
	v_add_f32_e32 v146, 1.0, v146
	v_add_f32_e32 v147, 1.0, v147
	v_rcp_f32_e32 v146, v146
	v_rcp_f32_e32 v147, v147
	v_mul_f32_e32 v152, 0xbfb8aa3b, v118
	v_mul_f32_e32 v153, 0xbfb8aa3b, v119
	v_exp_f32_e32 v152, v152
	v_exp_f32_e32 v153, v153
	v_pk_mul_f32 v[144:145], v[120:121], v[144:145]
	v_add_f32_e32 v150, 1.0, v150
	v_add_f32_e32 v151, 1.0, v151
	v_rcp_f32_e32 v150, v150
	v_rcp_f32_e32 v151, v151
	v_pk_mul_f32 v[146:147], v[122:123], v[146:147]
	v_add_f32_e32 v152, 1.0, v152
	v_add_f32_e32 v153, 1.0, v153
	v_cvt_pk_bf16_f32 v144, v144, v145
	v_rcp_f32_e32 v152, v152
	v_rcp_f32_e32 v153, v153
	v_pk_mul_f32 v[150:151], v[116:117], v[150:151]
	v_cvt_pk_bf16_f32 v145, v146, v147
	v_pk_mul_f32 v[152:153], v[118:119], v[152:153]
	v_cvt_pk_bf16_f32 v146, v150, v151
	v_cvt_pk_bf16_f32 v147, v152, v153
	global_store_dwordx4 v[148:149], v[144:147], off
	s_andn2_b64 vcc, exec, s[68:69]
	s_mov_b64 s[10:11], -1
	s_cbranch_vccz .LBB0_313

; __device__ __forceinline__ unsigned pk2(float lo, float hi) { return f2bf(lo) | (f2bf(hi) << 16); }
; __device__ __forceinline__ float sigmoidf_(float x) { return __builtin_amdgcn_rcpf(1.0f + __expf(-x)); }
; __device__ __forceinline__ void st8bf(bf16_t* p, f32x4 a, f32x4 b) { u32x4 w; w.x = pk2(a[0], a[1]); w.y = pk2(a[2], a[3]); w.z = pk2(b[0], b[1]); w.w = pk2(b[2], b[3]); st16(p, w); }
; __device__ __forceinline__ void stnt8(float* o, f32x4 a, f32x4 b) { __builtin_nontemporal_store(a, (f32x4*)o); __builtin_nontemporal_store(b, (f32x4*)(o + 4)); }
; __device__ __forceinline__ f32x4 sig4(f32x4 v) { f32x4 r; r[0] = sigmoidf_(v[0]); r[1] = sigmoidf_(v[1]); r[2] = sigmoidf_(v[2]); r[3] = sigmoidf_(v[3]); return r; }
;     __device__ __forceinline__ void st(int pn, int row, int c, f32x4 v0, f32x4 v1) const {
;         const bool smp = row >= MP; const int b = smp ? (row - MP) >> 2 : row >> 13, t = smp ? (row - MP) & 3 : row & (SEQ - 1);
;         if (pn < 6 || pn == 11 || pn == 12) st8bf((pn < 6 ? AG : BG) + (size_t)row * 512 + (pn < 6 ? pn - 4 : pn - 11) * 256 + c, v0 * sig4(v0), v1 * sig4(v1));
.LBB0_395:
	s_and_b64 s[76:77], s[66:67], exec
	s_cselect_b32 s77, s51, s79
	s_cselect_b32 s76, s33, s78
	v_lshl_add_u64 v[130:131], s[76:77], 0, v[118:119]
	v_lshl_add_u64 v[130:131], s[64:65], 1, v[130:131]
	v_mul_f32_e32 v133, 0xbfb8aa3b, v104
	v_lshlrev_b32_e32 v134, 1, v206
	v_mov_b32_e32 v135, v1
	v_exp_f32_e32 v133, v133
	v_lshl_add_u64 v[130:131], v[130:131], 0, v[134:135]
	v_mul_f32_e32 v134, 0xbfb8aa3b, v105
	v_exp_f32_e32 v135, v134
	v_mul_f32_e32 v134, 0xbfb8aa3b, v106
	v_exp_f32_e32 v136, v134
	v_add_f32_e32 v133, 1.0, v133
	v_rcp_f32_e32 v134, v133
	v_add_f32_e32 v133, 1.0, v135
	v_rcp_f32_e32 v135, v133
	v_add_f32_e32 v133, 1.0, v136
	v_mul_f32_e32 v136, 0xbfb8aa3b, v107
	v_exp_f32_e32 v137, v136
	v_mul_f32_e32 v136, 0xbfb8aa3b, v100
	v_exp_f32_e32 v138, v136
	v_rcp_f32_e32 v136, v133
	v_add_f32_e32 v133, 1.0, v137
	v_rcp_f32_e32 v137, v133
	v_add_f32_e32 v133, 1.0, v138
	v_mul_f32_e32 v139, 0xbfb8aa3b, v102
	v_rcp_f32_e32 v138, v133
	v_mul_f32_e32 v133, 0xbfb8aa3b, v101
	v_exp_f32_e32 v139, v139
	v_mul_f32_e32 v140, 0xbfb8aa3b, v103
	v_exp_f32_e32 v133, v133
	v_exp_f32_e32 v141, v140
	v_add_f32_e32 v139, 1.0, v139
	v_rcp_f32_e32 v140, v139
	v_add_f32_e32 v133, 1.0, v133
	v_add_f32_e32 v139, 1.0, v141
	v_pk_mul_f32 v[134:135], v[104:105], v[134:135]
	v_rcp_f32_e32 v141, v139
	v_rcp_f32_e32 v139, v133
	v_pk_mul_f32 v[136:137], v[106:107], v[136:137]
	v_cvt_pk_bf16_f32 v134, v134, v135
	v_pk_mul_f32 v[138:139], v[100:101], v[138:139]
	v_cvt_pk_bf16_f32 v135, v136, v137
	v_pk_mul_f32 v[140:141], v[102:103], v[140:141]
	v_cvt_pk_bf16_f32 v136, v138, v139
	v_cvt_pk_bf16_f32 v137, v140, v141
	global_store_dwordx4 v[130:131], v[134:137], off
	s_and_b64 vcc, exec, s[12:13]
	s_mov_b64 s[12:13], -1
	s_cbranch_vccz .LBB0_373

; __device__ __forceinline__ unsigned pk2(float lo, float hi) { return f2bf(lo) | (f2bf(hi) << 16); }
; __device__ __forceinline__ void st16f(float* p, f32x4 v) { st16(p, __builtin_bit_cast(u32x4, v)); }
; __device__ __forceinline__ void st8bf(bf16_t* p, f32x4 a, f32x4 b) { u32x4 w; w.x = pk2(a[0], a[1]); w.y = pk2(a[2], a[3]); w.z = pk2(b[0], b[1]); w.w = pk2(b[2], b[3]); st16(p, w); }
;     __device__ __forceinline__ void st(int pn, int row, int c, f32x4 v0, f32x4 v1) const {
;     ...
;         else if (pn == 10) { float* o = nullptr;
;             if (!smp) { if (t >= SEQ - 512) o = out + O_WIN + ((size_t)b * 512 + (t - (SEQ - 512))) * 256 + c; } else o = out + O_WINS + ((size_t)b * 512 + 508 + t) * 256 + c;
;             st8bf(KW + (size_t)row * 256 + c, v0, v1); if (o) { st16f(o, v0); st16f(o + 4, v1); } }
.LBB0_417:
	s_andn2_saveexec_b64 s[76:77], s[76:77]
	v_lshl_add_u64 v[114:115], v[214:215], 0, v[110:111]
	s_or_b64 exec, exec, s[76:77]
	v_cvt_pk_bf16_f32 v116, v88, v89
	v_cvt_pk_bf16_f32 v117, v90, v91
	v_cvt_pk_bf16_f32 v118, v84, v85
	v_lshl_add_u64 v[120:121], v[208:209], 0, v[108:109]
	v_cvt_pk_bf16_f32 v119, v86, v87
	v_cmp_ne_u64_e32 vcc, 0, v[114:115]
	global_store_dwordx4 v[120:121], v[116:119], off
	s_and_saveexec_b64 s[76:77], vcc
	s_cbranch_execz .LBB0_421
	global_store_dwordx4 v[114:115], v[88:91], off
	global_store_dwordx4 v[114:115], v[84:87], off offset:16

; __device__ __forceinline__ unsigned pk2(float lo, float hi) { return f2bf(lo) | (f2bf(hi) << 16); }
; __device__ __forceinline__ void st16f(float* p, f32x4 v) { st16(p, __builtin_bit_cast(u32x4, v)); }
; __device__ __forceinline__ void st8bf(bf16_t* p, f32x4 a, f32x4 b) { u32x4 w; w.x = pk2(a[0], a[1]); w.y = pk2(a[2], a[3]); w.z = pk2(b[0], b[1]); w.w = pk2(b[2], b[3]); st16(p, w); }
;     __device__ __forceinline__ void st(int pn, int row, int c, f32x4 v0, f32x4 v1) const {
;     ...
;         else if (pn == 8) { float* o = (smp ? out + O_KCS + (size_t)(row - MP) * 256 : out + O_KC + (size_t)row * 256) + c; st16f(o, v0); st16f(o + 4, v1); }
;         else if (pn == 9) { float* o = (smp ? out + O_KSS + (size_t)(row - MP) * 256 : out + O_KSEL + (size_t)row * 256) + c; st16f(o, v0); st16f(o + 4, v1); st8bf(KS + (size_t)row * 256 + c, v0, v1); }
.LBB0_423:
	s_andn2_b64 vcc, exec, s[76:77]
	s_cbranch_vccnz .LBB0_425
	v_lshl_add_u64 v[114:115], s[36:37], 0, v[102:103]
	v_lshl_add_u64 v[116:117], s[38:39], 0, v[106:107]
	v_cndmask_b32_e64 v115, v115, v117, s[8:9]
	v_cndmask_b32_e64 v114, v114, v116, s[8:9]
	v_lshlrev_b32_e32 v116, 2, v206
	v_mov_b32_e32 v117, v1
	v_cndmask_b32_e64 v119, v101, 0, s[8:9]
	v_cndmask_b32_e64 v118, v100, v100, s[8:9]
	v_lshl_add_u64 v[114:115], v[114:115], 0, v[116:117]
	global_store_dwordx4 v[114:115], v[88:91], off
	global_store_dwordx4 v[114:115], v[84:87], off offset:16
	v_lshlrev_b64 v[114:115], 9, v[118:119]
	v_lshl_add_u64 v[118:119], v[210:211], 0, v[114:115]
	v_cvt_pk_bf16_f32 v114, v88, v89
	v_cvt_pk_bf16_f32 v115, v90, v91
	v_cvt_pk_bf16_f32 v116, v84, v85
	v_cvt_pk_bf16_f32 v117, v86, v87
	global_store_dwordx4 v[118:119], v[114:117], off

; __device__ __forceinline__ unsigned pk2(float lo, float hi) { return f2bf(lo) | (f2bf(hi) << 16); }
; __device__ __forceinline__ float sigmoidf_(float x) { return __builtin_amdgcn_rcpf(1.0f + __expf(-x)); }
; __device__ __forceinline__ void st8bf(bf16_t* p, f32x4 a, f32x4 b) { u32x4 w; w.x = pk2(a[0], a[1]); w.y = pk2(a[2], a[3]); w.z = pk2(b[0], b[1]); w.w = pk2(b[2], b[3]); st16(p, w); }
; __device__ __forceinline__ void stnt8(float* o, f32x4 a, f32x4 b) { __builtin_nontemporal_store(a, (f32x4*)o); __builtin_nontemporal_store(b, (f32x4*)(o + 4)); }
; __device__ __forceinline__ f32x4 sig4(f32x4 v) { f32x4 r; r[0] = sigmoidf_(v[0]); r[1] = sigmoidf_(v[1]); r[2] = sigmoidf_(v[2]); r[3] = sigmoidf_(v[3]); return r; }
;     __device__ __forceinline__ void st(int pn, int row, int c, f32x4 v0, f32x4 v1) const {
;         const bool smp = row >= MP; const int b = smp ? (row - MP) >> 2 : row >> 13, t = smp ? (row - MP) & 3 : row & (SEQ - 1);
;         if (pn < 6 || pn == 11 || pn == 12) st8bf((pn < 6 ? AG : BG) + (size_t)row * 512 + (pn < 6 ? pn - 4 : pn - 11) * 256 + c, v0 * sig4(v0), v1 * sig4(v1));
.LBB0_455:
	s_and_b64 s[76:77], s[66:67], exec
	s_cselect_b32 s77, s51, s79
	s_cselect_b32 s76, s33, s78
	v_lshl_add_u64 v[114:115], s[76:77], 0, v[102:103]
	v_mul_f32_e32 v116, 0xbfb8aa3b, v88
	v_lshl_add_u64 v[114:115], s[64:65], 1, v[114:115]
	v_exp_f32_e32 v120, v116
	v_lshlrev_b32_e32 v116, 1, v206
	v_mov_b32_e32 v117, v1
	v_lshl_add_u64 v[118:119], v[114:115], 0, v[116:117]
	v_mul_f32_e32 v115, 0xbfb8aa3b, v89
	v_exp_f32_e32 v115, v115
	v_mul_f32_e32 v116, 0xbfb8aa3b, v90
	v_mul_f32_e32 v117, 0xbfb8aa3b, v91
	v_exp_f32_e32 v116, v116
	v_exp_f32_e32 v117, v117
	v_add_f32_e32 v114, 1.0, v120
	v_add_f32_e32 v115, 1.0, v115
	v_rcp_f32_e32 v114, v114
	v_rcp_f32_e32 v115, v115
	v_mul_f32_e32 v120, 0xbfb8aa3b, v84
	v_mul_f32_e32 v121, 0xbfb8aa3b, v85
	v_exp_f32_e32 v120, v120
	v_exp_f32_e32 v121, v121
	v_add_f32_e32 v116, 1.0, v116
	v_add_f32_e32 v117, 1.0, v117
	v_rcp_f32_e32 v116, v116
	v_rcp_f32_e32 v117, v117
	v_mul_f32_e32 v122, 0xbfb8aa3b, v86
	v_mul_f32_e32 v123, 0xbfb8aa3b, v87
	v_exp_f32_e32 v122, v122
	v_exp_f32_e32 v123, v123
	v_pk_mul_f32 v[114:115], v[88:89], v[114:115]
	v_add_f32_e32 v120, 1.0, v120
	v_add_f32_e32 v121, 1.0, v121
	v_rcp_f32_e32 v120, v120
	v_rcp_f32_e32 v121, v121
	v_pk_mul_f32 v[116:117], v[90:91], v[116:117]
	v_add_f32_e32 v122, 1.0, v122
	v_add_f32_e32 v123, 1.0, v123
	v_cvt_pk_bf16_f32 v114, v114, v115
	v_rcp_f32_e32 v122, v122
	v_rcp_f32_e32 v123, v123
	v_pk_mul_f32 v[120:121], v[84:85], v[120:121]
	v_cvt_pk_bf16_f32 v115, v116, v117
	v_pk_mul_f32 v[122:123], v[86:87], v[122:123]
	v_cvt_pk_bf16_f32 v116, v120, v121
	v_cvt_pk_bf16_f32 v117, v122, v123
	global_store_dwordx4 v[118:119], v[114:117], off
	s_and_b64 vcc, exec, s[12:13]
	s_mov_b64 s[12:13], -1
	s_cbranch_vccz .LBB0_433

; __device__ __forceinline__ unsigned pk2(float lo, float hi) { return f2bf(lo) | (f2bf(hi) << 16); }
; __device__ __forceinline__ void st16f(float* p, f32x4 v) { st16(p, __builtin_bit_cast(u32x4, v)); }
; __device__ __forceinline__ void st8bf(bf16_t* p, f32x4 a, f32x4 b) { u32x4 w; w.x = pk2(a[0], a[1]); w.y = pk2(a[2], a[3]); w.z = pk2(b[0], b[1]); w.w = pk2(b[2], b[3]); st16(p, w); }
;     __device__ __forceinline__ void st(int pn, int row, int c, f32x4 v0, f32x4 v1) const {
;     ...
;         else if (pn == 10) { float* o = nullptr;
;             if (!smp) { if (t >= SEQ - 512) o = out + O_WIN + ((size_t)b * 512 + (t - (SEQ - 512))) * 256 + c; } else o = out + O_WINS + ((size_t)b * 512 + 508 + t) * 256 + c;
;             st8bf(KW + (size_t)row * 256 + c, v0, v1); if (o) { st16f(o, v0); st16f(o + 4, v1); } }
.LBB0_477:
	s_andn2_saveexec_b64 s[76:77], s[76:77]
	v_lshl_add_u64 v[98:99], v[214:215], 0, v[94:95]
	s_or_b64 exec, exec, s[76:77]
	v_cvt_pk_bf16_f32 v100, v72, v73
	v_cvt_pk_bf16_f32 v101, v74, v75
	v_cvt_pk_bf16_f32 v102, v68, v69
	v_lshl_add_u64 v[104:105], v[208:209], 0, v[92:93]
	v_cvt_pk_bf16_f32 v103, v70, v71
	v_cmp_ne_u64_e32 vcc, 0, v[98:99]
	global_store_dwordx4 v[104:105], v[100:103], off
	s_and_saveexec_b64 s[76:77], vcc
	s_cbranch_execz .LBB0_481
	global_store_dwordx4 v[98:99], v[72:75], off
	global_store_dwordx4 v[98:99], v[68:71], off offset:16

; __device__ __forceinline__ unsigned pk2(float lo, float hi) { return f2bf(lo) | (f2bf(hi) << 16); }
; __device__ __forceinline__ void st16f(float* p, f32x4 v) { st16(p, __builtin_bit_cast(u32x4, v)); }
; __device__ __forceinline__ void st8bf(bf16_t* p, f32x4 a, f32x4 b) { u32x4 w; w.x = pk2(a[0], a[1]); w.y = pk2(a[2], a[3]); w.z = pk2(b[0], b[1]); w.w = pk2(b[2], b[3]); st16(p, w); }
;     __device__ __forceinline__ void st(int pn, int row, int c, f32x4 v0, f32x4 v1) const {
;     ...
;         else if (pn == 8) { float* o = (smp ? out + O_KCS + (size_t)(row - MP) * 256 : out + O_KC + (size_t)row * 256) + c; st16f(o, v0); st16f(o + 4, v1); }
;         else if (pn == 9) { float* o = (smp ? out + O_KSS + (size_t)(row - MP) * 256 : out + O_KSEL + (size_t)row * 256) + c; st16f(o, v0); st16f(o + 4, v1); st8bf(KS + (size_t)row * 256 + c, v0, v1); }
.LBB0_483:
	s_andn2_b64 vcc, exec, s[76:77]
	s_cbranch_vccnz .LBB0_485
	v_lshl_add_u64 v[98:99], s[36:37], 0, v[86:87]
	v_lshl_add_u64 v[100:101], s[38:39], 0, v[90:91]
	v_cndmask_b32_e64 v99, v99, v101, s[8:9]
	v_cndmask_b32_e64 v98, v98, v100, s[8:9]
	v_lshlrev_b32_e32 v100, 2, v206
	v_mov_b32_e32 v101, v1
	v_cndmask_b32_e64 v103, v85, 0, s[8:9]
	v_cndmask_b32_e64 v102, v84, v84, s[8:9]
	v_lshl_add_u64 v[98:99], v[98:99], 0, v[100:101]
	global_store_dwordx4 v[98:99], v[72:75], off
	global_store_dwordx4 v[98:99], v[68:71], off offset:16
	v_lshlrev_b64 v[98:99], 9, v[102:103]
	v_lshl_add_u64 v[102:103], v[210:211], 0, v[98:99]
	v_cvt_pk_bf16_f32 v98, v72, v73
	v_cvt_pk_bf16_f32 v99, v74, v75
	v_cvt_pk_bf16_f32 v100, v68, v69
	v_cvt_pk_bf16_f32 v101, v70, v71
	global_store_dwordx4 v[102:103], v[98:101], off

; __device__ __forceinline__ unsigned pk2(float lo, float hi) { return f2bf(lo) | (f2bf(hi) << 16); }
; __device__ __forceinline__ float sigmoidf_(float x) { return __builtin_amdgcn_rcpf(1.0f + __expf(-x)); }
; __device__ __forceinline__ void st8bf(bf16_t* p, f32x4 a, f32x4 b) { u32x4 w; w.x = pk2(a[0], a[1]); w.y = pk2(a[2], a[3]); w.z = pk2(b[0], b[1]); w.w = pk2(b[2], b[3]); st16(p, w); }
; __device__ __forceinline__ void stnt8(float* o, f32x4 a, f32x4 b) { __builtin_nontemporal_store(a, (f32x4*)o); __builtin_nontemporal_store(b, (f32x4*)(o + 4)); }
; __device__ __forceinline__ f32x4 sig4(f32x4 v) { f32x4 r; r[0] = sigmoidf_(v[0]); r[1] = sigmoidf_(v[1]); r[2] = sigmoidf_(v[2]); r[3] = sigmoidf_(v[3]); return r; }
;     __device__ __forceinline__ void st(int pn, int row, int c, f32x4 v0, f32x4 v1) const {
;         const bool smp = row >= MP; const int b = smp ? (row - MP) >> 2 : row >> 13, t = smp ? (row - MP) & 3 : row & (SEQ - 1);
;         if (pn < 6 || pn == 11 || pn == 12) st8bf((pn < 6 ? AG : BG) + (size_t)row * 512 + (pn < 6 ? pn - 4 : pn - 11) * 256 + c, v0 * sig4(v0), v1 * sig4(v1));
.LBB0_517:
	s_and_b64 s[76:77], s[66:67], exec
	s_cselect_b32 s77, s51, s79
	s_cselect_b32 s76, s33, s78
	v_lshl_add_u64 v[98:99], s[76:77], 0, v[86:87]
	v_mul_f32_e32 v100, 0xbfb8aa3b, v72
	v_lshl_add_u64 v[98:99], s[64:65], 1, v[98:99]
	v_exp_f32_e32 v104, v100
	v_lshlrev_b32_e32 v100, 1, v206
	v_mov_b32_e32 v101, v1
	v_lshl_add_u64 v[102:103], v[98:99], 0, v[100:101]
	v_mul_f32_e32 v99, 0xbfb8aa3b, v73
	v_exp_f32_e32 v99, v99
	v_mul_f32_e32 v100, 0xbfb8aa3b, v74
	v_mul_f32_e32 v101, 0xbfb8aa3b, v75
	v_exp_f32_e32 v100, v100
	v_exp_f32_e32 v101, v101
	v_add_f32_e32 v98, 1.0, v104
	v_add_f32_e32 v99, 1.0, v99
	v_rcp_f32_e32 v98, v98
	v_rcp_f32_e32 v99, v99
	v_mul_f32_e32 v104, 0xbfb8aa3b, v68
	v_mul_f32_e32 v105, 0xbfb8aa3b, v69
	v_exp_f32_e32 v104, v104
	v_exp_f32_e32 v105, v105
	v_add_f32_e32 v100, 1.0, v100
	v_add_f32_e32 v101, 1.0, v101
	v_rcp_f32_e32 v100, v100
	v_rcp_f32_e32 v101, v101
	v_mul_f32_e32 v106, 0xbfb8aa3b, v70
	v_mul_f32_e32 v107, 0xbfb8aa3b, v71
	v_exp_f32_e32 v106, v106
	v_exp_f32_e32 v107, v107
	v_pk_mul_f32 v[98:99], v[72:73], v[98:99]
	v_add_f32_e32 v104, 1.0, v104
	v_add_f32_e32 v105, 1.0, v105
	v_rcp_f32_e32 v104, v104
	v_rcp_f32_e32 v105, v105
	v_pk_mul_f32 v[100:101], v[74:75], v[100:101]
	v_add_f32_e32 v106, 1.0, v106
	v_add_f32_e32 v107, 1.0, v107
	v_cvt_pk_bf16_f32 v98, v98, v99
	v_rcp_f32_e32 v106, v106
	v_rcp_f32_e32 v107, v107
	v_pk_mul_f32 v[104:105], v[68:69], v[104:105]
	v_cvt_pk_bf16_f32 v99, v100, v101
	v_pk_mul_f32 v[106:107], v[70:71], v[106:107]
	v_cvt_pk_bf16_f32 v100, v104, v105
	v_cvt_pk_bf16_f32 v101, v106, v107
	global_store_dwordx4 v[102:103], v[98:101], off
	s_and_b64 vcc, exec, s[12:13]
	s_mov_b64 s[12:13], -1
	s_cbranch_vccz .LBB0_493

; __device__ __forceinline__ unsigned pk2(float lo, float hi) { return f2bf(lo) | (f2bf(hi) << 16); }
; __device__ __forceinline__ void st16f(float* p, f32x4 v) { st16(p, __builtin_bit_cast(u32x4, v)); }
; __device__ __forceinline__ void st8bf(bf16_t* p, f32x4 a, f32x4 b) { u32x4 w; w.x = pk2(a[0], a[1]); w.y = pk2(a[2], a[3]); w.z = pk2(b[0], b[1]); w.w = pk2(b[2], b[3]); st16(p, w); }
;     __device__ __forceinline__ void st(int pn, int row, int c, f32x4 v0, f32x4 v1) const {
;     ...
;         else if (pn == 10) { float* o = nullptr;
;             if (!smp) { if (t >= SEQ - 512) o = out + O_WIN + ((size_t)b * 512 + (t - (SEQ - 512))) * 256 + c; } else o = out + O_WINS + ((size_t)b * 512 + 508 + t) * 256 + c;
;             st8bf(KW + (size_t)row * 256 + c, v0, v1); if (o) { st16f(o, v0); st16f(o + 4, v1); } }
.LBB0_539:
	s_andn2_saveexec_b64 s[76:77], s[76:77]
	v_lshl_add_u64 v[82:83], v[214:215], 0, v[78:79]
	s_or_b64 exec, exec, s[76:77]
	v_cvt_pk_bf16_f32 v84, v56, v57
	v_cvt_pk_bf16_f32 v85, v58, v59
	v_cvt_pk_bf16_f32 v86, v52, v53
	v_lshl_add_u64 v[88:89], v[208:209], 0, v[76:77]
	v_cvt_pk_bf16_f32 v87, v54, v55
	v_cmp_ne_u64_e32 vcc, 0, v[82:83]
	global_store_dwordx4 v[88:89], v[84:87], off
	s_and_saveexec_b64 s[76:77], vcc
	s_cbranch_execz .LBB0_543
	global_store_dwordx4 v[82:83], v[56:59], off
	global_store_dwordx4 v[82:83], v[52:55], off offset:16

; __device__ __forceinline__ unsigned pk2(float lo, float hi) { return f2bf(lo) | (f2bf(hi) << 16); }
; __device__ __forceinline__ void st16f(float* p, f32x4 v) { st16(p, __builtin_bit_cast(u32x4, v)); }
; __device__ __forceinline__ void st8bf(bf16_t* p, f32x4 a, f32x4 b) { u32x4 w; w.x = pk2(a[0], a[1]); w.y = pk2(a[2], a[3]); w.z = pk2(b[0], b[1]); w.w = pk2(b[2], b[3]); st16(p, w); }
;     __device__ __forceinline__ void st(int pn, int row, int c, f32x4 v0, f32x4 v1) const {
;     ...
;         else if (pn == 8) { float* o = (smp ? out + O_KCS + (size_t)(row - MP) * 256 : out + O_KC + (size_t)row * 256) + c; st16f(o, v0); st16f(o + 4, v1); }
;         else if (pn == 9) { float* o = (smp ? out + O_KSS + (size_t)(row - MP) * 256 : out + O_KSEL + (size_t)row * 256) + c; st16f(o, v0); st16f(o + 4, v1); st8bf(KS + (size_t)row * 256 + c, v0, v1); }
.LBB0_545:
	s_andn2_b64 vcc, exec, s[76:77]
	s_cbranch_vccnz .LBB0_547
	v_lshl_add_u64 v[82:83], s[36:37], 0, v[70:71]
	v_lshl_add_u64 v[84:85], s[38:39], 0, v[74:75]
	v_cndmask_b32_e64 v83, v83, v85, s[6:7]
	v_cndmask_b32_e64 v82, v82, v84, s[6:7]
	v_lshlrev_b32_e32 v84, 2, v206
	v_mov_b32_e32 v85, v1
	v_cndmask_b32_e64 v87, v69, 0, s[6:7]
	v_cndmask_b32_e64 v86, v68, v68, s[6:7]
	v_lshl_add_u64 v[82:83], v[82:83], 0, v[84:85]
	global_store_dwordx4 v[82:83], v[56:59], off
	global_store_dwordx4 v[82:83], v[52:55], off offset:16
	v_lshlrev_b64 v[82:83], 9, v[86:87]
	v_lshl_add_u64 v[86:87], v[210:211], 0, v[82:83]
	v_cvt_pk_bf16_f32 v82, v56, v57
	v_cvt_pk_bf16_f32 v83, v58, v59
	v_cvt_pk_bf16_f32 v84, v52, v53
	v_cvt_pk_bf16_f32 v85, v54, v55
	global_store_dwordx4 v[86:87], v[82:85], off

; __device__ __forceinline__ unsigned pk2(float lo, float hi) { return f2bf(lo) | (f2bf(hi) << 16); }
; __device__ __forceinline__ float sigmoidf_(float x) { return __builtin_amdgcn_rcpf(1.0f + __expf(-x)); }
; __device__ __forceinline__ void st8bf(bf16_t* p, f32x4 a, f32x4 b) { u32x4 w; w.x = pk2(a[0], a[1]); w.y = pk2(a[2], a[3]); w.z = pk2(b[0], b[1]); w.w = pk2(b[2], b[3]); st16(p, w); }
; __device__ __forceinline__ void stnt8(float* o, f32x4 a, f32x4 b) { __builtin_nontemporal_store(a, (f32x4*)o); __builtin_nontemporal_store(b, (f32x4*)(o + 4)); }
; __device__ __forceinline__ f32x4 sig4(f32x4 v) { f32x4 r; r[0] = sigmoidf_(v[0]); r[1] = sigmoidf_(v[1]); r[2] = sigmoidf_(v[2]); r[3] = sigmoidf_(v[3]); return r; }
;     __device__ __forceinline__ void st(int pn, int row, int c, f32x4 v0, f32x4 v1) const {
;         const bool smp = row >= MP; const int b = smp ? (row - MP) >> 2 : row >> 13, t = smp ? (row - MP) & 3 : row & (SEQ - 1);
;         if (pn < 6 || pn == 11 || pn == 12) st8bf((pn < 6 ? AG : BG) + (size_t)row * 512 + (pn < 6 ? pn - 4 : pn - 11) * 256 + c, v0 * sig4(v0), v1 * sig4(v1));
.LBB0_579:
	s_and_b64 s[76:77], s[66:67], exec
	s_cselect_b32 s77, s51, s79
	s_cselect_b32 s76, s33, s78
	v_lshl_add_u64 v[82:83], s[76:77], 0, v[70:71]
	v_mul_f32_e32 v84, 0xbfb8aa3b, v56
	v_lshl_add_u64 v[82:83], s[64:65], 1, v[82:83]
	v_exp_f32_e32 v88, v84
	v_lshlrev_b32_e32 v84, 1, v206
	v_mov_b32_e32 v85, v1
	v_lshl_add_u64 v[86:87], v[82:83], 0, v[84:85]
	v_mul_f32_e32 v83, 0xbfb8aa3b, v57
	v_exp_f32_e32 v83, v83
	v_mul_f32_e32 v84, 0xbfb8aa3b, v58
	v_mul_f32_e32 v85, 0xbfb8aa3b, v59
	v_exp_f32_e32 v84, v84
	v_exp_f32_e32 v85, v85
	v_add_f32_e32 v82, 1.0, v88
	v_add_f32_e32 v83, 1.0, v83
	v_rcp_f32_e32 v82, v82
	v_rcp_f32_e32 v83, v83
	v_mul_f32_e32 v88, 0xbfb8aa3b, v52
	v_mul_f32_e32 v89, 0xbfb8aa3b, v53
	v_exp_f32_e32 v88, v88
	v_exp_f32_e32 v89, v89
	v_add_f32_e32 v84, 1.0, v84
	v_add_f32_e32 v85, 1.0, v85
	v_rcp_f32_e32 v84, v84
	v_rcp_f32_e32 v85, v85
	v_mul_f32_e32 v90, 0xbfb8aa3b, v54
	v_mul_f32_e32 v91, 0xbfb8aa3b, v55
	v_exp_f32_e32 v90, v90
	v_exp_f32_e32 v91, v91
	v_pk_mul_f32 v[82:83], v[56:57], v[82:83]
	v_add_f32_e32 v88, 1.0, v88
	v_add_f32_e32 v89, 1.0, v89
	v_rcp_f32_e32 v88, v88
	v_rcp_f32_e32 v89, v89
	v_pk_mul_f32 v[84:85], v[58:59], v[84:85]
	v_add_f32_e32 v90, 1.0, v90
	v_add_f32_e32 v91, 1.0, v91
	v_cvt_pk_bf16_f32 v82, v82, v83
	v_rcp_f32_e32 v90, v90
	v_rcp_f32_e32 v91, v91
	v_pk_mul_f32 v[88:89], v[52:53], v[88:89]
	v_cvt_pk_bf16_f32 v83, v84, v85
	v_pk_mul_f32 v[90:91], v[54:55], v[90:91]
	v_cvt_pk_bf16_f32 v84, v88, v89
	v_cvt_pk_bf16_f32 v85, v90, v91
	global_store_dwordx4 v[86:87], v[82:85], off
	s_and_b64 vcc, exec, s[12:13]
	s_mov_b64 s[12:13], -1
	s_cbranch_vccz .LBB0_555

; __device__ __forceinline__ unsigned pk2(float lo, float hi) { return f2bf(lo) | (f2bf(hi) << 16); }
; __device__ __forceinline__ float sigmoidf_(float x) { return __builtin_amdgcn_rcpf(1.0f + __expf(-x)); }
; __device__ __forceinline__ void st8bf(bf16_t* p, f32x4 a, f32x4 b) { u32x4 w; w.x = pk2(a[0], a[1]); w.y = pk2(a[2], a[3]); w.z = pk2(b[0], b[1]); w.w = pk2(b[2], b[3]); st16(p, w); }
; __device__ __forceinline__ void stnt8(float* o, f32x4 a, f32x4 b) { __builtin_nontemporal_store(a, (f32x4*)o); __builtin_nontemporal_store(b, (f32x4*)(o + 4)); }
; __device__ __forceinline__ f32x4 sig4(f32x4 v) { f32x4 r; r[0] = sigmoidf_(v[0]); r[1] = sigmoidf_(v[1]); r[2] = sigmoidf_(v[2]); r[3] = sigmoidf_(v[3]); return r; }
;     __device__ __forceinline__ void st(int pn, int row, int c, f32x4 v0, f32x4 v1) const {
;         const bool smp = row >= MP; const int b = smp ? (row - MP) >> 2 : row >> 13, t = smp ? (row - MP) & 3 : row & (SEQ - 1);
;         if (pn < 6 || pn == 11 || pn == 12) st8bf((pn < 6 ? AG : BG) + (size_t)row * 512 + (pn < 6 ? pn - 4 : pn - 11) * 256 + c, v0 * sig4(v0), v1 * sig4(v1));
.LBB0_639:
	s_and_b64 s[76:77], s[66:67], exec
	s_cselect_b32 s77, s51, s79
	s_cselect_b32 s76, s33, s78
	v_lshl_add_u64 v[66:67], s[76:77], 0, v[54:55]
	v_lshl_add_u64 v[66:67], s[64:65], 1, v[66:67]
	v_mul_f32_e32 v69, 0xbfb8aa3b, v40
	v_lshlrev_b32_e32 v70, 1, v206
	v_mov_b32_e32 v71, v1
	v_exp_f32_e32 v69, v69
	v_lshl_add_u64 v[66:67], v[66:67], 0, v[70:71]
	v_mul_f32_e32 v70, 0xbfb8aa3b, v41
	v_exp_f32_e32 v71, v70
	v_mul_f32_e32 v70, 0xbfb8aa3b, v42
	v_exp_f32_e32 v72, v70
	v_add_f32_e32 v69, 1.0, v69
	v_rcp_f32_e32 v70, v69
	v_add_f32_e32 v69, 1.0, v71
	v_rcp_f32_e32 v71, v69
	v_add_f32_e32 v69, 1.0, v72
	v_mul_f32_e32 v72, 0xbfb8aa3b, v43
	v_exp_f32_e32 v73, v72
	v_mul_f32_e32 v72, 0xbfb8aa3b, v36
	v_exp_f32_e32 v74, v72
	v_rcp_f32_e32 v72, v69
	v_add_f32_e32 v69, 1.0, v73
	v_rcp_f32_e32 v73, v69
	v_add_f32_e32 v69, 1.0, v74
	v_mul_f32_e32 v75, 0xbfb8aa3b, v38
	v_rcp_f32_e32 v74, v69
	v_mul_f32_e32 v69, 0xbfb8aa3b, v37
	v_exp_f32_e32 v75, v75
	v_mul_f32_e32 v76, 0xbfb8aa3b, v39
	v_exp_f32_e32 v69, v69
	v_exp_f32_e32 v77, v76
	v_add_f32_e32 v75, 1.0, v75
	v_rcp_f32_e32 v76, v75
	v_add_f32_e32 v69, 1.0, v69
	v_add_f32_e32 v75, 1.0, v77
	v_pk_mul_f32 v[70:71], v[40:41], v[70:71]
	v_rcp_f32_e32 v77, v75
	v_rcp_f32_e32 v75, v69
	v_pk_mul_f32 v[72:73], v[42:43], v[72:73]
	v_cvt_pk_bf16_f32 v70, v70, v71
	v_pk_mul_f32 v[74:75], v[36:37], v[74:75]
	v_cvt_pk_bf16_f32 v71, v72, v73
	v_pk_mul_f32 v[76:77], v[38:39], v[76:77]
	v_cvt_pk_bf16_f32 v72, v74, v75
	v_cvt_pk_bf16_f32 v73, v76, v77
	global_store_dwordx4 v[66:67], v[70:73], off
	s_and_b64 vcc, exec, s[12:13]
	s_mov_b64 s[12:13], -1
	s_cbranch_vccz .LBB0_617

; __device__ __forceinline__ unsigned pk2(float lo, float hi) { return f2bf(lo) | (f2bf(hi) << 16); }
; __device__ __forceinline__ void st16f(float* p, f32x4 v) { st16(p, __builtin_bit_cast(u32x4, v)); }
; __device__ __forceinline__ void st8bf(bf16_t* p, f32x4 a, f32x4 b) { u32x4 w; w.x = pk2(a[0], a[1]); w.y = pk2(a[2], a[3]); w.z = pk2(b[0], b[1]); w.w = pk2(b[2], b[3]); st16(p, w); }
;     __device__ __forceinline__ void st(int pn, int row, int c, f32x4 v0, f32x4 v1) const {
;     ...
;         else if (pn == 10) { float* o = nullptr;
;             if (!smp) { if (t >= SEQ - 512) o = out + O_WIN + ((size_t)b * 512 + (t - (SEQ - 512))) * 256 + c; } else o = out + O_WINS + ((size_t)b * 512 + 508 + t) * 256 + c;
;             st8bf(KW + (size_t)row * 256 + c, v0, v1); if (o) { st16f(o, v0); st16f(o + 4, v1); } }
.LBB0_661:
	s_andn2_saveexec_b64 s[76:77], s[76:77]
	v_lshl_add_u64 v[50:51], v[214:215], 0, v[46:47]
	s_or_b64 exec, exec, s[76:77]
	v_cvt_pk_bf16_f32 v52, v24, v25
	v_cvt_pk_bf16_f32 v53, v26, v27
	v_cvt_pk_bf16_f32 v54, v20, v21
	v_lshl_add_u64 v[56:57], v[208:209], 0, v[44:45]
	v_cvt_pk_bf16_f32 v55, v22, v23
	v_cmp_ne_u64_e32 vcc, 0, v[50:51]
	global_store_dwordx4 v[56:57], v[52:55], off
	s_and_saveexec_b64 s[76:77], vcc
	s_cbranch_execz .LBB0_665
	global_store_dwordx4 v[50:51], v[24:27], off
	global_store_dwordx4 v[50:51], v[20:23], off offset:16

; __device__ __forceinline__ unsigned pk2(float lo, float hi) { return f2bf(lo) | (f2bf(hi) << 16); }
; __device__ __forceinline__ void st16f(float* p, f32x4 v) { st16(p, __builtin_bit_cast(u32x4, v)); }
; __device__ __forceinline__ void st8bf(bf16_t* p, f32x4 a, f32x4 b) { u32x4 w; w.x = pk2(a[0], a[1]); w.y = pk2(a[2], a[3]); w.z = pk2(b[0], b[1]); w.w = pk2(b[2], b[3]); st16(p, w); }
;     __device__ __forceinline__ void st(int pn, int row, int c, f32x4 v0, f32x4 v1) const {
;     ...
;         else if (pn == 8) { float* o = (smp ? out + O_KCS + (size_t)(row - MP) * 256 : out + O_KC + (size_t)row * 256) + c; st16f(o, v0); st16f(o + 4, v1); }
;         else if (pn == 9) { float* o = (smp ? out + O_KSS + (size_t)(row - MP) * 256 : out + O_KSEL + (size_t)row * 256) + c; st16f(o, v0); st16f(o + 4, v1); st8bf(KS + (size_t)row * 256 + c, v0, v1); }
.LBB0_667:
	s_andn2_b64 vcc, exec, s[76:77]
	s_cbranch_vccnz .LBB0_669
	v_lshl_add_u64 v[50:51], s[36:37], 0, v[38:39]
	v_lshl_add_u64 v[52:53], s[38:39], 0, v[42:43]
	v_cndmask_b32_e64 v51, v51, v53, s[8:9]
	v_cndmask_b32_e64 v50, v50, v52, s[8:9]
	v_lshlrev_b32_e32 v52, 2, v206
	v_mov_b32_e32 v53, v1
	v_cndmask_b32_e64 v55, v37, 0, s[8:9]
	v_cndmask_b32_e64 v54, v36, v36, s[8:9]
	v_lshl_add_u64 v[50:51], v[50:51], 0, v[52:53]
	global_store_dwordx4 v[50:51], v[24:27], off
	global_store_dwordx4 v[50:51], v[20:23], off offset:16
	v_lshlrev_b64 v[50:51], 9, v[54:55]
	v_lshl_add_u64 v[54:55], v[210:211], 0, v[50:51]
	v_cvt_pk_bf16_f32 v50, v24, v25
	v_cvt_pk_bf16_f32 v51, v26, v27
	v_cvt_pk_bf16_f32 v52, v20, v21
	v_cvt_pk_bf16_f32 v53, v22, v23
	global_store_dwordx4 v[54:55], v[50:53], off

; __device__ __forceinline__ unsigned pk2(float lo, float hi) { return f2bf(lo) | (f2bf(hi) << 16); }
; __device__ __forceinline__ float sigmoidf_(float x) { return __builtin_amdgcn_rcpf(1.0f + __expf(-x)); }
; __device__ __forceinline__ void st8bf(bf16_t* p, f32x4 a, f32x4 b) { u32x4 w; w.x = pk2(a[0], a[1]); w.y = pk2(a[2], a[3]); w.z = pk2(b[0], b[1]); w.w = pk2(b[2], b[3]); st16(p, w); }
; __device__ __forceinline__ void stnt8(float* o, f32x4 a, f32x4 b) { __builtin_nontemporal_store(a, (f32x4*)o); __builtin_nontemporal_store(b, (f32x4*)(o + 4)); }
; __device__ __forceinline__ f32x4 sig4(f32x4 v) { f32x4 r; r[0] = sigmoidf_(v[0]); r[1] = sigmoidf_(v[1]); r[2] = sigmoidf_(v[2]); r[3] = sigmoidf_(v[3]); return r; }
;     __device__ __forceinline__ void st(int pn, int row, int c, f32x4 v0, f32x4 v1) const {
;         const bool smp = row >= MP; const int b = smp ? (row - MP) >> 2 : row >> 13, t = smp ? (row - MP) & 3 : row & (SEQ - 1);
;         if (pn < 6 || pn == 11 || pn == 12) st8bf((pn < 6 ? AG : BG) + (size_t)row * 512 + (pn < 6 ? pn - 4 : pn - 11) * 256 + c, v0 * sig4(v0), v1 * sig4(v1));
.LBB0_699:
	s_and_b64 s[76:77], s[66:67], exec
	s_cselect_b32 s77, s51, s79
	s_cselect_b32 s76, s33, s78
	v_lshl_add_u64 v[50:51], s[76:77], 0, v[38:39]
	v_mul_f32_e32 v52, 0xbfb8aa3b, v24
	v_lshl_add_u64 v[50:51], s[64:65], 1, v[50:51]
	v_exp_f32_e32 v56, v52
	v_lshlrev_b32_e32 v52, 1, v206
	v_mov_b32_e32 v53, v1
	v_lshl_add_u64 v[54:55], v[50:51], 0, v[52:53]
	v_mul_f32_e32 v51, 0xbfb8aa3b, v25
	v_exp_f32_e32 v51, v51
	v_mul_f32_e32 v52, 0xbfb8aa3b, v26
	v_mul_f32_e32 v53, 0xbfb8aa3b, v27
	v_exp_f32_e32 v52, v52
	v_exp_f32_e32 v53, v53
	v_add_f32_e32 v50, 1.0, v56
	v_add_f32_e32 v51, 1.0, v51
	v_rcp_f32_e32 v50, v50
	v_rcp_f32_e32 v51, v51
	v_mul_f32_e32 v56, 0xbfb8aa3b, v20
	v_mul_f32_e32 v57, 0xbfb8aa3b, v21
	v_exp_f32_e32 v56, v56
	v_exp_f32_e32 v57, v57
	v_add_f32_e32 v52, 1.0, v52
	v_add_f32_e32 v53, 1.0, v53
	v_rcp_f32_e32 v52, v52
	v_rcp_f32_e32 v53, v53
	v_mul_f32_e32 v58, 0xbfb8aa3b, v22
	v_mul_f32_e32 v59, 0xbfb8aa3b, v23
	v_exp_f32_e32 v58, v58
	v_exp_f32_e32 v59, v59
	v_pk_mul_f32 v[50:51], v[24:25], v[50:51]
	v_add_f32_e32 v56, 1.0, v56
	v_add_f32_e32 v57, 1.0, v57
	v_rcp_f32_e32 v56, v56
	v_rcp_f32_e32 v57, v57
	v_pk_mul_f32 v[52:53], v[26:27], v[52:53]
	v_add_f32_e32 v58, 1.0, v58
	v_add_f32_e32 v59, 1.0, v59
	v_cvt_pk_bf16_f32 v50, v50, v51
	v_rcp_f32_e32 v58, v58
	v_rcp_f32_e32 v59, v59
	v_pk_mul_f32 v[56:57], v[20:21], v[56:57]
	v_cvt_pk_bf16_f32 v51, v52, v53
	v_pk_mul_f32 v[58:59], v[22:23], v[58:59]
	v_cvt_pk_bf16_f32 v52, v56, v57
	v_cvt_pk_bf16_f32 v53, v58, v59
	global_store_dwordx4 v[54:55], v[50:53], off
	s_and_b64 vcc, exec, s[12:13]
	s_mov_b64 s[12:13], -1
	s_cbranch_vccz .LBB0_677

; __device__ __forceinline__ unsigned pk2(float lo, float hi) { return f2bf(lo) | (f2bf(hi) << 16); }
; __device__ __forceinline__ void st16f(float* p, f32x4 v) { st16(p, __builtin_bit_cast(u32x4, v)); }
; __device__ __forceinline__ void st8bf(bf16_t* p, f32x4 a, f32x4 b) { u32x4 w; w.x = pk2(a[0], a[1]); w.y = pk2(a[2], a[3]); w.z = pk2(b[0], b[1]); w.w = pk2(b[2], b[3]); st16(p, w); }
;     __device__ __forceinline__ void st(int pn, int row, int c, f32x4 v0, f32x4 v1) const {
;     ...
;         else if (pn == 10) { float* o = nullptr;
;             if (!smp) { if (t >= SEQ - 512) o = out + O_WIN + ((size_t)b * 512 + (t - (SEQ - 512))) * 256 + c; } else o = out + O_WINS + ((size_t)b * 512 + 508 + t) * 256 + c;
;             st8bf(KW + (size_t)row * 256 + c, v0, v1); if (o) { st16f(o, v0); st16f(o + 4, v1); } }
.LBB0_721:
	s_andn2_saveexec_b64 s[68:69], s[68:69]
	v_lshl_add_u64 v[34:35], v[214:215], 0, v[30:31]
	s_or_b64 exec, exec, s[68:69]
	v_cvt_pk_bf16_f32 v36, v8, v9
	v_cvt_pk_bf16_f32 v37, v10, v11
	v_cvt_pk_bf16_f32 v38, v4, v5
	v_lshl_add_u64 v[40:41], v[208:209], 0, v[28:29]
	v_cvt_pk_bf16_f32 v39, v6, v7
	v_cmp_ne_u64_e32 vcc, 0, v[34:35]
	global_store_dwordx4 v[40:41], v[36:39], off
	s_and_saveexec_b64 s[68:69], vcc
	s_cbranch_execz .LBB0_725
	global_store_dwordx4 v[34:35], v[8:11], off
	global_store_dwordx4 v[34:35], v[4:7], off offset:16

; __device__ __forceinline__ unsigned pk2(float lo, float hi) { return f2bf(lo) | (f2bf(hi) << 16); }
; __device__ __forceinline__ void st16f(float* p, f32x4 v) { st16(p, __builtin_bit_cast(u32x4, v)); }
; __device__ __forceinline__ void st8bf(bf16_t* p, f32x4 a, f32x4 b) { u32x4 w; w.x = pk2(a[0], a[1]); w.y = pk2(a[2], a[3]); w.z = pk2(b[0], b[1]); w.w = pk2(b[2], b[3]); st16(p, w); }
;     __device__ __forceinline__ void st(int pn, int row, int c, f32x4 v0, f32x4 v1) const {
;     ...
;         else if (pn == 8) { float* o = (smp ? out + O_KCS + (size_t)(row - MP) * 256 : out + O_KC + (size_t)row * 256) + c; st16f(o, v0); st16f(o + 4, v1); }
;         else if (pn == 9) { float* o = (smp ? out + O_KSS + (size_t)(row - MP) * 256 : out + O_KSEL + (size_t)row * 256) + c; st16f(o, v0); st16f(o + 4, v1); st8bf(KS + (size_t)row * 256 + c, v0, v1); }
.LBB0_727:
	s_andn2_b64 vcc, exec, s[68:69]
	s_cbranch_vccnz .LBB0_729
	v_lshl_add_u64 v[34:35], s[36:37], 0, v[22:23]
	v_lshl_add_u64 v[36:37], s[38:39], 0, v[26:27]
	v_cndmask_b32_e64 v35, v35, v37, s[8:9]
	v_cndmask_b32_e64 v34, v34, v36, s[8:9]
	v_lshlrev_b32_e32 v36, 2, v206
	v_mov_b32_e32 v37, v1
	v_cndmask_b32_e64 v39, v21, 0, s[8:9]
	v_cndmask_b32_e64 v38, v20, v20, s[8:9]
	v_lshl_add_u64 v[34:35], v[34:35], 0, v[36:37]
	global_store_dwordx4 v[34:35], v[8:11], off
	global_store_dwordx4 v[34:35], v[4:7], off offset:16
	v_lshlrev_b64 v[34:35], 9, v[38:39]
	v_lshl_add_u64 v[38:39], v[210:211], 0, v[34:35]
	v_cvt_pk_bf16_f32 v34, v8, v9
	v_cvt_pk_bf16_f32 v35, v10, v11
	v_cvt_pk_bf16_f32 v36, v4, v5
	v_cvt_pk_bf16_f32 v37, v6, v7
	global_store_dwordx4 v[38:39], v[34:37], off

; __device__ __forceinline__ unsigned pk2(float lo, float hi) { return f2bf(lo) | (f2bf(hi) << 16); }
; __device__ __forceinline__ float sigmoidf_(float x) { return __builtin_amdgcn_rcpf(1.0f + __expf(-x)); }
; __device__ __forceinline__ void st8bf(bf16_t* p, f32x4 a, f32x4 b) { u32x4 w; w.x = pk2(a[0], a[1]); w.y = pk2(a[2], a[3]); w.z = pk2(b[0], b[1]); w.w = pk2(b[2], b[3]); st16(p, w); }
; __device__ __forceinline__ void stnt8(float* o, f32x4 a, f32x4 b) { __builtin_nontemporal_store(a, (f32x4*)o); __builtin_nontemporal_store(b, (f32x4*)(o + 4)); }
; __device__ __forceinline__ f32x4 sig4(f32x4 v) { f32x4 r; r[0] = sigmoidf_(v[0]); r[1] = sigmoidf_(v[1]); r[2] = sigmoidf_(v[2]); r[3] = sigmoidf_(v[3]); return r; }
;     __device__ __forceinline__ void st(int pn, int row, int c, f32x4 v0, f32x4 v1) const {
;         const bool smp = row >= MP; const int b = smp ? (row - MP) >> 2 : row >> 13, t = smp ? (row - MP) & 3 : row & (SEQ - 1);
;         if (pn < 6 || pn == 11 || pn == 12) st8bf((pn < 6 ? AG : BG) + (size_t)row * 512 + (pn < 6 ? pn - 4 : pn - 11) * 256 + c, v0 * sig4(v0), v1 * sig4(v1));
.LBB0_769:
	s_and_b64 s[4:5], s[66:67], exec
	s_cselect_b32 s5, s51, s79
	s_cselect_b32 s4, s33, s78
	v_lshl_add_u64 v[22:23], s[4:5], 0, v[22:23]
	v_mul_f32_e32 v0, 0xbfb8aa3b, v16
	v_exp_f32_e32 v0, v0
	v_lshl_add_u64 v[22:23], s[64:65], 1, v[22:23]
	v_mov_b32_e32 v35, v1
	v_mul_f32_e32 v21, 0xbfb8aa3b, v17
	v_lshl_add_u64 v[26:27], v[22:23], 0, v[34:35]
	v_exp_f32_e32 v21, v21
	v_mul_f32_e32 v22, 0xbfb8aa3b, v18
	v_exp_f32_e32 v24, v22
	v_add_f32_e32 v0, 1.0, v0
	v_rcp_f32_e32 v22, v0
	v_add_f32_e32 v0, 1.0, v21
	v_mul_f32_e32 v21, 0xbfb8aa3b, v19
	v_rcp_f32_e32 v23, v0
	v_add_f32_e32 v0, 1.0, v24
	v_exp_f32_e32 v21, v21
	v_mul_f32_e32 v24, 0xbfb8aa3b, v12
	v_exp_f32_e32 v28, v24
	v_rcp_f32_e32 v24, v0
	v_add_f32_e32 v0, 1.0, v21
	v_rcp_f32_e32 v25, v0
	v_add_f32_e32 v0, 1.0, v28
	v_rcp_f32_e32 v28, v0
	v_mul_f32_e32 v0, 0xbfb8aa3b, v13
	v_mul_f32_e32 v21, 0xbfb8aa3b, v14
	v_exp_f32_e32 v0, v0
	v_exp_f32_e32 v21, v21
	v_mul_f32_e32 v29, 0xbfb8aa3b, v15
	v_exp_f32_e32 v29, v29
	v_add_f32_e32 v0, 1.0, v0
	v_add_f32_e32 v21, 1.0, v21
	v_pk_mul_f32 v[22:23], v[16:17], v[22:23]
	v_rcp_f32_e32 v30, v21
	v_add_f32_e32 v21, 1.0, v29
	v_rcp_f32_e32 v29, v0
	v_rcp_f32_e32 v31, v21
	v_pk_mul_f32 v[24:25], v[18:19], v[24:25]
	v_cvt_pk_bf16_f32 v22, v22, v23
	v_pk_mul_f32 v[28:29], v[12:13], v[28:29]
	v_cvt_pk_bf16_f32 v23, v24, v25
	v_pk_mul_f32 v[30:31], v[14:15], v[30:31]
	v_cvt_pk_bf16_f32 v24, v28, v29
	v_cvt_pk_bf16_f32 v25, v30, v31
	global_store_dwordx4 v[26:27], v[22:25], off offset:256

; #define LAS __attribute__((address_space(3)))
; __device__ __forceinline__ unsigned pk2(float lo, float hi) { return f2bf(lo) | (f2bf(hi) << 16); }
; __device__ __forceinline__ float siluf_(float x) { return x * sigmoidf_(x); }
; __device__ __forceinline__ void conv_unit_piped(const Prm& P, Ctx& C, int b, int t0, unsigned (&ur)[62], const float (&w)[31], const float bias, bool has_next, int nb, int nt0) {
;     ...
;     for (int rq = 0; rq < NRW; ++rq) {
;         const int i = C.wave + rq * NWAVES;
;         if (i < NT) {
;             const size_t row = (size_t)(row0 + i);
;             f32x4 v0 = *(const LAS f32x4*)(y + i * 512 + c8), v1 = *(const LAS f32x4*)(y + i * 512 + c8 + 4);
;             const float s = ((v0[0] + v0[1]) + (v0[2] + v0[3])) + ((v1[0] + v1[1]) + (v1[2] + v1[3]));
;             const float mean = wave_sum(s) * (1.f / 512.f);
;             v0 = v0 - mean; v1 = v1 - mean;
;             const float q2 = ((v0[0] * v0[0] + v0[1] * v0[1]) + (v0[2] * v0[2] + v0[3] * v0[3])) + ((v1[0] * v1[0] + v1[1] * v1[1]) + (v1[2] * v1[2] + v1[3] * v1[3]));
;             const float rstd = 1.f / sqrtf(wave_sum(q2) * (1.f / 512.f) + LN_EPS);
;             const u32x4 ag = agv[rq];
;             f32x4 z0 = v0 * rstd * g0 + b0, z1 = v1 * rstd * g1 + b1;
;             z0[0] = siluf_(z0[0]) * bflo(ag.x); z0[1] = siluf_(z0[1]) * bfhi(ag.x); z0[2] = siluf_(z0[2]) * bflo(ag.y); z0[3] = siluf_(z0[3]) * bfhi(ag.y);
;             z1[0] = siluf_(z1[0]) * bflo(ag.z); z1[1] = siluf_(z1[1]) * bfhi(ag.z); z1[2] = siluf_(z1[2]) * bflo(ag.w); z1[3] = siluf_(z1[3]) * bfhi(ag.w);
;             u32x4 o; o.x = pk2(z0[0], z0[1]); o.y = pk2(z0[2], z0[3]); o.z = pk2(z1[0], z1[1]); o.w = pk2(z1[2], z1[3]);
;             *(u32x4*)(H2 + row * 1024 + c8) = o;
;         }
;     }
.LBB0_987:
	s_waitcnt vmcnt(32)
	v_add_u32_e32 v28, s59, v162
	ds_read_b128 v[24:27], v28
	ds_read_b128 v[28:31], v28 offset:16
	s_waitcnt lgkmcnt(1)
	v_mov_b32_e32 v164, v24
	s_waitcnt lgkmcnt(0)
	v_mov_b32_e32 v165, v28
	v_mov_b32_e32 v166, v25
	v_mov_b32_e32 v167, v29
	v_pk_add_f32 v[164:165], v[164:165], v[166:167]
	v_mov_b32_e32 v166, v26
	v_mov_b32_e32 v167, v30
	v_mov_b32_e32 v168, v27
	v_mov_b32_e32 v169, v31
	v_pk_add_f32 v[166:167], v[166:167], v[168:169]
	s_nop 0
	v_pk_add_f32 v[164:165], v[164:165], v[166:167]
	s_nop 0
	v_add_f32_e32 v163, v164, v165
	v_mov_b32_e32 v164, 0
	s_nop 0
	v_add_f32_dpp v163, v163, v163 row_shr:1 row_mask:0xf bank_mask:0xf bound_ctrl:1
	s_nop 1
	v_add_f32_dpp v163, v163, v163 row_shr:2 row_mask:0xf bank_mask:0xf bound_ctrl:1
	s_nop 1
	v_add_f32_dpp v163, v163, v163 row_shr:4 row_mask:0xf bank_mask:0xf bound_ctrl:1
	s_nop 1
	v_add_f32_dpp v163, v163, v163 row_shr:8 row_mask:0xf bank_mask:0xf bound_ctrl:1
	s_nop 1
	v_mov_b32_dpp v164, v163 row_bcast:15 row_mask:0xa bank_mask:0xf
	v_add_f32_e32 v163, v163, v164
	v_mov_b32_e32 v164, 0
	s_nop 1
	v_mov_b32_dpp v164, v163 row_bcast:31 row_mask:0xc bank_mask:0xf
	v_add_f32_e32 v163, v163, v164
	s_nop 0
	v_readlane_b32 s2, v163, 63
	s_nop 1
	v_fma_f32 v27, s2, v187, v27
	v_fmac_f32_e32 v25, s2, v187
	v_fma_f32 v26, s2, v187, v26
	v_fma_f32 v24, s2, v187, v24
	v_mul_f32_e32 v163, v25, v25
	v_mul_f32_e32 v164, v27, v27
	v_fma_f32 v31, s2, v187, v31
	v_fmac_f32_e32 v29, s2, v187
	v_fmac_f32_e32 v163, v24, v24
	v_fmac_f32_e32 v164, v26, v26
	v_fma_f32 v30, s2, v187, v30
	v_fma_f32 v28, s2, v187, v28
	v_add_f32_e32 v163, v163, v164
	v_mul_f32_e32 v164, v29, v29
	v_mul_f32_e32 v165, v31, v31
	v_fmac_f32_e32 v164, v28, v28
	v_fmac_f32_e32 v165, v30, v30
	v_add_f32_e32 v164, v164, v165
	v_add_f32_e32 v163, v163, v164
	v_mov_b32_e32 v164, 0
	s_nop 0
	v_add_f32_dpp v163, v163, v163 row_shr:1 row_mask:0xf bank_mask:0xf bound_ctrl:1
	s_nop 1
	v_add_f32_dpp v163, v163, v163 row_shr:2 row_mask:0xf bank_mask:0xf bound_ctrl:1
	s_nop 1
	v_add_f32_dpp v163, v163, v163 row_shr:4 row_mask:0xf bank_mask:0xf bound_ctrl:1
	s_nop 1
	v_add_f32_dpp v163, v163, v163 row_shr:8 row_mask:0xf bank_mask:0xf bound_ctrl:1
	s_nop 1
	v_mov_b32_dpp v164, v163 row_bcast:15 row_mask:0xa bank_mask:0xf
	v_add_f32_e32 v163, v163, v164
	v_mov_b32_e32 v164, 0
	s_nop 1
	v_mov_b32_dpp v164, v163 row_bcast:31 row_mask:0xc bank_mask:0xf
	v_add_f32_e32 v163, v163, v164
	s_nop 0
	v_readlane_b32 s2, v163, 63
	s_nop 1
	v_fma_f32 v163, s2, v188, v185
	v_mul_f32_e32 v164, 0x4f800000, v163
	v_cmp_gt_f32_e32 vcc, s63, v163
	s_nop 1
	v_cndmask_b32_e32 v163, v163, v164, vcc
	v_sqrt_f32_e32 v164, v163
	s_nop 0
	v_add_u32_e32 v165, -1, v164
	v_fma_f32 v166, -v165, v164, v163
	v_cmp_ge_f32_e64 s[2:3], 0, v166
	v_add_u32_e32 v166, 1, v164
	s_nop 0
	v_cndmask_b32_e64 v165, v164, v165, s[2:3]
	v_fma_f32 v164, -v166, v164, v163
	v_cmp_lt_f32_e64 s[2:3], 0, v164
	s_nop 1
	v_cndmask_b32_e64 v164, v165, v166, s[2:3]
	v_mul_f32_e32 v165, 0x37800000, v164
	v_cndmask_b32_e32 v164, v164, v165, vcc
	v_cmp_class_f32_e32 vcc, v163, v186
	s_nop 1
	v_cndmask_b32_e32 v163, v164, v163, vcc
	v_div_scale_f32 v164, s[2:3], v163, v163, 1.0
	v_rcp_f32_e32 v165, v164
	s_or_b32 s2, s66, s58
	s_ashr_i32 s3, s2, 31
	s_lshl_b64 s[2:3], s[2:3], 11
	v_fma_f32 v166, -v164, v165, 1.0
	v_fmac_f32_e32 v165, v166, v165
	v_div_scale_f32 v166, vcc, 1.0, v163, 1.0
	v_mul_f32_e32 v167, v166, v165
	v_fma_f32 v168, -v164, v167, v166
	v_fmac_f32_e32 v167, v168, v165
	v_fma_f32 v164, -v164, v167, v166
	v_div_fmas_f32 v164, v164, v165, v167
	v_div_fixup_f32 v164, v164, v163, 1.0
	v_pk_mul_f32 v[24:25], v[24:25], v[164:165] op_sel_hi:[1,0]
	v_pk_mul_f32 v[26:27], v[26:27], v[164:165] op_sel_hi:[1,0]
	v_pk_fma_f32 v[24:25], v[8:9], v[24:25], v[12:13]
	v_pk_mul_f32 v[28:29], v[28:29], v[164:165] op_sel_hi:[1,0]
	v_mul_f32_e32 v163, 0xbfb8aa3b, v24
	v_pk_mul_f32 v[30:31], v[30:31], v[164:165] op_sel_hi:[1,0]
	v_exp_f32_e32 v163, v163
	v_mul_f32_e32 v164, 0xbfb8aa3b, v25
	v_exp_f32_e32 v165, v164
	v_pk_fma_f32 v[26:27], v[10:11], v[26:27], v[14:15]
	v_add_f32_e32 v163, 1.0, v163
	v_rcp_f32_e32 v164, v163
	v_add_f32_e32 v163, 1.0, v165
	v_mul_f32_e32 v165, 0xbfb8aa3b, v26
	v_exp_f32_e32 v165, v165
	v_mul_f32_e32 v166, 0xbfb8aa3b, v27
	v_exp_f32_e32 v167, v166
	v_pk_fma_f32 v[28:29], v[0:1], v[28:29], v[4:5]
	v_rcp_f32_e32 v166, v163
	v_add_f32_e32 v163, 1.0, v165
	v_rcp_f32_e32 v165, v163
	v_add_f32_e32 v163, 1.0, v167
	v_mul_f32_e32 v167, 0xbfb8aa3b, v28
	v_exp_f32_e32 v168, v167
	v_mul_f32_e32 v167, 0xbfb8aa3b, v29
	v_exp_f32_e32 v169, v167
	v_pk_fma_f32 v[30:31], v[2:3], v[30:31], v[6:7]
	v_rcp_f32_e32 v167, v163
	v_add_f32_e32 v163, 1.0, v168
	v_rcp_f32_e32 v168, v163
	v_add_f32_e32 v163, 1.0, v169
	v_mul_f32_e32 v169, 0xbfb8aa3b, v30
	v_exp_f32_e32 v169, v169
	v_mul_f32_e32 v170, 0xbfb8aa3b, v31
	v_exp_f32_e32 v171, v170
	v_rcp_f32_e32 v170, v163
	v_add_f32_e32 v163, 1.0, v169
	v_rcp_f32_e32 v169, v163
	v_add_f32_e32 v163, 1.0, v171
	v_rcp_f32_e32 v171, v163
	v_mov_b32_e32 v172, v24
	v_mov_b32_e32 v173, v26
	v_mov_b32_e32 v26, v25
	v_pk_mul_f32 v[164:165], v[172:173], v[164:165]
	v_lshlrev_b32_e32 v173, 16, v21
	v_lshlrev_b32_e32 v172, 16, v20
	v_pk_mul_f32 v[24:25], v[26:27], v[166:167]
	v_and_b32_e32 v21, 0xffff0000, v21
	v_and_b32_e32 v20, 0xffff0000, v20
	v_pk_mul_f32 v[20:21], v[24:25], v[20:21]
	v_mov_b32_e32 v24, v28
	v_mov_b32_e32 v25, v30
	v_pk_mul_f32 v[24:25], v[24:25], v[168:169]
	v_lshlrev_b32_e32 v27, 16, v23
	v_lshlrev_b32_e32 v26, 16, v22
	v_mov_b32_e32 v30, v29
	v_pk_mul_f32 v[24:25], v[24:25], v[26:27]
	v_pk_mul_f32 v[26:27], v[30:31], v[170:171]
	v_and_b32_e32 v23, 0xffff0000, v23
	v_and_b32_e32 v22, 0xffff0000, v22
	v_pk_mul_f32 v[22:23], v[26:27], v[22:23]
	v_pk_mul_f32 v[164:165], v[164:165], v[172:173]
	v_cvt_pk_bf16_f32 v23, v25, v23
	v_cvt_pk_bf16_f32 v22, v24, v22
	v_cvt_pk_bf16_f32 v21, v165, v21
	v_cvt_pk_bf16_f32 v20, v164, v20
	v_lshl_add_u64 v[24:25], v[98:99], 0, s[2:3]
	global_store_dwordx4 v[24:25], v[20:23], off
	s_and_b64 vcc, exec, s[0:1]
	s_cbranch_vccnz .LBB0_913
	s_branch .LBB0_991

; template <int NT, bool SMP>
; __device__ __forceinline__ void conv_body(const Prm& P, Ctx& C, int b, int t0) {
;     ...
;     float uu[30 + NT];
; #pragma unroll
;     for (int i = 0; i < 30 + NT; ++i) {
;         if (SMP) uu[i] = i < 30 ? P.state_conv[((size_t)b * 30 + i) * 512 + c] : bf2f(U[(size_t)(row0 + i - 30) * 512 + c]);
;         else { const int ti = t0 - 30 + i; uu[i] = ti >= 0 ? bf2f(U[(size_t)(row0 + i - 30) * 512 + c]) : 0.f; }
;     }
;     float w[31];
; #pragma unroll
;     for (int k = 0; k < 31; ++k) w[k] = P.conv_w[k * 512 + c];
;     const float bias = P.conv_b[c];
.LBB0_995:
	v_add_co_u32_e32 v66, vcc, 0x1000, v64
	s_ashr_i32 s7, s6, 31
	s_nop 0
	v_addc_co_u32_e32 v67, vcc, 0, v65, vcc
	v_add_co_u32_e32 v72, vcc, 0x2000, v64
	s_lshl_b64 s[0:1], s[6:7], 10
	s_nop 0
	v_addc_co_u32_e32 v73, vcc, 0, v65, vcc
	v_add_co_u32_e32 v74, vcc, 0x3000, v64
	s_waitcnt vmcnt(0)
	v_lshl_add_u64 v[94:95], v[0:1], 0, s[0:1]
	v_addc_co_u32_e32 v75, vcc, 0, v65, vcc
	v_add_co_u32_e32 v76, vcc, 0x4000, v64
	s_add_i32 s0, s6, 1
	s_nop 0
	v_addc_co_u32_e32 v77, vcc, 0, v65, vcc
	s_ashr_i32 s1, s0, 31
	global_load_dword v82, v[64:65], off
	global_load_dword v83, v[64:65], off offset:2048
	global_load_dword v70, v[66:67], off
	global_load_dword v71, v[66:67], off offset:2048
	global_load_dword v68, v[72:73], off
	global_load_dword v69, v[72:73], off offset:2048
	s_nop 0
	global_load_dword v66, v[74:75], off
	global_load_dword v67, v[74:75], off offset:2048
	global_load_dword v72, v[76:77], off
	global_load_dword v73, v[76:77], off offset:2048
	v_add_co_u32_e32 v74, vcc, 0x5000, v64
	s_lshl_b64 s[0:1], s[0:1], 10
	s_nop 0
	v_addc_co_u32_e32 v75, vcc, 0, v65, vcc
	v_lshl_add_u64 v[96:97], v[0:1], 0, s[0:1]
	s_add_i32 s0, s6, 2
	v_add_co_u32_e32 v80, vcc, 0x6000, v64
	s_ashr_i32 s1, s0, 31
	s_nop 0
	v_addc_co_u32_e32 v81, vcc, 0, v65, vcc
	s_lshl_b64 s[0:1], s[0:1], 10
	v_add_co_u32_e32 v90, vcc, s16, v64
	v_lshl_add_u64 v[98:99], v[0:1], 0, s[0:1]
	s_add_i32 s0, s6, 3
	v_addc_co_u32_e32 v91, vcc, 0, v65, vcc
	s_ashr_i32 s1, s0, 31
	v_add_co_u32_e32 v92, vcc, 0x8000, v64
	s_lshl_b64 s[0:1], s[0:1], 10
	s_nop 0
	v_addc_co_u32_e32 v93, vcc, 0, v65, vcc
	global_load_dword v78, v[74:75], off
	global_load_dword v79, v[74:75], off offset:2048
	global_load_dword v76, v[80:81], off
	global_load_dword v77, v[80:81], off offset:2048
	s_nop 0
	global_load_dword v74, v[90:91], off
	global_load_dword v75, v[90:91], off offset:2048
	global_load_dword v80, v[92:93], off
	global_load_dword v81, v[92:93], off offset:2048
	v_lshl_add_u64 v[100:101], v[0:1], 0, s[0:1]
	global_load_ushort v89, v[94:95], off
	global_load_ushort v105, v[96:97], off
	global_load_ushort v107, v[98:99], off
	global_load_ushort v109, v[100:101], off
	v_add_co_u32_e32 v90, vcc, 0x9000, v64
	s_waitcnt vmcnt(19)
	v_mov_b32_e32 v175, v70
	v_addc_co_u32_e32 v91, vcc, 0, v65, vcc
	v_add_co_u32_e32 v92, vcc, 0xa000, v64
	s_waitcnt vmcnt(18)
	v_mov_b32_e32 v176, v71
	v_addc_co_u32_e32 v93, vcc, 0, v65, vcc
	v_add_co_u32_e32 v94, vcc, 0xb000, v64
	v_mov_b32_e32 v174, v83
	s_nop 0
	v_addc_co_u32_e32 v95, vcc, 0, v65, vcc
	v_add_co_u32_e32 v96, vcc, 0xc000, v64
	s_waitcnt vmcnt(17)
	v_mov_b32_e32 v177, v68
	v_addc_co_u32_e32 v97, vcc, 0, v65, vcc
	global_load_dword v98, v[90:91], off
	global_load_dword v99, v[90:91], off offset:2048
	s_nop 0
	global_load_dword v90, v[92:93], off
	global_load_dword v91, v[92:93], off offset:2048
	s_nop 0
	global_load_dword v92, v[94:95], off
	global_load_dword v93, v[94:95], off offset:2048
	s_nop 0
	global_load_dword v94, v[96:97], off
	global_load_dword v95, v[96:97], off offset:2048
	v_add_co_u32_e32 v96, vcc, 0xd000, v64
	s_waitcnt vmcnt(24)
	v_mov_b32_e32 v178, v69
	v_addc_co_u32_e32 v97, vcc, 0, v65, vcc
	v_add_co_u32_e32 v100, vcc, 0xe000, v64
	s_waitcnt vmcnt(23)
	v_mov_b32_e32 v179, v66
	v_addc_co_u32_e32 v101, vcc, 0, v65, vcc
	global_load_dword v102, v[96:97], off
	global_load_dword v103, v[96:97], off offset:2048
	s_nop 0
	global_load_dword v96, v[100:101], off
	global_load_dword v97, v[100:101], off offset:2048
	s_nop 0
	global_load_dword v100, v[62:63], off
	global_load_dword v104, v[2:3], off
	global_load_dword v106, v[2:3], off offset:2048
	global_load_dword v108, v[4:5], off
	global_load_dword v110, v[6:7], off
	global_load_dword v112, v[8:9], off
	global_load_dword v114, v[10:11], off
	global_load_dword v116, v[12:13], off
	global_load_dword v118, v[14:15], off
	global_load_dword v122, v[16:17], off
	global_load_dword v124, v[18:19], off
	global_load_dword v126, v[20:21], off
	global_load_dword v128, v[22:23], off
	global_load_dword v130, v[24:25], off
	global_load_dword v132, v[26:27], off
	global_load_dword v134, v[28:29], off
	global_load_dword v136, v[30:31], off
	global_load_dword v138, v[32:33], off
	global_load_dword v140, v[34:35], off
	global_load_dword v142, v[36:37], off
	global_load_dword v144, v[38:39], off
	global_load_dword v146, v[40:41], off
	global_load_dword v148, v[42:43], off
	global_load_dword v150, v[44:45], off
	global_load_dword v152, v[46:47], off
	global_load_dword v154, v[48:49], off
	global_load_dword v156, v[50:51], off
	global_load_dword v158, v[52:53], off
	global_load_dword v160, v[54:55], off
	global_load_dword v162, v[56:57], off
	global_load_dword v164, v[58:59], off
	global_load_dword v166, v[60:61], off
	s_waitcnt vmcnt(58)
	v_mov_b32_e32 v180, v67
	s_waitcnt vmcnt(57)
	v_mov_b32_e32 v181, v72
	s_waitcnt vmcnt(56)
	v_mov_b32_e32 v182, v73
	s_waitcnt vmcnt(55)
	v_mov_b32_e32 v183, v78
	s_waitcnt vmcnt(54)
	v_mov_b32_e32 v184, v79
	s_waitcnt vmcnt(53)
	v_mov_b32_e32 v185, v76
	s_waitcnt vmcnt(52)
	v_mov_b32_e32 v186, v77
	s_waitcnt vmcnt(51)
	v_mov_b32_e32 v187, v74
	s_waitcnt vmcnt(50)
	v_mov_b32_e32 v188, v75
	s_waitcnt vmcnt(49)
	v_mov_b32_e32 v189, v80
	s_waitcnt vmcnt(48)
	v_mov_b32_e32 v190, v81
	s_waitcnt vmcnt(47)
	v_lshlrev_b32_e32 v168, 16, v89
	s_waitcnt vmcnt(46)
	v_lshlrev_b32_e32 v170, 16, v105
	v_mov_b32_e32 v203, v168
	v_mov_b32_e32 v169, v170
	s_waitcnt vmcnt(45)
	v_lshlrev_b32_e32 v171, 16, v107
	s_waitcnt vmcnt(44)
	v_lshlrev_b32_e32 v173, 16, v109
	v_mov_b32_e32 v172, v171
	s_andn2_b64 vcc, exec, s[2:3]
	s_waitcnt vmcnt(35)
	v_mov_b32_e32 v199, v102
	s_waitcnt vmcnt(34)
; template <int NT, bool SMP>
; __device__ __forceinline__ void conv_body(const Prm& P, Ctx& C, int b, int t0) {
;     ...
;     if constexpr ((NT & 1) == 0 && CONV_PK) {
;         constexpr int HB = NT >= 8 ? 8 : NT;
; #pragma unroll
;         for (int h0 = 0; h0 < NT; h0 += HB) {
;             f32x2 ue[(30 + HB) / 2], uo[(30 + HB) / 2 - 1];
; #pragma unroll
;             for (int j = 0; j < (30 + HB) / 2; ++j) ue[j] = (f32x2){uu[h0 + 2 * j], uu[h0 + 2 * j + 1]};
; #pragma unroll
;             for (int j = 0; j < (30 + HB) / 2 - 1; ++j) uo[j] = (f32x2){uu[h0 + 2 * j + 1], uu[h0 + 2 * j + 2]};
; #pragma unroll
;             for (int i = 0; i < HB; i += 2) { f32x2 a = (f32x2){bias, bias};
; #pragma unroll
;                 for (int k = 0; k < 31; ++k) { const f32x2 wk = (f32x2){w[k], w[k]}; a = __builtin_elementwise_fma(wk, ((i + k) & 1) ? uo[(i + k - 1) / 2] : ue[(i + k) / 2], a); }
;                 y[(h0 + i) * 512 + c] = a[0]; y[(h0 + i + 1) * 512 + c] = a[1]; }
;             asm volatile("" ::: "memory");
;         }
	v_mov_b32_e32 v200, v103
	s_waitcnt vmcnt(33)
	v_mov_b32_e32 v201, v96
	s_waitcnt vmcnt(32)
	v_mov_b32_e32 v202, v97
	s_waitcnt vmcnt(30)
	v_pk_fma_f32 v[82:83], v[104:105], v[82:83], v[100:101] op_sel_hi:[0,1,0]
	s_waitcnt vmcnt(29)
	v_pk_fma_f32 v[82:83], v[106:107], v[174:175], v[82:83] op_sel_hi:[0,1,1]
	s_waitcnt vmcnt(28)
	v_pk_fma_f32 v[82:83], v[108:109], v[70:71], v[82:83] op_sel_hi:[0,1,1]
	v_pk_fma_f32 v[70:71], v[104:105], v[70:71], v[100:101] op_sel_hi:[0,1,0]
	s_waitcnt vmcnt(27)
	v_pk_fma_f32 v[82:83], v[110:111], v[176:177], v[82:83] op_sel_hi:[0,1,1]
	v_pk_fma_f32 v[70:71], v[106:107], v[176:177], v[70:71] op_sel_hi:[0,1,1]
	s_waitcnt vmcnt(26)
	v_pk_fma_f32 v[82:83], v[112:113], v[68:69], v[82:83] op_sel_hi:[0,1,1]
	v_pk_fma_f32 v[68:69], v[108:109], v[68:69], v[70:71] op_sel_hi:[0,1,1]
	s_waitcnt vmcnt(25)
	v_pk_fma_f32 v[82:83], v[114:115], v[178:179], v[82:83] op_sel_hi:[0,1,1]
	v_pk_fma_f32 v[68:69], v[110:111], v[178:179], v[68:69] op_sel_hi:[0,1,1]
	s_waitcnt vmcnt(24)
	v_pk_fma_f32 v[82:83], v[116:117], v[66:67], v[82:83] op_sel_hi:[0,1,1]
	v_pk_fma_f32 v[66:67], v[112:113], v[66:67], v[68:69] op_sel_hi:[0,1,1]
	v_pk_fma_f32 v[66:67], v[114:115], v[180:181], v[66:67] op_sel_hi:[0,1,1]
	v_pk_fma_f32 v[66:67], v[116:117], v[72:73], v[66:67] op_sel_hi:[0,1,1]
	s_waitcnt vmcnt(23)
	v_pk_fma_f32 v[82:83], v[118:119], v[180:181], v[82:83] op_sel_hi:[0,1,1]
	v_pk_fma_f32 v[66:67], v[118:119], v[182:183], v[66:67] op_sel_hi:[0,1,1]
	s_waitcnt vmcnt(22)
	v_pk_fma_f32 v[82:83], v[122:123], v[72:73], v[82:83] op_sel_hi:[0,1,1]
	v_pk_fma_f32 v[66:67], v[122:123], v[78:79], v[66:67] op_sel_hi:[0,1,1]
	s_waitcnt vmcnt(21)
	v_pk_fma_f32 v[82:83], v[124:125], v[182:183], v[82:83] op_sel_hi:[0,1,1]
	v_pk_fma_f32 v[66:67], v[124:125], v[184:185], v[66:67] op_sel_hi:[0,1,1]
	s_waitcnt vmcnt(20)
	v_pk_fma_f32 v[82:83], v[126:127], v[78:79], v[82:83] op_sel_hi:[0,1,1]
	v_pk_fma_f32 v[66:67], v[126:127], v[76:77], v[66:67] op_sel_hi:[0,1,1]
	s_waitcnt vmcnt(19)
	v_pk_fma_f32 v[82:83], v[128:129], v[184:185], v[82:83] op_sel_hi:[0,1,1]
	v_pk_fma_f32 v[66:67], v[128:129], v[186:187], v[66:67] op_sel_hi:[0,1,1]
	s_waitcnt vmcnt(18)
	v_pk_fma_f32 v[82:83], v[130:131], v[76:77], v[82:83] op_sel_hi:[0,1,1]
	v_pk_fma_f32 v[66:67], v[130:131], v[74:75], v[66:67] op_sel_hi:[0,1,1]
	s_waitcnt vmcnt(17)
	v_pk_fma_f32 v[82:83], v[132:133], v[186:187], v[82:83] op_sel_hi:[0,1,1]
	v_pk_fma_f32 v[66:67], v[132:133], v[188:189], v[66:67] op_sel_hi:[0,1,1]
	v_mov_b32_e32 v191, v98
	s_waitcnt vmcnt(16)
	v_pk_fma_f32 v[82:83], v[134:135], v[74:75], v[82:83] op_sel_hi:[0,1,1]
	v_pk_fma_f32 v[66:67], v[134:135], v[80:81], v[66:67] op_sel_hi:[0,1,1]
	s_waitcnt vmcnt(15)
	v_pk_fma_f32 v[82:83], v[136:137], v[188:189], v[82:83] op_sel_hi:[0,1,1]
	v_pk_fma_f32 v[66:67], v[136:137], v[190:191], v[66:67] op_sel_hi:[0,1,1]
	v_mov_b32_e32 v192, v99
	v_mov_b32_e32 v193, v90
	s_waitcnt vmcnt(14)
	v_pk_fma_f32 v[82:83], v[138:139], v[80:81], v[82:83] op_sel_hi:[0,1,1]
	v_pk_fma_f32 v[66:67], v[138:139], v[98:99], v[66:67] op_sel_hi:[0,1,1]
	s_waitcnt vmcnt(13)
	v_pk_fma_f32 v[82:83], v[140:141], v[190:191], v[82:83] op_sel_hi:[0,1,1]
	v_pk_fma_f32 v[66:67], v[140:141], v[192:193], v[66:67] op_sel_hi:[0,1,1]
	v_mov_b32_e32 v194, v91
	v_mov_b32_e32 v195, v92
	s_waitcnt vmcnt(12)
	v_pk_fma_f32 v[82:83], v[142:143], v[98:99], v[82:83] op_sel_hi:[0,1,1]
	v_pk_fma_f32 v[66:67], v[142:143], v[90:91], v[66:67] op_sel_hi:[0,1,1]
	s_waitcnt vmcnt(11)
	v_pk_fma_f32 v[82:83], v[144:145], v[192:193], v[82:83] op_sel_hi:[0,1,1]
	v_pk_fma_f32 v[66:67], v[144:145], v[194:195], v[66:67] op_sel_hi:[0,1,1]
	v_mov_b32_e32 v196, v93
	v_mov_b32_e32 v197, v94
	s_waitcnt vmcnt(10)
	v_pk_fma_f32 v[82:83], v[146:147], v[90:91], v[82:83] op_sel_hi:[0,1,1]
	v_pk_fma_f32 v[66:67], v[146:147], v[92:93], v[66:67] op_sel_hi:[0,1,1]
	s_waitcnt vmcnt(9)
	v_pk_fma_f32 v[82:83], v[148:149], v[194:195], v[82:83] op_sel_hi:[0,1,1]
	v_pk_fma_f32 v[66:67], v[148:149], v[196:197], v[66:67] op_sel_hi:[0,1,1]
	v_mov_b32_e32 v198, v95
	s_waitcnt vmcnt(8)
	v_pk_fma_f32 v[82:83], v[150:151], v[92:93], v[82:83] op_sel_hi:[0,1,1]
	v_pk_fma_f32 v[66:67], v[150:151], v[94:95], v[66:67] op_sel_hi:[0,1,1]
	s_waitcnt vmcnt(7)
	v_pk_fma_f32 v[82:83], v[152:153], v[196:197], v[82:83] op_sel_hi:[0,1,1]
	v_pk_fma_f32 v[66:67], v[152:153], v[198:199], v[66:67] op_sel_hi:[0,1,1]
	s_waitcnt vmcnt(6)
	v_pk_fma_f32 v[82:83], v[154:155], v[94:95], v[82:83] op_sel_hi:[0,1,1]
	v_pk_fma_f32 v[66:67], v[154:155], v[102:103], v[66:67] op_sel_hi:[0,1,1]
	s_waitcnt vmcnt(5)
	v_pk_fma_f32 v[82:83], v[156:157], v[198:199], v[82:83] op_sel_hi:[0,1,1]
	v_pk_fma_f32 v[66:67], v[156:157], v[200:201], v[66:67] op_sel_hi:[0,1,1]
	s_waitcnt vmcnt(4)
	v_pk_fma_f32 v[82:83], v[158:159], v[102:103], v[82:83] op_sel_hi:[0,1,1]
	v_pk_fma_f32 v[66:67], v[158:159], v[96:97], v[66:67] op_sel_hi:[0,1,1]
	s_waitcnt vmcnt(3)
	v_pk_fma_f32 v[82:83], v[160:161], v[200:201], v[82:83] op_sel_hi:[0,1,1]
	v_pk_fma_f32 v[66:67], v[160:161], v[202:203], v[66:67] op_sel_hi:[0,1,1]
	s_waitcnt vmcnt(2)
	v_pk_fma_f32 v[82:83], v[162:163], v[96:97], v[82:83] op_sel_hi:[0,1,1]
	v_pk_fma_f32 v[66:67], v[162:163], v[168:169], v[66:67] op_sel_hi:[0,1,1]
	s_waitcnt vmcnt(1)
	v_pk_fma_f32 v[82:83], v[164:165], v[202:203], v[82:83] op_sel_hi:[0,1,1]
	v_pk_fma_f32 v[66:67], v[164:165], v[170:171], v[66:67] op_sel_hi:[0,1,1]
	s_waitcnt vmcnt(0)
	v_pk_fma_f32 v[82:83], v[166:167], v[168:169], v[82:83] op_sel_hi:[0,1,1]
	v_pk_fma_f32 v[66:67], v[166:167], v[172:173], v[66:67] op_sel_hi:[0,1,1]
	ds_write2st64_b32 v84, v82, v83 offset1:8
	ds_write2st64_b32 v84, v66, v67 offset0:16 offset1:24
	s_waitcnt lgkmcnt(0)
	s_barrier
; template <int NT, bool SMP>
; __device__ __forceinline__ void conv_body(const Prm& P, Ctx& C, int b, int t0) {
;     ...
;     __syncthreads();
;     const bf16_t* AG = (const bf16_t*)(P.ws + WS_AG); bf16_t* H2 = (bf16_t*)(P.ws + WS_H2);
;     int l8_; asm volatile("v_mbcnt_lo_u32_b32 %0, -1, 0\n\tv_mbcnt_hi_u32_b32 %0, -1, %0" : "=v"(l8_));
;     const int c8 = 8 * l8_;
	v_mbcnt_lo_u32_b32 v66, -1, 0
	v_mbcnt_hi_u32_b32 v66, -1, v66
	s_cbranch_vccnz .LBB0_994
; #define LAS __attribute__((address_space(3)))
; __device__ __forceinline__ unsigned pk2(float lo, float hi) { return f2bf(lo) | (f2bf(hi) << 16); }
; template <int NT, bool SMP>
; __device__ __forceinline__ void conv_body(const Prm& P, Ctx& C, int b, int t0) {
;     ...
;     const bf16_t* AG = (const bf16_t*)(P.ws + WS_AG); bf16_t* H2 = (bf16_t*)(P.ws + WS_H2);
;     int l8_; asm volatile("v_mbcnt_lo_u32_b32 %0, -1, 0\n\tv_mbcnt_hi_u32_b32 %0, -1, %0" : "=v"(l8_));
;     const int c8 = 8 * l8_;
;     const f32x4 g0 = *(const f32x4*)(P.conv_ln_g + c8), g1 = *(const f32x4*)(P.conv_ln_g + c8 + 4), b0 = *(const f32x4*)(P.conv_ln_b + c8), b1 = *(const f32x4*)(P.conv_ln_b + c8 + 4);
;     constexpr int NRW = (NT + NWAVES - 1) / NWAVES;
;     u32x4 agv[NRW];
; #pragma unroll
;     for (int rq = 0; rq < NRW; ++rq) { const int i = C.wave + rq * NWAVES; agv[rq] = i < NT ? *(const u32x4*)(AG + (size_t)(row0 + i) * 512 + c8) : (u32x4){0u, 0u, 0u, 0u}; }
; #pragma unroll
;     for (int rq = 0; rq < NRW; ++rq) {
;         const int i = C.wave + rq * NWAVES;
;         if (i < NT) {
;             const size_t row = (size_t)(row0 + i);
;             f32x4 v0 = *(const LAS f32x4*)(y + i * 512 + c8), v1 = *(const LAS f32x4*)(y + i * 512 + c8 + 4);
;             const float s = ((v0[0] + v0[1]) + (v0[2] + v0[3])) + ((v1[0] + v1[1]) + (v1[2] + v1[3]));
;             const float mean = wave_sum(s) * (1.f / 512.f);
;             v0 = v0 - mean; v1 = v1 - mean;
;             const float q2 = ((v0[0] * v0[0] + v0[1] * v0[1]) + (v0[2] * v0[2] + v0[3] * v0[3])) + ((v1[0] * v1[0] + v1[1] * v1[1]) + (v1[2] * v1[2] + v1[3] * v1[3]));
;             const float rstd = 1.f / sqrtf(wave_sum(q2) * (1.f / 512.f) + LN_EPS);
;             const u32x4 ag = agv[rq];
;             f32x4 z0 = v0 * rstd * g0 + b0, z1 = v1 * rstd * g1 + b1;
;             z0[0] = siluf_(z0[0]) * bflo(ag.x); z0[1] = siluf_(z0[1]) * bfhi(ag.x); z0[2] = siluf_(z0[2]) * bflo(ag.y); z0[3] = siluf_(z0[3]) * bfhi(ag.y);
;             z1[0] = siluf_(z1[0]) * bflo(ag.z); z1[1] = siluf_(z1[1]) * bfhi(ag.z); z1[2] = siluf_(z1[2]) * bflo(ag.w); z1[3] = siluf_(z1[3]) * bfhi(ag.w);
;             u32x4 o; o.x = pk2(z0[0], z0[1]); o.y = pk2(z0[2], z0[3]); o.z = pk2(z1[0], z1[1]); o.w = pk2(z1[2], z1[3]);
;             *(u32x4*)(H2 + row * 1024 + c8) = o;
;         }
;     }
	v_readlane_b32 s36, v250, 32
	v_lshlrev_b32_e32 v90, 3, v66
	v_readlane_b32 s44, v250, 40
	v_readlane_b32 s45, v250, 41
	v_ashrrev_i32_e32 v91, 31, v90
	v_readlane_b32 s46, v250, 42
	v_readlane_b32 s47, v250, 43
	s_mov_b64 s[20:21], s[44:45]
	v_lshlrev_b64 v[76:77], 2, v[90:91]
	s_mov_b64 s[22:23], s[46:47]
	v_lshl_add_u64 v[72:73], s[22:23], 0, v[76:77]
	v_lshl_add_u64 v[80:81], s[20:21], 0, v[76:77]
	global_load_dwordx4 v[68:71], v[72:73], off offset:16
	s_nop 0
	global_load_dwordx4 v[72:75], v[72:73], off
	s_nop 0
	global_load_dwordx4 v[76:79], v[80:81], off offset:16
	s_nop 0
	global_load_dwordx4 v[80:83], v[80:81], off
	s_add_i32 s8, s96, s6
	v_lshlrev_b64 v[102:103], 1, v[90:91]
	s_ashr_i32 s9, s8, 31
	v_lshl_add_u32 v66, v66, 5, s26
	v_lshl_add_u64 v[98:99], s[28:29], 0, v[102:103]
	ds_read_b128 v[90:93], v66
	ds_read_b128 v[94:97], v66 offset:16
	s_lshl_b64 s[0:1], s[8:9], 10
	v_lshl_add_u64 v[66:67], v[98:99], 0, s[0:1]
	global_load_dwordx4 v[98:101], v[66:67], off
	s_waitcnt lgkmcnt(1)
	v_mov_b32_e32 v66, v90
	s_waitcnt lgkmcnt(0)
	v_mov_b32_e32 v67, v94
	v_mov_b32_e32 v104, v91
	v_mov_b32_e32 v105, v95
	v_pk_add_f32 v[66:67], v[66:67], v[104:105]
	v_mov_b32_e32 v104, v92
	v_mov_b32_e32 v105, v96
	v_mov_b32_e32 v106, v93
	v_mov_b32_e32 v107, v97
	v_pk_add_f32 v[104:105], v[104:105], v[106:107]
	v_readlane_b32 s37, v250, 33
	v_pk_add_f32 v[66:67], v[66:67], v[104:105]
	v_readlane_b32 s38, v250, 34
	v_add_f32_e32 v66, v66, v67
	v_mov_b32_e32 v67, 0
	v_readlane_b32 s39, v250, 35
	v_add_f32_dpp v66, v66, v66 row_shr:1 row_mask:0xf bank_mask:0xf bound_ctrl:1
	v_readlane_b32 s40, v250, 36
	v_readlane_b32 s41, v250, 37
	v_add_f32_dpp v66, v66, v66 row_shr:2 row_mask:0xf bank_mask:0xf bound_ctrl:1
	v_readlane_b32 s42, v250, 38
	v_readlane_b32 s43, v250, 39
	v_add_f32_dpp v66, v66, v66 row_shr:4 row_mask:0xf bank_mask:0xf bound_ctrl:1
	v_readlane_b32 s48, v250, 44
	v_readlane_b32 s49, v250, 45
	v_add_f32_dpp v66, v66, v66 row_shr:8 row_mask:0xf bank_mask:0xf bound_ctrl:1
	v_readlane_b32 s50, v250, 46
	v_readlane_b32 s51, v250, 47
	v_mov_b32_dpp v67, v66 row_bcast:15 row_mask:0xa bank_mask:0xf
	v_add_f32_e32 v66, v66, v67
	v_mov_b32_e32 v67, 0
	s_nop 1
	v_mov_b32_dpp v67, v66 row_bcast:31 row_mask:0xc bank_mask:0xf
	v_add_f32_e32 v66, v66, v67
	s_nop 0
	v_readlane_b32 s0, v66, 63
	s_nop 1
	v_fma_f32 v67, s0, v87, v93
	v_fmac_f32_e32 v91, s0, v87
	v_fma_f32 v66, s0, v87, v92
	v_fma_f32 v90, s0, v87, v90
	v_fma_f32 v92, s0, v87, v96
	v_mul_f32_e32 v89, v91, v91
	v_mul_f32_e32 v96, v67, v67
	v_fma_f32 v93, s0, v87, v97
	v_fmac_f32_e32 v95, s0, v87
	v_fmac_f32_e32 v89, v90, v90
	v_fmac_f32_e32 v96, v66, v66
	v_fma_f32 v94, s0, v87, v94
	v_add_f32_e32 v89, v89, v96
	v_mul_f32_e32 v96, v95, v95
	v_mul_f32_e32 v97, v93, v93
	v_fmac_f32_e32 v96, v94, v94
	v_fmac_f32_e32 v97, v92, v92
	v_add_f32_e32 v96, v96, v97
	v_add_f32_e32 v89, v89, v96
	v_mov_b32_e32 v96, 0
	s_nop 0
	v_add_f32_dpp v89, v89, v89 row_shr:1 row_mask:0xf bank_mask:0xf bound_ctrl:1
	s_nop 1
	v_add_f32_dpp v89, v89, v89 row_shr:2 row_mask:0xf bank_mask:0xf bound_ctrl:1
	s_nop 1
	v_add_f32_dpp v89, v89, v89 row_shr:4 row_mask:0xf bank_mask:0xf bound_ctrl:1
	s_nop 1
	v_add_f32_dpp v89, v89, v89 row_shr:8 row_mask:0xf bank_mask:0xf bound_ctrl:1
	s_nop 1
	v_mov_b32_dpp v96, v89 row_bcast:15 row_mask:0xa bank_mask:0xf
	v_add_f32_e32 v89, v89, v96
	v_mov_b32_e32 v96, 0
	s_nop 1
	v_mov_b32_dpp v96, v89 row_bcast:31 row_mask:0xc bank_mask:0xf
	v_add_f32_e32 v89, v89, v96
	s_nop 0
	v_readlane_b32 s0, v89, 63
	s_nop 1
	v_fma_f32 v89, s0, v88, v85
	v_mul_f32_e32 v96, 0x4f800000, v89
	v_cmp_gt_f32_e32 vcc, s18, v89
	s_nop 1
	v_cndmask_b32_e32 v89, v89, v96, vcc
	v_sqrt_f32_e32 v96, v89
	s_nop 0
	v_add_u32_e32 v97, -1, v96
	v_fma_f32 v104, -v97, v96, v89
	v_cmp_ge_f32_e64 s[0:1], 0, v104
	v_add_u32_e32 v104, 1, v96
	s_nop 0
	v_cndmask_b32_e64 v97, v96, v97, s[0:1]
	v_fma_f32 v96, -v104, v96, v89
	v_cmp_lt_f32_e64 s[0:1], 0, v96
	s_nop 1
	v_cndmask_b32_e64 v96, v97, v104, s[0:1]
	v_mul_f32_e32 v97, 0x37800000, v96
	v_cndmask_b32_e32 v96, v96, v97, vcc
	v_cmp_class_f32_e32 vcc, v89, v86
	s_nop 1
	v_cndmask_b32_e32 v89, v96, v89, vcc
	v_div_scale_f32 v104, s[0:1], v89, v89, 1.0
	v_rcp_f32_e32 v105, v104
	v_lshl_add_u64 v[96:97], s[30:31], 0, v[102:103]
	s_lshl_b64 s[0:1], s[8:9], 11
	v_fma_f32 v102, -v104, v105, 1.0
	v_fmac_f32_e32 v105, v102, v105
	v_div_scale_f32 v102, vcc, 1.0, v89, 1.0
	v_mul_f32_e32 v103, v102, v105
	v_fma_f32 v106, -v104, v103, v102
	v_fmac_f32_e32 v103, v106, v105
	v_fma_f32 v102, -v104, v103, v102
	v_div_fmas_f32 v102, v102, v105, v103
	v_div_fixup_f32 v102, v102, v89, 1.0
	v_pk_mul_f32 v[90:91], v[90:91], v[102:103] op_sel_hi:[1,0]
	v_pk_mul_f32 v[66:67], v[66:67], v[102:103] op_sel_hi:[1,0]
	s_waitcnt vmcnt(1)
	v_pk_fma_f32 v[72:73], v[80:81], v[90:91], v[72:73]
	v_pk_mul_f32 v[80:81], v[92:93], v[102:103] op_sel_hi:[1,0]
	v_pk_fma_f32 v[66:67], v[82:83], v[66:67], v[74:75]
	v_pk_fma_f32 v[70:71], v[78:79], v[80:81], v[70:71]
	v_mul_f32_e32 v78, 0xbfb8aa3b, v72
	v_exp_f32_e32 v78, v78
	v_pk_mul_f32 v[74:75], v[94:95], v[102:103] op_sel_hi:[1,0]
	v_mul_f32_e32 v79, 0xbfb8aa3b, v73
	v_exp_f32_e32 v79, v79
	v_pk_fma_f32 v[68:69], v[76:77], v[74:75], v[68:69]
	v_mul_f32_e32 v76, 0xbfb8aa3b, v66
	v_exp_f32_e32 v77, v76
	v_mul_f32_e32 v76, 0xbfb8aa3b, v67
	v_add_f32_e32 v74, 1.0, v78
	v_exp_f32_e32 v78, v76
	v_add_f32_e32 v75, 1.0, v79
	v_mul_f32_e32 v79, 0xbfb8aa3b, v69
	v_mul_f32_e32 v80, 0xbfb8aa3b, v70
	v_exp_f32_e32 v79, v79
	v_exp_f32_e32 v81, v80
	v_mul_f32_e32 v80, 0xbfb8aa3b, v71
	v_rcp_f32_e32 v76, v75
	v_add_f32_e32 v75, 1.0, v77
	v_add_f32_e32 v77, 1.0, v78
	v_mul_f32_e32 v78, 0xbfb8aa3b, v68
	v_exp_f32_e32 v82, v80
	v_exp_f32_e32 v78, v78
	v_rcp_f32_e32 v77, v77
	v_add_f32_e32 v79, 1.0, v79
	v_rcp_f32_e32 v80, v79
	v_add_f32_e32 v79, 1.0, v81
	v_add_f32_e32 v81, 1.0, v82
	v_add_f32_e32 v78, 1.0, v78
	v_rcp_f32_e32 v81, v81
	v_rcp_f32_e32 v74, v74
	v_rcp_f32_e32 v75, v75
	v_rcp_f32_e32 v78, v78
	v_rcp_f32_e32 v79, v79
	v_mov_b32_e32 v93, v66
	v_mov_b32_e32 v66, v73
	s_waitcnt vmcnt(0)
	v_and_b32_e32 v83, 0xffff0000, v99
	v_and_b32_e32 v82, 0xffff0000, v98
	v_pk_mul_f32 v[66:67], v[66:67], v[76:77]
	v_mov_b32_e32 v92, v72
	v_pk_mul_f32 v[66:67], v[66:67], v[82:83]
	v_mov_b32_e32 v83, v70
	v_mov_b32_e32 v70, v69
	v_and_b32_e32 v73, 0xffff0000, v101
	v_and_b32_e32 v72, 0xffff0000, v100
	v_mov_b32_e32 v82, v68
	v_pk_mul_f32 v[68:69], v[70:71], v[80:81]
	v_lshlrev_b32_e32 v91, 16, v99
	v_lshlrev_b32_e32 v90, 16, v98
	v_pk_mul_f32 v[74:75], v[92:93], v[74:75]
	v_lshlrev_b32_e32 v77, 16, v101
	v_lshlrev_b32_e32 v76, 16, v100
	v_pk_mul_f32 v[78:79], v[82:83], v[78:79]
	v_pk_mul_f32 v[68:69], v[68:69], v[72:73]
	v_pk_mul_f32 v[74:75], v[74:75], v[90:91]
	v_pk_mul_f32 v[76:77], v[78:79], v[76:77]
	v_cvt_pk_bf16_f32 v69, v77, v69
	v_cvt_pk_bf16_f32 v68, v76, v68
	v_cvt_pk_bf16_f32 v67, v75, v67
	v_cvt_pk_bf16_f32 v66, v74, v66
	v_lshl_add_u64 v[70:71], v[96:97], 0, s[0:1]
	global_store_dwordx4 v[70:71], v[66:69], off
	s_branch .LBB0_994

; #define LAS __attribute__((address_space(3)))
; __device__ __forceinline__ float ex2(float x) { return __builtin_amdgcn_exp2f(x); }
; __device__ __forceinline__ int crow(int r, int hi) { return (r & 3) + 8 * (r >> 2) + 4 * hi; }
; #define MFMA32(a, b, c) __builtin_amdgcn_mfma_f32_32x32x16_bf16((a), (b), (c), 0, 0, 0)
; __device__ __forceinline__ float quad_sum(float v) { v += __int_as_float(dpp_x1(__float_as_int(v))); v += __int_as_float(dpp_x2(__float_as_int(v))); return v; }
; __device__ __forceinline__ void cmp_task_lds(const Prm& P, Ctx& C, int b, int kvh, int tg, CStream& CS, const LAS bf16_t* wlb, const int NGW, bf16x8 (&qnx)[4], int& qnx_tg, const int tg_next) {
;     ...
; #pragma unroll
;                 for (int dk = 0; dk < 4; ++dk) { const LAS unsigned char* vp = vb + (dk >> 1) * 32 * CK_VS + (32 * tile + 16 * (dk & 1)) * 2; vlo[dk] = *(const LAS s16x4*)vp; vhh[dk] = *(const LAS s16x4*)(vp + 16); }
;                 __builtin_amdgcn_sched_barrier(0);
;                 if (tile < nfull) {
; #pragma unroll
;                     for (int r = 0; r < 16; ++r) S[r] = ex2(S[r] - ml);
;                 } else {
; #pragma unroll
;                     for (int r = 0; r < 16; ++r) { const bool valid = (32 * tile + crow(r, hi)) < nvq; S[r] = valid ? ex2(S[r] - ml) : 0.f; }
;                 }
; #pragma unroll
;                 for (int i = 0; i < 4; ++i) { const float v = quad_sum(S[4 * i] + S[4 * i + 1] + S[4 * i + 2]); if (g == tt) cur4[i] = v; }
;                 bf16x8 pf[2]; pf[0] = pack8(S, 0); pf[1] = pack8(S, 8);
; #pragma unroll
;                 for (int dk = 0; dk < 4; ++dk)
;                     o[dk >> 1] = MFMA32(((bf16x8){vlo[dk][0], vlo[dk][1], vlo[dk][2], vlo[dk][3], vhh[dk][0], vhh[dk][1], vhh[dk][2], vhh[dk][3]}), pf[dk & 1], o[dk >> 1]);
.LBB0_1100:
	v_mov_b32_e32 v2, v52
	v_mov_b32_e32 v3, v48
	v_mov_b32_e32 v4, v53
	v_mov_b32_e32 v5, v49
	v_pk_add_f32 v[2:3], v[2:3], v[4:5]
	v_mov_b32_e32 v4, v54
	v_mov_b32_e32 v5, v50
	v_pk_add_f32 v[2:3], v[4:5], v[2:3]
	s_nop 1
	v_mov_b32_dpp v5, v3 quad_perm:[1,0,3,2] row_mask:0xf bank_mask:0xf bound_ctrl:1
	s_nop 0
	v_mov_b32_dpp v4, v2 quad_perm:[1,0,3,2] row_mask:0xf bank_mask:0xf bound_ctrl:1
	v_pk_add_f32 v[2:3], v[2:3], v[4:5]
	s_nop 0
	s_nop 0
	v_mov_b32_dpp v5, v3 quad_perm:[2,3,0,1] row_mask:0xf bank_mask:0xf bound_ctrl:1
	v_mov_b32_dpp v4, v2 quad_perm:[2,3,0,1] row_mask:0xf bank_mask:0xf bound_ctrl:1
	v_pk_add_f32 v[2:3], v[2:3], v[4:5]
	v_cndmask_b32_e64 v152, v152, v2, s[10:11]
	v_cvt_pk_bf16_f32 v2, v48, v49
	v_cndmask_b32_e64 v153, v153, v3, s[10:11]
	v_cvt_pk_bf16_f32 v3, v50, v51
	v_cvt_pk_bf16_f32 v4, v52, v53
	v_cvt_pk_bf16_f32 v5, v54, v55
	v_cvt_pk_bf16_f32 v48, v56, v57
	s_waitcnt lgkmcnt(6)
	v_mfma_f32_32x32x16_bf16 v[32:47], v[116:119], v[2:5], v[32:47]
	v_cvt_pk_bf16_f32 v49, v58, v59
	v_cvt_pk_bf16_f32 v50, v60, v61
	s_waitcnt lgkmcnt(2)
	v_mfma_f32_32x32x16_bf16 v[16:31], v[10:13], v[2:5], v[16:31]
	v_cvt_pk_bf16_f32 v51, v62, v63
	v_mov_b32_e32 v212, v60
	v_mov_b32_e32 v213, v56
	v_mfma_f32_32x32x16_bf16 v[32:47], v[112:115], v[48:51], v[32:47]
	v_mov_b32_e32 v52, v61
	v_mov_b32_e32 v53, v57
	v_add_f32_e64 v52, v212, v52
	v_add_f32_e64 v53, v213, v53
	v_mov_b32_e32 v54, v62
	v_mov_b32_e32 v55, v58
	v_pk_add_f32 v[52:53], v[54:55], v[52:53]
	s_waitcnt lgkmcnt(0)
	v_mfma_f32_32x32x16_bf16 v[16:31], v[6:9], v[48:51], v[16:31]
	v_mov_b32_dpp v55, v53 quad_perm:[1,0,3,2] row_mask:0xf bank_mask:0xf bound_ctrl:1
	v_mov_b32_dpp v54, v52 quad_perm:[1,0,3,2] row_mask:0xf bank_mask:0xf bound_ctrl:1
	v_add_f32_e64 v2, v52, v54
	v_add_f32_e64 v3, v53, v55
	s_nop 1
	v_mov_b32_dpp v5, v3 quad_perm:[2,3,0,1] row_mask:0xf bank_mask:0xf bound_ctrl:1
	v_mov_b32_dpp v4, v2 quad_perm:[2,3,0,1] row_mask:0xf bank_mask:0xf bound_ctrl:1
	v_pk_add_f32 v[2:3], v[2:3], v[4:5]
	s_nop 0
	v_cndmask_b32_e64 v155, v155, v3, s[10:11]
	v_cndmask_b32_e64 v154, v154, v2, s[10:11]

; #define LAS __attribute__((address_space(3)))
; __device__ __forceinline__ float ex2(float x) { return __builtin_amdgcn_exp2f(x); }
; __device__ __forceinline__ int crow(int r, int hi) { return (r & 3) + 8 * (r >> 2) + 4 * hi; }
; #define MFMA32(a, b, c) __builtin_amdgcn_mfma_f32_32x32x16_bf16((a), (b), (c), 0, 0, 0)
; __device__ __forceinline__ float quad_sum(float v) { v += __int_as_float(dpp_x1(__float_as_int(v))); v += __int_as_float(dpp_x2(__float_as_int(v))); return v; }
; __device__ __forceinline__ void cmp_task_lds(const Prm& P, Ctx& C, int b, int kvh, int tg, CStream& CS, const LAS bf16_t* wlb, const int NGW, bf16x8 (&qnx)[4], int& qnx_tg, const int tg_next) {
;     ...
; #pragma unroll
;                 for (int dk = 0; dk < 4; ++dk) { const LAS unsigned char* vp = vb + (dk >> 1) * 32 * CK_VS + (32 * tile + 16 * (dk & 1)) * 2; vlo[dk] = *(const LAS s16x4*)vp; vhh[dk] = *(const LAS s16x4*)(vp + 16); }
;                 __builtin_amdgcn_sched_barrier(0);
;                 if (tile < nfull) {
; #pragma unroll
;                     for (int r = 0; r < 16; ++r) S[r] = ex2(S[r] - ml);
;                 } else {
; #pragma unroll
;                     for (int r = 0; r < 16; ++r) { const bool valid = (32 * tile + crow(r, hi)) < nvq; S[r] = valid ? ex2(S[r] - ml) : 0.f; }
;                 }
; #pragma unroll
;                 for (int i = 0; i < 4; ++i) { const float v = quad_sum(S[4 * i] + S[4 * i + 1] + S[4 * i + 2]); if (g == tt) cur4[i] = v; }
;                 bf16x8 pf[2]; pf[0] = pack8(S, 0); pf[1] = pack8(S, 8);
; #pragma unroll
;                 for (int dk = 0; dk < 4; ++dk)
;                     o[dk >> 1] = MFMA32(((bf16x8){vlo[dk][0], vlo[dk][1], vlo[dk][2], vlo[dk][3], vhh[dk][0], vhh[dk][1], vhh[dk][2], vhh[dk][3]}), pf[dk & 1], o[dk >> 1]);
.LBB0_1304:
	v_mov_b32_e32 v2, v52
	v_mov_b32_e32 v3, v48
	v_mov_b32_e32 v4, v53
	v_mov_b32_e32 v5, v49
	v_pk_add_f32 v[2:3], v[2:3], v[4:5]
	v_mov_b32_e32 v4, v54
	v_mov_b32_e32 v5, v50
	v_pk_add_f32 v[2:3], v[4:5], v[2:3]
	s_nop 1
	v_mov_b32_dpp v5, v3 quad_perm:[1,0,3,2] row_mask:0xf bank_mask:0xf bound_ctrl:1
	s_nop 0
	v_mov_b32_dpp v4, v2 quad_perm:[1,0,3,2] row_mask:0xf bank_mask:0xf bound_ctrl:1
	v_pk_add_f32 v[2:3], v[2:3], v[4:5]
	s_nop 0
	s_nop 0
	v_mov_b32_dpp v5, v3 quad_perm:[2,3,0,1] row_mask:0xf bank_mask:0xf bound_ctrl:1
	v_mov_b32_dpp v4, v2 quad_perm:[2,3,0,1] row_mask:0xf bank_mask:0xf bound_ctrl:1
	v_pk_add_f32 v[2:3], v[2:3], v[4:5]
	v_cndmask_b32_e64 v204, v204, v2, s[6:7]
	v_cvt_pk_bf16_f32 v2, v48, v49
	v_cndmask_b32_e64 v205, v205, v3, s[6:7]
	v_cvt_pk_bf16_f32 v3, v50, v51
	v_cvt_pk_bf16_f32 v4, v52, v53
	v_cvt_pk_bf16_f32 v5, v54, v55
	v_cvt_pk_bf16_f32 v48, v56, v57
	s_waitcnt lgkmcnt(6)
	v_mfma_f32_32x32x16_bf16 v[32:47], v[184:187], v[2:5], v[32:47]
	v_cvt_pk_bf16_f32 v49, v58, v59
	v_cvt_pk_bf16_f32 v50, v60, v61
	s_waitcnt lgkmcnt(2)
	v_mfma_f32_32x32x16_bf16 v[16:31], v[10:13], v[2:5], v[16:31]
	v_cvt_pk_bf16_f32 v51, v62, v63
	v_mov_b32_e32 v208, v60
	v_mov_b32_e32 v209, v56
	v_mfma_f32_32x32x16_bf16 v[32:47], v[180:183], v[48:51], v[32:47]
	v_mov_b32_e32 v52, v61
	v_mov_b32_e32 v53, v57
	v_add_f32_e64 v52, v208, v52
	v_add_f32_e64 v53, v209, v53
	v_mov_b32_e32 v54, v62
	v_mov_b32_e32 v55, v58
	v_pk_add_f32 v[52:53], v[54:55], v[52:53]
	s_waitcnt lgkmcnt(0)
	v_mfma_f32_32x32x16_bf16 v[16:31], v[6:9], v[48:51], v[16:31]
	v_mov_b32_dpp v55, v53 quad_perm:[1,0,3,2] row_mask:0xf bank_mask:0xf bound_ctrl:1
	v_mov_b32_dpp v54, v52 quad_perm:[1,0,3,2] row_mask:0xf bank_mask:0xf bound_ctrl:1
	v_add_f32_e64 v2, v52, v54
	v_add_f32_e64 v3, v53, v55
	s_nop 1
	v_mov_b32_dpp v5, v3 quad_perm:[2,3,0,1] row_mask:0xf bank_mask:0xf bound_ctrl:1
	v_mov_b32_dpp v4, v2 quad_perm:[2,3,0,1] row_mask:0xf bank_mask:0xf bound_ctrl:1
	v_pk_add_f32 v[2:3], v[2:3], v[4:5]
	s_nop 0
	v_cndmask_b32_e64 v207, v207, v3, s[6:7]
	v_cndmask_b32_e64 v206, v206, v2, s[6:7]

; #define LAS __attribute__((address_space(3)))
; __device__ __forceinline__ unsigned f2bf(float f) { unsigned u = __builtin_bit_cast(unsigned, f); return (u + 0x7fffu + ((u >> 16) & 1u)) >> 16; }
; __device__ __forceinline__ unsigned pk2(float lo, float hi) { return f2bf(lo) | (f2bf(hi) << 16); }
; __device__ __forceinline__ int crow(int r, int hi) { return (r & 3) + 8 * (r >> 2) + 4 * hi; }
; template <int MODE, int THRL>
; __device__ __forceinline__ void attn_unit(const Prm& P, int b, int h, int qb, LAS char* shm, int wid) {
;     ...
;   if (hi == 0) { const float gte = ((const float*)(P.ws + WS_G))[(row0 + r32) * 24 + h * 3 + (MODE == 0 ? 1 : 2)]; wsf[32 + r32] = l_reg > 0.f ? gte * __builtin_amdgcn_rcpf(l_reg) : 0.f; }
;   asm volatile("s_waitcnt lgkmcnt(0)" ::: "memory");
;   float rli[16];
; #pragma unroll
;   for (int r = 0; r < 16; ++r) rli[r] = wsf[32 + crow(r, hi)];
;   { LAS bf16_t* stg = (LAS bf16_t*)(shm + (MODE == 0 ? LDS_OS2 : LDS_OST)) + wid * 2048;
; #pragma unroll
;     for (int r = 0; r < 16; ++r) { const int orow = crow(r, hi);
; #pragma unroll
;       for (int d0 = 0; d0 < 2; ++d0) stg[orow * 64 + d0 * 32 + r32] = (bf16_t)f2bf(o[d0][r] * rli[r]); }
;     asm volatile("s_waitcnt lgkmcnt(0)" ::: "memory");
;     if (MODE == 1) {
;       const LAS bf16_t* stg2 = (const LAS bf16_t*)(shm + LDS_OS2) + wid * 2048;
;       bf16_t* hp = (bf16_t*)(P.ws + WS_H2) + row0 * 1024 + 512 + h * 64;
; #pragma unroll
;       for (int i = 0; i < 4; ++i) { const int row = i * 8 + (lane_e >> 3), ch = lane_e & 7;
;         const u32x4 a = *(const LAS u32x4*)(stg + row * 64 + ch * 8), s2 = *(const LAS u32x4*)(stg2 + row * 64 + ch * 8);
;         const u32x4 oc = ocv[i], bg = bgv[i];
;         u32x4 w;
;         w.x = pk2((bflo(a.x) + bflo(s2.x) + bflo(oc.x)) * bflo(bg.x), (bfhi(a.x) + bfhi(s2.x) + bfhi(oc.x)) * bfhi(bg.x));
;         w.y = pk2((bflo(a.y) + bflo(s2.y) + bflo(oc.y)) * bflo(bg.y), (bfhi(a.y) + bfhi(s2.y) + bfhi(oc.y)) * bfhi(bg.y));
;         w.z = pk2((bflo(a.z) + bflo(s2.z) + bflo(oc.z)) * bflo(bg.z), (bfhi(a.z) + bfhi(s2.z) + bfhi(oc.z)) * bfhi(bg.z));
;         w.w = pk2((bflo(a.w) + bflo(s2.w) + bflo(oc.w)) * bflo(bg.w), (bfhi(a.w) + bfhi(s2.w) + bfhi(oc.w)) * bfhi(bg.w));
;         *(u32x4*)(hp + (long)row * 1024 + ch * 8) = w; }
.LBB0_1481:
	s_or_b64 exec, exec, s[0:1]
	s_waitcnt lgkmcnt(0)
	ds_read_b128 v[74:77], v80 offset:49280
	ds_read_b128 v[82:85], v80 offset:49312
	ds_read_b128 v[86:89], v80 offset:49344
	ds_read_b128 v[78:81], v80 offset:49376
	v_lshlrev_b32_e32 v90, 1, v204
	v_lshlrev_b32_e32 v91, 9, v206
	v_readlane_b32 s2, v251, 47
	s_waitcnt lgkmcnt(3)
	v_mul_f32_e32 v32, v32, v74
	s_movk_i32 s3, 0x7fff
	v_add3_u32 v90, s2, v90, v91
	v_cvt_pk_bf16_f32 v32, v32, v32
	v_mul_f32_e32 v16, v16, v74
	ds_write_b16_d16_hi v90, v32 offset:55296
	v_cvt_pk_bf16_f32 v16, v16, v16
	ds_write_b16_d16_hi v90, v16 offset:55360
	v_mul_f32_e32 v16, v33, v75
	v_cvt_pk_bf16_f32 v16, v16, v16
	ds_write_b16_d16_hi v90, v16 offset:55424
	v_mul_f32_e32 v16, v17, v75
	v_cvt_pk_bf16_f32 v16, v16, v16
	ds_write_b16_d16_hi v90, v16 offset:55488
	v_mul_f32_e32 v16, v34, v76
	v_cvt_pk_bf16_f32 v16, v16, v16
	ds_write_b16_d16_hi v90, v16 offset:55552
	v_mul_f32_e32 v16, v18, v76
	v_cvt_pk_bf16_f32 v16, v16, v16
	ds_write_b16_d16_hi v90, v16 offset:55616
	v_mul_f32_e32 v16, v35, v77
	v_cvt_pk_bf16_f32 v16, v16, v16
	ds_write_b16_d16_hi v90, v16 offset:55680
	v_mul_f32_e32 v16, v19, v77
	v_cvt_pk_bf16_f32 v16, v16, v16
	ds_write_b16_d16_hi v90, v16 offset:55744
	s_waitcnt lgkmcnt(10)
	v_mul_f32_e32 v16, v36, v82
	v_cvt_pk_bf16_f32 v16, v16, v16
	ds_write_b16_d16_hi v90, v16 offset:56320
	v_mul_f32_e32 v16, v20, v82
	v_cvt_pk_bf16_f32 v16, v16, v16
	ds_write_b16_d16_hi v90, v16 offset:56384
	v_mul_f32_e32 v16, v37, v83
	v_cvt_pk_bf16_f32 v16, v16, v16
	ds_write_b16_d16_hi v90, v16 offset:56448
	v_mul_f32_e32 v16, v21, v83
	v_cvt_pk_bf16_f32 v16, v16, v16
	ds_write_b16_d16_hi v90, v16 offset:56512
	v_mul_f32_e32 v16, v38, v84
	v_cvt_pk_bf16_f32 v16, v16, v16
	ds_write_b16_d16_hi v90, v16 offset:56576
	v_mul_f32_e32 v16, v22, v84
	v_cvt_pk_bf16_f32 v16, v16, v16
	ds_write_b16_d16_hi v90, v16 offset:56640
	v_mul_f32_e32 v16, v39, v85
	v_cvt_pk_bf16_f32 v16, v16, v16
	ds_write_b16_d16_hi v90, v16 offset:56704
	v_mul_f32_e32 v16, v23, v85
	v_cvt_pk_bf16_f32 v16, v16, v16
	ds_write_b16_d16_hi v90, v16 offset:56768
	s_waitcnt lgkmcnt(14)
	v_mul_f32_e32 v16, v40, v86
	v_cvt_pk_bf16_f32 v16, v16, v16
	ds_write_b16_d16_hi v90, v16 offset:57344
	v_mul_f32_e32 v16, v24, v86
	v_cvt_pk_bf16_f32 v16, v16, v16
	ds_write_b16_d16_hi v90, v16 offset:57408
	v_mul_f32_e32 v16, v41, v87
	v_cvt_pk_bf16_f32 v16, v16, v16
	ds_write_b16_d16_hi v90, v16 offset:57472
	v_mul_f32_e32 v16, v25, v87
	v_cvt_pk_bf16_f32 v16, v16, v16
	ds_write_b16_d16_hi v90, v16 offset:57536
	v_mul_f32_e32 v16, v42, v88
	v_cvt_pk_bf16_f32 v16, v16, v16
	ds_write_b16_d16_hi v90, v16 offset:57600
	v_mul_f32_e32 v16, v26, v88
	v_cvt_pk_bf16_f32 v16, v16, v16
	ds_write_b16_d16_hi v90, v16 offset:57664
	v_mul_f32_e32 v16, v43, v89
	v_cvt_pk_bf16_f32 v16, v16, v16
	ds_write_b16_d16_hi v90, v16 offset:57728
	v_mul_f32_e32 v16, v27, v89
	v_cvt_pk_bf16_f32 v16, v16, v16
	ds_write_b16_d16_hi v90, v16 offset:57792
	v_mul_f32_e32 v16, v44, v78
	v_cvt_pk_bf16_f32 v16, v16, v16
	ds_write_b16_d16_hi v90, v16 offset:58368
	v_mul_f32_e32 v16, v28, v78
	v_cvt_pk_bf16_f32 v16, v16, v16
	ds_write_b16_d16_hi v90, v16 offset:58432
	v_mul_f32_e32 v16, v45, v79
	v_cvt_pk_bf16_f32 v16, v16, v16
	ds_write_b16_d16_hi v90, v16 offset:58496
	v_mul_f32_e32 v16, v29, v79
	v_cvt_pk_bf16_f32 v16, v16, v16
	ds_write_b16_d16_hi v90, v16 offset:58560
	v_mul_f32_e32 v16, v46, v80
	v_cvt_pk_bf16_f32 v16, v16, v16
	ds_write_b16_d16_hi v90, v16 offset:58624
	v_mul_f32_e32 v16, v30, v80
	v_cvt_pk_bf16_f32 v16, v16, v16
	ds_write_b16_d16_hi v90, v16 offset:58688
	v_mul_f32_e32 v16, v47, v81
	v_cvt_pk_bf16_f32 v16, v16, v16
	ds_write_b16_d16_hi v90, v16 offset:58752
	v_mul_f32_e32 v16, v31, v81
	v_cvt_pk_bf16_f32 v16, v16, v16
	ds_write_b16_d16_hi v90, v16 offset:58816
	v_add_u32_e32 v32, s2, v0
	v_add_u32_e32 v33, s46, v0
	v_lshlrev_b32_e32 v16, 7, v72
	s_waitcnt lgkmcnt(0)
	v_add_u32_e32 v17, v32, v16
	v_add_u32_e32 v16, v33, v16
	ds_read_b128 v[18:21], v17 offset:55296
	ds_read_b128 v[22:25], v16
	s_lshl_b64 s[0:1], s[4:5], 11
	v_readlane_b32 s4, v250, 49
	v_readlane_b32 s8, v250, 53
	s_waitcnt lgkmcnt(1)
	v_lshlrev_b32_e32 v27, 16, v19
	v_lshlrev_b32_e32 v26, 16, v18
	s_waitcnt lgkmcnt(0)
	v_lshlrev_b32_e32 v29, 16, v23
	v_lshlrev_b32_e32 v28, 16, v22
	v_and_b32_e32 v19, 0xffff0000, v19
	v_and_b32_e32 v18, 0xffff0000, v18
	v_and_b32_e32 v23, 0xffff0000, v23
	v_and_b32_e32 v22, 0xffff0000, v22
	v_pk_add_f32 v[26:27], v[26:27], v[28:29]
	s_waitcnt vmcnt(7)
	v_lshlrev_b32_e32 v29, 16, v61
	v_lshlrev_b32_e32 v28, 16, v60
	v_pk_add_f32 v[18:19], v[18:19], v[22:23]
	v_and_b32_e32 v23, 0xffff0000, v61
	v_and_b32_e32 v22, 0xffff0000, v60
	v_pk_add_f32 v[26:27], v[26:27], v[28:29]
	s_waitcnt vmcnt(6)
; #define LAS __attribute__((address_space(3)))
; __device__ __forceinline__ unsigned pk2(float lo, float hi) { return f2bf(lo) | (f2bf(hi) << 16); }
; template <int MODE, int THRL>
; __device__ __forceinline__ void attn_unit(const Prm& P, int b, int h, int qb, LAS char* shm, int wid) {
;     ...
;     if (MODE == 1) {
;       const LAS bf16_t* stg2 = (const LAS bf16_t*)(shm + LDS_OS2) + wid * 2048;
;       bf16_t* hp = (bf16_t*)(P.ws + WS_H2) + row0 * 1024 + 512 + h * 64;
; #pragma unroll
;       for (int i = 0; i < 4; ++i) { const int row = i * 8 + (lane_e >> 3), ch = lane_e & 7;
;         const u32x4 a = *(const LAS u32x4*)(stg + row * 64 + ch * 8), s2 = *(const LAS u32x4*)(stg2 + row * 64 + ch * 8);
;         const u32x4 oc = ocv[i], bg = bgv[i];
;         u32x4 w;
;         w.x = pk2((bflo(a.x) + bflo(s2.x) + bflo(oc.x)) * bflo(bg.x), (bfhi(a.x) + bfhi(s2.x) + bfhi(oc.x)) * bfhi(bg.x));
;         w.y = pk2((bflo(a.y) + bflo(s2.y) + bflo(oc.y)) * bflo(bg.y), (bfhi(a.y) + bfhi(s2.y) + bfhi(oc.y)) * bfhi(bg.y));
;         w.z = pk2((bflo(a.z) + bflo(s2.z) + bflo(oc.z)) * bflo(bg.z), (bfhi(a.z) + bfhi(s2.z) + bfhi(oc.z)) * bfhi(bg.z));
;         w.w = pk2((bflo(a.w) + bflo(s2.w) + bflo(oc.w)) * bflo(bg.w), (bfhi(a.w) + bfhi(s2.w) + bfhi(oc.w)) * bfhi(bg.w));
;         *(u32x4*)(hp + (long)row * 1024 + ch * 8) = w; }
	v_lshlrev_b32_e32 v29, 16, v65
	v_lshlrev_b32_e32 v28, 16, v64
	v_pk_add_f32 v[18:19], v[18:19], v[22:23]
	v_and_b32_e32 v23, 0xffff0000, v65
	v_and_b32_e32 v22, 0xffff0000, v64
	v_readlane_b32 s9, v250, 54
	s_add_u32 s0, s8, s0
	v_pk_mul_f32 v[26:27], v[26:27], v[28:29]
	v_pk_mul_f32 v[18:19], v[18:19], v[22:23]
	v_lshlrev_b32_e32 v23, 16, v21
	v_lshlrev_b32_e32 v22, 16, v20
	v_lshlrev_b32_e32 v29, 16, v25
	v_lshlrev_b32_e32 v28, 16, v24
	v_and_b32_e32 v21, 0xffff0000, v21
	v_and_b32_e32 v20, 0xffff0000, v20
	v_and_b32_e32 v25, 0xffff0000, v25
	v_and_b32_e32 v24, 0xffff0000, v24
	s_addc_u32 s1, s9, s1
	v_pk_add_f32 v[20:21], v[20:21], v[24:25]
	v_and_b32_e32 v25, 0xffff0000, v63
	v_and_b32_e32 v24, 0xffff0000, v62
	s_add_u32 s0, s0, s24
	v_pk_add_f32 v[22:23], v[22:23], v[28:29]
	v_lshlrev_b32_e32 v29, 16, v63
	v_lshlrev_b32_e32 v28, 16, v62
	v_pk_add_f32 v[20:21], v[20:21], v[24:25]
	v_and_b32_e32 v25, 0xffff0000, v67
	v_and_b32_e32 v24, 0xffff0000, v66
	s_addc_u32 s1, s1, 0
	v_pk_add_f32 v[22:23], v[22:23], v[28:29]
	v_lshlrev_b32_e32 v29, 16, v67
	v_lshlrev_b32_e32 v28, 16, v66
	v_pk_mul_f32 v[20:21], v[20:21], v[24:25]
	v_lshl_add_u64 v[16:17], s[0:1], 0, v[0:1]
	v_pk_mul_f32 v[22:23], v[22:23], v[28:29]
	s_mov_b64 s[0:1], 0x13400400
	v_lshl_add_u64 v[16:17], v[16:17], 0, s[0:1]
	s_mov_b32 s0, 0xffff0000
	v_cvt_pk_bf16_f32 v21, v23, v21
	v_lshlrev_b32_e32 v0, 7, v70
	v_cvt_pk_bf16_f32 v20, v22, v20
	v_add_u32_e32 v22, v32, v0
	v_add_u32_e32 v0, v33, v0
	v_cvt_pk_bf16_f32 v19, v27, v19
	v_cvt_pk_bf16_f32 v18, v26, v18
	ds_read_b128 v[22:25], v22 offset:55296
	ds_read_b128 v[26:29], v0
	v_lshlrev_b64 v[30:31], 11, v[72:73]
	v_lshl_add_u64 v[30:31], v[16:17], 0, v[30:31]
	global_store_dwordx4 v[30:31], v[18:21], off
	v_lshlrev_b64 v[30:31], 11, v[70:71]
	v_lshl_add_u64 v[30:31], v[16:17], 0, v[30:31]
	s_waitcnt lgkmcnt(1)
	v_lshlrev_b32_e32 v19, 16, v23
	v_lshlrev_b32_e32 v18, 16, v22
	s_waitcnt lgkmcnt(0)
	v_lshlrev_b32_e32 v21, 16, v27
	v_lshlrev_b32_e32 v20, 16, v26
	v_pk_add_f32 v[18:19], v[18:19], v[20:21]
	s_waitcnt vmcnt(6)
	v_lshlrev_b32_e32 v21, 16, v53
	v_lshlrev_b32_e32 v20, 16, v52
	v_pk_add_f32 v[18:19], v[18:19], v[20:21]
	s_waitcnt vmcnt(5)
	v_lshlrev_b32_e32 v21, 16, v57
	v_lshlrev_b32_e32 v20, 16, v56
	v_pk_mul_f32 v[18:19], v[18:19], v[20:21]
	v_and_b32_e32 v21, 0xffff0000, v23
	v_and_b32_e32 v20, 0xffff0000, v22
	v_and_b32_e32 v23, 0xffff0000, v27
	v_and_b32_e32 v22, 0xffff0000, v26
	v_pk_add_f32 v[20:21], v[20:21], v[22:23]
	v_and_b32_e32 v23, 0xffff0000, v53
	v_and_b32_e32 v22, 0xffff0000, v52
	v_pk_add_f32 v[20:21], v[20:21], v[22:23]
	v_and_b32_e32 v23, 0xffff0000, v57
	v_and_b32_e32 v22, 0xffff0000, v56
	v_pk_mul_f32 v[20:21], v[20:21], v[22:23]
	v_lshlrev_b32_e32 v23, 16, v25
	v_lshlrev_b32_e32 v22, 16, v24
	v_lshlrev_b32_e32 v27, 16, v29
	v_lshlrev_b32_e32 v26, 16, v28
	v_pk_add_f32 v[22:23], v[22:23], v[26:27]
	v_lshlrev_b32_e32 v27, 16, v55
	v_lshlrev_b32_e32 v26, 16, v54
	v_pk_add_f32 v[22:23], v[22:23], v[26:27]
	v_lshlrev_b32_e32 v27, 16, v59
	v_lshlrev_b32_e32 v26, 16, v58
	v_pk_mul_f32 v[22:23], v[22:23], v[26:27]
	v_and_b32_e32 v25, 0xffff0000, v25
	v_and_b32_e32 v24, 0xffff0000, v24
	v_and_b32_e32 v27, 0xffff0000, v29
	v_and_b32_e32 v26, 0xffff0000, v28
	v_pk_add_f32 v[24:25], v[24:25], v[26:27]
	v_and_b32_e32 v27, 0xffff0000, v55
	v_and_b32_e32 v26, 0xffff0000, v54
	v_pk_add_f32 v[24:25], v[24:25], v[26:27]
	v_and_b32_e32 v27, 0xffff0000, v59
	v_and_b32_e32 v26, 0xffff0000, v58
	v_pk_mul_f32 v[24:25], v[24:25], v[26:27]
	v_bfe_u32 v28, v20, 16, 1
	v_bfe_u32 v26, v24, 16, 1
	v_bfe_u32 v0, v25, 16, 1
	v_bfe_u32 v27, v21, 16, 1
	v_add3_u32 v28, v20, v28, s3
	v_add3_u32 v20, v24, v26, s3
	v_bfe_u32 v26, v23, 16, 1
	v_add3_u32 v27, v21, v27, s3
	v_add3_u32 v0, v25, v0, s3
	v_bfe_u32 v21, v18, 16, 1
	v_bfe_u32 v25, v22, 16, 1
	v_add3_u32 v23, v23, v26, s3
	v_bfe_u32 v24, v19, 16, 1
	v_add3_u32 v22, v22, v25, s3
	v_add3_u32 v18, v18, v21, s3
	v_lshrrev_b32_e32 v21, 16, v23
	v_add3_u32 v19, v19, v24, s3
	v_lshrrev_b32_e32 v22, 16, v22
	v_and_or_b32 v21, v0, s0, v21
	v_lshlrev_b32_e32 v0, 7, v68
	v_lshrrev_b32_e32 v18, 16, v18
	v_lshrrev_b32_e32 v19, 16, v19
	v_and_or_b32 v20, v20, s0, v22
	v_add_u32_e32 v22, v32, v0
	v_add_u32_e32 v0, v33, v0
	v_and_or_b32 v19, v27, s0, v19
	v_and_or_b32 v18, v28, s0, v18
	ds_read_b128 v[22:25], v22 offset:55296
	ds_read_b128 v[26:29], v0
	global_store_dwordx4 v[30:31], v[18:21], off
	v_readlane_b32 s5, v250, 50
	v_readlane_b32 s6, v250, 51
	s_waitcnt lgkmcnt(1)
; #define LAS __attribute__((address_space(3)))
; __device__ __forceinline__ unsigned pk2(float lo, float hi) { return f2bf(lo) | (f2bf(hi) << 16); }
; template <int MODE, int THRL>
; __device__ __forceinline__ void attn_unit(const Prm& P, int b, int h, int qb, LAS char* shm, int wid) {
;     ...
;     if (MODE == 1) {
;       const LAS bf16_t* stg2 = (const LAS bf16_t*)(shm + LDS_OS2) + wid * 2048;
;       bf16_t* hp = (bf16_t*)(P.ws + WS_H2) + row0 * 1024 + 512 + h * 64;
; #pragma unroll
;       for (int i = 0; i < 4; ++i) { const int row = i * 8 + (lane_e >> 3), ch = lane_e & 7;
;         const u32x4 a = *(const LAS u32x4*)(stg + row * 64 + ch * 8), s2 = *(const LAS u32x4*)(stg2 + row * 64 + ch * 8);
;         const u32x4 oc = ocv[i], bg = bgv[i];
;         u32x4 w;
;         w.x = pk2((bflo(a.x) + bflo(s2.x) + bflo(oc.x)) * bflo(bg.x), (bfhi(a.x) + bfhi(s2.x) + bfhi(oc.x)) * bfhi(bg.x));
;         w.y = pk2((bflo(a.y) + bflo(s2.y) + bflo(oc.y)) * bflo(bg.y), (bfhi(a.y) + bfhi(s2.y) + bfhi(oc.y)) * bfhi(bg.y));
;         w.z = pk2((bflo(a.z) + bflo(s2.z) + bflo(oc.z)) * bflo(bg.z), (bfhi(a.z) + bfhi(s2.z) + bfhi(oc.z)) * bfhi(bg.z));
;         w.w = pk2((bflo(a.w) + bflo(s2.w) + bflo(oc.w)) * bflo(bg.w), (bfhi(a.w) + bfhi(s2.w) + bfhi(oc.w)) * bfhi(bg.w));
;         *(u32x4*)(hp + (long)row * 1024 + ch * 8) = w; }
;     }
;   }
;   asm volatile("s_waitcnt vmcnt(0) lgkmcnt(0)\n\ts_barrier" ::: "memory");
	v_lshlrev_b32_e32 v19, 16, v23
	v_lshlrev_b32_e32 v18, 16, v22
	s_waitcnt lgkmcnt(0)
	v_lshlrev_b32_e32 v21, 16, v27
	v_lshlrev_b32_e32 v20, 16, v26
	v_pk_add_f32 v[18:19], v[18:19], v[20:21]
	s_waitcnt vmcnt(5)
	v_lshlrev_b32_e32 v21, 16, v11
	v_lshlrev_b32_e32 v20, 16, v10
	v_pk_add_f32 v[18:19], v[18:19], v[20:21]
	s_waitcnt vmcnt(4)
	v_lshlrev_b32_e32 v21, 16, v49
	v_lshlrev_b32_e32 v20, 16, v48
	v_pk_mul_f32 v[18:19], v[18:19], v[20:21]
	v_and_b32_e32 v21, 0xffff0000, v23
	v_and_b32_e32 v20, 0xffff0000, v22
	v_and_b32_e32 v23, 0xffff0000, v27
	v_and_b32_e32 v22, 0xffff0000, v26
	v_pk_add_f32 v[20:21], v[20:21], v[22:23]
	v_and_b32_e32 v11, 0xffff0000, v11
	v_and_b32_e32 v10, 0xffff0000, v10
	v_pk_add_f32 v[10:11], v[20:21], v[10:11]
	v_and_b32_e32 v21, 0xffff0000, v49
	v_and_b32_e32 v20, 0xffff0000, v48
	v_pk_mul_f32 v[10:11], v[10:11], v[20:21]
	v_lshlrev_b32_e32 v21, 16, v25
	v_lshlrev_b32_e32 v20, 16, v24
	v_lshlrev_b32_e32 v23, 16, v29
	v_lshlrev_b32_e32 v22, 16, v28
	v_pk_add_f32 v[20:21], v[20:21], v[22:23]
	v_lshlrev_b32_e32 v23, 16, v13
	v_lshlrev_b32_e32 v22, 16, v12
	v_pk_add_f32 v[20:21], v[20:21], v[22:23]
	v_lshlrev_b32_e32 v23, 16, v51
	v_lshlrev_b32_e32 v22, 16, v50
	v_pk_mul_f32 v[20:21], v[20:21], v[22:23]
	v_and_b32_e32 v23, 0xffff0000, v25
	v_and_b32_e32 v22, 0xffff0000, v24
	v_and_b32_e32 v25, 0xffff0000, v29
	v_and_b32_e32 v24, 0xffff0000, v28
	v_pk_add_f32 v[22:23], v[22:23], v[24:25]
	v_and_b32_e32 v13, 0xffff0000, v13
	v_and_b32_e32 v12, 0xffff0000, v12
	v_pk_add_f32 v[12:13], v[22:23], v[12:13]
	v_and_b32_e32 v23, 0xffff0000, v51
	v_and_b32_e32 v22, 0xffff0000, v50
	v_pk_mul_f32 v[12:13], v[12:13], v[22:23]
	v_cvt_pk_bf16_f32 v13, v21, v13
	v_lshlrev_b32_e32 v0, 7, v14
	v_cvt_pk_bf16_f32 v10, v18, v10
	v_add_u32_e32 v18, v32, v0
	v_add_u32_e32 v0, v33, v0
	v_cvt_pk_bf16_f32 v12, v20, v12
	v_cvt_pk_bf16_f32 v11, v19, v11
	ds_read_b128 v[18:21], v18 offset:55296
	ds_read_b128 v[22:25], v0
	v_lshlrev_b64 v[26:27], 11, v[68:69]
	v_lshl_add_u64 v[26:27], v[16:17], 0, v[26:27]
	global_store_dwordx4 v[26:27], v[10:13], off
	v_readlane_b32 s7, v250, 52
	v_readlane_b32 s10, v250, 55
	s_waitcnt lgkmcnt(1)
	v_lshlrev_b32_e32 v11, 16, v19
	v_lshlrev_b32_e32 v10, 16, v18
	s_waitcnt lgkmcnt(0)
	v_lshlrev_b32_e32 v13, 16, v23
	v_lshlrev_b32_e32 v12, 16, v22
	v_pk_add_f32 v[10:11], v[10:11], v[12:13]
	s_waitcnt vmcnt(4)
	v_lshlrev_b32_e32 v13, 16, v3
	v_lshlrev_b32_e32 v12, 16, v2
	v_pk_add_f32 v[10:11], v[10:11], v[12:13]
	s_waitcnt vmcnt(3)
	v_lshlrev_b32_e32 v13, 16, v7
	v_lshlrev_b32_e32 v12, 16, v6
	v_pk_mul_f32 v[10:11], v[10:11], v[12:13]
	v_and_b32_e32 v13, 0xffff0000, v19
	v_and_b32_e32 v12, 0xffff0000, v18
	v_and_b32_e32 v19, 0xffff0000, v23
	v_and_b32_e32 v18, 0xffff0000, v22
	v_pk_add_f32 v[12:13], v[12:13], v[18:19]
	v_and_b32_e32 v3, 0xffff0000, v3
	v_and_b32_e32 v2, 0xffff0000, v2
	v_pk_add_f32 v[2:3], v[12:13], v[2:3]
	v_and_b32_e32 v7, 0xffff0000, v7
	v_and_b32_e32 v6, 0xffff0000, v6
	v_pk_mul_f32 v[2:3], v[2:3], v[6:7]
	v_lshlrev_b32_e32 v7, 16, v21
	v_lshlrev_b32_e32 v6, 16, v20
	v_lshlrev_b32_e32 v13, 16, v25
	v_lshlrev_b32_e32 v12, 16, v24
	v_pk_add_f32 v[6:7], v[6:7], v[12:13]
	v_lshlrev_b32_e32 v13, 16, v5
	v_lshlrev_b32_e32 v12, 16, v4
	v_pk_add_f32 v[6:7], v[6:7], v[12:13]
	v_lshlrev_b32_e32 v13, 16, v9
	v_lshlrev_b32_e32 v12, 16, v8
	v_pk_mul_f32 v[6:7], v[6:7], v[12:13]
	v_and_b32_e32 v13, 0xffff0000, v21
	v_and_b32_e32 v12, 0xffff0000, v20
	v_and_b32_e32 v19, 0xffff0000, v25
	v_and_b32_e32 v18, 0xffff0000, v24
	v_pk_add_f32 v[12:13], v[12:13], v[18:19]
	v_and_b32_e32 v5, 0xffff0000, v5
	v_and_b32_e32 v4, 0xffff0000, v4
	v_pk_add_f32 v[4:5], v[12:13], v[4:5]
	v_and_b32_e32 v9, 0xffff0000, v9
	v_and_b32_e32 v8, 0xffff0000, v8
	v_pk_mul_f32 v[4:5], v[4:5], v[8:9]
	v_bfe_u32 v0, v5, 16, 1
	v_add3_u32 v0, v5, v0, s3
	v_bfe_u32 v12, v7, 16, 1
	v_add3_u32 v7, v7, v12, s3
	v_lshrrev_b32_e32 v5, 16, v7
	v_cvt_pk_bf16_f32 v4, v6, v4
	v_lshlrev_b64 v[6:7], 11, v[14:15]
	v_and_or_b32 v5, v0, s0, v5
	v_cvt_pk_bf16_f32 v3, v11, v3
	v_cvt_pk_bf16_f32 v2, v10, v2
	v_lshl_add_u64 v[6:7], v[16:17], 0, v[6:7]
	global_store_dwordx4 v[6:7], v[2:5], off
	s_waitcnt lgkmcnt(0)
	s_barrier
	v_readlane_b32 s0, v251, 63
	s_add_i32 s0, s0, 1
	s_mov_b64 s[2:3], 0
	v_writelane_b32 v251, s0, 63
	v_readlane_b32 s11, v250, 56

; #define LAS __attribute__((address_space(3)))
; __device__ __forceinline__ unsigned f2bf(float f) { unsigned u = __builtin_bit_cast(unsigned, f); return (u + 0x7fffu + ((u >> 16) & 1u)) >> 16; }
; __device__ __forceinline__ float ex2(float x) { return __builtin_amdgcn_exp2f(x); }
; __device__ __forceinline__ void sample_task_part2(const Prm& P, Ctx& C, int b, int kvh, int ts) {
;     ...
;     for (int gq = 0; gq < 4; ++gq) { const float ls = wave_sum(As.l[gq]), lw = wave_sum(Aw.l[gq]);
;         LAS float* ps = part + ((0 * 8 + C.wave) * 4 + gq) * 66; LAS float* pw = part + ((1 * 8 + C.wave) * 4 + gq) * 66;
;         if (lane == 0) { ps[0] = As.m[gq]; ps[1] = ls; pw[0] = Aw.m[gq]; pw[1] = lw; } ps[2 + lane] = As.o[gq]; pw[2 + lane] = Aw.o[gq]; }
;     __syncthreads();
;     { const int br = tid >> 8, gq = (tid >> 6) & 3, d = tid & 63; float M = NEGB;
;         for (int w = 0; w < 8; ++w) M = fmaxf(M, part[((br * 8 + w) * 4 + gq) * 66]);
;         float L = 0.f, O = 0.f;
;         for (int w = 0; w < 8; ++w) { const LAS float* pp = part + ((br * 8 + w) * 4 + gq) * 66; const float f = ex2(pp[0] - M); L += pp[1] * f; O += pp[2 + d] * f; }
;         res[(br * 4 + gq) * 64 + d] = L > 0.f ? O / L : 0.f; }
;     __syncthreads();
;     if (tid < 256) { const int gq = tid >> 6, d = tid & 63, head = 4 * kvh + gq; const float* G = (const float*)(P.ws + WS_G) + row * 24 + head * 3;
;         float v = ocs[gq * 64 + d] + G[1] * res[gq * 64 + d] + G[2] * res[(4 + gq) * 64 + d];
;         v *= bf2f(((const bf16_t*)(P.ws + WS_BG))[row * 512 + head * 64 + d]);
;         ((bf16_t*)(P.ws + WS_H2))[row * 1024 + 512 + head * 64 + d] = (bf16_t)f2bf(v); }
.LBB0_1584:
	s_or_b64 exec, exec, s[0:1]
	v_readlane_b32 s0, v251, 30
	ds_write_b32 v0, v101 offset:57120
	v_ashrrev_i32_e32 v2, 6, v117
	v_lshl_add_u32 v0, v98, 2, s0
	ds_write_b32 v0, v113 offset:9248
	v_and_b32_e32 v22, 3, v2
	v_lshrrev_b32_e32 v0, 3, v117
	s_mov_b32 s0, 0x1fffffe0
	v_and_or_b32 v0, v0, s0, v22
	s_movk_i32 s0, 0x108
	v_mul_lo_u32 v0, v0, s0
	v_add_u32_e32 v20, 0, v0
	v_add_u32_e32 v0, 0xdc00, v20
	s_waitcnt lgkmcnt(0)
	s_barrier
	ds_read2_b64 v[4:7], v0 offset1:132
	v_add_u32_e32 v3, 0xe400, v20
	ds_read2_b64 v[8:11], v3 offset0:8 offset1:140
	v_add_u32_e32 v3, 0xec00, v20
	ds_read2_b64 v[12:15], v3 offset0:16 offset1:148
	v_add_u32_e32 v3, 0xf400, v20
	ds_read2_b64 v[16:19], v3 offset0:24 offset1:156
	s_mov_b32 s0, 0xf149f2ca
	s_waitcnt lgkmcnt(3)
	v_max3_f32 v0, v4, s0, v6
	s_waitcnt lgkmcnt(2)
	v_max3_f32 v0, v0, v8, v10
	s_waitcnt lgkmcnt(1)
	v_max3_f32 v0, v0, v12, v14
	s_waitcnt lgkmcnt(0)
	v_max3_f32 v23, v0, v16, v18
	v_and_b32_e32 v0, 63, v98
	v_sub_f32_e32 v3, v4, v23
	v_exp_f32_e32 v21, v3
	v_lshlrev_b32_e32 v3, 2, v0
	v_add_u32_e32 v24, v20, v3
	ds_read_b32 v4, v24 offset:56328
	s_waitcnt lgkmcnt(0)
	v_fma_f32 v25, v4, v21, 0
	v_sub_f32_e32 v4, v6, v23
	v_exp_f32_e32 v20, v4
	v_mov_b32_e32 v4, v7
	v_pk_mul_f32 v[4:5], v[4:5], v[20:21]
	s_nop 0
	v_add_f32_e32 v5, 0, v5
	v_add_f32_e32 v21, v4, v5
	ds_read_b32 v4, v24 offset:57384
	ds_read_b32 v5, v24 offset:58440
	s_waitcnt lgkmcnt(1)
	v_fmac_f32_e32 v25, v20, v4
	v_sub_f32_e32 v4, v8, v23
	v_exp_f32_e32 v4, v4
	s_waitcnt lgkmcnt(0)
	v_fmac_f32_e32 v25, v4, v5
	v_sub_f32_e32 v5, v10, v23
	v_exp_f32_e32 v5, v5
	v_mov_b32_e32 v10, v9
	v_pk_mul_f32 v[6:7], v[4:5], v[10:11]
	s_nop 0
	v_add_f32_e32 v4, v21, v6
	v_add_f32_e32 v8, v4, v7
	ds_read_b32 v4, v24 offset:59496
	s_waitcnt lgkmcnt(0)
	v_fmac_f32_e32 v25, v5, v4
	v_sub_f32_e32 v4, v12, v23
	ds_read_b32 v5, v24 offset:60552
	v_exp_f32_e32 v4, v4
	s_waitcnt lgkmcnt(0)
	v_fmac_f32_e32 v25, v4, v5
	v_sub_f32_e32 v5, v14, v23
	v_exp_f32_e32 v5, v5
	v_mov_b32_e32 v14, v13
	v_pk_mul_f32 v[6:7], v[4:5], v[14:15]
	s_nop 0
	v_add_f32_e32 v4, v8, v6
	v_add_f32_e32 v8, v4, v7
	ds_read_b32 v4, v24 offset:61608
	s_waitcnt lgkmcnt(0)
	v_fmac_f32_e32 v25, v5, v4
	v_sub_f32_e32 v4, v16, v23
	ds_read_b32 v5, v24 offset:62664
	v_exp_f32_e32 v4, v4
	s_waitcnt lgkmcnt(0)
	v_fmac_f32_e32 v25, v4, v5
	v_sub_f32_e32 v5, v18, v23
	v_exp_f32_e32 v5, v5
	v_mov_b32_e32 v18, v17
	v_pk_mul_f32 v[6:7], v[4:5], v[18:19]
	s_nop 0
	v_add_f32_e32 v4, v8, v6
	ds_read_b32 v6, v24 offset:63720
	v_add_f32_e32 v4, v4, v7
	v_cmp_lt_f32_e64 s[0:1], 0, v4
	s_waitcnt lgkmcnt(0)
	v_fmac_f32_e32 v25, v5, v6
	v_div_scale_f32 v5, s[2:3], v4, v4, v25
	v_rcp_f32_e32 v6, v5
	s_nop 0
	v_fma_f32 v7, -v5, v6, 1.0
	v_fmac_f32_e32 v6, v7, v6
	v_div_scale_f32 v7, vcc, v25, v4, v25
	v_mul_f32_e32 v8, v7, v6
	v_fma_f32 v9, -v5, v8, v7
	v_fmac_f32_e32 v8, v9, v6
	v_fma_f32 v5, -v5, v8, v7
	v_div_fmas_f32 v5, v5, v6, v8
	v_div_fixup_f32 v4, v5, v4, v25
	v_cndmask_b32_e64 v4, 0, v4, s[0:1]
	v_and_b32_e32 v5, 0x3fffff00, v117
	v_readlane_b32 s0, v251, 62
	v_lshlrev_b32_e32 v6, 8, v22
	s_nop 0
	v_lshl_add_u32 v5, v5, 2, s0
	s_movk_i32 s0, 0x100
	v_add3_u32 v5, v5, v6, v3
	v_cmp_gt_i32_e32 vcc, s0, v117
	ds_write_b32 v5, v4
	s_waitcnt lgkmcnt(0)
	s_barrier
	s_and_saveexec_b64 s[0:1], vcc
	s_cbranch_execz .LBB0_1486
	v_readlane_b32 s2, v250, 58
	v_readlane_b32 s3, v250, 59
	s_add_u32 s2, s2, s25
	s_addc_u32 s3, s3, 0
	s_add_u32 s2, s2, 0x8000
	s_addc_u32 s3, s3, 0
	v_readlane_b32 s4, v253, 25
	s_mul_hi_u32 s5, s2, 0x60
	v_readlane_b32 s6, v251, 21
	v_add_u32_e32 v6, s4, v2
	s_mul_i32 s4, s3, 0x60
	s_add_i32 s5, s5, s4
	s_mul_i32 s4, s2, 0x60
	s_add_u32 s4, s6, s4
	v_readlane_b32 s6, v251, 22
	v_lshl_add_u32 v4, v6, 1, v6
	s_addc_u32 s5, s6, s5
	v_ashrrev_i32_e32 v5, 31, v4
	v_lshl_add_u64 v[4:5], v[4:5], 2, s[4:5]
	global_load_dwordx2 v[4:5], v[4:5], off offset:4
	v_lshlrev_b32_e32 v2, 2, v117
	v_and_b32_e32 v8, 0x3fffffc0, v117
	v_add_u32_e32 v7, 0, v2
	v_readlane_b32 s4, v251, 62
	v_lshlrev_b32_e32 v8, 2, v8
	v_add_u32_e32 v7, 0x12600, v7
	v_add_u32_e32 v2, s4, v2
	v_add3_u32 v3, s4, v8, v3
	ds_read_b32 v7, v7
	ds_read_b32 v2, v2
	ds_read_b32 v3, v3 offset:1024
	s_lshl_b64 s[4:5], s[2:3], 10
	v_readlane_b32 s6, v251, 31
	s_add_u32 s4, s6, s4
	v_readlane_b32 s6, v251, 32
	s_addc_u32 s5, s6, s5
	v_lshlrev_b32_e32 v0, 1, v0
	s_lshl_b64 s[2:3], s[2:3], 11
	s_waitcnt vmcnt(0) lgkmcnt(0)
	v_pk_mul_f32 v[2:3], v[4:5], v[2:3]
	s_nop 0
	v_add_f32_e32 v2, v7, v2
	v_add_f32_e32 v7, v2, v3
	v_lshlrev_b32_e32 v2, 6, v6
	v_ashrrev_i32_e32 v3, 31, v2
	v_lshlrev_b64 v[2:3], 1, v[2:3]
	v_lshl_add_u64 v[4:5], s[4:5], 0, v[2:3]
	v_lshl_add_u64 v[4:5], v[4:5], 0, v[0:1]
	global_load_ushort v4, v[4:5], off
	v_readlane_b32 s4, v251, 33
	s_add_u32 s2, s4, s2
	v_readlane_b32 s4, v251, 34
	s_addc_u32 s3, s4, s3
	v_lshl_add_u64 v[2:3], s[2:3], 0, v[2:3]
	v_lshl_add_u64 v[2:3], v[2:3], 0, v[0:1]
	s_waitcnt vmcnt(0)
	v_lshlrev_b32_e32 v4, 16, v4
	v_mul_f32_e32 v4, v7, v4
	v_cvt_pk_bf16_f32 v4, v4, v4
	global_store_short_d16_hi v[2:3], v4, off
	s_branch .LBB0_1486

; #define LAS __attribute__((address_space(3)))
; template <int MODE, int THRL>
; __device__ __forceinline__ void attn_unit(const Prm& P, int b, int h, int qb, LAS char* shm, int wid) {
;   int lane; asm volatile("v_mbcnt_lo_u32_b32 %0, -1, 0\n\tv_mbcnt_hi_u32_b32 %0, -1, %0" : "=v"(lane));
;   const int r32 = lane & 31, hi = lane >> 5;
;   const int kvh = h >> 2;
;   const long rowbase = (long)b * SEQ; const int q0 = qb * QB;
;   const int NT = MODE == 0 ? 4 * qb + 4 : (qb >= 2 ? 12 : 4 * qb + 4);
;   const int t_lo = 4 * qb + 4 - NT;
;   const bool lowband = (MODE == 1) && (NT == 12);
;   const float NEG = MODE == 0 ? -INFINITY : -1024.f;
;   const bf16_t* Qw = (const bf16_t*)(P.ws + WS_Q) + (rowbase + q0 + wid * QBLK) * QP + h * 64;
;   const bf16_t* Kh = (const bf16_t*)(P.ws + (MODE == 0 ? WS_KS : WS_KW)) + (rowbase + (long)t_lo * KVBLK) * KP + kvh * 64;
;   const bf16_t* Vh = Kh + 128;
;   const unsigned lds0 = (unsigned)(uintptr_t)shm;
;   LAS float* wsf = (LAS float*)(shm + LDS_WS + wid * WSB);
;   LAS unsigned* selp = (LAS unsigned*)(shm + LDS_WS + wid * WSB + 256) + r32;
;   const unsigned ksoff = (unsigned)(lane * KP + wid * 8) * 2u;
;   const unsigned vsoff = (unsigned)((16 * (wid & 3) + (lane >> 2)) * KP + (wid >> 2) * 32 + (lane & 3) * 8) * 2u;
;   const unsigned kdst = lds0 + LDS_K + wid * 1024, vdst = lds0 + LDS_V + wid * 1024;
;     ...
;   const int vb0 = (int)(lds0 + LDS_V) + ((lane >> 4) & 1) * 32 + (lane & 3) * 8 + (4 * hi + ((lane & 15) >> 2)) * 64;
;   bf16x8 kf[8];
;   const lds_cptr shm3 = (lds_cptr)shm; const lds_cptr kp0 = shm3 + LDS_K + hi * 1024 + r32 * 16; const lds_cptr vp0 = shm3 + LDS_V + ((lane >> 4) & 1) * 32 + (lane & 3) * 8 + (4 * hi + ((lane & 15) >> 2)) * 64;
;   DMA_K(0, 0); DMA_V(0, 0); DMA_K(1, SLOTB);
;   bf16x8 qr[4];
; #pragma unroll
;   for (int d0 = 0; d0 < 4; ++d0) qr[d0] = *(const bf16x8*)(&Qw[(long)r32 * QP + d0 * 16 + hi * 8]);
;     ...
;   float rli[16];
; #pragma unroll
;   for (int r = 0; r < 16; ++r) rli[r] = wsf[32 + crow(r, hi)];
;   { LAS bf16_t* stg = (LAS bf16_t*)(shm + (MODE == 0 ? LDS_OS2 : LDS_OST)) + wid * 2048;
; #pragma unroll
;     for (int r = 0; r < 16; ++r) { const int orow = crow(r, hi);
; #pragma unroll
;       for (int d0 = 0; d0 < 2; ++d0) stg[orow * 64 + d0 * 32 + r32] = (bf16_t)f2bf(o[d0][r] * rli[r]); }
;     asm volatile("s_waitcnt lgkmcnt(0)" ::: "memory");
.LBB0_1679:
	s_or_b64 exec, exec, s[2:3]
	s_waitcnt lgkmcnt(0)
	ds_read_b128 v[4:7], v2 offset:49280
	ds_read_b128 v[8:11], v2 offset:49312
	ds_read_b128 v[12:15], v2 offset:49344
	ds_read_b128 v[48:51], v2 offset:49376
	v_lshlrev_b32_e32 v0, 9, v189
	v_lshlrev_b32_e32 v2, 1, v188
	v_add3_u32 v0, s46, v0, v2
	s_waitcnt lgkmcnt(3)
	v_mul_f32_e32 v2, v32, v4
	s_movk_i32 s0, 0x7fff
	v_cvt_pk_bf16_f32 v2, v2, v2
	ds_write_b16_d16_hi v0, v2
	v_mul_f32_e32 v2, v16, v4
	v_cvt_pk_bf16_f32 v2, v2, v2
	ds_write_b16_d16_hi v0, v2 offset:64
	v_mul_f32_e32 v2, v33, v5
	v_cvt_pk_bf16_f32 v2, v2, v2
	ds_write_b16_d16_hi v0, v2 offset:128
	v_mul_f32_e32 v2, v17, v5
	v_cvt_pk_bf16_f32 v2, v2, v2
	ds_write_b16_d16_hi v0, v2 offset:192
	v_mul_f32_e32 v2, v34, v6
	v_cvt_pk_bf16_f32 v2, v2, v2
	ds_write_b16_d16_hi v0, v2 offset:256
	v_mul_f32_e32 v2, v18, v6
	v_cvt_pk_bf16_f32 v2, v2, v2
	ds_write_b16_d16_hi v0, v2 offset:320
	v_mul_f32_e32 v2, v35, v7
	v_cvt_pk_bf16_f32 v2, v2, v2
	ds_write_b16_d16_hi v0, v2 offset:384
	v_mul_f32_e32 v2, v19, v7
	v_cvt_pk_bf16_f32 v2, v2, v2
	ds_write_b16_d16_hi v0, v2 offset:448
	s_waitcnt lgkmcnt(10)
	v_mul_f32_e32 v2, v36, v8
	v_cvt_pk_bf16_f32 v2, v2, v2
	ds_write_b16_d16_hi v0, v2 offset:1024
	v_mul_f32_e32 v2, v20, v8
	v_cvt_pk_bf16_f32 v2, v2, v2
	ds_write_b16_d16_hi v0, v2 offset:1088
	v_mul_f32_e32 v2, v37, v9
	v_cvt_pk_bf16_f32 v2, v2, v2
	ds_write_b16_d16_hi v0, v2 offset:1152
	v_mul_f32_e32 v2, v21, v9
	v_cvt_pk_bf16_f32 v2, v2, v2
	ds_write_b16_d16_hi v0, v2 offset:1216
	v_mul_f32_e32 v2, v38, v10
	v_cvt_pk_bf16_f32 v2, v2, v2
	ds_write_b16_d16_hi v0, v2 offset:1280
	v_mul_f32_e32 v2, v22, v10
	v_cvt_pk_bf16_f32 v2, v2, v2
	ds_write_b16_d16_hi v0, v2 offset:1344
	v_mul_f32_e32 v2, v39, v11
	v_cvt_pk_bf16_f32 v2, v2, v2
	ds_write_b16_d16_hi v0, v2 offset:1408
	v_mul_f32_e32 v2, v23, v11
	v_cvt_pk_bf16_f32 v2, v2, v2
	ds_write_b16_d16_hi v0, v2 offset:1472
	s_waitcnt lgkmcnt(14)
	v_mul_f32_e32 v2, v40, v12
	v_cvt_pk_bf16_f32 v2, v2, v2
	ds_write_b16_d16_hi v0, v2 offset:2048
	v_mul_f32_e32 v2, v24, v12
	v_cvt_pk_bf16_f32 v2, v2, v2
	ds_write_b16_d16_hi v0, v2 offset:2112
	v_mul_f32_e32 v2, v41, v13
	v_cvt_pk_bf16_f32 v2, v2, v2
	ds_write_b16_d16_hi v0, v2 offset:2176
	v_mul_f32_e32 v2, v25, v13
	v_cvt_pk_bf16_f32 v2, v2, v2
	ds_write_b16_d16_hi v0, v2 offset:2240
	v_mul_f32_e32 v2, v42, v14
	v_cvt_pk_bf16_f32 v2, v2, v2
	ds_write_b16_d16_hi v0, v2 offset:2304
	v_mul_f32_e32 v2, v26, v14
	v_cvt_pk_bf16_f32 v2, v2, v2
	ds_write_b16_d16_hi v0, v2 offset:2368
	v_mul_f32_e32 v2, v43, v15
	v_cvt_pk_bf16_f32 v2, v2, v2
	ds_write_b16_d16_hi v0, v2 offset:2432
	v_mul_f32_e32 v2, v27, v15
	v_cvt_pk_bf16_f32 v2, v2, v2
	ds_write_b16_d16_hi v0, v2 offset:2496
	v_mul_f32_e32 v2, v44, v48
	v_cvt_pk_bf16_f32 v2, v2, v2
	ds_write_b16_d16_hi v0, v2 offset:3072
	v_mul_f32_e32 v2, v28, v48
	v_cvt_pk_bf16_f32 v2, v2, v2
	ds_write_b16_d16_hi v0, v2 offset:3136
	v_mul_f32_e32 v2, v45, v49
	v_cvt_pk_bf16_f32 v2, v2, v2
	ds_write_b16_d16_hi v0, v2 offset:3200
	v_mul_f32_e32 v2, v29, v49
	v_cvt_pk_bf16_f32 v2, v2, v2
	ds_write_b16_d16_hi v0, v2 offset:3264
	v_mul_f32_e32 v2, v46, v50
	v_cvt_pk_bf16_f32 v2, v2, v2
	ds_write_b16_d16_hi v0, v2 offset:3328
	v_mul_f32_e32 v2, v30, v50
	v_cvt_pk_bf16_f32 v2, v2, v2
	ds_write_b16_d16_hi v0, v2 offset:3392
	v_mul_f32_e32 v2, v47, v51
	v_cvt_pk_bf16_f32 v2, v2, v2
	ds_write_b16_d16_hi v0, v2 offset:3456
	v_mul_f32_e32 v2, v31, v51
	s_cmp_lt_i32 s21, 2
	s_cselect_b32 s29, s31, 12
	v_cvt_pk_bf16_f32 v2, v2, v2
	s_sub_i32 s0, s31, s29
	v_readlane_b32 s2, v251, 18
	v_readlane_b32 s3, v251, 19
	s_add_u32 s1, s2, s8
	s_addc_u32 s2, s3, s9
	s_lshl_b32 s24, s30, 1
	s_add_u32 s8, s1, s24
	s_addc_u32 s9, s2, 0
	s_ashr_i32 s1, s0, 31
	s_lshl_b64 s[0:1], s[0:1], 15
	v_readlane_b32 s2, v251, 41
	s_add_u32 s0, s2, s0
	v_readlane_b32 s2, v251, 42
	ds_write_b16_d16_hi v0, v2 offset:3520
	s_addc_u32 s1, s2, s1
	s_waitcnt lgkmcnt(0)
	s_add_u32 s0, s0, s6
	s_waitcnt vmcnt(0) lgkmcnt(0)
	s_barrier
	v_mbcnt_lo_u32_b32 v208, -1, 0
	v_mbcnt_hi_u32_b32 v208, -1, v208
	s_addc_u32 s1, s1, s7
	v_lshrrev_b32_e32 v0, 2, v208
	s_add_u32 s2, s0, s27
	v_add_u32_e32 v0, s42, v0
	v_lshlrev_b32_e32 v2, 3, v208
	v_ashrrev_i32_e32 v206, 5, v208
	s_addc_u32 s3, s1, 0
	v_lshl_add_u32 v0, v0, 8, s43
	v_and_b32_e32 v210, 24, v2
	s_add_u32 s10, s2, 0x100
	v_lshl_add_u32 v220, v208, 9, s41
	v_or_b32_e32 v0, v0, v210
	s_mov_b32 s0, m0
	s_mov_b32 m0, s44
	s_nop 0
	global_load_lds_dwordx4 v220, s[2:3]
	s_mov_b32 m0, s0
	v_lshlrev_b32_e32 v2, 3, v206
	v_and_b32_e32 v204, 31, v208
	s_addc_u32 s11, s3, 0
	v_lshlrev_b32_e32 v222, 1, v0
	s_mov_b32 s0, m0
	s_mov_b32 m0, s45
	s_nop 0
	global_load_lds_dwordx4 v222, s[10:11]
	s_mov_b32 m0, s0
	v_ashrrev_i32_e32 v3, 31, v2
	s_add_u32 s0, s2, 0x8000
	v_lshl_add_u64 v[2:3], v[2:3], 1, s[8:9]
	v_lshlrev_b32_e32 v0, 10, v204
	s_addc_u32 s1, s3, 0
	s_mov_b32 s6, m0
	s_mov_b32 m0, s26
	s_nop 0
	global_load_lds_dwordx4 v220, s[0:1]
	s_mov_b32 m0, s6
	v_lshl_add_u64 v[2:3], v[2:3], 0, v[0:1]
	global_load_dwordx4 v[140:143], v[2:3], off
	global_load_dwordx4 v[136:139], v[2:3], off offset:32
	global_load_dwordx4 v[132:135], v[2:3], off offset:64
	global_load_dwordx4 v[128:131], v[2:3], off offset:96
	v_lshlrev_b32_e32 v0, 10, v206
	v_lshlrev_b32_e32 v4, 4, v204
	v_add3_u32 v226, 0, v0, v4
	v_mov_b32_e32 v2, v1
	v_mov_b32_e32 v3, v1
	v_mov_b32_e32 v4, v1
	v_mov_b32_e32 v5, v1
	v_mov_b32_e32 v6, v1
	v_mov_b32_e32 v7, v1
	v_mov_b32_e32 v8, v1
	v_mov_b32_e32 v9, v1
	v_mov_b32_e32 v10, v1
	v_mov_b32_e32 v11, v1
	v_mov_b32_e32 v12, v1
	v_mov_b32_e32 v13, v1
	v_mov_b32_e32 v14, v1
	v_mov_b32_e32 v15, v1
	v_mov_b32_e32 v0, v1
	v_mov_b64_e32 v[16:17], v[14:15]
	v_mov_b64_e32 v[14:15], v[12:13]
	v_mov_b64_e32 v[12:13], v[10:11]
	v_mov_b64_e32 v[10:11], v[8:9]
	v_mov_b64_e32 v[8:9], v[6:7]
	v_mov_b64_e32 v[6:7], v[4:5]
	v_mov_b64_e32 v[4:5], v[2:3]
	v_mov_b64_e32 v[2:3], v[0:1]
	s_add_u32 s0, s2, 0x10000
	s_addc_u32 s1, s3, 0
	s_mov_b32 s6, m0
	s_mov_b32 m0, s28
	s_nop 0
	global_load_lds_dwordx4 v220, s[0:1]
	s_mov_b32 m0, s6
	s_waitcnt vmcnt(3) lgkmcnt(0)
	s_barrier
; #define LAS __attribute__((address_space(3)))
; #define MFMA32(a, b, c) __builtin_amdgcn_mfma_f32_32x32x16_bf16((a), (b), (c), 0, 0, 0)
; #define CMASK(P0, P1, t) do { int jb_ = (t) - (NT - 4); if (jb_ >= 0) cmask(P0, P1, jb_, qrel, hi, NEG); if (lowband && (t) < 4) lmask(P0, P1, (t), qrel, hi, NEG); } while (0)
; #define CMASK(P0, P1, t) do { if (lowband && (t) < 4) lmask(P0, P1, (t), qrel, hi, NEG); } while (0)
; #define CMASK(P0, P1, t) do { int jb_ = (t) - (NT - 4); if (jb_ >= 0) cmask(P0, P1, jb_, qrel, hi, NEG); if (lowband && (t) < 4) lmask(P0, P1, (t), qrel, hi, NEG); } while (0)
; __device__ __forceinline__ void cmask(f32x16& p0, f32x16& p1, int jb, int qrel, int hi, float NEG) {
;   asm volatile("" : "+v"(qrel));
;   const int kb = 64 * jb + 4 * hi;
; #pragma unroll
;   for (int r = 0; r < 16; ++r) { const int kv = kb + (r & 3) + 8 * (r >> 2); if (kv > qrel) p0[r] = NEG; if (kv + 32 > qrel) p1[r] = NEG; }
; }
; template <int MODE, int THRL>
; __device__ __forceinline__ void attn_unit(const Prm& P, int b, int h, int qb, LAS char* shm, int wid) {
;     ...
;   {
;     const lds_cptr kb = shm3 + LDS_K + hi * 1024 + r32 * 16;
; #pragma unroll
;     for (int d0 = 0; d0 < 4; ++d0) {
;       const bf16x8 b0 = *(const LAS bf16x8*)(kb + d0 * 2048), b1 = *(const LAS bf16x8*)(kb + d0 * 2048 + 512);
;       if (d0 == 0) { pA0 = MFMA32(b0, qr[0], negm); pA1 = MFMA32(b1, qr[0], negm); }
;       else { pA0 = MFMA32(b0, qr[d0], pA0); pA1 = MFMA32(b1, qr[d0], pA1); } }
;   }
;   asm volatile("s_nop 15\n\ts_nop 7" : "+v"(pA0), "+v"(pA1)); CMASK(pA0, pA1, 0);
	ds_read_b128 v[34:37], v226
	s_waitcnt vmcnt(3) lgkmcnt(0)
	v_mfma_f32_32x32x16_bf16 v[18:33], v[34:37], v[140:143], v[2:17]
	ds_read_b128 v[34:37], v226 offset:512
	v_readlane_b32 s0, v251, 53
	s_cmp_gt_u32 s29, 4
	s_nop 0
	v_or_b32_e32 v218, s0, v204
	s_waitcnt lgkmcnt(0)
	v_mfma_f32_32x32x16_bf16 v[2:17], v[34:37], v[140:143], v[2:17]
	ds_read_b128 v[34:37], v226 offset:2048
	s_waitcnt vmcnt(2) lgkmcnt(0)
	v_mfma_f32_32x32x16_bf16 v[18:33], v[34:37], v[136:139], v[18:33]
	ds_read_b128 v[34:37], v226 offset:2560
	s_waitcnt lgkmcnt(0)
	v_mfma_f32_32x32x16_bf16 v[2:17], v[34:37], v[136:139], v[2:17]
	ds_read_b128 v[34:37], v226 offset:4096
	s_waitcnt vmcnt(1) lgkmcnt(0)
	v_mfma_f32_32x32x16_bf16 v[18:33], v[34:37], v[132:135], v[18:33]
	ds_read_b128 v[34:37], v226 offset:4608
	s_waitcnt lgkmcnt(0)
	v_mfma_f32_32x32x16_bf16 v[2:17], v[34:37], v[132:135], v[2:17]
	ds_read_b128 v[34:37], v226 offset:6144
	s_waitcnt vmcnt(0) lgkmcnt(0)
	v_mfma_f32_32x32x16_bf16 v[18:33], v[34:37], v[128:131], v[18:33]
	ds_read_b128 v[34:37], v226 offset:6656
	s_waitcnt lgkmcnt(0)
	v_mfma_f32_32x32x16_bf16 v[2:17], v[34:37], v[128:131], v[2:17]
	s_nop 15
	s_nop 7
	s_cbranch_scc1 .LBB0_1681
	v_lshlrev_b32_e32 v34, 2, v206
	v_mov_b32_e32 v0, v218
	v_add_u32_e32 v35, 32, v34
	s_nop 0
	v_cmp_le_i32_e32 vcc, v35, v0
	v_add_u32_e32 v35, 33, v34
	s_nop 4
	v_cndmask_b32_e32 v2, v219, v2, vcc
	v_cmp_lt_i32_e32 vcc, v34, v0
	s_nop 1
	v_cndmask_b32_e32 v19, v219, v19, vcc
	v_cmp_le_i32_e32 vcc, v34, v0
	s_nop 1
	v_cndmask_b32_e32 v18, v219, v18, vcc
	v_cmp_le_i32_e32 vcc, v35, v0
	v_or_b32_e32 v35, 2, v34
	s_nop 0
	v_cndmask_b32_e32 v3, v219, v3, vcc
	v_cmp_le_i32_e32 vcc, v35, v0
	v_add_u32_e32 v35, 34, v34
	s_nop 0
	v_cndmask_b32_e32 v20, v219, v20, vcc
	v_cmp_le_i32_e32 vcc, v35, v0
	v_or_b32_e32 v35, 3, v34
	s_nop 0
	v_cndmask_b32_e32 v4, v219, v4, vcc
	v_cmp_le_i32_e32 vcc, v35, v0
	v_add_u32_e32 v35, 35, v34
	s_nop 0
	v_cndmask_b32_e32 v21, v219, v21, vcc
	v_cmp_le_i32_e32 vcc, v35, v0
	v_add_u32_e32 v35, 8, v34
	s_nop 0
	v_cndmask_b32_e32 v5, v219, v5, vcc
	v_cmp_le_i32_e32 vcc, v35, v0
	v_add_u32_e32 v35, 40, v34
	s_nop 0
	v_cndmask_b32_e32 v22, v219, v22, vcc
	v_cmp_le_i32_e32 vcc, v35, v0
	v_add_u32_e32 v35, 9, v34
	s_nop 0
	v_cndmask_b32_e32 v6, v219, v6, vcc
	v_cmp_le_i32_e32 vcc, v35, v0
	v_add_u32_e32 v35, 41, v34
	s_nop 0
	v_cndmask_b32_e32 v23, v219, v23, vcc
	v_cmp_le_i32_e32 vcc, v35, v0
	v_add_u32_e32 v35, 10, v34
	s_nop 0
	v_cndmask_b32_e32 v7, v219, v7, vcc
	v_cmp_le_i32_e32 vcc, v35, v0
	v_add_u32_e32 v35, 42, v34
	s_nop 0
	v_cndmask_b32_e32 v24, v219, v24, vcc
	v_cmp_le_i32_e32 vcc, v35, v0
	v_add_u32_e32 v35, 11, v34
	s_nop 0
	v_cndmask_b32_e32 v8, v219, v8, vcc
	v_cmp_le_i32_e32 vcc, v35, v0
	v_add_u32_e32 v35, 43, v34
	s_nop 0
	v_cndmask_b32_e32 v25, v219, v25, vcc
	v_cmp_le_i32_e32 vcc, v35, v0
	v_add_u32_e32 v35, 16, v34
	s_nop 0
	v_cndmask_b32_e32 v9, v219, v9, vcc
	v_cmp_le_i32_e32 vcc, v35, v0
	v_add_u32_e32 v35, 48, v34
	s_nop 0
	v_cndmask_b32_e32 v26, v219, v26, vcc
	v_cmp_le_i32_e32 vcc, v35, v0
	v_add_u32_e32 v35, 17, v34
	s_nop 0
	v_cndmask_b32_e32 v10, v219, v10, vcc
	v_cmp_le_i32_e32 vcc, v35, v0
	v_add_u32_e32 v35, 49, v34
	s_nop 0
	v_cndmask_b32_e32 v27, v219, v27, vcc
	v_cmp_le_i32_e32 vcc, v35, v0
	v_add_u32_e32 v35, 18, v34
	s_nop 0
	v_cndmask_b32_e32 v11, v219, v11, vcc
	v_cmp_le_i32_e32 vcc, v35, v0
	v_add_u32_e32 v35, 50, v34
	s_nop 0
	v_cndmask_b32_e32 v28, v219, v28, vcc
	v_cmp_le_i32_e32 vcc, v35, v0
	v_add_u32_e32 v35, 19, v34
	s_nop 0
	v_cndmask_b32_e32 v12, v219, v12, vcc
	v_cmp_le_i32_e32 vcc, v35, v0
	v_add_u32_e32 v35, 51, v34
	s_nop 0
	v_cndmask_b32_e32 v29, v219, v29, vcc
	v_cmp_le_i32_e32 vcc, v35, v0
	v_add_u32_e32 v35, 24, v34
	s_nop 0
	v_cndmask_b32_e32 v13, v219, v13, vcc
	v_cmp_le_i32_e32 vcc, v35, v0
	v_add_u32_e32 v35, 56, v34
	s_nop 0
	v_cndmask_b32_e32 v30, v219, v30, vcc
	v_cmp_le_i32_e32 vcc, v35, v0
	v_add_u32_e32 v35, 25, v34
	s_nop 0
	v_cndmask_b32_e32 v14, v219, v14, vcc
	v_cmp_le_i32_e32 vcc, v35, v0
	v_add_u32_e32 v35, 57, v34
	s_nop 0
	v_cndmask_b32_e32 v31, v219, v31, vcc
	v_cmp_le_i32_e32 vcc, v35, v0
	v_add_u32_e32 v35, 26, v34
	s_nop 0
	v_cndmask_b32_e32 v15, v219, v15, vcc
	v_cmp_le_i32_e32 vcc, v35, v0
	v_add_u32_e32 v35, 58, v34
	s_nop 0
	v_cndmask_b32_e32 v32, v219, v32, vcc
	v_cmp_le_i32_e32 vcc, v35, v0
	v_add_u32_e32 v35, 27, v34
	v_add_u32_e32 v34, 59, v34
	v_cndmask_b32_e32 v16, v219, v16, vcc
	v_cmp_le_i32_e32 vcc, v35, v0
	s_nop 1
	v_cndmask_b32_e32 v33, v219, v33, vcc
	v_cmp_le_i32_e32 vcc, v34, v0
	s_nop 1
	v_cndmask_b32_e32 v17, v219, v17, vcc

; __device__ __forceinline__ unsigned pk2(float lo, float hi) { return f2bf(lo) | (f2bf(hi) << 16); }
; #define EPI_LOOP_ROWS(body) _Pragma("unroll") for (int ai = 0; ai < 2; ++ai) _Pragma("unroll") for (int m = 0; m < 4; ++m) { const int row = u.pm * 256 + ai * 128 + wr * 64 + m * 16 + fr; body }
; __device__ __forceinline__ void st8bf(bf16_t* p, f32x4 a, f32x4 b) { u32x4 w; w.x = pk2(a[0], a[1]); w.y = pk2(a[2], a[3]); w.z = pk2(b[0], b[1]); w.w = pk2(b[2], b[3]); st16(p, w); }
;     __device__ __forceinline__ void operator()(const f32x4 (&acc)[2][2][4][2], const pg8::Unit& u, int wr, int wc, int fr, int fq) const {
;         const int cw = wc * 32 + 8 * fq;
;         EPI_LOOP_ROWS( _Pragma("unroll") for (int bj = 0; bj < 2; ++bj) st8bf(W3P + (size_t)row * 1024 + u.pn * 256 + bj * 128 + cw, acc[ai][bj][m][0], acc[ai][bj][m][1]); )
;     }
.LBB0_1777:
	v_lshl_add_u32 v128, s0, 8, v128
	v_or_b32_e32 v134, s13, v129
	v_ashrrev_i32_e32 v129, 31, v128
	v_lshlrev_b64 v[130:131], 11, v[128:129]
	s_movk_i32 s4, 0x7fff
	s_mov_b32 s5, 0xffff0000
	v_cvt_pk_bf16_f32 v124, v124, v125
	v_cvt_pk_bf16_f32 v125, v126, v127
	v_cvt_pk_bf16_f32 v126, v120, v121
	v_cvt_pk_bf16_f32 v127, v122, v123
	v_cvt_pk_bf16_f32 v116, v116, v117
	v_cvt_pk_bf16_f32 v117, v118, v119
	v_cvt_pk_bf16_f32 v118, v112, v113
	v_cvt_pk_bf16_f32 v108, v108, v109
	v_cvt_pk_bf16_f32 v109, v110, v111
	v_cvt_pk_bf16_f32 v110, v104, v105
	v_cvt_pk_bf16_f32 v111, v106, v107
	v_cvt_pk_bf16_f32 v100, v100, v101
	v_cvt_pk_bf16_f32 v101, v102, v103
	v_cvt_pk_bf16_f32 v102, v96, v97
	v_cvt_pk_bf16_f32 v92, v92, v93
	v_cvt_pk_bf16_f32 v93, v94, v95
	v_cvt_pk_bf16_f32 v94, v88, v89
	v_cvt_pk_bf16_f32 v95, v90, v91
	v_cvt_pk_bf16_f32 v84, v84, v85
	v_cvt_pk_bf16_f32 v85, v86, v87
	v_cvt_pk_bf16_f32 v86, v80, v81
	v_cvt_pk_bf16_f32 v76, v76, v77
	v_cvt_pk_bf16_f32 v77, v78, v79
	v_cvt_pk_bf16_f32 v78, v72, v73
	v_cvt_pk_bf16_f32 v79, v74, v75
	v_cvt_pk_bf16_f32 v68, v68, v69
	v_cvt_pk_bf16_f32 v69, v70, v71
	v_cvt_pk_bf16_f32 v70, v60, v61
	v_readlane_b32 s24, v250, 49
	v_readlane_b32 s28, v250, 53
	v_cvt_pk_bf16_f32 v87, v82, v83
	v_or_b32_e32 v80, 48, v128
	v_readlane_b32 s29, v250, 54
	s_add_u32 s2, s28, 0x2b00000
	v_ashrrev_i32_e32 v81, 31, v80
	v_cvt_pk_bf16_f32 v71, v62, v63
	v_add_u32_e32 v60, 0x80, v128
	s_addc_u32 s3, s29, 0
	v_lshlrev_b64 v[80:81], 11, v[80:81]
	v_ashrrev_i32_e32 v61, 31, v60
	v_lshl_add_u64 v[130:131], s[2:3], 0, v[130:131]
	s_lshl_b32 s0, s12, 9
	v_lshl_add_u64 v[80:81], s[2:3], 0, v[80:81]
	v_lshlrev_b64 v[60:61], 11, v[60:61]
	v_lshl_add_u64 v[132:133], v[130:131], 0, s[0:1]
	v_lshlrev_b32_e32 v130, 1, v134
	v_mov_b32_e32 v131, 0
	v_lshl_add_u64 v[80:81], v[80:81], 0, s[0:1]
	v_lshl_add_u64 v[60:61], s[2:3], 0, v[60:61]
	v_lshl_add_u64 v[80:81], v[80:81], 0, v[130:131]
	v_lshl_add_u64 v[60:61], v[60:61], 0, s[0:1]
	global_store_dwordx4 v[80:81], v[68:71], off offset:256
	s_nop 1
	v_lshl_add_u64 v[68:69], v[60:61], 0, v[130:131]
	v_cvt_pk_bf16_f32 v60, v64, v65
	v_cvt_pk_bf16_f32 v61, v66, v67
	v_cvt_pk_bf16_f32 v62, v56, v57
	v_cvt_pk_bf16_f32 v63, v58, v59
	v_cvt_pk_bf16_f32 v52, v52, v53
	v_cvt_pk_bf16_f32 v53, v54, v55
	v_cvt_pk_bf16_f32 v54, v48, v49
	v_cvt_pk_bf16_f32 v44, v44, v45
	v_cvt_pk_bf16_f32 v45, v46, v47
	v_cvt_pk_bf16_f32 v46, v40, v41
	v_cvt_pk_bf16_f32 v47, v42, v43
	v_cvt_pk_bf16_f32 v36, v36, v37
	v_cvt_pk_bf16_f32 v37, v38, v39
	v_cvt_pk_bf16_f32 v38, v32, v33
	v_cvt_pk_bf16_f32 v28, v28, v29
	v_cvt_pk_bf16_f32 v29, v30, v31
	v_cvt_pk_bf16_f32 v30, v24, v25
	v_cvt_pk_bf16_f32 v31, v26, v27
	v_cvt_pk_bf16_f32 v20, v20, v21
	v_cvt_pk_bf16_f32 v21, v22, v23
	v_cvt_pk_bf16_f32 v22, v16, v17
	v_cvt_pk_bf16_f32 v12, v12, v13
	v_cvt_pk_bf16_f32 v13, v14, v15
	v_cvt_pk_bf16_f32 v14, v8, v9
	v_cvt_pk_bf16_f32 v15, v10, v11
	v_cvt_pk_bf16_f32 v4, v4, v5
	v_cvt_pk_bf16_f32 v5, v6, v7
	v_cvt_pk_bf16_f32 v119, v114, v115
	v_or_b32_e32 v112, 16, v128
	v_cvt_pk_bf16_f32 v103, v98, v99
	v_or_b32_e32 v96, 32, v128
	v_cvt_pk_bf16_f32 v55, v50, v51
	v_add_u32_e32 v48, 0x90, v128
	v_cvt_pk_bf16_f32 v39, v34, v35
	v_add_u32_e32 v32, 0xa0, v128
	v_cvt_pk_bf16_f32 v23, v18, v19
	v_add_u32_e32 v16, 0xb0, v128
	v_ashrrev_i32_e32 v113, 31, v112
	v_ashrrev_i32_e32 v97, 31, v96
	v_ashrrev_i32_e32 v49, 31, v48
	v_ashrrev_i32_e32 v33, 31, v32
	v_ashrrev_i32_e32 v17, 31, v16
	v_lshlrev_b64 v[112:113], 11, v[112:113]
	v_lshlrev_b64 v[96:97], 11, v[96:97]
	v_lshlrev_b64 v[48:49], 11, v[48:49]
	v_lshlrev_b64 v[32:33], 11, v[32:33]
	v_lshlrev_b64 v[16:17], 11, v[16:17]
	v_cvt_pk_bf16_f32 v6, v0, v1
	v_lshl_add_u64 v[112:113], s[2:3], 0, v[112:113]
	v_lshl_add_u64 v[96:97], s[2:3], 0, v[96:97]
	v_lshl_add_u64 v[48:49], s[2:3], 0, v[48:49]
	v_lshl_add_u64 v[32:33], s[2:3], 0, v[32:33]
	v_lshl_add_u64 v[16:17], s[2:3], 0, v[16:17]
	v_lshl_add_u64 v[112:113], v[112:113], 0, s[0:1]
	v_lshl_add_u64 v[96:97], v[96:97], 0, s[0:1]
	v_lshl_add_u64 v[48:49], v[48:49], 0, s[0:1]
	v_lshl_add_u64 v[32:33], v[32:33], 0, s[0:1]
	v_lshl_add_u64 v[16:17], v[16:17], 0, s[0:1]
	v_lshl_add_u64 v[132:133], v[132:133], 0, v[130:131]
	v_lshl_add_u64 v[112:113], v[112:113], 0, v[130:131]
	v_lshl_add_u64 v[96:97], v[96:97], 0, v[130:131]
	v_lshl_add_u64 v[48:49], v[48:49], 0, v[130:131]
	v_lshl_add_u64 v[32:33], v[32:33], 0, v[130:131]
	v_lshl_add_u64 v[16:17], v[16:17], 0, v[130:131]
	v_cvt_pk_bf16_f32 v7, v2, v3
	global_store_dwordx4 v[132:133], v[124:127], off
	global_store_dwordx4 v[132:133], v[116:119], off offset:256
	global_store_dwordx4 v[112:113], v[108:111], off
	global_store_dwordx4 v[112:113], v[100:103], off offset:256
	global_store_dwordx4 v[96:97], v[92:95], off
	global_store_dwordx4 v[96:97], v[84:87], off offset:256
	global_store_dwordx4 v[80:81], v[76:79], off
	global_store_dwordx4 v[68:69], v[60:63], off
	global_store_dwordx4 v[68:69], v[52:55], off offset:256
	global_store_dwordx4 v[48:49], v[44:47], off
	global_store_dwordx4 v[48:49], v[36:39], off offset:256
	global_store_dwordx4 v[32:33], v[28:31], off
	global_store_dwordx4 v[32:33], v[20:23], off offset:256
	global_store_dwordx4 v[16:17], v[12:15], off
	global_store_dwordx4 v[16:17], v[4:7], off offset:256
	s_waitcnt vmcnt(0)
	v_readlane_b32 s31, v250, 56
	v_readlane_b32 s25, v250, 50
	v_readlane_b32 s26, v250, 51
	v_readlane_b32 s27, v250, 52
	v_readlane_b32 s30, v250, 55
	s_barrier

;     ...
;         if (LNL >= 0) {
;             for (int j = 0; j < 4; ++j) { const int mt2 = lnflag[j];
;                 if (mt2 >= 0) {
;                     __builtin_amdgcn_fence(__ATOMIC_ACQUIRE, "agent");
;                     const float* dps = (const float*)(P.ws + (LNL == 0 ? WS_DPS : WS_DPS2));
; #pragma unroll 1
;                     for (int rr = 0; rr < 2; ++rr) { const int rs = 16 * mt2 + 2 * C.wave + rr; const size_t m = (size_t)MP + rs;
;                         if (LNL == 0) ln_row(P.x_sample + (size_t)rs * DM, dps + (size_t)rs * DM, P.ln_g, P.ln_b, (float*)(P.ws + WS_X1) + m * DM, (bf16_t*)(P.ws + WS_X1A) + m * DM, lane);
;                         else ln_row((const float*)(P.ws + WS_X1) + m * DM, dps + (size_t)rs * DM, P.ln_g + DM, P.ln_b + DM, P.out + O_YS + (size_t)rs * DM, nullptr, lane); }
;                 } }
.LBB0_1854:
	ds_read_b32 v0, v33 offset:16396
	s_waitcnt lgkmcnt(0)
	v_cmp_gt_i32_e32 vcc, 0, v0
	v_readfirstlane_b32 s4, v0
	s_cbranch_vccnz .LBB0_1857
	s_lshl_b32 s22, s4, 4
	s_add_i32 s22, s22, s28
	s_mov_b32 s4, 0
	s_mov_b64 s[20:21], -1
	s_waitcnt vmcnt(0)
	buffer_inv sc1
.LBB0_1856:
	s_or_b32 s8, s4, s22
	s_lshl_b64 s[4:5], s[8:9], 10
	s_add_u32 s4, s4, 0x2000000
	s_addc_u32 s5, s5, 0
	s_lshl_b64 s[38:39], s[8:9], 12
	v_lshl_add_u64 v[68:69], v[16:17], 0, s[38:39]
	v_lshl_add_u64 v[72:73], v[14:15], 0, s[38:39]
	global_load_dwordx4 v[40:43], v[18:19], off
	global_load_dwordx4 v[44:47], v[20:21], off
	global_load_dwordx4 v[4:7], v[72:73], off
	global_load_dwordx4 v[48:51], v[68:69], off
	global_load_dwordx4 v[52:55], v[68:69], off offset:1024
	global_load_dwordx4 v[56:59], v[72:73], off offset:1024
	global_load_dwordx4 v[60:63], v[72:73], off offset:2048
	global_load_dwordx4 v[64:67], v[68:69], off offset:2048
	s_nop 0
	global_load_dwordx4 v[68:71], v[68:69], off offset:3072
	s_nop 0
	global_load_dwordx4 v[72:75], v[72:73], off offset:3072
	v_mov_b32_e32 v39, 0
	v_mov_b32_e32 v76, 0
	v_lshl_add_u64 v[2:3], s[4:5], 2, v[22:23]
	v_lshl_add_u64 v[0:1], s[4:5], 1, v[24:25]
	v_mov_b32_e32 v77, 0
	v_mov_b32_e32 v78, 0
	s_waitcnt vmcnt(6)
	v_pk_fma_f32 v[48:49], v[48:49], s[18:19], v[4:5] op_sel_hi:[1,0,1]
	v_pk_fma_f32 v[50:51], v[50:51], s[18:19], v[6:7] op_sel_hi:[1,0,1]
	s_waitcnt vmcnt(4)
	v_pk_fma_f32 v[52:53], v[52:53], s[18:19], v[56:57] op_sel_hi:[1,0,1]
	v_pk_fma_f32 v[54:55], v[54:55], s[18:19], v[58:59] op_sel_hi:[1,0,1]
	s_waitcnt vmcnt(2)
	v_pk_fma_f32 v[56:57], v[66:67], s[18:19], v[62:63] op_sel_hi:[1,0,1]
	v_pk_fma_f32 v[58:59], v[64:65], s[18:19], v[60:61] op_sel_hi:[1,0,1]
	v_pk_mov_b32 v[60:61], v[48:49], v[50:51] op_sel:[1,0]
	v_mov_b32_e32 v62, v48
	v_mov_b32_e32 v63, v51
	v_pk_mov_b32 v[64:65], v[52:53], v[54:55] op_sel:[1,0]
	v_mov_b32_e32 v66, v52
	v_mov_b32_e32 v67, v55
	v_pk_add_f32 v[60:61], v[60:61], v[62:63]
	v_pk_add_f32 v[62:63], v[64:65], v[66:67]
	s_waitcnt vmcnt(0)
; __device__ __forceinline__ unsigned pk2(float lo, float hi) { return f2bf(lo) | (f2bf(hi) << 16); }
; __device__ __forceinline__ void ln_row(const float* xin, const float* dp, const float* gam, const float* bet, float* of, bf16_t* ob, int lane) {
;     f32x4 v[4]; float s = 0.f;
; #pragma unroll
;     for (int j = 0; j < 4; ++j) { const f32x4 a = *(const f32x4*)(xin + 4 * lane + 256 * j), d = *(const f32x4*)(dp + 4 * lane + 256 * j); v[j] = a * ALPHA + d; s += (v[j][0] + v[j][1]) + (v[j][2] + v[j][3]); }
;     const float mean = wave_sum(s) * (1.f / DM); float q = 0.f;
; #pragma unroll
;     for (int j = 0; j < 4; ++j) { v[j] = v[j] - mean; q += (v[j][0] * v[j][0] + v[j][1] * v[j][1]) + (v[j][2] * v[j][2] + v[j][3] * v[j][3]); }
;     const float rstd = 1.f / sqrtf(wave_sum(q) * (1.f / DM) + LN_EPS);
; #pragma unroll
;     for (int j = 0; j < 4; ++j) { const f32x4 gg = *(const f32x4*)(gam + 4 * lane + 256 * j), bb = *(const f32x4*)(bet + 4 * lane + 256 * j); const f32x4 o = v[j] * rstd * gg + bb;
;         *(f32x4*)(of + 4 * lane + 256 * j) = o;
;         if (ob) { u32x2 w; w.x = pk2(o[0], o[1]); w.y = pk2(o[2], o[3]); *(u32x2*)(ob + 4 * lane + 256 * j) = w; } }
; }
	v_pk_fma_f32 v[6:7], v[70:71], s[18:19], v[74:75] op_sel_hi:[1,0,1]
	v_pk_fma_f32 v[4:5], v[68:69], s[18:19], v[72:73] op_sel_hi:[1,0,1]
	v_add_f32_e32 v66, v60, v61
	v_pk_add_f32 v[60:61], v[62:63], v[62:63] op_sel:[0,1] op_sel_hi:[1,0]
	v_add_f32_e32 v68, v58, v59
	v_add_f32_e32 v70, v56, v57
	v_mov_b32_e32 v73, v4
	v_mov_b32_e32 v69, v6
	v_mov_b32_e32 v71, v7
	v_add_f32_e32 v72, 0, v66
	v_mov_b32_e32 v61, v5
	v_pk_add_f32 v[64:65], v[68:69], v[70:71]
	v_pk_add_f32 v[60:61], v[72:73], v[60:61]
	s_nop 0
	v_pk_add_f32 v[60:61], v[60:61], v[64:65]
	s_nop 0
	v_add_f32_e32 v60, v60, v61
	s_nop 1
	v_add_f32_dpp v60, v60, v60 row_shr:1 row_mask:0xf bank_mask:0xf bound_ctrl:1
	s_nop 1
	v_add_f32_dpp v60, v60, v60 row_shr:2 row_mask:0xf bank_mask:0xf bound_ctrl:1
	s_nop 1
	v_add_f32_dpp v60, v60, v60 row_shr:4 row_mask:0xf bank_mask:0xf bound_ctrl:1
	s_nop 1
	v_add_f32_dpp v60, v60, v60 row_shr:8 row_mask:0xf bank_mask:0xf bound_ctrl:1
	s_nop 1
	v_mov_b32_dpp v39, v60 row_bcast:15 row_mask:0xa bank_mask:0xf
	v_add_f32_e32 v39, v60, v39
	s_nop 1
	v_mov_b32_dpp v76, v39 row_bcast:31 row_mask:0xc bank_mask:0xf
	v_add_f32_e32 v39, v39, v76
	s_nop 0
	v_readlane_b32 s4, v39, 63
	s_nop 1
	v_fmac_f32_e32 v51, s4, v37
	v_fmac_f32_e32 v49, s4, v37
	v_fmac_f32_e32 v55, s4, v37
	v_fmac_f32_e32 v53, s4, v37
	v_fma_f32 v50, s4, v37, v50
	v_fma_f32 v48, s4, v37, v48
	v_fma_f32 v54, s4, v37, v54
	v_fma_f32 v52, s4, v37, v52
	v_fmac_f32_e32 v57, s4, v37
	v_fmac_f32_e32 v59, s4, v37
	v_mul_f32_e32 v39, v49, v49
	v_mul_f32_e32 v60, v51, v51
	v_mul_f32_e32 v61, v53, v53
	v_mul_f32_e32 v62, v55, v55
	v_fma_f32 v56, s4, v37, v56
	v_fma_f32 v58, s4, v37, v58
	v_fmac_f32_e32 v7, s4, v37
	v_fmac_f32_e32 v5, s4, v37
	v_mul_f32_e32 v63, v59, v59
	v_mul_f32_e32 v64, v57, v57
	v_fmac_f32_e32 v39, v48, v48
	v_fmac_f32_e32 v60, v50, v50
	v_fmac_f32_e32 v61, v52, v52
	v_fmac_f32_e32 v62, v54, v54
	v_fma_f32 v6, s4, v37, v6
	v_fma_f32 v4, s4, v37, v4
	v_mul_f32_e32 v65, v5, v5
	v_mul_f32_e32 v66, v7, v7
	v_fmac_f32_e32 v63, v58, v58
	v_fmac_f32_e32 v64, v56, v56
	v_add_f32_e32 v39, v39, v60
	v_add_f32_e32 v60, v61, v62
	v_fmac_f32_e32 v65, v4, v4
	v_fmac_f32_e32 v66, v6, v6
	v_add_f32_e32 v61, v63, v64
	v_add_f32_e32 v39, v39, v60
	v_add_f32_e32 v62, v65, v66
	v_add_f32_e32 v39, v61, v39
	v_add_f32_e32 v39, v62, v39
	s_nop 1
	v_add_f32_dpp v39, v39, v39 row_shr:1 row_mask:0xf bank_mask:0xf bound_ctrl:1
	s_nop 1
	v_add_f32_dpp v39, v39, v39 row_shr:2 row_mask:0xf bank_mask:0xf bound_ctrl:1
	s_nop 1
	v_add_f32_dpp v39, v39, v39 row_shr:4 row_mask:0xf bank_mask:0xf bound_ctrl:1
	s_nop 1
	v_add_f32_dpp v39, v39, v39 row_shr:8 row_mask:0xf bank_mask:0xf bound_ctrl:1
	s_nop 1
	v_mov_b32_dpp v77, v39 row_bcast:15 row_mask:0xa bank_mask:0xf
	v_add_f32_e32 v39, v39, v77
	s_nop 1
	v_mov_b32_dpp v78, v39 row_bcast:31 row_mask:0xc bank_mask:0xf
	v_add_f32_e32 v39, v39, v78
	s_nop 0
	v_readlane_b32 s4, v39, 63
	s_nop 1
	v_fma_f32 v39, s4, v38, v34
	v_mul_f32_e32 v60, 0x4f800000, v39
	v_cmp_gt_f32_e32 vcc, s31, v39
	s_nop 1
	v_cndmask_b32_e32 v39, v39, v60, vcc
	v_sqrt_f32_e32 v60, v39
	s_nop 0
	v_add_u32_e32 v61, -1, v60
	v_add_u32_e32 v62, 1, v60
	v_fma_f32 v63, -v61, v60, v39
	v_fma_f32 v64, -v62, v60, v39
	v_cmp_ge_f32_e64 s[4:5], 0, v63
	s_nop 1
	v_cndmask_b32_e64 v60, v60, v61, s[4:5]
	v_cmp_lt_f32_e64 s[4:5], 0, v64
	s_nop 1
	v_cndmask_b32_e64 v60, v60, v62, s[4:5]
	v_mul_f32_e32 v61, 0x37800000, v60
	v_cndmask_b32_e32 v60, v60, v61, vcc
	v_cmp_class_f32_e32 vcc, v39, v35
	s_nop 1
	v_cndmask_b32_e32 v39, v60, v39, vcc
	v_div_scale_f32 v60, s[4:5], v39, v39, 1.0
	v_rcp_f32_e32 v62, v60
	v_div_scale_f32 v61, vcc, 1.0, v39, 1.0
	s_mov_b32 s4, 1
	v_fma_f32 v63, -v60, v62, 1.0
	v_fmac_f32_e32 v62, v63, v62
	v_mul_f32_e32 v63, v61, v62
	v_fma_f32 v64, -v60, v63, v61
	v_fmac_f32_e32 v63, v64, v62
	v_fma_f32 v60, -v60, v63, v61
	v_div_fmas_f32 v60, v60, v62, v63
	v_div_fixup_f32 v60, v60, v39, 1.0
	v_pk_mul_f32 v[48:49], v[48:49], v[60:61] op_sel_hi:[1,0]
	v_pk_mul_f32 v[50:51], v[50:51], v[60:61] op_sel_hi:[1,0]
	v_pk_fma_f32 v[40:41], v[40:41], v[48:49], v[44:45]
	v_pk_fma_f32 v[42:43], v[42:43], v[50:51], v[46:47]
	global_store_dwordx4 v[2:3], v[40:43], off
	s_nop 0
	s_nop 0
	v_cvt_pk_bf16_f32 v40, v40, v41
	v_cvt_pk_bf16_f32 v41, v42, v43
	global_store_dwordx2 v[0:1], v[40:41], off
	global_load_dwordx4 v[40:43], v[18:19], off offset:1024
	s_nop 0
	global_load_dwordx4 v[44:47], v[20:21], off offset:1024
	v_pk_mul_f32 v[48:49], v[54:55], v[60:61] op_sel_hi:[1,0]
	v_pk_mul_f32 v[50:51], v[52:53], v[60:61] op_sel_hi:[1,0]
	v_pk_mul_f32 v[6:7], v[6:7], v[60:61] op_sel_hi:[1,0]
	v_pk_mul_f32 v[4:5], v[4:5], v[60:61] op_sel_hi:[1,0]
	s_and_b64 vcc, exec, s[20:21]
	s_mov_b64 s[20:21], 0
	s_waitcnt vmcnt(0)
	v_pk_fma_f32 v[40:41], v[40:41], v[50:51], v[44:45]
	v_pk_fma_f32 v[42:43], v[42:43], v[48:49], v[46:47]
	global_store_dwordx4 v[2:3], v[40:43], off offset:1024
	s_nop 0
	s_nop 0
	v_cvt_pk_bf16_f32 v40, v40, v41
	v_cvt_pk_bf16_f32 v41, v42, v43
	global_store_dwordx2 v[0:1], v[40:41], off offset:512
	global_load_dwordx4 v[40:43], v[18:19], off offset:2048
	s_nop 0
	global_load_dwordx4 v[44:47], v[20:21], off offset:2048
	v_pk_mul_f32 v[48:49], v[56:57], v[60:61] op_sel_hi:[1,0]
	v_pk_mul_f32 v[50:51], v[58:59], v[60:61] op_sel_hi:[1,0]
	s_waitcnt vmcnt(0)
	v_pk_fma_f32 v[42:43], v[48:49], v[42:43], v[46:47]
	v_pk_fma_f32 v[40:41], v[50:51], v[40:41], v[44:45]
	global_store_dwordx4 v[2:3], v[40:43], off offset:2048
	s_nop 0
	s_nop 0
	v_cvt_pk_bf16_f32 v40, v40, v41
	v_cvt_pk_bf16_f32 v41, v42, v43
	global_store_dwordx2 v[0:1], v[40:41], off offset:1024
	global_load_dwordx4 v[40:43], v[18:19], off offset:3072
	s_nop 0
	global_load_dwordx4 v[44:47], v[20:21], off offset:3072
	s_waitcnt vmcnt(0)
	v_pk_fma_f32 v[4:5], v[4:5], v[40:41], v[44:45]
	v_pk_fma_f32 v[6:7], v[6:7], v[42:43], v[46:47]
	global_store_dwordx4 v[2:3], v[4:7], off offset:3072
	v_cvt_pk_bf16_f32 v2, v4, v5
	v_cvt_pk_bf16_f32 v3, v6, v7
	global_store_dwordx2 v[0:1], v[2:3], off offset:1536
	s_cbranch_vccnz .LBB0_1856
.LBB0_1857:
	s_barrier
	s_and_saveexec_b64 s[4:5], s[0:1]
	s_cbranch_execz .LBB0_1832
	ds_write_b32 v29, v36 offset:16384
	s_branch .LBB0_1832

; __device__ __forceinline__ unsigned pk2(float lo, float hi) { return f2bf(lo) | (f2bf(hi) << 16); }
;     __device__ __forceinline__ void fused(f32x4 (&acc)[2][2][4][2], const pg8::Unit& u, int wr, int wc, int fr, int fq, LAS unsigned char* lds, int wid, int lane) const {
;     ...
;         const float qnan = __builtin_nanf("");
; #pragma unroll
;         for (int ai = 0; ai < 2; ++ai)
; #pragma unroll
;             for (int m = 0; m < 4; ++m) { const int r = ai * 128 + wr * 64 + m * 16 + fr; const f32x2v sr = S[r]; const size_t off = (size_t)(u.pm * 256 + r) * DM + col0;
; #pragma unroll
;                 for (int bj = 0; bj < 2; ++bj)
; #pragma unroll
;                     for (int n = 0; n < 2; ++n) { f32x4 o = (acc[ai][bj][m][n] - sr.x) * sr.y * gg[bj][n] + bb[bj][n];
;                         if (bad) o = (f32x4){qnan, qnan, qnan, qnan};
;                         if (outf) *(f32x4*)(outf + off + bj * 128 + n * 16) = o;
;                         if (outb) { u32x2 w; w.x = pk2(o[0], o[1]); w.y = pk2(o[2], o[3]); *(u32x2*)(outb + off + bj * 128 + n * 16) = w; } } }
.LBB0_1917:
	s_or_b64 exec, exec, s[40:41]
	s_waitcnt lgkmcnt(0)
	s_barrier
	s_waitcnt lgkmcnt(1)
	ds_read_b64 v[180:181], v195
	ds_read_b64 v[182:183], v197
	ds_read_b64 v[184:185], v199
	ds_read_b64 v[186:187], v201
	s_waitcnt lgkmcnt(4)
	v_cmp_eq_u32_e32 vcc, 0, v164
	s_waitcnt lgkmcnt(3)
	v_sub_f32_e32 v145, v145, v180
	v_sub_f32_e32 v144, v144, v180
	v_pk_mul_f32 v[144:145], v[180:181], v[144:145] op_sel:[1,0]
	v_sub_f32_e32 v147, v147, v180
	s_waitcnt vmcnt(5)
	v_pk_fma_f32 v[144:145], v[88:89], v[144:145], v[92:93]
	v_sub_f32_e32 v146, v146, v180
	v_cndmask_b32_e32 v144, v217, v144, vcc
	v_pk_mul_f32 v[146:147], v[180:181], v[146:147] op_sel:[1,0]
	v_cndmask_b32_e32 v145, v217, v145, vcc
	v_pk_fma_f32 v[146:147], v[90:91], v[146:147], v[94:95]
	v_cndmask_b32_e32 v146, v217, v146, vcc
	v_cndmask_b32_e32 v147, v217, v147, vcc
	v_cvt_pk_bf16_f32 v144, v144, v145
	v_sub_f32_e32 v133, v133, v180
	v_sub_f32_e32 v132, v132, v180
	v_pk_mul_f32 v[132:133], v[180:181], v[132:133] op_sel:[1,0]
	v_cvt_pk_bf16_f32 v145, v146, v147
	v_lshl_add_u64 v[146:147], s[14:15], 0, v[178:179]
	s_waitcnt vmcnt(4)
	v_pk_fma_f32 v[132:133], v[76:77], v[132:133], v[80:81]
	v_lshl_add_u64 v[146:147], v[146:147], 0, v[176:177]
	v_sub_f32_e32 v135, v135, v180
	v_sub_f32_e32 v134, v134, v180
	v_cndmask_b32_e32 v132, v217, v132, vcc
	global_store_dwordx2 v[146:147], v[144:145], off
	v_pk_mul_f32 v[134:135], v[180:181], v[134:135] op_sel:[1,0]
	v_cndmask_b32_e32 v133, v217, v133, vcc
	v_pk_fma_f32 v[134:135], v[78:79], v[134:135], v[82:83]
	v_cndmask_b32_e32 v134, v217, v134, vcc
	v_cndmask_b32_e32 v135, v217, v135, vcc
	v_cvt_pk_bf16_f32 v132, v132, v133
	v_sub_f32_e32 v117, v117, v180
	v_sub_f32_e32 v116, v116, v180
	v_pk_mul_f32 v[116:117], v[180:181], v[116:117] op_sel:[1,0]
	s_waitcnt vmcnt(2)
	v_pk_fma_f32 v[116:117], v[52:53], v[116:117], v[56:57]
	v_cvt_pk_bf16_f32 v133, v134, v135
	v_sub_f32_e32 v119, v119, v180
	v_sub_f32_e32 v118, v118, v180
	v_cndmask_b32_e32 v116, v217, v116, vcc
	global_store_dwordx2 v[146:147], v[132:133], off offset:32
	v_pk_mul_f32 v[118:119], v[180:181], v[118:119] op_sel:[1,0]
	v_cndmask_b32_e32 v117, v217, v117, vcc
	v_pk_fma_f32 v[118:119], v[54:55], v[118:119], v[58:59]
	v_cndmask_b32_e32 v118, v217, v118, vcc
	v_cndmask_b32_e32 v119, v217, v119, vcc
	v_cvt_pk_bf16_f32 v116, v116, v117
	v_sub_f32_e32 v101, v101, v180
	v_sub_f32_e32 v100, v100, v180
	v_pk_mul_f32 v[100:101], v[180:181], v[100:101] op_sel:[1,0]
	s_waitcnt vmcnt(2)
	v_pk_fma_f32 v[100:101], v[20:21], v[100:101], v[32:33]
	v_cvt_pk_bf16_f32 v117, v118, v119
	v_sub_f32_e32 v103, v103, v180
	v_sub_f32_e32 v102, v102, v180
	v_cndmask_b32_e32 v100, v217, v100, vcc
	global_store_dwordx2 v[146:147], v[116:117], off offset:256
	v_pk_mul_f32 v[102:103], v[180:181], v[102:103] op_sel:[1,0]
	v_cndmask_b32_e32 v101, v217, v101, vcc
	v_pk_fma_f32 v[102:103], v[22:23], v[102:103], v[34:35]
	v_cndmask_b32_e32 v102, v217, v102, vcc
	v_cndmask_b32_e32 v103, v217, v103, vcc
	v_cvt_pk_bf16_f32 v100, v100, v101
	v_cvt_pk_bf16_f32 v101, v102, v103
	s_waitcnt lgkmcnt(2)
	v_sub_f32_e32 v103, v149, v182
	v_sub_f32_e32 v102, v148, v182
	v_pk_mul_f32 v[102:103], v[182:183], v[102:103] op_sel:[1,0]
	v_sub_f32_e32 v117, v151, v182
	v_pk_fma_f32 v[102:103], v[88:89], v[102:103], v[92:93]
	v_sub_f32_e32 v116, v150, v182
	v_cndmask_b32_e32 v102, v217, v102, vcc
	v_pk_mul_f32 v[116:117], v[182:183], v[116:117] op_sel:[1,0]
	v_cndmask_b32_e32 v103, v217, v103, vcc
	v_pk_fma_f32 v[116:117], v[90:91], v[116:117], v[94:95]
	global_store_dwordx2 v[146:147], v[100:101], off offset:288
	v_add_u32_e32 v100, s31, v196
	v_cndmask_b32_e32 v116, v217, v116, vcc
	v_ashrrev_i32_e32 v101, 31, v100
	v_cndmask_b32_e32 v117, v217, v117, vcc
	v_cvt_pk_bf16_f32 v102, v102, v103
	v_lshlrev_b64 v[100:101], 11, v[100:101]
	v_lshl_add_u64 v[100:101], s[14:15], 0, v[100:101]
	v_cvt_pk_bf16_f32 v103, v116, v117
	v_lshl_add_u64 v[100:101], v[100:101], 0, v[176:177]
	global_store_dwordx2 v[100:101], v[102:103], off
	v_sub_f32_e32 v103, v137, v182
	v_sub_f32_e32 v102, v136, v182
	v_pk_mul_f32 v[102:103], v[182:183], v[102:103] op_sel:[1,0]
	v_sub_f32_e32 v117, v139, v182
	v_pk_fma_f32 v[102:103], v[76:77], v[102:103], v[80:81]
	v_sub_f32_e32 v116, v138, v182
	v_cndmask_b32_e32 v102, v217, v102, vcc
	v_pk_mul_f32 v[116:117], v[182:183], v[116:117] op_sel:[1,0]
	v_cndmask_b32_e32 v103, v217, v103, vcc
	v_pk_fma_f32 v[116:117], v[78:79], v[116:117], v[82:83]
	v_cndmask_b32_e32 v116, v217, v116, vcc
	v_cndmask_b32_e32 v117, v217, v117, vcc
	v_cvt_pk_bf16_f32 v102, v102, v103
	v_cvt_pk_bf16_f32 v103, v116, v117
	global_store_dwordx2 v[100:101], v[102:103], off offset:32
	v_sub_f32_e32 v103, v121, v182
	v_sub_f32_e32 v102, v120, v182
	v_pk_mul_f32 v[102:103], v[182:183], v[102:103] op_sel:[1,0]
	v_sub_f32_e32 v117, v123, v182
	v_pk_fma_f32 v[102:103], v[52:53], v[102:103], v[56:57]
	v_sub_f32_e32 v116, v122, v182
	v_cndmask_b32_e32 v102, v217, v102, vcc
	v_pk_mul_f32 v[116:117], v[182:183], v[116:117] op_sel:[1,0]
	v_cndmask_b32_e32 v103, v217, v103, vcc
	v_pk_fma_f32 v[116:117], v[54:55], v[116:117], v[58:59]
	v_cndmask_b32_e32 v116, v217, v116, vcc
	v_cndmask_b32_e32 v117, v217, v117, vcc
	v_cvt_pk_bf16_f32 v102, v102, v103
	v_cvt_pk_bf16_f32 v103, v116, v117
	global_store_dwordx2 v[100:101], v[102:103], off offset:256
	v_sub_f32_e32 v103, v105, v182
	v_sub_f32_e32 v102, v104, v182
	v_pk_mul_f32 v[102:103], v[182:183], v[102:103] op_sel:[1,0]
	v_sub_f32_e32 v105, v107, v182
	v_pk_fma_f32 v[102:103], v[20:21], v[102:103], v[32:33]
	v_sub_f32_e32 v104, v106, v182
	v_cndmask_b32_e32 v102, v217, v102, vcc
	v_pk_mul_f32 v[104:105], v[182:183], v[104:105] op_sel:[1,0]
	v_cndmask_b32_e32 v103, v217, v103, vcc
	v_pk_fma_f32 v[104:105], v[22:23], v[104:105], v[34:35]
	v_cndmask_b32_e32 v104, v217, v104, vcc
	v_cndmask_b32_e32 v105, v217, v105, vcc
	v_cvt_pk_bf16_f32 v102, v102, v103
	v_cvt_pk_bf16_f32 v103, v104, v105
	global_store_dwordx2 v[100:101], v[102:103], off offset:288
	s_waitcnt lgkmcnt(1)
; __device__ __forceinline__ unsigned pk2(float lo, float hi) { return f2bf(lo) | (f2bf(hi) << 16); }
;     __device__ __forceinline__ void fused(f32x4 (&acc)[2][2][4][2], const pg8::Unit& u, int wr, int wc, int fr, int fq, LAS unsigned char* lds, int wid, int lane) const {
;     ...
;         const float qnan = __builtin_nanf("");
; #pragma unroll
;         for (int ai = 0; ai < 2; ++ai)
; #pragma unroll
;             for (int m = 0; m < 4; ++m) { const int r = ai * 128 + wr * 64 + m * 16 + fr; const f32x2v sr = S[r]; const size_t off = (size_t)(u.pm * 256 + r) * DM + col0;
; #pragma unroll
;                 for (int bj = 0; bj < 2; ++bj)
; #pragma unroll
;                     for (int n = 0; n < 2; ++n) { f32x4 o = (acc[ai][bj][m][n] - sr.x) * sr.y * gg[bj][n] + bb[bj][n];
;                         if (bad) o = (f32x4){qnan, qnan, qnan, qnan};
;                         if (outf) *(f32x4*)(outf + off + bj * 128 + n * 16) = o;
;                         if (outb) { u32x2 w; w.x = pk2(o[0], o[1]); w.y = pk2(o[2], o[3]); *(u32x2*)(outb + off + bj * 128 + n * 16) = w; } } }
	v_sub_f32_e32 v103, v157, v184
	v_sub_f32_e32 v102, v156, v184
	v_pk_mul_f32 v[102:103], v[184:185], v[102:103] op_sel:[1,0]
	v_sub_f32_e32 v105, v159, v184
	v_pk_fma_f32 v[102:103], v[88:89], v[102:103], v[92:93]
	v_sub_f32_e32 v104, v158, v184
	v_cndmask_b32_e32 v102, v217, v102, vcc
	v_pk_mul_f32 v[104:105], v[184:185], v[104:105] op_sel:[1,0]
	v_cndmask_b32_e32 v103, v217, v103, vcc
	v_pk_fma_f32 v[104:105], v[90:91], v[104:105], v[94:95]
	v_add_u32_e32 v100, s31, v198
	v_cndmask_b32_e32 v104, v217, v104, vcc
	v_ashrrev_i32_e32 v101, 31, v100
	v_cndmask_b32_e32 v105, v217, v105, vcc
	v_cvt_pk_bf16_f32 v102, v102, v103
	v_lshlrev_b64 v[100:101], 11, v[100:101]
	v_lshl_add_u64 v[100:101], s[14:15], 0, v[100:101]
	v_cvt_pk_bf16_f32 v103, v104, v105
	v_lshl_add_u64 v[100:101], v[100:101], 0, v[176:177]
	global_store_dwordx2 v[100:101], v[102:103], off
	v_sub_f32_e32 v103, v141, v184
	v_sub_f32_e32 v102, v140, v184
	v_pk_mul_f32 v[102:103], v[184:185], v[102:103] op_sel:[1,0]
	v_sub_f32_e32 v105, v143, v184
	v_pk_fma_f32 v[102:103], v[76:77], v[102:103], v[80:81]
	v_sub_f32_e32 v104, v142, v184
	v_cndmask_b32_e32 v102, v217, v102, vcc
	v_pk_mul_f32 v[104:105], v[184:185], v[104:105] op_sel:[1,0]
	v_cndmask_b32_e32 v103, v217, v103, vcc
	v_pk_fma_f32 v[104:105], v[78:79], v[104:105], v[82:83]
	v_cndmask_b32_e32 v104, v217, v104, vcc
	v_cndmask_b32_e32 v105, v217, v105, vcc
	v_cvt_pk_bf16_f32 v102, v102, v103
	v_cvt_pk_bf16_f32 v103, v104, v105
	global_store_dwordx2 v[100:101], v[102:103], off offset:32
	v_sub_f32_e32 v103, v125, v184
	v_sub_f32_e32 v102, v124, v184
	v_pk_mul_f32 v[102:103], v[184:185], v[102:103] op_sel:[1,0]
	v_sub_f32_e32 v105, v127, v184
	v_pk_fma_f32 v[102:103], v[52:53], v[102:103], v[56:57]
	v_sub_f32_e32 v104, v126, v184
	v_cndmask_b32_e32 v102, v217, v102, vcc
	v_pk_mul_f32 v[104:105], v[184:185], v[104:105] op_sel:[1,0]
	v_cndmask_b32_e32 v103, v217, v103, vcc
	v_pk_fma_f32 v[104:105], v[54:55], v[104:105], v[58:59]
	v_cndmask_b32_e32 v104, v217, v104, vcc
	v_cndmask_b32_e32 v105, v217, v105, vcc
	v_cvt_pk_bf16_f32 v102, v102, v103
	v_cvt_pk_bf16_f32 v103, v104, v105
	global_store_dwordx2 v[100:101], v[102:103], off offset:256
	v_sub_f32_e32 v103, v109, v184
	v_sub_f32_e32 v102, v108, v184
	v_pk_mul_f32 v[102:103], v[184:185], v[102:103] op_sel:[1,0]
	v_sub_f32_e32 v105, v111, v184
	v_pk_fma_f32 v[102:103], v[20:21], v[102:103], v[32:33]
	v_sub_f32_e32 v104, v110, v184
	v_cndmask_b32_e32 v102, v217, v102, vcc
	v_pk_mul_f32 v[104:105], v[184:185], v[104:105] op_sel:[1,0]
	v_cndmask_b32_e32 v103, v217, v103, vcc
	v_pk_fma_f32 v[104:105], v[22:23], v[104:105], v[34:35]
	v_cndmask_b32_e32 v104, v217, v104, vcc
	v_cndmask_b32_e32 v105, v217, v105, vcc
	v_cvt_pk_bf16_f32 v102, v102, v103
	v_cvt_pk_bf16_f32 v103, v104, v105
	global_store_dwordx2 v[100:101], v[102:103], off offset:288
	s_waitcnt lgkmcnt(0)
	v_sub_f32_e32 v103, v153, v186
	v_sub_f32_e32 v102, v152, v186
	v_pk_mul_f32 v[102:103], v[186:187], v[102:103] op_sel:[1,0]
	v_sub_f32_e32 v105, v155, v186
	v_pk_fma_f32 v[102:103], v[88:89], v[102:103], v[92:93]
	v_sub_f32_e32 v104, v154, v186
	v_cndmask_b32_e32 v102, v217, v102, vcc
	v_pk_mul_f32 v[104:105], v[186:187], v[104:105] op_sel:[1,0]
	v_cndmask_b32_e32 v103, v217, v103, vcc
	v_pk_fma_f32 v[104:105], v[90:91], v[104:105], v[94:95]
	v_add_u32_e32 v100, s31, v200
	v_cndmask_b32_e32 v104, v217, v104, vcc
	v_ashrrev_i32_e32 v101, 31, v100
	v_cndmask_b32_e32 v105, v217, v105, vcc
	v_cvt_pk_bf16_f32 v102, v102, v103
	v_lshlrev_b64 v[100:101], 11, v[100:101]
	v_lshl_add_u64 v[100:101], s[14:15], 0, v[100:101]
	v_cvt_pk_bf16_f32 v103, v104, v105
	v_lshl_add_u64 v[100:101], v[100:101], 0, v[176:177]
	global_store_dwordx2 v[100:101], v[102:103], off
	v_sub_f32_e32 v103, v129, v186
	v_sub_f32_e32 v102, v128, v186
	v_pk_mul_f32 v[102:103], v[186:187], v[102:103] op_sel:[1,0]
	v_sub_f32_e32 v105, v131, v186
	v_pk_fma_f32 v[102:103], v[76:77], v[102:103], v[80:81]
	v_sub_f32_e32 v104, v130, v186
	v_cndmask_b32_e32 v102, v217, v102, vcc
	v_pk_mul_f32 v[104:105], v[186:187], v[104:105] op_sel:[1,0]
	v_cndmask_b32_e32 v103, v217, v103, vcc
	v_pk_fma_f32 v[104:105], v[78:79], v[104:105], v[82:83]
	v_cndmask_b32_e32 v104, v217, v104, vcc
	v_cndmask_b32_e32 v105, v217, v105, vcc
	v_cvt_pk_bf16_f32 v102, v102, v103
	v_cvt_pk_bf16_f32 v103, v104, v105
	global_store_dwordx2 v[100:101], v[102:103], off offset:32
	v_sub_f32_e32 v103, v113, v186
	v_sub_f32_e32 v102, v112, v186
	v_pk_mul_f32 v[102:103], v[186:187], v[102:103] op_sel:[1,0]
	v_sub_f32_e32 v105, v115, v186
	v_pk_fma_f32 v[102:103], v[52:53], v[102:103], v[56:57]
	v_sub_f32_e32 v104, v114, v186
	v_cndmask_b32_e32 v102, v217, v102, vcc
	v_pk_mul_f32 v[104:105], v[186:187], v[104:105] op_sel:[1,0]
	v_cndmask_b32_e32 v103, v217, v103, vcc
	v_pk_fma_f32 v[104:105], v[54:55], v[104:105], v[58:59]
	v_cndmask_b32_e32 v104, v217, v104, vcc
	v_cndmask_b32_e32 v105, v217, v105, vcc
	v_cvt_pk_bf16_f32 v102, v102, v103
	v_sub_f32_e32 v97, v97, v186
	v_sub_f32_e32 v96, v96, v186
	v_pk_mul_f32 v[96:97], v[186:187], v[96:97] op_sel:[1,0]
	v_pk_fma_f32 v[96:97], v[20:21], v[96:97], v[32:33]
	v_cvt_pk_bf16_f32 v103, v104, v105
	v_sub_f32_e32 v99, v99, v186
	v_sub_f32_e32 v98, v98, v186
	v_cndmask_b32_e32 v96, v217, v96, vcc
	global_store_dwordx2 v[100:101], v[102:103], off offset:256
	v_pk_mul_f32 v[98:99], v[186:187], v[98:99] op_sel:[1,0]
	v_cndmask_b32_e32 v97, v217, v97, vcc
	v_pk_fma_f32 v[98:99], v[22:23], v[98:99], v[34:35]
	v_cndmask_b32_e32 v98, v217, v98, vcc
	v_cndmask_b32_e32 v99, v217, v99, vcc
	v_cvt_pk_bf16_f32 v96, v96, v97
	v_cvt_pk_bf16_f32 v97, v98, v99
	global_store_dwordx2 v[100:101], v[96:97], off offset:288
	ds_read_b64 v[96:97], v203
	v_add_u32_e32 v104, s31, v202
	v_ashrrev_i32_e32 v105, 31, v104
	ds_read_b64 v[98:99], v205
	ds_read_b64 v[100:101], v207
	ds_read_b64 v[102:103], v209
	s_waitcnt lgkmcnt(3)
; __device__ __forceinline__ unsigned pk2(float lo, float hi) { return f2bf(lo) | (f2bf(hi) << 16); }
;     __device__ __forceinline__ void fused(f32x4 (&acc)[2][2][4][2], const pg8::Unit& u, int wr, int wc, int fr, int fq, LAS unsigned char* lds, int wid, int lane) const {
;     ...
;         const float qnan = __builtin_nanf("");
; #pragma unroll
;         for (int ai = 0; ai < 2; ++ai)
; #pragma unroll
;             for (int m = 0; m < 4; ++m) { const int r = ai * 128 + wr * 64 + m * 16 + fr; const f32x2v sr = S[r]; const size_t off = (size_t)(u.pm * 256 + r) * DM + col0;
; #pragma unroll
;                 for (int bj = 0; bj < 2; ++bj)
; #pragma unroll
;                     for (int n = 0; n < 2; ++n) { f32x4 o = (acc[ai][bj][m][n] - sr.x) * sr.y * gg[bj][n] + bb[bj][n];
;                         if (bad) o = (f32x4){qnan, qnan, qnan, qnan};
;                         if (outf) *(f32x4*)(outf + off + bj * 128 + n * 16) = o;
;                         if (outb) { u32x2 w; w.x = pk2(o[0], o[1]); w.y = pk2(o[2], o[3]); *(u32x2*)(outb + off + bj * 128 + n * 16) = w; } } }
	v_sub_f32_e32 v61, v61, v96
	v_sub_f32_e32 v60, v60, v96
	v_pk_mul_f32 v[60:61], v[96:97], v[60:61] op_sel:[1,0]
	v_sub_f32_e32 v63, v63, v96
	v_pk_fma_f32 v[60:61], v[88:89], v[60:61], v[92:93]
	v_sub_f32_e32 v62, v62, v96
	v_cndmask_b32_e32 v60, v217, v60, vcc
	v_pk_mul_f32 v[62:63], v[96:97], v[62:63] op_sel:[1,0]
	v_cndmask_b32_e32 v61, v217, v61, vcc
	v_pk_fma_f32 v[62:63], v[90:91], v[62:63], v[94:95]
	v_cndmask_b32_e32 v62, v217, v62, vcc
	v_cndmask_b32_e32 v63, v217, v63, vcc
	v_cvt_pk_bf16_f32 v60, v60, v61
	v_sub_f32_e32 v37, v37, v96
	v_sub_f32_e32 v36, v36, v96
	v_cvt_pk_bf16_f32 v61, v62, v63
	v_lshlrev_b64 v[62:63], 11, v[104:105]
	v_pk_mul_f32 v[36:37], v[96:97], v[36:37] op_sel:[1,0]
	v_lshl_add_u64 v[62:63], s[14:15], 0, v[62:63]
	v_pk_fma_f32 v[36:37], v[76:77], v[36:37], v[80:81]
	v_lshl_add_u64 v[62:63], v[62:63], 0, v[176:177]
	v_sub_f32_e32 v39, v39, v96
	v_sub_f32_e32 v38, v38, v96
	v_cndmask_b32_e32 v36, v217, v36, vcc
	global_store_dwordx2 v[62:63], v[60:61], off
	v_pk_mul_f32 v[38:39], v[96:97], v[38:39] op_sel:[1,0]
	v_cndmask_b32_e32 v37, v217, v37, vcc
	v_pk_fma_f32 v[38:39], v[78:79], v[38:39], v[82:83]
	v_cndmask_b32_e32 v38, v217, v38, vcc
	v_cndmask_b32_e32 v39, v217, v39, vcc
	v_cvt_pk_bf16_f32 v36, v36, v37
	v_sub_f32_e32 v13, v13, v96
	v_sub_f32_e32 v12, v12, v96
	v_pk_mul_f32 v[12:13], v[96:97], v[12:13] op_sel:[1,0]
	v_pk_fma_f32 v[12:13], v[52:53], v[12:13], v[56:57]
	v_cvt_pk_bf16_f32 v37, v38, v39
	v_sub_f32_e32 v15, v15, v96
	v_sub_f32_e32 v14, v14, v96
	v_cndmask_b32_e32 v12, v217, v12, vcc
	global_store_dwordx2 v[62:63], v[36:37], off offset:32
	v_pk_mul_f32 v[14:15], v[96:97], v[14:15] op_sel:[1,0]
	v_cndmask_b32_e32 v13, v217, v13, vcc
	v_pk_fma_f32 v[14:15], v[54:55], v[14:15], v[58:59]
	v_cndmask_b32_e32 v14, v217, v14, vcc
	v_cndmask_b32_e32 v15, v217, v15, vcc
	v_cvt_pk_bf16_f32 v12, v12, v13
	v_sub_f32_e32 v1, v1, v96
	v_sub_f32_e32 v0, v0, v96
	v_pk_mul_f32 v[0:1], v[96:97], v[0:1] op_sel:[1,0]
	v_pk_fma_f32 v[0:1], v[20:21], v[0:1], v[32:33]
	v_cvt_pk_bf16_f32 v13, v14, v15
	v_sub_f32_e32 v3, v3, v96
	v_sub_f32_e32 v2, v2, v96
	v_cndmask_b32_e32 v0, v217, v0, vcc
	global_store_dwordx2 v[62:63], v[12:13], off offset:256
	v_pk_mul_f32 v[2:3], v[96:97], v[2:3] op_sel:[1,0]
	v_cndmask_b32_e32 v1, v217, v1, vcc
	v_pk_fma_f32 v[2:3], v[22:23], v[2:3], v[34:35]
	v_cndmask_b32_e32 v2, v217, v2, vcc
	v_cndmask_b32_e32 v3, v217, v3, vcc
	v_cvt_pk_bf16_f32 v0, v0, v1
	v_cvt_pk_bf16_f32 v1, v2, v3
	s_waitcnt lgkmcnt(2)
	v_sub_f32_e32 v3, v65, v98
	v_sub_f32_e32 v2, v64, v98
	v_pk_mul_f32 v[2:3], v[98:99], v[2:3] op_sel:[1,0]
	v_sub_f32_e32 v13, v67, v98
	v_pk_fma_f32 v[2:3], v[88:89], v[2:3], v[92:93]
	v_sub_f32_e32 v12, v66, v98
	v_cndmask_b32_e32 v2, v217, v2, vcc
	v_pk_mul_f32 v[12:13], v[98:99], v[12:13] op_sel:[1,0]
	v_cndmask_b32_e32 v3, v217, v3, vcc
	v_pk_fma_f32 v[12:13], v[90:91], v[12:13], v[94:95]
	global_store_dwordx2 v[62:63], v[0:1], off offset:288
	v_add_u32_e32 v0, s31, v204
	v_cndmask_b32_e32 v12, v217, v12, vcc
	v_ashrrev_i32_e32 v1, 31, v0
	v_cndmask_b32_e32 v13, v217, v13, vcc
	v_cvt_pk_bf16_f32 v2, v2, v3
	v_lshlrev_b64 v[0:1], 11, v[0:1]
	v_lshl_add_u64 v[0:1], s[14:15], 0, v[0:1]
	v_cvt_pk_bf16_f32 v3, v12, v13
	v_lshl_add_u64 v[0:1], v[0:1], 0, v[176:177]
	global_store_dwordx2 v[0:1], v[2:3], off
	v_sub_f32_e32 v3, v41, v98
	v_sub_f32_e32 v2, v40, v98
	v_pk_mul_f32 v[2:3], v[98:99], v[2:3] op_sel:[1,0]
	v_sub_f32_e32 v13, v43, v98
	v_pk_fma_f32 v[2:3], v[76:77], v[2:3], v[80:81]
	v_sub_f32_e32 v12, v42, v98
	v_cndmask_b32_e32 v2, v217, v2, vcc
	v_pk_mul_f32 v[12:13], v[98:99], v[12:13] op_sel:[1,0]
	v_cndmask_b32_e32 v3, v217, v3, vcc
	v_pk_fma_f32 v[12:13], v[78:79], v[12:13], v[82:83]
	v_cndmask_b32_e32 v12, v217, v12, vcc
	v_cndmask_b32_e32 v13, v217, v13, vcc
	v_cvt_pk_bf16_f32 v2, v2, v3
	v_cvt_pk_bf16_f32 v3, v12, v13
	global_store_dwordx2 v[0:1], v[2:3], off offset:32
	v_sub_f32_e32 v3, v25, v98
	v_sub_f32_e32 v2, v24, v98
	v_pk_mul_f32 v[2:3], v[98:99], v[2:3] op_sel:[1,0]
	v_sub_f32_e32 v13, v27, v98
	v_pk_fma_f32 v[2:3], v[52:53], v[2:3], v[56:57]
	v_sub_f32_e32 v12, v26, v98
	v_cndmask_b32_e32 v2, v217, v2, vcc
	v_pk_mul_f32 v[12:13], v[98:99], v[12:13] op_sel:[1,0]
	v_cndmask_b32_e32 v3, v217, v3, vcc
	v_pk_fma_f32 v[12:13], v[54:55], v[12:13], v[58:59]
	v_cndmask_b32_e32 v12, v217, v12, vcc
	v_cndmask_b32_e32 v13, v217, v13, vcc
	v_cvt_pk_bf16_f32 v2, v2, v3
	v_cvt_pk_bf16_f32 v3, v12, v13
	global_store_dwordx2 v[0:1], v[2:3], off offset:256
	v_sub_f32_e32 v3, v5, v98
	v_sub_f32_e32 v2, v4, v98
	v_pk_mul_f32 v[2:3], v[98:99], v[2:3] op_sel:[1,0]
	v_sub_f32_e32 v5, v7, v98
	v_pk_fma_f32 v[2:3], v[20:21], v[2:3], v[32:33]
	v_sub_f32_e32 v4, v6, v98
	v_cndmask_b32_e32 v2, v217, v2, vcc
	v_pk_mul_f32 v[4:5], v[98:99], v[4:5] op_sel:[1,0]
	v_cndmask_b32_e32 v3, v217, v3, vcc
	v_pk_fma_f32 v[4:5], v[22:23], v[4:5], v[34:35]
	v_cndmask_b32_e32 v4, v217, v4, vcc
	v_cndmask_b32_e32 v5, v217, v5, vcc
	v_cvt_pk_bf16_f32 v2, v2, v3
	v_cvt_pk_bf16_f32 v3, v4, v5
	global_store_dwordx2 v[0:1], v[2:3], off offset:288
	s_waitcnt lgkmcnt(1)
; __device__ __forceinline__ unsigned pk2(float lo, float hi) { return f2bf(lo) | (f2bf(hi) << 16); }
;     __device__ __forceinline__ void fused(f32x4 (&acc)[2][2][4][2], const pg8::Unit& u, int wr, int wc, int fr, int fq, LAS unsigned char* lds, int wid, int lane) const {
;     ...
;         const float qnan = __builtin_nanf("");
; #pragma unroll
;         for (int ai = 0; ai < 2; ++ai)
; #pragma unroll
;             for (int m = 0; m < 4; ++m) { const int r = ai * 128 + wr * 64 + m * 16 + fr; const f32x2v sr = S[r]; const size_t off = (size_t)(u.pm * 256 + r) * DM + col0;
; #pragma unroll
;                 for (int bj = 0; bj < 2; ++bj)
; #pragma unroll
;                     for (int n = 0; n < 2; ++n) { f32x4 o = (acc[ai][bj][m][n] - sr.x) * sr.y * gg[bj][n] + bb[bj][n];
;                         if (bad) o = (f32x4){qnan, qnan, qnan, qnan};
;                         if (outf) *(f32x4*)(outf + off + bj * 128 + n * 16) = o;
;                         if (outb) { u32x2 w; w.x = pk2(o[0], o[1]); w.y = pk2(o[2], o[3]); *(u32x2*)(outb + off + bj * 128 + n * 16) = w; } } }
	v_sub_f32_e32 v3, v69, v100
	v_sub_f32_e32 v2, v68, v100
	v_pk_mul_f32 v[2:3], v[100:101], v[2:3] op_sel:[1,0]
	v_sub_f32_e32 v5, v71, v100
	v_pk_fma_f32 v[2:3], v[88:89], v[2:3], v[92:93]
	v_sub_f32_e32 v4, v70, v100
	v_cndmask_b32_e32 v2, v217, v2, vcc
	v_pk_mul_f32 v[4:5], v[100:101], v[4:5] op_sel:[1,0]
	v_cndmask_b32_e32 v3, v217, v3, vcc
	v_pk_fma_f32 v[4:5], v[90:91], v[4:5], v[94:95]
	v_add_u32_e32 v0, s31, v206
	v_cndmask_b32_e32 v4, v217, v4, vcc
	v_ashrrev_i32_e32 v1, 31, v0
	v_cndmask_b32_e32 v5, v217, v5, vcc
	v_cvt_pk_bf16_f32 v2, v2, v3
	v_lshlrev_b64 v[0:1], 11, v[0:1]
	v_lshl_add_u64 v[0:1], s[14:15], 0, v[0:1]
	v_cvt_pk_bf16_f32 v3, v4, v5
	v_lshl_add_u64 v[0:1], v[0:1], 0, v[176:177]
	global_store_dwordx2 v[0:1], v[2:3], off
	v_sub_f32_e32 v3, v45, v100
	v_sub_f32_e32 v2, v44, v100
	v_pk_mul_f32 v[2:3], v[100:101], v[2:3] op_sel:[1,0]
	v_sub_f32_e32 v5, v47, v100
	v_pk_fma_f32 v[2:3], v[76:77], v[2:3], v[80:81]
	v_sub_f32_e32 v4, v46, v100
	v_cndmask_b32_e32 v2, v217, v2, vcc
	v_pk_mul_f32 v[4:5], v[100:101], v[4:5] op_sel:[1,0]
	v_cndmask_b32_e32 v3, v217, v3, vcc
	v_pk_fma_f32 v[4:5], v[78:79], v[4:5], v[82:83]
	v_cndmask_b32_e32 v4, v217, v4, vcc
	v_cndmask_b32_e32 v5, v217, v5, vcc
	v_cvt_pk_bf16_f32 v2, v2, v3
	v_cvt_pk_bf16_f32 v3, v4, v5
	global_store_dwordx2 v[0:1], v[2:3], off offset:32
	v_sub_f32_e32 v3, v29, v100
	v_sub_f32_e32 v2, v28, v100
	v_pk_mul_f32 v[2:3], v[100:101], v[2:3] op_sel:[1,0]
	v_sub_f32_e32 v5, v31, v100
	v_pk_fma_f32 v[2:3], v[52:53], v[2:3], v[56:57]
	v_sub_f32_e32 v4, v30, v100
	v_cndmask_b32_e32 v2, v217, v2, vcc
	v_pk_mul_f32 v[4:5], v[100:101], v[4:5] op_sel:[1,0]
	v_cndmask_b32_e32 v3, v217, v3, vcc
	v_pk_fma_f32 v[4:5], v[54:55], v[4:5], v[58:59]
	v_cndmask_b32_e32 v4, v217, v4, vcc
	v_cndmask_b32_e32 v5, v217, v5, vcc
	v_cvt_pk_bf16_f32 v2, v2, v3
	v_cvt_pk_bf16_f32 v3, v4, v5
	global_store_dwordx2 v[0:1], v[2:3], off offset:256
	v_sub_f32_e32 v3, v9, v100
	v_sub_f32_e32 v2, v8, v100
	v_pk_mul_f32 v[2:3], v[100:101], v[2:3] op_sel:[1,0]
	v_sub_f32_e32 v5, v11, v100
	v_pk_fma_f32 v[2:3], v[20:21], v[2:3], v[32:33]
	v_sub_f32_e32 v4, v10, v100
	v_cndmask_b32_e32 v2, v217, v2, vcc
	v_pk_mul_f32 v[4:5], v[100:101], v[4:5] op_sel:[1,0]
	v_cndmask_b32_e32 v3, v217, v3, vcc
	v_pk_fma_f32 v[4:5], v[22:23], v[4:5], v[34:35]
	v_cndmask_b32_e32 v4, v217, v4, vcc
	v_cndmask_b32_e32 v5, v217, v5, vcc
	v_cvt_pk_bf16_f32 v2, v2, v3
	v_cvt_pk_bf16_f32 v3, v4, v5
	global_store_dwordx2 v[0:1], v[2:3], off offset:288
	s_waitcnt lgkmcnt(0)
	v_sub_f32_e32 v3, v85, v102
	v_sub_f32_e32 v2, v84, v102
	v_pk_mul_f32 v[2:3], v[102:103], v[2:3] op_sel:[1,0]
	v_sub_f32_e32 v5, v87, v102
	v_pk_fma_f32 v[2:3], v[88:89], v[2:3], v[92:93]
	v_sub_f32_e32 v4, v86, v102
	v_cndmask_b32_e32 v2, v217, v2, vcc
	v_pk_mul_f32 v[4:5], v[102:103], v[4:5] op_sel:[1,0]
	v_cndmask_b32_e32 v3, v217, v3, vcc
	v_pk_fma_f32 v[4:5], v[90:91], v[4:5], v[94:95]
	v_add_u32_e32 v0, s31, v208
	v_cndmask_b32_e32 v4, v217, v4, vcc
	v_ashrrev_i32_e32 v1, 31, v0
	v_cndmask_b32_e32 v5, v217, v5, vcc
	v_cvt_pk_bf16_f32 v2, v2, v3
	v_lshlrev_b64 v[0:1], 11, v[0:1]
	v_lshl_add_u64 v[0:1], s[14:15], 0, v[0:1]
	v_cvt_pk_bf16_f32 v3, v4, v5
	v_lshl_add_u64 v[0:1], v[0:1], 0, v[176:177]
	global_store_dwordx2 v[0:1], v[2:3], off
	v_sub_f32_e32 v3, v73, v102
	v_sub_f32_e32 v2, v72, v102
	v_pk_mul_f32 v[2:3], v[102:103], v[2:3] op_sel:[1,0]
	v_sub_f32_e32 v5, v75, v102
	v_pk_fma_f32 v[2:3], v[76:77], v[2:3], v[80:81]
	v_sub_f32_e32 v4, v74, v102
	v_cndmask_b32_e32 v2, v217, v2, vcc
	v_pk_mul_f32 v[4:5], v[102:103], v[4:5] op_sel:[1,0]
	v_cndmask_b32_e32 v3, v217, v3, vcc
	v_pk_fma_f32 v[4:5], v[78:79], v[4:5], v[82:83]
	v_cndmask_b32_e32 v4, v217, v4, vcc
	v_cndmask_b32_e32 v5, v217, v5, vcc
	v_cvt_pk_bf16_f32 v2, v2, v3
	v_cvt_pk_bf16_f32 v3, v4, v5
	global_store_dwordx2 v[0:1], v[2:3], off offset:32
	v_sub_f32_e32 v3, v49, v102
	v_sub_f32_e32 v2, v48, v102
	v_pk_mul_f32 v[2:3], v[102:103], v[2:3] op_sel:[1,0]
	v_sub_f32_e32 v5, v51, v102
	v_pk_fma_f32 v[2:3], v[52:53], v[2:3], v[56:57]
	v_sub_f32_e32 v4, v50, v102
	v_cndmask_b32_e32 v2, v217, v2, vcc
	v_pk_mul_f32 v[4:5], v[102:103], v[4:5] op_sel:[1,0]
	v_cndmask_b32_e32 v3, v217, v3, vcc
	v_pk_fma_f32 v[4:5], v[54:55], v[4:5], v[58:59]
	v_cndmask_b32_e32 v4, v217, v4, vcc
	v_cndmask_b32_e32 v5, v217, v5, vcc
	v_cvt_pk_bf16_f32 v2, v2, v3
	v_cvt_pk_bf16_f32 v3, v4, v5
	global_store_dwordx2 v[0:1], v[2:3], off offset:256
	v_sub_f32_e32 v3, v17, v102
	v_sub_f32_e32 v2, v16, v102
	v_pk_mul_f32 v[2:3], v[102:103], v[2:3] op_sel:[1,0]
	v_sub_f32_e32 v5, v19, v102
	v_pk_fma_f32 v[2:3], v[20:21], v[2:3], v[32:33]
	v_sub_f32_e32 v4, v18, v102
	v_cndmask_b32_e32 v2, v217, v2, vcc
	v_pk_mul_f32 v[4:5], v[102:103], v[4:5] op_sel:[1,0]
	v_cndmask_b32_e32 v3, v217, v3, vcc
	v_pk_fma_f32 v[4:5], v[22:23], v[4:5], v[34:35]
	v_cndmask_b32_e32 v4, v217, v4, vcc
	v_cndmask_b32_e32 v5, v217, v5, vcc
	v_cvt_pk_bf16_f32 v2, v2, v3
	v_cvt_pk_bf16_f32 v3, v4, v5
	s_andn2_b64 vcc, exec, s[8:9]
	s_mov_b64 s[8:9], -1
	global_store_dwordx2 v[0:1], v[2:3], off offset:288
	s_cbranch_vccnz .LBB0_1866
	s_andn2_b64 vcc, exec, s[16:17]
	s_cbranch_vccnz .LBB0_1865
	s_barrier
	s_branch .LBB0_1865

; __device__ __forceinline__ void st16f(float* p, f32x4 v) { st16(p, __builtin_bit_cast(u32x4, v)); }
; __device__ __forceinline__ void st8bf(bf16_t* p, f32x4 a, f32x4 b) { u32x4 w; w.x = pk2(a[0], a[1]); w.y = pk2(a[2], a[3]); w.z = pk2(b[0], b[1]); w.w = pk2(b[2], b[3]); st16(p, w); }
; __device__ __forceinline__ f32x4 sig4(f32x4 v) { f32x4 r; r[0] = sigmoidf_(v[0]); r[1] = sigmoidf_(v[1]); r[2] = sigmoidf_(v[2]); r[3] = sigmoidf_(v[3]); return r; }
;     __device__ __forceinline__ void st_glu(int pn, int row, int c, f32x4 a0, f32x4 a1, f32x4 g0, f32x4 g1) const {
;         const bool smp = row >= MP; const int b = smp ? (row - MP) >> 2 : row >> 13, t = smp ? (row - MP) & 3 : row & (SEQ - 1);
;         const f32x4 v0 = a0 * sig4(g0), v1 = a1 * sig4(g1);
;         const int col = pn * 128 + c;
;         st8bf(U + (size_t)row * 512 + col, v0, v1);
;         float* o = nullptr;
;         if (!smp) { if (t >= SEQ - 30) o = out + O_CONV + ((size_t)b * 30 + (t - (SEQ - 30))) * 512 + col; }
;         else o = out + O_CONVS + ((size_t)b * 30 + 26 + t) * 512 + col;
;         if (o) { st16f(o, v0); st16f(o + 4, v1); }
.LBB0_1988:
	s_or_b64 exec, exec, s[8:9]
	v_lshlrev_b64 v[22:23], 11, v[16:17]
	v_lshl_add_u64 v[22:23], s[52:53], 0, v[22:23]
	v_lshl_add_u64 v[26:27], v[18:19], 1, v[22:23]
	v_cvt_pk_bf16_f32 v22, v4, v5
	v_cvt_pk_bf16_f32 v23, v6, v7
	v_cvt_pk_bf16_f32 v24, v0, v1
	v_cvt_pk_bf16_f32 v25, v2, v3
	v_cmp_ne_u64_e64 s[8:9], 0, v[20:21]
	global_store_dwordx4 v[26:27], v[22:25], off
	s_and_saveexec_b64 s[10:11], s[8:9]
	s_cbranch_execz .LBB0_1990
	global_store_dwordx4 v[20:21], v[4:7], off
	global_store_dwordx4 v[20:21], v[0:3], off offset:16

; __device__ __forceinline__ void st16f(float* p, f32x4 v) { st16(p, __builtin_bit_cast(u32x4, v)); }
; __device__ __forceinline__ void st8bf(bf16_t* p, f32x4 a, f32x4 b) { u32x4 w; w.x = pk2(a[0], a[1]); w.y = pk2(a[2], a[3]); w.z = pk2(b[0], b[1]); w.w = pk2(b[2], b[3]); st16(p, w); }
;     __device__ __forceinline__ void st(int pn, int row, int c, f32x4 v0, f32x4 v1) const {
;         const bool smp = row >= MP; const int b = smp ? (row - MP) >> 2 : row >> 13, t = smp ? (row - MP) & 3 : row & (SEQ - 1);
;         if (pn < 4) { const int col = pn * 256 + c; float* o = nullptr;
;             if (smp) o = out + O_POOLS + ((size_t)b * 15 + 11 + t) * 1024 + col;
;             st8bf(V + (size_t)row * 1024 + col, v0, v1); if (o) { st16f(o, v0); st16f(o + 4, v1); }
.LBB0_2051:
	v_readlane_b32 s4, v250, 60
	v_readlane_b32 s5, v250, 61
	v_add_u32_e32 v138, 0xffff8000, v150
	s_and_b64 s[42:43], s[4:5], s[42:43]
	v_readlane_b32 s4, v251, 2
	s_lshl_b32 s46, s46, 23
	v_lshrrev_b32_e32 v138, 2, v138
	v_readlane_b32 s5, v251, 3
	s_sub_i32 s68, 0.5, s46
	v_mad_u64_u32 v[152:153], s[46:47], v138, 15, v[128:129]
	s_and_b64 s[44:45], s[4:5], s[44:45]
	v_lshlrev_b64 v[156:157], 12, v[152:153]
	v_lshlrev_b64 v[152:153], 10, v[150:151]
	s_andn2_b64 vcc, exec, s[74:75]
	v_mad_u64_u32 v[154:155], s[46:47], v138, s90, 0
	s_cbranch_vccnz .LBB0_2071
	v_or_b32_e32 v160, s70, v140
	v_ashrrev_i32_e32 v161, 31, v160
	v_lshl_add_u64 v[162:163], v[152:153], 1, s[52:53]
	v_lshl_add_u64 v[166:167], v[160:161], 1, v[162:163]
	v_cvt_pk_bf16_f32 v162, v124, v125
	v_cvt_pk_bf16_f32 v163, v126, v127
	v_cvt_pk_bf16_f32 v164, v120, v121
	v_cvt_pk_bf16_f32 v165, v122, v123
	global_store_dwordx4 v[166:167], v[162:165], off
	s_and_saveexec_b64 s[46:47], s[48:49]
	s_cbranch_execz .LBB0_2070
;     __device__ __forceinline__ void st(int pn, int row, int c, f32x4 v0, f32x4 v1) const {
;     ...
;             if (smp) {
;                 const int w = 2 << pn;
;                 float x[8] = {v0[0], v0[1], v0[2], v0[3], v1[0], v1[1], v1[2], v1[3]}, s[8];
; #pragma unroll
;                 for (int e = 0; e < 8; ++e) { s[e] = 0.f;
; #pragma unroll
;                     for (int tp = 0; tp < 4; ++tp) { const float xo = quad_bcast(x[e], tp); if (tp <= t && t - tp < w) s[e] += xo; } }
;                 const int e_lo = 15 + t - w + 1;
; #pragma unroll
;                 for (int e2 = 0; e2 < 15; ++e2) if (e2 >= e_lo) { const float* sp = state_pool + ((size_t)b * 15 + e2) * 1024 + col; const f32x4 a = *(const f32x4*)sp, d = *(const f32x4*)(sp + 4);
;                     s[0] += a[0]; s[1] += a[1]; s[2] += a[2]; s[3] += a[3]; s[4] += d[0]; s[5] += d[1]; s[6] += d[2]; s[7] += d[3]; }
	v_mov_b32_dpp v138, v124 quad_perm:[0,0,0,0] row_mask:0xf bank_mask:0xf bound_ctrl:1
	v_add_f32_e32 v138, 0, v138
	v_cndmask_b32_e64 v138, 0, v138, s[40:41]
	v_readlane_b32 s4, v250, 58
	v_readlane_b32 s5, v250, 59
	v_add_f32_dpp v151, v124, v138 quad_perm:[1,1,1,1] row_mask:0xf bank_mask:0xf bound_ctrl:1
	v_cndmask_b32_e64 v138, v138, v151, s[44:45]
	v_lshl_add_u64 v[162:163], s[4:5], 0, v[156:157]
	v_lshlrev_b64 v[170:171], 2, v[160:161]
	v_add_f32_dpp v151, v124, v138 quad_perm:[2,2,2,2] row_mask:0xf bank_mask:0xf bound_ctrl:1
	v_cndmask_b32_e64 v138, v138, v151, s[42:43]
	v_lshl_add_u64 v[162:163], v[162:163], 0, v[170:171]
	global_store_dwordx4 v[162:163], v[124:127], off
	global_store_dwordx4 v[162:163], v[120:123], off offset:16
	v_add_f32_dpp v151, v124, v138 quad_perm:[3,3,3,3] row_mask:0xf bank_mask:0xf bound_ctrl:1
	v_cndmask_b32_e64 v162, v138, v151, s[0:1]
	v_mov_b32_dpp v138, v125 quad_perm:[0,0,0,0] row_mask:0xf bank_mask:0xf bound_ctrl:1
	v_add_f32_e32 v138, 0, v138
	v_cndmask_b32_e64 v138, 0, v138, s[40:41]
	v_readlane_b32 s4, v250, 12
	v_readlane_b32 s16, v250, 24
	v_add_f32_dpp v151, v125, v138 quad_perm:[1,1,1,1] row_mask:0xf bank_mask:0xf bound_ctrl:1
	v_cndmask_b32_e64 v138, v138, v151, s[44:45]
	v_readlane_b32 s17, v250, 25
	v_readlane_b32 s5, v250, 13
	v_add_f32_dpp v151, v125, v138 quad_perm:[2,2,2,2] row_mask:0xf bank_mask:0xf bound_ctrl:1
	v_cndmask_b32_e64 v138, v138, v151, s[42:43]
	v_lshl_add_u64 v[170:171], s[16:17], 0, v[170:171]
	v_lshl_add_u64 v[170:171], v[170:171], 0, v[154:155]
	v_add_f32_dpp v151, v125, v138 quad_perm:[3,3,3,3] row_mask:0xf bank_mask:0xf bound_ctrl:1
	v_cndmask_b32_e64 v163, v138, v151, s[0:1]
	v_mov_b32_dpp v138, v126 quad_perm:[0,0,0,0] row_mask:0xf bank_mask:0xf bound_ctrl:1
	v_add_f32_e32 v138, 0, v138
	v_cndmask_b32_e64 v138, 0, v138, s[40:41]
	v_readlane_b32 s6, v250, 14
	v_readlane_b32 s7, v250, 15
	v_add_f32_dpp v151, v126, v138 quad_perm:[1,1,1,1] row_mask:0xf bank_mask:0xf bound_ctrl:1
	v_cndmask_b32_e64 v138, v138, v151, s[44:45]
	v_readlane_b32 s8, v250, 16
	v_readlane_b32 s9, v250, 17
	v_add_f32_dpp v151, v126, v138 quad_perm:[2,2,2,2] row_mask:0xf bank_mask:0xf bound_ctrl:1
	v_cndmask_b32_e64 v138, v138, v151, s[42:43]
	v_readlane_b32 s10, v250, 18
	v_readlane_b32 s11, v250, 19
	v_add_f32_dpp v151, v126, v138 quad_perm:[3,3,3,3] row_mask:0xf bank_mask:0xf bound_ctrl:1
	v_cndmask_b32_e64 v164, v138, v151, s[0:1]
	v_mov_b32_dpp v138, v127 quad_perm:[0,0,0,0] row_mask:0xf bank_mask:0xf bound_ctrl:1
	v_add_f32_e32 v138, 0, v138
	v_cndmask_b32_e64 v138, 0, v138, s[40:41]
	v_readlane_b32 s12, v250, 20
	v_readlane_b32 s13, v250, 21
	v_add_f32_dpp v151, v127, v138 quad_perm:[1,1,1,1] row_mask:0xf bank_mask:0xf bound_ctrl:1
	v_cndmask_b32_e64 v138, v138, v151, s[44:45]
	v_readlane_b32 s14, v250, 22
	v_readlane_b32 s15, v250, 23
	v_add_f32_dpp v151, v127, v138 quad_perm:[2,2,2,2] row_mask:0xf bank_mask:0xf bound_ctrl:1
	v_cndmask_b32_e64 v138, v138, v151, s[42:43]
	v_readlane_b32 s18, v250, 26
	v_readlane_b32 s19, v250, 27
	v_add_f32_dpp v151, v127, v138 quad_perm:[3,3,3,3] row_mask:0xf bank_mask:0xf bound_ctrl:1
	v_cndmask_b32_e64 v165, v138, v151, s[0:1]
	v_mov_b32_dpp v138, v120 quad_perm:[0,0,0,0] row_mask:0xf bank_mask:0xf bound_ctrl:1
	v_add_f32_e32 v138, 0, v138
	v_cndmask_b32_e64 v138, 0, v138, s[40:41]
	s_nop 1
	v_add_f32_dpp v151, v120, v138 quad_perm:[1,1,1,1] row_mask:0xf bank_mask:0xf bound_ctrl:1
	v_cndmask_b32_e64 v138, v138, v151, s[44:45]
	s_nop 1
	v_add_f32_dpp v151, v120, v138 quad_perm:[2,2,2,2] row_mask:0xf bank_mask:0xf bound_ctrl:1
	v_cndmask_b32_e64 v138, v138, v151, s[42:43]
	s_nop 1
	v_add_f32_dpp v151, v120, v138 quad_perm:[3,3,3,3] row_mask:0xf bank_mask:0xf bound_ctrl:1
	v_cndmask_b32_e64 v166, v138, v151, s[0:1]
	v_mov_b32_dpp v138, v121 quad_perm:[0,0,0,0] row_mask:0xf bank_mask:0xf bound_ctrl:1
	v_add_f32_e32 v138, 0, v138
	v_cndmask_b32_e64 v138, 0, v138, s[40:41]
	s_nop 1
	v_add_f32_dpp v151, v121, v138 quad_perm:[1,1,1,1] row_mask:0xf bank_mask:0xf bound_ctrl:1
	v_cndmask_b32_e64 v138, v138, v151, s[44:45]
	s_nop 1
	v_add_f32_dpp v151, v121, v138 quad_perm:[2,2,2,2] row_mask:0xf bank_mask:0xf bound_ctrl:1
	v_cndmask_b32_e64 v138, v138, v151, s[42:43]
	s_nop 1
	v_add_f32_dpp v151, v121, v138 quad_perm:[3,3,3,3] row_mask:0xf bank_mask:0xf bound_ctrl:1
	v_cndmask_b32_e64 v167, v138, v151, s[0:1]
	v_mov_b32_dpp v138, v122 quad_perm:[0,0,0,0] row_mask:0xf bank_mask:0xf bound_ctrl:1
	v_add_f32_e32 v138, 0, v138
	v_cndmask_b32_e64 v138, 0, v138, s[40:41]
	s_nop 1
	v_add_f32_dpp v151, v122, v138 quad_perm:[1,1,1,1] row_mask:0xf bank_mask:0xf bound_ctrl:1
	v_cndmask_b32_e64 v138, v138, v151, s[44:45]
	s_nop 1
	v_add_f32_dpp v151, v122, v138 quad_perm:[2,2,2,2] row_mask:0xf bank_mask:0xf bound_ctrl:1
	v_cndmask_b32_e64 v138, v138, v151, s[42:43]
	s_nop 1
	v_add_f32_dpp v151, v122, v138 quad_perm:[3,3,3,3] row_mask:0xf bank_mask:0xf bound_ctrl:1
	v_cndmask_b32_e64 v168, v138, v151, s[0:1]
	v_mov_b32_dpp v138, v123 quad_perm:[0,0,0,0] row_mask:0xf bank_mask:0xf bound_ctrl:1
	v_add_f32_e32 v138, 0, v138
	v_cndmask_b32_e64 v138, 0, v138, s[40:41]
	s_nop 1
	v_add_f32_dpp v151, v123, v138 quad_perm:[1,1,1,1] row_mask:0xf bank_mask:0xf bound_ctrl:1
	v_cndmask_b32_e64 v138, v138, v151, s[44:45]
	s_nop 1
	v_add_f32_dpp v151, v123, v138 quad_perm:[2,2,2,2] row_mask:0xf bank_mask:0xf bound_ctrl:1
	v_cndmask_b32_e64 v138, v138, v151, s[42:43]
	s_nop 1
	v_add_f32_dpp v151, v123, v138 quad_perm:[3,3,3,3] row_mask:0xf bank_mask:0xf bound_ctrl:1
	v_cndmask_b32_e64 v169, v138, v151, s[0:1]
	s_and_saveexec_b64 s[74:75], s[38:39]
	s_cbranch_execz .LBB0_2404
	global_load_dwordx4 v[180:183], v[170:171], off offset:16
	global_load_dwordx4 v[184:187], v[170:171], off
	s_waitcnt vmcnt(0)
	v_pk_add_f32 v[166:167], v[166:167], v[180:181]
	v_pk_add_f32 v[168:169], v[168:169], v[182:183]
	v_pk_add_f32 v[164:165], v[164:165], v[186:187]
	v_pk_add_f32 v[162:163], v[162:163], v[184:185]
	s_or_b64 exec, exec, s[74:75]
	s_and_saveexec_b64 s[74:75], s[36:37]
	s_cbranch_execnz .LBB0_2405

; __device__ __forceinline__ void st16f(float* p, f32x4 v) { st16(p, __builtin_bit_cast(u32x4, v)); }
; __device__ __forceinline__ void st8bf(bf16_t* p, f32x4 a, f32x4 b) { u32x4 w; w.x = pk2(a[0], a[1]); w.y = pk2(a[2], a[3]); w.z = pk2(b[0], b[1]); w.w = pk2(b[2], b[3]); st16(p, w); }
;     __device__ __forceinline__ void st(int pn, int row, int c, f32x4 v0, f32x4 v1) const {
;         const bool smp = row >= MP; const int b = smp ? (row - MP) >> 2 : row >> 13, t = smp ? (row - MP) & 3 : row & (SEQ - 1);
;         if (pn < 4) { const int col = pn * 256 + c; float* o = nullptr;
;             if (smp) o = out + O_POOLS + ((size_t)b * 15 + 11 + t) * 1024 + col;
;             st8bf(V + (size_t)row * 1024 + col, v0, v1); if (o) { st16f(o, v0); st16f(o + 4, v1); }
;             if (smp) {
;                 const int w = 2 << pn;
;                 float x[8] = {v0[0], v0[1], v0[2], v0[3], v1[0], v1[1], v1[2], v1[3]}, s[8];
; #pragma unroll
;                 for (int e = 0; e < 8; ++e) { s[e] = 0.f;
; #pragma unroll
;                     for (int tp = 0; tp < 4; ++tp) { const float xo = quad_bcast(x[e], tp); if (tp <= t && t - tp < w) s[e] += xo; } }
;                 const int e_lo = 15 + t - w + 1;
; #pragma unroll
;                 for (int e2 = 0; e2 < 15; ++e2) if (e2 >= e_lo) { const float* sp = state_pool + ((size_t)b * 15 + e2) * 1024 + col; const f32x4 a = *(const f32x4*)sp, d = *(const f32x4*)(sp + 4);
;                     s[0] += a[0]; s[1] += a[1]; s[2] += a[2]; s[3] += a[3]; s[4] += d[0]; s[5] += d[1]; s[6] += d[2]; s[7] += d[3]; }
.LBB0_2073:
	s_andn2_b64 vcc, exec, s[72:73]
	s_cbranch_vccnz .LBB0_2093
	s_ashr_i32 s71, s70, 31
	v_lshl_add_u64 v[122:123], v[152:153], 1, s[52:53]
	v_lshl_add_u64 v[120:121], s[70:71], 0, v[140:141]
	v_lshl_add_u64 v[126:127], v[120:121], 1, v[122:123]
	v_cvt_pk_bf16_f32 v122, v116, v117
	v_cvt_pk_bf16_f32 v123, v118, v119
	v_cvt_pk_bf16_f32 v124, v112, v113
	v_cvt_pk_bf16_f32 v125, v114, v115
	global_store_dwordx4 v[126:127], v[122:125], off offset:256
	s_and_saveexec_b64 s[72:73], s[48:49]
	s_cbranch_execz .LBB0_2092
	v_readlane_b32 s4, v250, 58
	v_readlane_b32 s5, v250, 59
	v_lshlrev_b64 v[158:159], 2, v[120:121]
	s_nop 0
	v_lshl_add_u64 v[122:123], s[4:5], 0, v[156:157]
	v_lshl_add_u64 v[122:123], v[122:123], 0, v[158:159]
	global_store_dwordx4 v[122:123], v[116:119], off offset:512
	global_store_dwordx4 v[122:123], v[112:115], off offset:528
	v_mov_b32_dpp v122, v116 quad_perm:[0,0,0,0] row_mask:0xf bank_mask:0xf bound_ctrl:1
	v_add_f32_e32 v122, 0, v122
	v_cndmask_b32_e64 v122, 0, v122, s[40:41]
	v_readlane_b32 s4, v250, 12
	v_readlane_b32 s16, v250, 24
	v_add_f32_dpp v123, v116, v122 quad_perm:[1,1,1,1] row_mask:0xf bank_mask:0xf bound_ctrl:1
	v_cndmask_b32_e64 v122, v122, v123, s[44:45]
	v_readlane_b32 s17, v250, 25
	v_readlane_b32 s5, v250, 13
	v_add_f32_dpp v123, v116, v122 quad_perm:[2,2,2,2] row_mask:0xf bank_mask:0xf bound_ctrl:1
	v_cndmask_b32_e64 v122, v122, v123, s[42:43]
	v_lshl_add_u64 v[158:159], s[16:17], 0, v[158:159]
	v_lshl_add_u64 v[154:155], v[158:159], 0, v[154:155]
	v_add_f32_dpp v123, v116, v122 quad_perm:[3,3,3,3] row_mask:0xf bank_mask:0xf bound_ctrl:1
	v_cndmask_b32_e64 v122, v122, v123, s[0:1]
	v_readlane_b32 s6, v250, 14
	v_mov_b32_dpp v123, v117 quad_perm:[0,0,0,0] row_mask:0xf bank_mask:0xf bound_ctrl:1
	v_add_f32_e32 v123, 0, v123
	v_cndmask_b32_e64 v123, 0, v123, s[40:41]
	v_readlane_b32 s7, v250, 15
	v_readlane_b32 s8, v250, 16
	v_add_f32_dpp v124, v117, v123 quad_perm:[1,1,1,1] row_mask:0xf bank_mask:0xf bound_ctrl:1
	v_cndmask_b32_e64 v123, v123, v124, s[44:45]
	v_readlane_b32 s9, v250, 17
	v_readlane_b32 s10, v250, 18
	v_add_f32_dpp v124, v117, v123 quad_perm:[2,2,2,2] row_mask:0xf bank_mask:0xf bound_ctrl:1
	v_cndmask_b32_e64 v123, v123, v124, s[42:43]
	v_readlane_b32 s11, v250, 19
	v_readlane_b32 s12, v250, 20
	v_add_f32_dpp v124, v117, v123 quad_perm:[3,3,3,3] row_mask:0xf bank_mask:0xf bound_ctrl:1
	v_cndmask_b32_e64 v123, v123, v124, s[0:1]
	v_readlane_b32 s13, v250, 21
	v_mov_b32_dpp v124, v118 quad_perm:[0,0,0,0] row_mask:0xf bank_mask:0xf bound_ctrl:1
	v_add_f32_e32 v124, 0, v124
	v_cndmask_b32_e64 v124, 0, v124, s[40:41]
	v_readlane_b32 s14, v250, 22
	v_readlane_b32 s15, v250, 23
	v_add_f32_dpp v125, v118, v124 quad_perm:[1,1,1,1] row_mask:0xf bank_mask:0xf bound_ctrl:1
	v_cndmask_b32_e64 v124, v124, v125, s[44:45]
	v_readlane_b32 s18, v250, 26
	v_readlane_b32 s19, v250, 27
	v_add_f32_dpp v125, v118, v124 quad_perm:[2,2,2,2] row_mask:0xf bank_mask:0xf bound_ctrl:1
	v_cndmask_b32_e64 v124, v124, v125, s[42:43]
	s_nop 1
	v_add_f32_dpp v125, v118, v124 quad_perm:[3,3,3,3] row_mask:0xf bank_mask:0xf bound_ctrl:1
	v_cndmask_b32_e64 v124, v124, v125, s[0:1]
	s_nop 0
	v_mov_b32_dpp v125, v119 quad_perm:[0,0,0,0] row_mask:0xf bank_mask:0xf bound_ctrl:1
	v_add_f32_e32 v125, 0, v125
	v_cndmask_b32_e64 v125, 0, v125, s[40:41]
	s_nop 1
	v_add_f32_dpp v126, v119, v125 quad_perm:[1,1,1,1] row_mask:0xf bank_mask:0xf bound_ctrl:1
	v_cndmask_b32_e64 v125, v125, v126, s[44:45]
	s_nop 1
	v_add_f32_dpp v126, v119, v125 quad_perm:[2,2,2,2] row_mask:0xf bank_mask:0xf bound_ctrl:1
	v_cndmask_b32_e64 v125, v125, v126, s[42:43]
	s_nop 1
	v_add_f32_dpp v126, v119, v125 quad_perm:[3,3,3,3] row_mask:0xf bank_mask:0xf bound_ctrl:1
	v_cndmask_b32_e64 v125, v125, v126, s[0:1]
	s_nop 0
	v_mov_b32_dpp v126, v112 quad_perm:[0,0,0,0] row_mask:0xf bank_mask:0xf bound_ctrl:1
	v_add_f32_e32 v126, 0, v126
	v_cndmask_b32_e64 v126, 0, v126, s[40:41]
	s_nop 1
	v_add_f32_dpp v127, v112, v126 quad_perm:[1,1,1,1] row_mask:0xf bank_mask:0xf bound_ctrl:1
	v_cndmask_b32_e64 v126, v126, v127, s[44:45]
	s_nop 1
	v_add_f32_dpp v127, v112, v126 quad_perm:[2,2,2,2] row_mask:0xf bank_mask:0xf bound_ctrl:1
	v_cndmask_b32_e64 v126, v126, v127, s[42:43]
	s_nop 1
	v_add_f32_dpp v127, v112, v126 quad_perm:[3,3,3,3] row_mask:0xf bank_mask:0xf bound_ctrl:1
	v_cndmask_b32_e64 v126, v126, v127, s[0:1]
	s_nop 0
	v_mov_b32_dpp v127, v113 quad_perm:[0,0,0,0] row_mask:0xf bank_mask:0xf bound_ctrl:1
	v_add_f32_e32 v127, 0, v127
	v_cndmask_b32_e64 v127, 0, v127, s[40:41]
	s_nop 1
	v_add_f32_dpp v138, v113, v127 quad_perm:[1,1,1,1] row_mask:0xf bank_mask:0xf bound_ctrl:1
	v_cndmask_b32_e64 v127, v127, v138, s[44:45]
	s_nop 1
	v_add_f32_dpp v138, v113, v127 quad_perm:[2,2,2,2] row_mask:0xf bank_mask:0xf bound_ctrl:1
	v_cndmask_b32_e64 v127, v127, v138, s[42:43]
	s_nop 1
	v_add_f32_dpp v138, v113, v127 quad_perm:[3,3,3,3] row_mask:0xf bank_mask:0xf bound_ctrl:1
	v_cndmask_b32_e64 v127, v127, v138, s[0:1]
	s_nop 0
	v_mov_b32_dpp v138, v114 quad_perm:[0,0,0,0] row_mask:0xf bank_mask:0xf bound_ctrl:1
	v_add_f32_e32 v138, 0, v138
	v_cndmask_b32_e64 v138, 0, v138, s[40:41]
	s_nop 1
	v_add_f32_dpp v151, v114, v138 quad_perm:[1,1,1,1] row_mask:0xf bank_mask:0xf bound_ctrl:1
	v_cndmask_b32_e64 v138, v138, v151, s[44:45]
	s_nop 1
	v_add_f32_dpp v151, v114, v138 quad_perm:[2,2,2,2] row_mask:0xf bank_mask:0xf bound_ctrl:1
	v_cndmask_b32_e64 v138, v138, v151, s[42:43]
	s_nop 1
	v_add_f32_dpp v151, v114, v138 quad_perm:[3,3,3,3] row_mask:0xf bank_mask:0xf bound_ctrl:1
	v_cndmask_b32_e64 v156, v138, v151, s[0:1]
	v_mov_b32_dpp v138, v115 quad_perm:[0,0,0,0] row_mask:0xf bank_mask:0xf bound_ctrl:1
	v_add_f32_e32 v138, 0, v138
	v_cndmask_b32_e64 v138, 0, v138, s[40:41]
	s_nop 1
	v_add_f32_dpp v151, v115, v138 quad_perm:[1,1,1,1] row_mask:0xf bank_mask:0xf bound_ctrl:1
	v_cndmask_b32_e64 v138, v138, v151, s[44:45]
	s_nop 1
	v_add_f32_dpp v151, v115, v138 quad_perm:[2,2,2,2] row_mask:0xf bank_mask:0xf bound_ctrl:1
	v_cndmask_b32_e64 v138, v138, v151, s[42:43]
	s_nop 1
	v_add_f32_dpp v151, v115, v138 quad_perm:[3,3,3,3] row_mask:0xf bank_mask:0xf bound_ctrl:1
	v_cndmask_b32_e64 v157, v138, v151, s[0:1]
	s_and_saveexec_b64 s[48:49], s[38:39]
	s_cbranch_execz .LBB0_2418
	global_load_dwordx4 v[158:161], v[154:155], off offset:528
	global_load_dwordx4 v[162:165], v[154:155], off offset:512
	s_waitcnt vmcnt(0)
	v_pk_add_f32 v[126:127], v[126:127], v[158:159]
	v_pk_add_f32 v[156:157], v[156:157], v[160:161]
	v_pk_add_f32 v[124:125], v[124:125], v[164:165]
	v_pk_add_f32 v[122:123], v[122:123], v[162:163]
	s_or_b64 exec, exec, s[48:49]
	s_and_saveexec_b64 s[48:49], s[36:37]
	s_cbranch_execnz .LBB0_2419

; __device__ __forceinline__ void st16f(float* p, f32x4 v) { st16(p, __builtin_bit_cast(u32x4, v)); }
; __device__ __forceinline__ void st8bf(bf16_t* p, f32x4 a, f32x4 b) { u32x4 w; w.x = pk2(a[0], a[1]); w.y = pk2(a[2], a[3]); w.z = pk2(b[0], b[1]); w.w = pk2(b[2], b[3]); st16(p, w); }
;     __device__ __forceinline__ void st(int pn, int row, int c, f32x4 v0, f32x4 v1) const {
;         const bool smp = row >= MP; const int b = smp ? (row - MP) >> 2 : row >> 13, t = smp ? (row - MP) & 3 : row & (SEQ - 1);
;         if (pn < 4) { const int col = pn * 256 + c; float* o = nullptr;
;             if (smp) o = out + O_POOLS + ((size_t)b * 15 + 11 + t) * 1024 + col;
;             st8bf(V + (size_t)row * 1024 + col, v0, v1); if (o) { st16f(o, v0); st16f(o + 4, v1); }
;             if (smp) {
;                 const int w = 2 << pn;
;                 float x[8] = {v0[0], v0[1], v0[2], v0[3], v1[0], v1[1], v1[2], v1[3]}, s[8];
; #pragma unroll
;                 for (int e = 0; e < 8; ++e) { s[e] = 0.f;
; #pragma unroll
;                     for (int tp = 0; tp < 4; ++tp) { const float xo = quad_bcast(x[e], tp); if (tp <= t && t - tp < w) s[e] += xo; } }
;                 const int e_lo = 15 + t - w + 1;
; #pragma unroll
;                 for (int e2 = 0; e2 < 15; ++e2) if (e2 >= e_lo) { const float* sp = state_pool + ((size_t)b * 15 + e2) * 1024 + col; const f32x4 a = *(const f32x4*)sp, d = *(const f32x4*)(sp + 4);
;                     s[0] += a[0]; s[1] += a[1]; s[2] += a[2]; s[3] += a[3]; s[4] += d[0]; s[5] += d[1]; s[6] += d[2]; s[7] += d[3]; }
;                 const float inv = 1.f / (float)w;
;                 st8bf(DMs + (size_t)row * 1024 + col, (f32x4){s[0] * inv - x[0], s[1] * inv - x[1], s[2] * inv - x[2], s[3] * inv - x[3]}, (f32x4){s[4] * inv - x[4], s[5] * inv - x[5], s[6] * inv - x[6], s[7] * inv - x[7]});
;             } }
.LBB0_2095:
	s_nop 1
	v_add_u32_e32 v114, 0xffff8010, v150
	v_lshrrev_b32_e32 v120, 2, v114
	v_mad_u64_u32 v[114:115], s[74:75], v120, 15, v[128:129]
	v_lshlrev_b64 v[116:117], 12, v[114:115]
	v_lshlrev_b64 v[112:113], 10, v[112:113]
	s_andn2_b64 vcc, exec, s[72:73]
	v_mad_u64_u32 v[114:115], s[72:73], v120, s90, 0
	s_cbranch_vccnz .LBB0_2116
	v_or_b32_e32 v120, s70, v140
	v_ashrrev_i32_e32 v121, 31, v120
	v_lshl_add_u64 v[122:123], v[112:113], 1, s[52:53]
	v_lshl_add_u64 v[126:127], v[120:121], 1, v[122:123]
	v_cvt_pk_bf16_f32 v122, v108, v109
	v_cvt_pk_bf16_f32 v123, v110, v111
	v_cvt_pk_bf16_f32 v124, v104, v105
	v_cvt_pk_bf16_f32 v125, v106, v107
	global_store_dwordx4 v[126:127], v[122:125], off
	s_and_saveexec_b64 s[72:73], s[48:49]
	s_cbranch_execz .LBB0_2114
	v_readlane_b32 s4, v250, 58
	v_readlane_b32 s5, v250, 59
	v_lshlrev_b64 v[154:155], 2, v[120:121]
	s_nop 0
	v_lshl_add_u64 v[122:123], s[4:5], 0, v[116:117]
	v_lshl_add_u64 v[122:123], v[122:123], 0, v[154:155]
	global_store_dwordx4 v[122:123], v[108:111], off
	global_store_dwordx4 v[122:123], v[104:107], off offset:16
	v_mov_b32_dpp v122, v108 quad_perm:[0,0,0,0] row_mask:0xf bank_mask:0xf bound_ctrl:1
	v_add_f32_e32 v122, 0, v122
	v_cndmask_b32_e64 v122, 0, v122, s[40:41]
	v_readlane_b32 s4, v250, 12
	v_readlane_b32 s16, v250, 24
	v_add_f32_dpp v123, v108, v122 quad_perm:[1,1,1,1] row_mask:0xf bank_mask:0xf bound_ctrl:1
	v_cndmask_b32_e64 v122, v122, v123, s[44:45]
	v_readlane_b32 s17, v250, 25
	v_readlane_b32 s5, v250, 13
	v_add_f32_dpp v123, v108, v122 quad_perm:[2,2,2,2] row_mask:0xf bank_mask:0xf bound_ctrl:1
	v_cndmask_b32_e64 v122, v122, v123, s[42:43]
	v_lshl_add_u64 v[154:155], s[16:17], 0, v[154:155]
	v_lshl_add_u64 v[154:155], v[154:155], 0, v[114:115]
	v_add_f32_dpp v123, v108, v122 quad_perm:[3,3,3,3] row_mask:0xf bank_mask:0xf bound_ctrl:1
	v_cndmask_b32_e64 v122, v122, v123, s[0:1]
	v_readlane_b32 s6, v250, 14
	v_mov_b32_dpp v123, v109 quad_perm:[0,0,0,0] row_mask:0xf bank_mask:0xf bound_ctrl:1
	v_add_f32_e32 v123, 0, v123
	v_cndmask_b32_e64 v123, 0, v123, s[40:41]
	v_readlane_b32 s7, v250, 15
	v_readlane_b32 s8, v250, 16
	v_add_f32_dpp v124, v109, v123 quad_perm:[1,1,1,1] row_mask:0xf bank_mask:0xf bound_ctrl:1
	v_cndmask_b32_e64 v123, v123, v124, s[44:45]
	v_readlane_b32 s9, v250, 17
	v_readlane_b32 s10, v250, 18
	v_add_f32_dpp v124, v109, v123 quad_perm:[2,2,2,2] row_mask:0xf bank_mask:0xf bound_ctrl:1
	v_cndmask_b32_e64 v123, v123, v124, s[42:43]
	v_readlane_b32 s11, v250, 19
	v_readlane_b32 s12, v250, 20
	v_add_f32_dpp v124, v109, v123 quad_perm:[3,3,3,3] row_mask:0xf bank_mask:0xf bound_ctrl:1
	v_cndmask_b32_e64 v123, v123, v124, s[0:1]
	v_readlane_b32 s13, v250, 21
	v_mov_b32_dpp v124, v110 quad_perm:[0,0,0,0] row_mask:0xf bank_mask:0xf bound_ctrl:1
	v_add_f32_e32 v124, 0, v124
	v_cndmask_b32_e64 v124, 0, v124, s[40:41]
	v_readlane_b32 s14, v250, 22
	v_readlane_b32 s15, v250, 23
	v_add_f32_dpp v125, v110, v124 quad_perm:[1,1,1,1] row_mask:0xf bank_mask:0xf bound_ctrl:1
	v_cndmask_b32_e64 v124, v124, v125, s[44:45]
	v_readlane_b32 s18, v250, 26
	v_readlane_b32 s19, v250, 27
	v_add_f32_dpp v125, v110, v124 quad_perm:[2,2,2,2] row_mask:0xf bank_mask:0xf bound_ctrl:1
	v_cndmask_b32_e64 v124, v124, v125, s[42:43]
	s_nop 1
	v_add_f32_dpp v125, v110, v124 quad_perm:[3,3,3,3] row_mask:0xf bank_mask:0xf bound_ctrl:1
	v_cndmask_b32_e64 v124, v124, v125, s[0:1]
	s_nop 0
	v_mov_b32_dpp v125, v111 quad_perm:[0,0,0,0] row_mask:0xf bank_mask:0xf bound_ctrl:1
	v_add_f32_e32 v125, 0, v125
	v_cndmask_b32_e64 v125, 0, v125, s[40:41]
	s_nop 1
	v_add_f32_dpp v126, v111, v125 quad_perm:[1,1,1,1] row_mask:0xf bank_mask:0xf bound_ctrl:1
	v_cndmask_b32_e64 v125, v125, v126, s[44:45]
	s_nop 1
	v_add_f32_dpp v126, v111, v125 quad_perm:[2,2,2,2] row_mask:0xf bank_mask:0xf bound_ctrl:1
	v_cndmask_b32_e64 v125, v125, v126, s[42:43]
	s_nop 1
	v_add_f32_dpp v126, v111, v125 quad_perm:[3,3,3,3] row_mask:0xf bank_mask:0xf bound_ctrl:1
	v_cndmask_b32_e64 v125, v125, v126, s[0:1]
	s_nop 0
	v_mov_b32_dpp v126, v104 quad_perm:[0,0,0,0] row_mask:0xf bank_mask:0xf bound_ctrl:1
	v_add_f32_e32 v126, 0, v126
	v_cndmask_b32_e64 v126, 0, v126, s[40:41]
	s_nop 1
	v_add_f32_dpp v127, v104, v126 quad_perm:[1,1,1,1] row_mask:0xf bank_mask:0xf bound_ctrl:1
	v_cndmask_b32_e64 v126, v126, v127, s[44:45]
	s_nop 1
	v_add_f32_dpp v127, v104, v126 quad_perm:[2,2,2,2] row_mask:0xf bank_mask:0xf bound_ctrl:1
	v_cndmask_b32_e64 v126, v126, v127, s[42:43]
	s_nop 1
	v_add_f32_dpp v127, v104, v126 quad_perm:[3,3,3,3] row_mask:0xf bank_mask:0xf bound_ctrl:1
	v_cndmask_b32_e64 v126, v126, v127, s[0:1]
	s_nop 0
	v_mov_b32_dpp v127, v105 quad_perm:[0,0,0,0] row_mask:0xf bank_mask:0xf bound_ctrl:1
	v_add_f32_e32 v127, 0, v127
	v_cndmask_b32_e64 v127, 0, v127, s[40:41]
	s_nop 1
	v_add_f32_dpp v138, v105, v127 quad_perm:[1,1,1,1] row_mask:0xf bank_mask:0xf bound_ctrl:1
	v_cndmask_b32_e64 v127, v127, v138, s[44:45]
	s_nop 1
	v_add_f32_dpp v138, v105, v127 quad_perm:[2,2,2,2] row_mask:0xf bank_mask:0xf bound_ctrl:1
	v_cndmask_b32_e64 v127, v127, v138, s[42:43]
	s_nop 1
	v_add_f32_dpp v138, v105, v127 quad_perm:[3,3,3,3] row_mask:0xf bank_mask:0xf bound_ctrl:1
	v_cndmask_b32_e64 v127, v127, v138, s[0:1]
	s_nop 0
	v_mov_b32_dpp v138, v106 quad_perm:[0,0,0,0] row_mask:0xf bank_mask:0xf bound_ctrl:1
	v_add_f32_e32 v138, 0, v138
	v_cndmask_b32_e64 v138, 0, v138, s[40:41]
	s_nop 1
	v_add_f32_dpp v151, v106, v138 quad_perm:[1,1,1,1] row_mask:0xf bank_mask:0xf bound_ctrl:1
	v_cndmask_b32_e64 v138, v138, v151, s[44:45]
	s_nop 1
	v_add_f32_dpp v151, v106, v138 quad_perm:[2,2,2,2] row_mask:0xf bank_mask:0xf bound_ctrl:1
	v_cndmask_b32_e64 v138, v138, v151, s[42:43]
	s_nop 1
	v_add_f32_dpp v151, v106, v138 quad_perm:[3,3,3,3] row_mask:0xf bank_mask:0xf bound_ctrl:1
	v_cndmask_b32_e64 v152, v138, v151, s[0:1]
	v_mov_b32_dpp v138, v107 quad_perm:[0,0,0,0] row_mask:0xf bank_mask:0xf bound_ctrl:1
	v_add_f32_e32 v138, 0, v138
	v_cndmask_b32_e64 v138, 0, v138, s[40:41]
	s_nop 1
	v_add_f32_dpp v151, v107, v138 quad_perm:[1,1,1,1] row_mask:0xf bank_mask:0xf bound_ctrl:1
	v_cndmask_b32_e64 v138, v138, v151, s[44:45]
	s_nop 1
	v_add_f32_dpp v151, v107, v138 quad_perm:[2,2,2,2] row_mask:0xf bank_mask:0xf bound_ctrl:1
	v_cndmask_b32_e64 v138, v138, v151, s[42:43]
	s_nop 1
	v_add_f32_dpp v151, v107, v138 quad_perm:[3,3,3,3] row_mask:0xf bank_mask:0xf bound_ctrl:1
	v_cndmask_b32_e64 v153, v138, v151, s[0:1]
	s_and_saveexec_b64 s[74:75], s[38:39]
	s_cbranch_execz .LBB0_2432
	global_load_dwordx4 v[156:159], v[154:155], off offset:16
	global_load_dwordx4 v[160:163], v[154:155], off
	s_waitcnt vmcnt(0)
	v_pk_add_f32 v[126:127], v[126:127], v[156:157]
	v_pk_add_f32 v[152:153], v[152:153], v[158:159]
	v_pk_add_f32 v[124:125], v[124:125], v[162:163]
	v_pk_add_f32 v[122:123], v[122:123], v[160:161]
	s_or_b64 exec, exec, s[74:75]
	s_and_saveexec_b64 s[74:75], s[36:37]
	s_cbranch_execnz .LBB0_2433

; __device__ __forceinline__ void st16f(float* p, f32x4 v) { st16(p, __builtin_bit_cast(u32x4, v)); }
; __device__ __forceinline__ void st8bf(bf16_t* p, f32x4 a, f32x4 b) { u32x4 w; w.x = pk2(a[0], a[1]); w.y = pk2(a[2], a[3]); w.z = pk2(b[0], b[1]); w.w = pk2(b[2], b[3]); st16(p, w); }
;     __device__ __forceinline__ void st(int pn, int row, int c, f32x4 v0, f32x4 v1) const {
;         const bool smp = row >= MP; const int b = smp ? (row - MP) >> 2 : row >> 13, t = smp ? (row - MP) & 3 : row & (SEQ - 1);
;         if (pn < 4) { const int col = pn * 256 + c; float* o = nullptr;
;             if (smp) o = out + O_POOLS + ((size_t)b * 15 + 11 + t) * 1024 + col;
;             st8bf(V + (size_t)row * 1024 + col, v0, v1); if (o) { st16f(o, v0); st16f(o + 4, v1); }
;             if (smp) {
;                 const int w = 2 << pn;
;                 float x[8] = {v0[0], v0[1], v0[2], v0[3], v1[0], v1[1], v1[2], v1[3]}, s[8];
; #pragma unroll
;                 for (int e = 0; e < 8; ++e) { s[e] = 0.f;
; #pragma unroll
;                     for (int tp = 0; tp < 4; ++tp) { const float xo = quad_bcast(x[e], tp); if (tp <= t && t - tp < w) s[e] += xo; } }
;                 const int e_lo = 15 + t - w + 1;
; #pragma unroll
;                 for (int e2 = 0; e2 < 15; ++e2) if (e2 >= e_lo) { const float* sp = state_pool + ((size_t)b * 15 + e2) * 1024 + col; const f32x4 a = *(const f32x4*)sp, d = *(const f32x4*)(sp + 4);
;                     s[0] += a[0]; s[1] += a[1]; s[2] += a[2]; s[3] += a[3]; s[4] += d[0]; s[5] += d[1]; s[6] += d[2]; s[7] += d[3]; }
;                 const float inv = 1.f / (float)w;
;                 st8bf(DMs + (size_t)row * 1024 + col, (f32x4){s[0] * inv - x[0], s[1] * inv - x[1], s[2] * inv - x[2], s[3] * inv - x[3]}, (f32x4){s[4] * inv - x[4], s[5] * inv - x[5], s[6] * inv - x[6], s[7] * inv - x[7]});
;             } }
.LBB0_2139:
	s_nop 1
	v_add_u32_e32 v98, 0xffff8020, v150
	v_lshrrev_b32_e32 v104, 2, v98
	v_mad_u64_u32 v[98:99], s[74:75], v104, 15, v[128:129]
	v_lshlrev_b64 v[100:101], 12, v[98:99]
	v_lshlrev_b64 v[96:97], 10, v[96:97]
	s_andn2_b64 vcc, exec, s[72:73]
	v_mad_u64_u32 v[98:99], s[72:73], v104, s90, 0
	s_cbranch_vccnz .LBB0_2160
	v_or_b32_e32 v104, s70, v140
	v_ashrrev_i32_e32 v105, 31, v104
	v_lshl_add_u64 v[106:107], v[96:97], 1, s[52:53]
	v_lshl_add_u64 v[110:111], v[104:105], 1, v[106:107]
	v_cvt_pk_bf16_f32 v106, v92, v93
	v_cvt_pk_bf16_f32 v107, v94, v95
	v_cvt_pk_bf16_f32 v108, v88, v89
	v_cvt_pk_bf16_f32 v109, v90, v91
	global_store_dwordx4 v[110:111], v[106:109], off
	s_and_saveexec_b64 s[72:73], s[48:49]
	s_cbranch_execz .LBB0_2158
	v_readlane_b32 s4, v250, 58
	v_readlane_b32 s5, v250, 59
	v_lshlrev_b64 v[114:115], 2, v[104:105]
	s_nop 0
	v_lshl_add_u64 v[106:107], s[4:5], 0, v[100:101]
	v_lshl_add_u64 v[106:107], v[106:107], 0, v[114:115]
	global_store_dwordx4 v[106:107], v[92:95], off
	global_store_dwordx4 v[106:107], v[88:91], off offset:16
	v_mov_b32_dpp v106, v92 quad_perm:[0,0,0,0] row_mask:0xf bank_mask:0xf bound_ctrl:1
	v_add_f32_e32 v106, 0, v106
	v_cndmask_b32_e64 v106, 0, v106, s[40:41]
	v_readlane_b32 s4, v250, 12
	v_readlane_b32 s16, v250, 24
	v_add_f32_dpp v107, v92, v106 quad_perm:[1,1,1,1] row_mask:0xf bank_mask:0xf bound_ctrl:1
	v_cndmask_b32_e64 v106, v106, v107, s[44:45]
	v_readlane_b32 s17, v250, 25
	v_readlane_b32 s5, v250, 13
	v_add_f32_dpp v107, v92, v106 quad_perm:[2,2,2,2] row_mask:0xf bank_mask:0xf bound_ctrl:1
	v_cndmask_b32_e64 v106, v106, v107, s[42:43]
	v_lshl_add_u64 v[114:115], s[16:17], 0, v[114:115]
	v_lshl_add_u64 v[114:115], v[114:115], 0, v[98:99]
	v_add_f32_dpp v107, v92, v106 quad_perm:[3,3,3,3] row_mask:0xf bank_mask:0xf bound_ctrl:1
	v_cndmask_b32_e64 v106, v106, v107, s[0:1]
	v_readlane_b32 s6, v250, 14
	v_mov_b32_dpp v107, v93 quad_perm:[0,0,0,0] row_mask:0xf bank_mask:0xf bound_ctrl:1
	v_add_f32_e32 v107, 0, v107
	v_cndmask_b32_e64 v107, 0, v107, s[40:41]
	v_readlane_b32 s7, v250, 15
	v_readlane_b32 s8, v250, 16
	v_add_f32_dpp v108, v93, v107 quad_perm:[1,1,1,1] row_mask:0xf bank_mask:0xf bound_ctrl:1
	v_cndmask_b32_e64 v107, v107, v108, s[44:45]
	v_readlane_b32 s9, v250, 17
	v_readlane_b32 s10, v250, 18
	v_add_f32_dpp v108, v93, v107 quad_perm:[2,2,2,2] row_mask:0xf bank_mask:0xf bound_ctrl:1
	v_cndmask_b32_e64 v107, v107, v108, s[42:43]
	v_readlane_b32 s11, v250, 19
	v_readlane_b32 s12, v250, 20
	v_add_f32_dpp v108, v93, v107 quad_perm:[3,3,3,3] row_mask:0xf bank_mask:0xf bound_ctrl:1
	v_cndmask_b32_e64 v107, v107, v108, s[0:1]
	v_readlane_b32 s13, v250, 21
	v_mov_b32_dpp v108, v94 quad_perm:[0,0,0,0] row_mask:0xf bank_mask:0xf bound_ctrl:1
	v_add_f32_e32 v108, 0, v108
	v_cndmask_b32_e64 v108, 0, v108, s[40:41]
	v_readlane_b32 s14, v250, 22
	v_readlane_b32 s15, v250, 23
	v_add_f32_dpp v109, v94, v108 quad_perm:[1,1,1,1] row_mask:0xf bank_mask:0xf bound_ctrl:1
	v_cndmask_b32_e64 v108, v108, v109, s[44:45]
	v_readlane_b32 s18, v250, 26
	v_readlane_b32 s19, v250, 27
	v_add_f32_dpp v109, v94, v108 quad_perm:[2,2,2,2] row_mask:0xf bank_mask:0xf bound_ctrl:1
	v_cndmask_b32_e64 v108, v108, v109, s[42:43]
	s_nop 1
	v_add_f32_dpp v109, v94, v108 quad_perm:[3,3,3,3] row_mask:0xf bank_mask:0xf bound_ctrl:1
	v_cndmask_b32_e64 v108, v108, v109, s[0:1]
	s_nop 0
	v_mov_b32_dpp v109, v95 quad_perm:[0,0,0,0] row_mask:0xf bank_mask:0xf bound_ctrl:1
	v_add_f32_e32 v109, 0, v109
	v_cndmask_b32_e64 v109, 0, v109, s[40:41]
	s_nop 1
	v_add_f32_dpp v110, v95, v109 quad_perm:[1,1,1,1] row_mask:0xf bank_mask:0xf bound_ctrl:1
	v_cndmask_b32_e64 v109, v109, v110, s[44:45]
	s_nop 1
	v_add_f32_dpp v110, v95, v109 quad_perm:[2,2,2,2] row_mask:0xf bank_mask:0xf bound_ctrl:1
	v_cndmask_b32_e64 v109, v109, v110, s[42:43]
	s_nop 1
	v_add_f32_dpp v110, v95, v109 quad_perm:[3,3,3,3] row_mask:0xf bank_mask:0xf bound_ctrl:1
	v_cndmask_b32_e64 v109, v109, v110, s[0:1]
	s_nop 0
	v_mov_b32_dpp v110, v88 quad_perm:[0,0,0,0] row_mask:0xf bank_mask:0xf bound_ctrl:1
	v_add_f32_e32 v110, 0, v110
	v_cndmask_b32_e64 v110, 0, v110, s[40:41]
	s_nop 1
	v_add_f32_dpp v111, v88, v110 quad_perm:[1,1,1,1] row_mask:0xf bank_mask:0xf bound_ctrl:1
	v_cndmask_b32_e64 v110, v110, v111, s[44:45]
	s_nop 1
	v_add_f32_dpp v111, v88, v110 quad_perm:[2,2,2,2] row_mask:0xf bank_mask:0xf bound_ctrl:1
	v_cndmask_b32_e64 v110, v110, v111, s[42:43]
	s_nop 1
	v_add_f32_dpp v111, v88, v110 quad_perm:[3,3,3,3] row_mask:0xf bank_mask:0xf bound_ctrl:1
	v_cndmask_b32_e64 v110, v110, v111, s[0:1]
	s_nop 0
	v_mov_b32_dpp v111, v89 quad_perm:[0,0,0,0] row_mask:0xf bank_mask:0xf bound_ctrl:1
	v_add_f32_e32 v111, 0, v111
	v_cndmask_b32_e64 v111, 0, v111, s[40:41]
	s_nop 1
	v_add_f32_dpp v112, v89, v111 quad_perm:[1,1,1,1] row_mask:0xf bank_mask:0xf bound_ctrl:1
	v_cndmask_b32_e64 v111, v111, v112, s[44:45]
	s_nop 1
	v_add_f32_dpp v112, v89, v111 quad_perm:[2,2,2,2] row_mask:0xf bank_mask:0xf bound_ctrl:1
	v_cndmask_b32_e64 v111, v111, v112, s[42:43]
	s_nop 1
	v_add_f32_dpp v112, v89, v111 quad_perm:[3,3,3,3] row_mask:0xf bank_mask:0xf bound_ctrl:1
	v_cndmask_b32_e64 v111, v111, v112, s[0:1]
	s_nop 0
	v_mov_b32_dpp v112, v90 quad_perm:[0,0,0,0] row_mask:0xf bank_mask:0xf bound_ctrl:1
	v_add_f32_e32 v112, 0, v112
	v_cndmask_b32_e64 v112, 0, v112, s[40:41]
	s_nop 1
	v_add_f32_dpp v113, v90, v112 quad_perm:[1,1,1,1] row_mask:0xf bank_mask:0xf bound_ctrl:1
	v_cndmask_b32_e64 v112, v112, v113, s[44:45]
	s_nop 1
	v_add_f32_dpp v113, v90, v112 quad_perm:[2,2,2,2] row_mask:0xf bank_mask:0xf bound_ctrl:1
	v_cndmask_b32_e64 v112, v112, v113, s[42:43]
	s_nop 1
	v_add_f32_dpp v113, v90, v112 quad_perm:[3,3,3,3] row_mask:0xf bank_mask:0xf bound_ctrl:1
	v_cndmask_b32_e64 v112, v112, v113, s[0:1]
	s_nop 0
	v_mov_b32_dpp v113, v91 quad_perm:[0,0,0,0] row_mask:0xf bank_mask:0xf bound_ctrl:1
	v_add_f32_e32 v113, 0, v113
	v_cndmask_b32_e64 v113, 0, v113, s[40:41]
	s_nop 1
	v_add_f32_dpp v116, v91, v113 quad_perm:[1,1,1,1] row_mask:0xf bank_mask:0xf bound_ctrl:1
	v_cndmask_b32_e64 v113, v113, v116, s[44:45]
	s_nop 1
	v_add_f32_dpp v116, v91, v113 quad_perm:[2,2,2,2] row_mask:0xf bank_mask:0xf bound_ctrl:1
	v_cndmask_b32_e64 v113, v113, v116, s[42:43]
	s_nop 1
	v_add_f32_dpp v116, v91, v113 quad_perm:[3,3,3,3] row_mask:0xf bank_mask:0xf bound_ctrl:1
	v_cndmask_b32_e64 v113, v113, v116, s[0:1]
	s_and_saveexec_b64 s[74:75], s[38:39]
	s_cbranch_execz .LBB0_2460
	global_load_dwordx4 v[116:119], v[114:115], off offset:16
	global_load_dwordx4 v[120:123], v[114:115], off
	s_waitcnt vmcnt(0)
	v_pk_add_f32 v[110:111], v[110:111], v[116:117]
	v_pk_add_f32 v[112:113], v[112:113], v[118:119]
	v_pk_add_f32 v[108:109], v[108:109], v[122:123]
	v_pk_add_f32 v[106:107], v[106:107], v[120:121]
	s_or_b64 exec, exec, s[74:75]
	s_and_saveexec_b64 s[74:75], s[36:37]
	s_cbranch_execnz .LBB0_2461

; __device__ __forceinline__ void st16f(float* p, f32x4 v) { st16(p, __builtin_bit_cast(u32x4, v)); }
; __device__ __forceinline__ void st8bf(bf16_t* p, f32x4 a, f32x4 b) { u32x4 w; w.x = pk2(a[0], a[1]); w.y = pk2(a[2], a[3]); w.z = pk2(b[0], b[1]); w.w = pk2(b[2], b[3]); st16(p, w); }
;     __device__ __forceinline__ void st(int pn, int row, int c, f32x4 v0, f32x4 v1) const {
;         const bool smp = row >= MP; const int b = smp ? (row - MP) >> 2 : row >> 13, t = smp ? (row - MP) & 3 : row & (SEQ - 1);
;         if (pn < 4) { const int col = pn * 256 + c; float* o = nullptr;
;             if (smp) o = out + O_POOLS + ((size_t)b * 15 + 11 + t) * 1024 + col;
;             st8bf(V + (size_t)row * 1024 + col, v0, v1); if (o) { st16f(o, v0); st16f(o + 4, v1); }
;             if (smp) {
;                 const int w = 2 << pn;
;                 float x[8] = {v0[0], v0[1], v0[2], v0[3], v1[0], v1[1], v1[2], v1[3]}, s[8];
; #pragma unroll
;                 for (int e = 0; e < 8; ++e) { s[e] = 0.f;
; #pragma unroll
;                     for (int tp = 0; tp < 4; ++tp) { const float xo = quad_bcast(x[e], tp); if (tp <= t && t - tp < w) s[e] += xo; } }
;                 const int e_lo = 15 + t - w + 1;
; #pragma unroll
;                 for (int e2 = 0; e2 < 15; ++e2) if (e2 >= e_lo) { const float* sp = state_pool + ((size_t)b * 15 + e2) * 1024 + col; const f32x4 a = *(const f32x4*)sp, d = *(const f32x4*)(sp + 4);
;                     s[0] += a[0]; s[1] += a[1]; s[2] += a[2]; s[3] += a[3]; s[4] += d[0]; s[5] += d[1]; s[6] += d[2]; s[7] += d[3]; }
;                 const float inv = 1.f / (float)w;
;                 st8bf(DMs + (size_t)row * 1024 + col, (f32x4){s[0] * inv - x[0], s[1] * inv - x[1], s[2] * inv - x[2], s[3] * inv - x[3]}, (f32x4){s[4] * inv - x[4], s[5] * inv - x[5], s[6] * inv - x[6], s[7] * inv - x[7]});
;             } }
.LBB0_2183:
	s_nop 1
	v_add_u32_e32 v82, 0xffff8030, v150
	v_lshrrev_b32_e32 v88, 2, v82
	v_mad_u64_u32 v[82:83], s[74:75], v88, 15, v[128:129]
	v_lshlrev_b64 v[84:85], 12, v[82:83]
	v_lshlrev_b64 v[80:81], 10, v[80:81]
	s_andn2_b64 vcc, exec, s[72:73]
	v_mad_u64_u32 v[82:83], s[72:73], v88, s90, 0
	s_cbranch_vccnz .LBB0_2204
	v_or_b32_e32 v88, s70, v140
	v_ashrrev_i32_e32 v89, 31, v88
	v_lshl_add_u64 v[90:91], v[80:81], 1, s[52:53]
	v_lshl_add_u64 v[94:95], v[88:89], 1, v[90:91]
	v_cvt_pk_bf16_f32 v90, v76, v77
	v_cvt_pk_bf16_f32 v91, v78, v79
	v_cvt_pk_bf16_f32 v92, v72, v73
	v_cvt_pk_bf16_f32 v93, v74, v75
	global_store_dwordx4 v[94:95], v[90:93], off
	s_and_saveexec_b64 s[72:73], s[48:49]
	s_cbranch_execz .LBB0_2202
	v_readlane_b32 s4, v250, 58
	v_readlane_b32 s5, v250, 59
	v_lshlrev_b64 v[98:99], 2, v[88:89]
	s_nop 0
	v_lshl_add_u64 v[90:91], s[4:5], 0, v[84:85]
	v_lshl_add_u64 v[90:91], v[90:91], 0, v[98:99]
	global_store_dwordx4 v[90:91], v[76:79], off
	global_store_dwordx4 v[90:91], v[72:75], off offset:16
	v_mov_b32_dpp v90, v76 quad_perm:[0,0,0,0] row_mask:0xf bank_mask:0xf bound_ctrl:1
	v_add_f32_e32 v90, 0, v90
	v_cndmask_b32_e64 v90, 0, v90, s[40:41]
	v_readlane_b32 s4, v250, 12
	v_readlane_b32 s16, v250, 24
	v_add_f32_dpp v91, v76, v90 quad_perm:[1,1,1,1] row_mask:0xf bank_mask:0xf bound_ctrl:1
	v_cndmask_b32_e64 v90, v90, v91, s[44:45]
	v_readlane_b32 s17, v250, 25
	v_readlane_b32 s5, v250, 13
	v_add_f32_dpp v91, v76, v90 quad_perm:[2,2,2,2] row_mask:0xf bank_mask:0xf bound_ctrl:1
	v_cndmask_b32_e64 v90, v90, v91, s[42:43]
	v_lshl_add_u64 v[98:99], s[16:17], 0, v[98:99]
	v_lshl_add_u64 v[98:99], v[98:99], 0, v[82:83]
	v_add_f32_dpp v91, v76, v90 quad_perm:[3,3,3,3] row_mask:0xf bank_mask:0xf bound_ctrl:1
	v_cndmask_b32_e64 v90, v90, v91, s[0:1]
	v_readlane_b32 s6, v250, 14
	v_mov_b32_dpp v91, v77 quad_perm:[0,0,0,0] row_mask:0xf bank_mask:0xf bound_ctrl:1
	v_add_f32_e32 v91, 0, v91
	v_cndmask_b32_e64 v91, 0, v91, s[40:41]
	v_readlane_b32 s7, v250, 15
	v_readlane_b32 s8, v250, 16
	v_add_f32_dpp v92, v77, v91 quad_perm:[1,1,1,1] row_mask:0xf bank_mask:0xf bound_ctrl:1
	v_cndmask_b32_e64 v91, v91, v92, s[44:45]
	v_readlane_b32 s9, v250, 17
	v_readlane_b32 s10, v250, 18
	v_add_f32_dpp v92, v77, v91 quad_perm:[2,2,2,2] row_mask:0xf bank_mask:0xf bound_ctrl:1
	v_cndmask_b32_e64 v91, v91, v92, s[42:43]
	v_readlane_b32 s11, v250, 19
	v_readlane_b32 s12, v250, 20
	v_add_f32_dpp v92, v77, v91 quad_perm:[3,3,3,3] row_mask:0xf bank_mask:0xf bound_ctrl:1
	v_cndmask_b32_e64 v91, v91, v92, s[0:1]
	v_readlane_b32 s13, v250, 21
	v_mov_b32_dpp v92, v78 quad_perm:[0,0,0,0] row_mask:0xf bank_mask:0xf bound_ctrl:1
	v_add_f32_e32 v92, 0, v92
	v_cndmask_b32_e64 v92, 0, v92, s[40:41]
	v_readlane_b32 s14, v250, 22
	v_readlane_b32 s15, v250, 23
	v_add_f32_dpp v93, v78, v92 quad_perm:[1,1,1,1] row_mask:0xf bank_mask:0xf bound_ctrl:1
	v_cndmask_b32_e64 v92, v92, v93, s[44:45]
	v_readlane_b32 s18, v250, 26
	v_readlane_b32 s19, v250, 27
	v_add_f32_dpp v93, v78, v92 quad_perm:[2,2,2,2] row_mask:0xf bank_mask:0xf bound_ctrl:1
	v_cndmask_b32_e64 v92, v92, v93, s[42:43]
	s_nop 1
	v_add_f32_dpp v93, v78, v92 quad_perm:[3,3,3,3] row_mask:0xf bank_mask:0xf bound_ctrl:1
	v_cndmask_b32_e64 v92, v92, v93, s[0:1]
	s_nop 0
	v_mov_b32_dpp v93, v79 quad_perm:[0,0,0,0] row_mask:0xf bank_mask:0xf bound_ctrl:1
	v_add_f32_e32 v93, 0, v93
	v_cndmask_b32_e64 v93, 0, v93, s[40:41]
	s_nop 1
	v_add_f32_dpp v94, v79, v93 quad_perm:[1,1,1,1] row_mask:0xf bank_mask:0xf bound_ctrl:1
	v_cndmask_b32_e64 v93, v93, v94, s[44:45]
	s_nop 1
	v_add_f32_dpp v94, v79, v93 quad_perm:[2,2,2,2] row_mask:0xf bank_mask:0xf bound_ctrl:1
	v_cndmask_b32_e64 v93, v93, v94, s[42:43]
	s_nop 1
	v_add_f32_dpp v94, v79, v93 quad_perm:[3,3,3,3] row_mask:0xf bank_mask:0xf bound_ctrl:1
	v_cndmask_b32_e64 v93, v93, v94, s[0:1]
	s_nop 0
	v_mov_b32_dpp v94, v72 quad_perm:[0,0,0,0] row_mask:0xf bank_mask:0xf bound_ctrl:1
	v_add_f32_e32 v94, 0, v94
	v_cndmask_b32_e64 v94, 0, v94, s[40:41]
	s_nop 1
	v_add_f32_dpp v95, v72, v94 quad_perm:[1,1,1,1] row_mask:0xf bank_mask:0xf bound_ctrl:1
	v_cndmask_b32_e64 v94, v94, v95, s[44:45]
	s_nop 1
	v_add_f32_dpp v95, v72, v94 quad_perm:[2,2,2,2] row_mask:0xf bank_mask:0xf bound_ctrl:1
	v_cndmask_b32_e64 v94, v94, v95, s[42:43]
	s_nop 1
	v_add_f32_dpp v95, v72, v94 quad_perm:[3,3,3,3] row_mask:0xf bank_mask:0xf bound_ctrl:1
	v_cndmask_b32_e64 v94, v94, v95, s[0:1]
	s_nop 0
	v_mov_b32_dpp v95, v73 quad_perm:[0,0,0,0] row_mask:0xf bank_mask:0xf bound_ctrl:1
	v_add_f32_e32 v95, 0, v95
	v_cndmask_b32_e64 v95, 0, v95, s[40:41]
	s_nop 1
	v_add_f32_dpp v96, v73, v95 quad_perm:[1,1,1,1] row_mask:0xf bank_mask:0xf bound_ctrl:1
	v_cndmask_b32_e64 v95, v95, v96, s[44:45]
	s_nop 1
	v_add_f32_dpp v96, v73, v95 quad_perm:[2,2,2,2] row_mask:0xf bank_mask:0xf bound_ctrl:1
	v_cndmask_b32_e64 v95, v95, v96, s[42:43]
	s_nop 1
	v_add_f32_dpp v96, v73, v95 quad_perm:[3,3,3,3] row_mask:0xf bank_mask:0xf bound_ctrl:1
	v_cndmask_b32_e64 v95, v95, v96, s[0:1]
	s_nop 0
	v_mov_b32_dpp v96, v74 quad_perm:[0,0,0,0] row_mask:0xf bank_mask:0xf bound_ctrl:1
	v_add_f32_e32 v96, 0, v96
	v_cndmask_b32_e64 v96, 0, v96, s[40:41]
	s_nop 1
	v_add_f32_dpp v97, v74, v96 quad_perm:[1,1,1,1] row_mask:0xf bank_mask:0xf bound_ctrl:1
	v_cndmask_b32_e64 v96, v96, v97, s[44:45]
	s_nop 1
	v_add_f32_dpp v97, v74, v96 quad_perm:[2,2,2,2] row_mask:0xf bank_mask:0xf bound_ctrl:1
	v_cndmask_b32_e64 v96, v96, v97, s[42:43]
	s_nop 1
	v_add_f32_dpp v97, v74, v96 quad_perm:[3,3,3,3] row_mask:0xf bank_mask:0xf bound_ctrl:1
	v_cndmask_b32_e64 v96, v96, v97, s[0:1]
	s_nop 0
	v_mov_b32_dpp v97, v75 quad_perm:[0,0,0,0] row_mask:0xf bank_mask:0xf bound_ctrl:1
	v_add_f32_e32 v97, 0, v97
	v_cndmask_b32_e64 v97, 0, v97, s[40:41]
	s_nop 1
	v_add_f32_dpp v100, v75, v97 quad_perm:[1,1,1,1] row_mask:0xf bank_mask:0xf bound_ctrl:1
	v_cndmask_b32_e64 v97, v97, v100, s[44:45]
	s_nop 1
	v_add_f32_dpp v100, v75, v97 quad_perm:[2,2,2,2] row_mask:0xf bank_mask:0xf bound_ctrl:1
	v_cndmask_b32_e64 v97, v97, v100, s[42:43]
	s_nop 1
	v_add_f32_dpp v100, v75, v97 quad_perm:[3,3,3,3] row_mask:0xf bank_mask:0xf bound_ctrl:1
	v_cndmask_b32_e64 v97, v97, v100, s[0:1]
	s_and_saveexec_b64 s[74:75], s[38:39]
	s_cbranch_execz .LBB0_2488
	global_load_dwordx4 v[100:103], v[98:99], off offset:16
	global_load_dwordx4 v[104:107], v[98:99], off
	s_waitcnt vmcnt(0)
	v_pk_add_f32 v[94:95], v[94:95], v[100:101]
	v_pk_add_f32 v[96:97], v[96:97], v[102:103]
	v_pk_add_f32 v[92:93], v[92:93], v[106:107]
	v_pk_add_f32 v[90:91], v[90:91], v[104:105]
	s_or_b64 exec, exec, s[74:75]
	s_and_saveexec_b64 s[74:75], s[36:37]
	s_cbranch_execnz .LBB0_2489

; __device__ __forceinline__ void st16f(float* p, f32x4 v) { st16(p, __builtin_bit_cast(u32x4, v)); }
; __device__ __forceinline__ void st8bf(bf16_t* p, f32x4 a, f32x4 b) { u32x4 w; w.x = pk2(a[0], a[1]); w.y = pk2(a[2], a[3]); w.z = pk2(b[0], b[1]); w.w = pk2(b[2], b[3]); st16(p, w); }
;     __device__ __forceinline__ void st(int pn, int row, int c, f32x4 v0, f32x4 v1) const {
;         const bool smp = row >= MP; const int b = smp ? (row - MP) >> 2 : row >> 13, t = smp ? (row - MP) & 3 : row & (SEQ - 1);
;         if (pn < 4) { const int col = pn * 256 + c; float* o = nullptr;
;             if (smp) o = out + O_POOLS + ((size_t)b * 15 + 11 + t) * 1024 + col;
;             st8bf(V + (size_t)row * 1024 + col, v0, v1); if (o) { st16f(o, v0); st16f(o + 4, v1); }
;             if (smp) {
;                 const int w = 2 << pn;
;                 float x[8] = {v0[0], v0[1], v0[2], v0[3], v1[0], v1[1], v1[2], v1[3]}, s[8];
; #pragma unroll
;                 for (int e = 0; e < 8; ++e) { s[e] = 0.f;
; #pragma unroll
;                     for (int tp = 0; tp < 4; ++tp) { const float xo = quad_bcast(x[e], tp); if (tp <= t && t - tp < w) s[e] += xo; } }
;                 const int e_lo = 15 + t - w + 1;
; #pragma unroll
;                 for (int e2 = 0; e2 < 15; ++e2) if (e2 >= e_lo) { const float* sp = state_pool + ((size_t)b * 15 + e2) * 1024 + col; const f32x4 a = *(const f32x4*)sp, d = *(const f32x4*)(sp + 4);
;                     s[0] += a[0]; s[1] += a[1]; s[2] += a[2]; s[3] += a[3]; s[4] += d[0]; s[5] += d[1]; s[6] += d[2]; s[7] += d[3]; }
;                 const float inv = 1.f / (float)w;
;                 st8bf(DMs + (size_t)row * 1024 + col, (f32x4){s[0] * inv - x[0], s[1] * inv - x[1], s[2] * inv - x[2], s[3] * inv - x[3]}, (f32x4){s[4] * inv - x[4], s[5] * inv - x[5], s[6] * inv - x[6], s[7] * inv - x[7]});
;             } }
.LBB0_2227:
	s_nop 1
	v_add_u32_e32 v66, 0xffff8080, v150
	v_lshrrev_b32_e32 v72, 2, v66
	v_mad_u64_u32 v[66:67], s[74:75], v72, 15, v[128:129]
	v_lshlrev_b64 v[68:69], 12, v[66:67]
	v_lshlrev_b64 v[64:65], 10, v[64:65]
	s_andn2_b64 vcc, exec, s[72:73]
	v_mad_u64_u32 v[66:67], s[72:73], v72, s90, 0
	s_cbranch_vccnz .LBB0_2248
	v_or_b32_e32 v72, s70, v140
	v_ashrrev_i32_e32 v73, 31, v72
	v_lshl_add_u64 v[74:75], v[64:65], 1, s[52:53]
	v_lshl_add_u64 v[78:79], v[72:73], 1, v[74:75]
	v_cvt_pk_bf16_f32 v74, v60, v61
	v_cvt_pk_bf16_f32 v75, v62, v63
	v_cvt_pk_bf16_f32 v76, v56, v57
	v_cvt_pk_bf16_f32 v77, v58, v59
	global_store_dwordx4 v[78:79], v[74:77], off
	s_and_saveexec_b64 s[72:73], s[48:49]
	s_cbranch_execz .LBB0_2246
	v_readlane_b32 s4, v250, 58
	v_readlane_b32 s5, v250, 59
	v_lshlrev_b64 v[82:83], 2, v[72:73]
	s_nop 0
	v_lshl_add_u64 v[74:75], s[4:5], 0, v[68:69]
	v_lshl_add_u64 v[74:75], v[74:75], 0, v[82:83]
	global_store_dwordx4 v[74:75], v[60:63], off
	global_store_dwordx4 v[74:75], v[56:59], off offset:16
	v_mov_b32_dpp v74, v60 quad_perm:[0,0,0,0] row_mask:0xf bank_mask:0xf bound_ctrl:1
	v_add_f32_e32 v74, 0, v74
	v_cndmask_b32_e64 v74, 0, v74, s[40:41]
	v_readlane_b32 s4, v250, 12
	v_readlane_b32 s16, v250, 24
	v_add_f32_dpp v75, v60, v74 quad_perm:[1,1,1,1] row_mask:0xf bank_mask:0xf bound_ctrl:1
	v_cndmask_b32_e64 v74, v74, v75, s[44:45]
	v_readlane_b32 s17, v250, 25
	v_readlane_b32 s5, v250, 13
	v_add_f32_dpp v75, v60, v74 quad_perm:[2,2,2,2] row_mask:0xf bank_mask:0xf bound_ctrl:1
	v_cndmask_b32_e64 v74, v74, v75, s[42:43]
	v_lshl_add_u64 v[82:83], s[16:17], 0, v[82:83]
	v_lshl_add_u64 v[82:83], v[82:83], 0, v[66:67]
	v_add_f32_dpp v75, v60, v74 quad_perm:[3,3,3,3] row_mask:0xf bank_mask:0xf bound_ctrl:1
	v_cndmask_b32_e64 v74, v74, v75, s[0:1]
	v_readlane_b32 s6, v250, 14
	v_mov_b32_dpp v75, v61 quad_perm:[0,0,0,0] row_mask:0xf bank_mask:0xf bound_ctrl:1
	v_add_f32_e32 v75, 0, v75
	v_cndmask_b32_e64 v75, 0, v75, s[40:41]
	v_readlane_b32 s7, v250, 15
	v_readlane_b32 s8, v250, 16
	v_add_f32_dpp v76, v61, v75 quad_perm:[1,1,1,1] row_mask:0xf bank_mask:0xf bound_ctrl:1
	v_cndmask_b32_e64 v75, v75, v76, s[44:45]
	v_readlane_b32 s9, v250, 17
	v_readlane_b32 s10, v250, 18
	v_add_f32_dpp v76, v61, v75 quad_perm:[2,2,2,2] row_mask:0xf bank_mask:0xf bound_ctrl:1
	v_cndmask_b32_e64 v75, v75, v76, s[42:43]
	v_readlane_b32 s11, v250, 19
	v_readlane_b32 s12, v250, 20
	v_add_f32_dpp v76, v61, v75 quad_perm:[3,3,3,3] row_mask:0xf bank_mask:0xf bound_ctrl:1
	v_cndmask_b32_e64 v75, v75, v76, s[0:1]
	v_readlane_b32 s13, v250, 21
	v_mov_b32_dpp v76, v62 quad_perm:[0,0,0,0] row_mask:0xf bank_mask:0xf bound_ctrl:1
	v_add_f32_e32 v76, 0, v76
	v_cndmask_b32_e64 v76, 0, v76, s[40:41]
	v_readlane_b32 s14, v250, 22
	v_readlane_b32 s15, v250, 23
	v_add_f32_dpp v77, v62, v76 quad_perm:[1,1,1,1] row_mask:0xf bank_mask:0xf bound_ctrl:1
	v_cndmask_b32_e64 v76, v76, v77, s[44:45]
	v_readlane_b32 s18, v250, 26
	v_readlane_b32 s19, v250, 27
	v_add_f32_dpp v77, v62, v76 quad_perm:[2,2,2,2] row_mask:0xf bank_mask:0xf bound_ctrl:1
	v_cndmask_b32_e64 v76, v76, v77, s[42:43]
	s_nop 1
	v_add_f32_dpp v77, v62, v76 quad_perm:[3,3,3,3] row_mask:0xf bank_mask:0xf bound_ctrl:1
	v_cndmask_b32_e64 v76, v76, v77, s[0:1]
	s_nop 0
	v_mov_b32_dpp v77, v63 quad_perm:[0,0,0,0] row_mask:0xf bank_mask:0xf bound_ctrl:1
	v_add_f32_e32 v77, 0, v77
	v_cndmask_b32_e64 v77, 0, v77, s[40:41]
	s_nop 1
	v_add_f32_dpp v78, v63, v77 quad_perm:[1,1,1,1] row_mask:0xf bank_mask:0xf bound_ctrl:1
	v_cndmask_b32_e64 v77, v77, v78, s[44:45]
	s_nop 1
	v_add_f32_dpp v78, v63, v77 quad_perm:[2,2,2,2] row_mask:0xf bank_mask:0xf bound_ctrl:1
	v_cndmask_b32_e64 v77, v77, v78, s[42:43]
	s_nop 1
	v_add_f32_dpp v78, v63, v77 quad_perm:[3,3,3,3] row_mask:0xf bank_mask:0xf bound_ctrl:1
	v_cndmask_b32_e64 v77, v77, v78, s[0:1]
	s_nop 0
	v_mov_b32_dpp v78, v56 quad_perm:[0,0,0,0] row_mask:0xf bank_mask:0xf bound_ctrl:1
	v_add_f32_e32 v78, 0, v78
	v_cndmask_b32_e64 v78, 0, v78, s[40:41]
	s_nop 1
	v_add_f32_dpp v79, v56, v78 quad_perm:[1,1,1,1] row_mask:0xf bank_mask:0xf bound_ctrl:1
	v_cndmask_b32_e64 v78, v78, v79, s[44:45]
	s_nop 1
	v_add_f32_dpp v79, v56, v78 quad_perm:[2,2,2,2] row_mask:0xf bank_mask:0xf bound_ctrl:1
	v_cndmask_b32_e64 v78, v78, v79, s[42:43]
	s_nop 1
	v_add_f32_dpp v79, v56, v78 quad_perm:[3,3,3,3] row_mask:0xf bank_mask:0xf bound_ctrl:1
	v_cndmask_b32_e64 v78, v78, v79, s[0:1]
	s_nop 0
	v_mov_b32_dpp v79, v57 quad_perm:[0,0,0,0] row_mask:0xf bank_mask:0xf bound_ctrl:1
	v_add_f32_e32 v79, 0, v79
	v_cndmask_b32_e64 v79, 0, v79, s[40:41]
	s_nop 1
	v_add_f32_dpp v80, v57, v79 quad_perm:[1,1,1,1] row_mask:0xf bank_mask:0xf bound_ctrl:1
	v_cndmask_b32_e64 v79, v79, v80, s[44:45]
	s_nop 1
	v_add_f32_dpp v80, v57, v79 quad_perm:[2,2,2,2] row_mask:0xf bank_mask:0xf bound_ctrl:1
	v_cndmask_b32_e64 v79, v79, v80, s[42:43]
	s_nop 1
	v_add_f32_dpp v80, v57, v79 quad_perm:[3,3,3,3] row_mask:0xf bank_mask:0xf bound_ctrl:1
	v_cndmask_b32_e64 v79, v79, v80, s[0:1]
	s_nop 0
	v_mov_b32_dpp v80, v58 quad_perm:[0,0,0,0] row_mask:0xf bank_mask:0xf bound_ctrl:1
	v_add_f32_e32 v80, 0, v80
	v_cndmask_b32_e64 v80, 0, v80, s[40:41]
	s_nop 1
	v_add_f32_dpp v81, v58, v80 quad_perm:[1,1,1,1] row_mask:0xf bank_mask:0xf bound_ctrl:1
	v_cndmask_b32_e64 v80, v80, v81, s[44:45]
	s_nop 1
	v_add_f32_dpp v81, v58, v80 quad_perm:[2,2,2,2] row_mask:0xf bank_mask:0xf bound_ctrl:1
	v_cndmask_b32_e64 v80, v80, v81, s[42:43]
	s_nop 1
	v_add_f32_dpp v81, v58, v80 quad_perm:[3,3,3,3] row_mask:0xf bank_mask:0xf bound_ctrl:1
	v_cndmask_b32_e64 v80, v80, v81, s[0:1]
	s_nop 0
	v_mov_b32_dpp v81, v59 quad_perm:[0,0,0,0] row_mask:0xf bank_mask:0xf bound_ctrl:1
	v_add_f32_e32 v81, 0, v81
	v_cndmask_b32_e64 v81, 0, v81, s[40:41]
	s_nop 1
	v_add_f32_dpp v84, v59, v81 quad_perm:[1,1,1,1] row_mask:0xf bank_mask:0xf bound_ctrl:1
	v_cndmask_b32_e64 v81, v81, v84, s[44:45]
	s_nop 1
	v_add_f32_dpp v84, v59, v81 quad_perm:[2,2,2,2] row_mask:0xf bank_mask:0xf bound_ctrl:1
	v_cndmask_b32_e64 v81, v81, v84, s[42:43]
	s_nop 1
	v_add_f32_dpp v84, v59, v81 quad_perm:[3,3,3,3] row_mask:0xf bank_mask:0xf bound_ctrl:1
	v_cndmask_b32_e64 v81, v81, v84, s[0:1]
	s_and_saveexec_b64 s[74:75], s[38:39]
	s_cbranch_execz .LBB0_2516
	global_load_dwordx4 v[84:87], v[82:83], off offset:16
	global_load_dwordx4 v[88:91], v[82:83], off
	s_waitcnt vmcnt(0)
	v_pk_add_f32 v[78:79], v[78:79], v[84:85]
	v_pk_add_f32 v[80:81], v[80:81], v[86:87]
	v_pk_add_f32 v[76:77], v[76:77], v[90:91]
	v_pk_add_f32 v[74:75], v[74:75], v[88:89]
	s_or_b64 exec, exec, s[74:75]
	s_and_saveexec_b64 s[74:75], s[36:37]
	s_cbranch_execnz .LBB0_2517

; __device__ __forceinline__ void st16f(float* p, f32x4 v) { st16(p, __builtin_bit_cast(u32x4, v)); }
; __device__ __forceinline__ void st8bf(bf16_t* p, f32x4 a, f32x4 b) { u32x4 w; w.x = pk2(a[0], a[1]); w.y = pk2(a[2], a[3]); w.z = pk2(b[0], b[1]); w.w = pk2(b[2], b[3]); st16(p, w); }
;     __device__ __forceinline__ void st(int pn, int row, int c, f32x4 v0, f32x4 v1) const {
;         const bool smp = row >= MP; const int b = smp ? (row - MP) >> 2 : row >> 13, t = smp ? (row - MP) & 3 : row & (SEQ - 1);
;         if (pn < 4) { const int col = pn * 256 + c; float* o = nullptr;
;             if (smp) o = out + O_POOLS + ((size_t)b * 15 + 11 + t) * 1024 + col;
;             st8bf(V + (size_t)row * 1024 + col, v0, v1); if (o) { st16f(o, v0); st16f(o + 4, v1); }
;             if (smp) {
;                 const int w = 2 << pn;
;                 float x[8] = {v0[0], v0[1], v0[2], v0[3], v1[0], v1[1], v1[2], v1[3]}, s[8];
; #pragma unroll
;                 for (int e = 0; e < 8; ++e) { s[e] = 0.f;
; #pragma unroll
;                     for (int tp = 0; tp < 4; ++tp) { const float xo = quad_bcast(x[e], tp); if (tp <= t && t - tp < w) s[e] += xo; } }
;                 const int e_lo = 15 + t - w + 1;
; #pragma unroll
;                 for (int e2 = 0; e2 < 15; ++e2) if (e2 >= e_lo) { const float* sp = state_pool + ((size_t)b * 15 + e2) * 1024 + col; const f32x4 a = *(const f32x4*)sp, d = *(const f32x4*)(sp + 4);
;                     s[0] += a[0]; s[1] += a[1]; s[2] += a[2]; s[3] += a[3]; s[4] += d[0]; s[5] += d[1]; s[6] += d[2]; s[7] += d[3]; }
;                 const float inv = 1.f / (float)w;
;                 st8bf(DMs + (size_t)row * 1024 + col, (f32x4){s[0] * inv - x[0], s[1] * inv - x[1], s[2] * inv - x[2], s[3] * inv - x[3]}, (f32x4){s[4] * inv - x[4], s[5] * inv - x[5], s[6] * inv - x[6], s[7] * inv - x[7]});
;             } }
.LBB0_2271:
	s_nop 1
	v_add_u32_e32 v50, 0xffff8090, v150
	v_lshrrev_b32_e32 v56, 2, v50
	v_mad_u64_u32 v[50:51], s[74:75], v56, 15, v[128:129]
	v_lshlrev_b64 v[52:53], 12, v[50:51]
	v_lshlrev_b64 v[48:49], 10, v[48:49]
	s_andn2_b64 vcc, exec, s[72:73]
	v_mad_u64_u32 v[50:51], s[72:73], v56, s90, 0
	s_cbranch_vccnz .LBB0_2292
	v_or_b32_e32 v56, s70, v140
	v_ashrrev_i32_e32 v57, 31, v56
	v_lshl_add_u64 v[58:59], v[48:49], 1, s[52:53]
	v_lshl_add_u64 v[62:63], v[56:57], 1, v[58:59]
	v_cvt_pk_bf16_f32 v58, v44, v45
	v_cvt_pk_bf16_f32 v59, v46, v47
	v_cvt_pk_bf16_f32 v60, v40, v41
	v_cvt_pk_bf16_f32 v61, v42, v43
	global_store_dwordx4 v[62:63], v[58:61], off
	s_and_saveexec_b64 s[72:73], s[48:49]
	s_cbranch_execz .LBB0_2290
	v_readlane_b32 s4, v250, 58
	v_readlane_b32 s5, v250, 59
	v_lshlrev_b64 v[66:67], 2, v[56:57]
	s_nop 0
	v_lshl_add_u64 v[58:59], s[4:5], 0, v[52:53]
	v_lshl_add_u64 v[58:59], v[58:59], 0, v[66:67]
	global_store_dwordx4 v[58:59], v[44:47], off
	global_store_dwordx4 v[58:59], v[40:43], off offset:16
	v_mov_b32_dpp v58, v44 quad_perm:[0,0,0,0] row_mask:0xf bank_mask:0xf bound_ctrl:1
	v_add_f32_e32 v58, 0, v58
	v_cndmask_b32_e64 v58, 0, v58, s[40:41]
	v_readlane_b32 s4, v250, 12
	v_readlane_b32 s16, v250, 24
	v_add_f32_dpp v59, v44, v58 quad_perm:[1,1,1,1] row_mask:0xf bank_mask:0xf bound_ctrl:1
	v_cndmask_b32_e64 v58, v58, v59, s[44:45]
	v_readlane_b32 s17, v250, 25
	v_readlane_b32 s5, v250, 13
	v_add_f32_dpp v59, v44, v58 quad_perm:[2,2,2,2] row_mask:0xf bank_mask:0xf bound_ctrl:1
	v_cndmask_b32_e64 v58, v58, v59, s[42:43]
	v_lshl_add_u64 v[66:67], s[16:17], 0, v[66:67]
	v_lshl_add_u64 v[66:67], v[66:67], 0, v[50:51]
	v_add_f32_dpp v59, v44, v58 quad_perm:[3,3,3,3] row_mask:0xf bank_mask:0xf bound_ctrl:1
	v_cndmask_b32_e64 v58, v58, v59, s[0:1]
	v_readlane_b32 s6, v250, 14
	v_mov_b32_dpp v59, v45 quad_perm:[0,0,0,0] row_mask:0xf bank_mask:0xf bound_ctrl:1
	v_add_f32_e32 v59, 0, v59
	v_cndmask_b32_e64 v59, 0, v59, s[40:41]
	v_readlane_b32 s7, v250, 15
	v_readlane_b32 s8, v250, 16
	v_add_f32_dpp v60, v45, v59 quad_perm:[1,1,1,1] row_mask:0xf bank_mask:0xf bound_ctrl:1
	v_cndmask_b32_e64 v59, v59, v60, s[44:45]
	v_readlane_b32 s9, v250, 17
	v_readlane_b32 s10, v250, 18
	v_add_f32_dpp v60, v45, v59 quad_perm:[2,2,2,2] row_mask:0xf bank_mask:0xf bound_ctrl:1
	v_cndmask_b32_e64 v59, v59, v60, s[42:43]
	v_readlane_b32 s11, v250, 19
	v_readlane_b32 s12, v250, 20
	v_add_f32_dpp v60, v45, v59 quad_perm:[3,3,3,3] row_mask:0xf bank_mask:0xf bound_ctrl:1
	v_cndmask_b32_e64 v59, v59, v60, s[0:1]
	v_readlane_b32 s13, v250, 21
	v_mov_b32_dpp v60, v46 quad_perm:[0,0,0,0] row_mask:0xf bank_mask:0xf bound_ctrl:1
	v_add_f32_e32 v60, 0, v60
	v_cndmask_b32_e64 v60, 0, v60, s[40:41]
	v_readlane_b32 s14, v250, 22
	v_readlane_b32 s15, v250, 23
	v_add_f32_dpp v61, v46, v60 quad_perm:[1,1,1,1] row_mask:0xf bank_mask:0xf bound_ctrl:1
	v_cndmask_b32_e64 v60, v60, v61, s[44:45]
	v_readlane_b32 s18, v250, 26
	v_readlane_b32 s19, v250, 27
	v_add_f32_dpp v61, v46, v60 quad_perm:[2,2,2,2] row_mask:0xf bank_mask:0xf bound_ctrl:1
	v_cndmask_b32_e64 v60, v60, v61, s[42:43]
	s_nop 1
	v_add_f32_dpp v61, v46, v60 quad_perm:[3,3,3,3] row_mask:0xf bank_mask:0xf bound_ctrl:1
	v_cndmask_b32_e64 v60, v60, v61, s[0:1]
	s_nop 0
	v_mov_b32_dpp v61, v47 quad_perm:[0,0,0,0] row_mask:0xf bank_mask:0xf bound_ctrl:1
	v_add_f32_e32 v61, 0, v61
	v_cndmask_b32_e64 v61, 0, v61, s[40:41]
	s_nop 1
	v_add_f32_dpp v62, v47, v61 quad_perm:[1,1,1,1] row_mask:0xf bank_mask:0xf bound_ctrl:1
	v_cndmask_b32_e64 v61, v61, v62, s[44:45]
	s_nop 1
	v_add_f32_dpp v62, v47, v61 quad_perm:[2,2,2,2] row_mask:0xf bank_mask:0xf bound_ctrl:1
	v_cndmask_b32_e64 v61, v61, v62, s[42:43]
	s_nop 1
	v_add_f32_dpp v62, v47, v61 quad_perm:[3,3,3,3] row_mask:0xf bank_mask:0xf bound_ctrl:1
	v_cndmask_b32_e64 v61, v61, v62, s[0:1]
	s_nop 0
	v_mov_b32_dpp v62, v40 quad_perm:[0,0,0,0] row_mask:0xf bank_mask:0xf bound_ctrl:1
	v_add_f32_e32 v62, 0, v62
	v_cndmask_b32_e64 v62, 0, v62, s[40:41]
	s_nop 1
	v_add_f32_dpp v63, v40, v62 quad_perm:[1,1,1,1] row_mask:0xf bank_mask:0xf bound_ctrl:1
	v_cndmask_b32_e64 v62, v62, v63, s[44:45]
	s_nop 1
	v_add_f32_dpp v63, v40, v62 quad_perm:[2,2,2,2] row_mask:0xf bank_mask:0xf bound_ctrl:1
	v_cndmask_b32_e64 v62, v62, v63, s[42:43]
	s_nop 1
	v_add_f32_dpp v63, v40, v62 quad_perm:[3,3,3,3] row_mask:0xf bank_mask:0xf bound_ctrl:1
	v_cndmask_b32_e64 v62, v62, v63, s[0:1]
	s_nop 0
	v_mov_b32_dpp v63, v41 quad_perm:[0,0,0,0] row_mask:0xf bank_mask:0xf bound_ctrl:1
	v_add_f32_e32 v63, 0, v63
	v_cndmask_b32_e64 v63, 0, v63, s[40:41]
	s_nop 1
	v_add_f32_dpp v64, v41, v63 quad_perm:[1,1,1,1] row_mask:0xf bank_mask:0xf bound_ctrl:1
	v_cndmask_b32_e64 v63, v63, v64, s[44:45]
	s_nop 1
	v_add_f32_dpp v64, v41, v63 quad_perm:[2,2,2,2] row_mask:0xf bank_mask:0xf bound_ctrl:1
	v_cndmask_b32_e64 v63, v63, v64, s[42:43]
	s_nop 1
	v_add_f32_dpp v64, v41, v63 quad_perm:[3,3,3,3] row_mask:0xf bank_mask:0xf bound_ctrl:1
	v_cndmask_b32_e64 v63, v63, v64, s[0:1]
	s_nop 0
	v_mov_b32_dpp v64, v42 quad_perm:[0,0,0,0] row_mask:0xf bank_mask:0xf bound_ctrl:1
	v_add_f32_e32 v64, 0, v64
	v_cndmask_b32_e64 v64, 0, v64, s[40:41]
	s_nop 1
	v_add_f32_dpp v65, v42, v64 quad_perm:[1,1,1,1] row_mask:0xf bank_mask:0xf bound_ctrl:1
	v_cndmask_b32_e64 v64, v64, v65, s[44:45]
	s_nop 1
	v_add_f32_dpp v65, v42, v64 quad_perm:[2,2,2,2] row_mask:0xf bank_mask:0xf bound_ctrl:1
	v_cndmask_b32_e64 v64, v64, v65, s[42:43]
	s_nop 1
	v_add_f32_dpp v65, v42, v64 quad_perm:[3,3,3,3] row_mask:0xf bank_mask:0xf bound_ctrl:1
	v_cndmask_b32_e64 v64, v64, v65, s[0:1]
	s_nop 0
	v_mov_b32_dpp v65, v43 quad_perm:[0,0,0,0] row_mask:0xf bank_mask:0xf bound_ctrl:1
	v_add_f32_e32 v65, 0, v65
	v_cndmask_b32_e64 v65, 0, v65, s[40:41]
	s_nop 1
	v_add_f32_dpp v68, v43, v65 quad_perm:[1,1,1,1] row_mask:0xf bank_mask:0xf bound_ctrl:1
	v_cndmask_b32_e64 v65, v65, v68, s[44:45]
	s_nop 1
	v_add_f32_dpp v68, v43, v65 quad_perm:[2,2,2,2] row_mask:0xf bank_mask:0xf bound_ctrl:1
	v_cndmask_b32_e64 v65, v65, v68, s[42:43]
	s_nop 1
	v_add_f32_dpp v68, v43, v65 quad_perm:[3,3,3,3] row_mask:0xf bank_mask:0xf bound_ctrl:1
	v_cndmask_b32_e64 v65, v65, v68, s[0:1]
	s_and_saveexec_b64 s[74:75], s[38:39]
	s_cbranch_execz .LBB0_2544
	global_load_dwordx4 v[68:71], v[66:67], off offset:16
	global_load_dwordx4 v[72:75], v[66:67], off
	s_waitcnt vmcnt(0)
	v_pk_add_f32 v[62:63], v[62:63], v[68:69]
	v_pk_add_f32 v[64:65], v[64:65], v[70:71]
	v_pk_add_f32 v[60:61], v[60:61], v[74:75]
	v_pk_add_f32 v[58:59], v[58:59], v[72:73]
	s_or_b64 exec, exec, s[74:75]
	s_and_saveexec_b64 s[74:75], s[36:37]
	s_cbranch_execnz .LBB0_2545

; __device__ __forceinline__ void st16f(float* p, f32x4 v) { st16(p, __builtin_bit_cast(u32x4, v)); }
; __device__ __forceinline__ void st8bf(bf16_t* p, f32x4 a, f32x4 b) { u32x4 w; w.x = pk2(a[0], a[1]); w.y = pk2(a[2], a[3]); w.z = pk2(b[0], b[1]); w.w = pk2(b[2], b[3]); st16(p, w); }
;     __device__ __forceinline__ void st(int pn, int row, int c, f32x4 v0, f32x4 v1) const {
;         const bool smp = row >= MP; const int b = smp ? (row - MP) >> 2 : row >> 13, t = smp ? (row - MP) & 3 : row & (SEQ - 1);
;         if (pn < 4) { const int col = pn * 256 + c; float* o = nullptr;
;             if (smp) o = out + O_POOLS + ((size_t)b * 15 + 11 + t) * 1024 + col;
;             st8bf(V + (size_t)row * 1024 + col, v0, v1); if (o) { st16f(o, v0); st16f(o + 4, v1); }
;             if (smp) {
;                 const int w = 2 << pn;
;                 float x[8] = {v0[0], v0[1], v0[2], v0[3], v1[0], v1[1], v1[2], v1[3]}, s[8];
; #pragma unroll
;                 for (int e = 0; e < 8; ++e) { s[e] = 0.f;
; #pragma unroll
;                     for (int tp = 0; tp < 4; ++tp) { const float xo = quad_bcast(x[e], tp); if (tp <= t && t - tp < w) s[e] += xo; } }
;                 const int e_lo = 15 + t - w + 1;
; #pragma unroll
;                 for (int e2 = 0; e2 < 15; ++e2) if (e2 >= e_lo) { const float* sp = state_pool + ((size_t)b * 15 + e2) * 1024 + col; const f32x4 a = *(const f32x4*)sp, d = *(const f32x4*)(sp + 4);
;                     s[0] += a[0]; s[1] += a[1]; s[2] += a[2]; s[3] += a[3]; s[4] += d[0]; s[5] += d[1]; s[6] += d[2]; s[7] += d[3]; }
;                 const float inv = 1.f / (float)w;
;                 st8bf(DMs + (size_t)row * 1024 + col, (f32x4){s[0] * inv - x[0], s[1] * inv - x[1], s[2] * inv - x[2], s[3] * inv - x[3]}, (f32x4){s[4] * inv - x[4], s[5] * inv - x[5], s[6] * inv - x[6], s[7] * inv - x[7]});
;             } }
.LBB0_2315:
	s_nop 1
	v_add_u32_e32 v34, 0xffff80a0, v150
	v_lshrrev_b32_e32 v40, 2, v34
	v_mad_u64_u32 v[34:35], s[74:75], v40, 15, v[128:129]
	v_lshlrev_b64 v[36:37], 12, v[34:35]
	v_lshlrev_b64 v[32:33], 10, v[32:33]
	s_andn2_b64 vcc, exec, s[72:73]
	v_mad_u64_u32 v[34:35], s[72:73], v40, s90, 0
	s_cbranch_vccnz .LBB0_2336
	v_or_b32_e32 v40, s70, v140
	v_ashrrev_i32_e32 v41, 31, v40
	v_lshl_add_u64 v[42:43], v[32:33], 1, s[52:53]
	v_lshl_add_u64 v[46:47], v[40:41], 1, v[42:43]
	v_cvt_pk_bf16_f32 v42, v28, v29
	v_cvt_pk_bf16_f32 v43, v30, v31
	v_cvt_pk_bf16_f32 v44, v24, v25
	v_cvt_pk_bf16_f32 v45, v26, v27
	global_store_dwordx4 v[46:47], v[42:45], off
	s_and_saveexec_b64 s[72:73], s[48:49]
	s_cbranch_execz .LBB0_2334
	v_readlane_b32 s4, v250, 58
	v_readlane_b32 s5, v250, 59
	v_lshlrev_b64 v[50:51], 2, v[40:41]
	s_nop 0
	v_lshl_add_u64 v[42:43], s[4:5], 0, v[36:37]
	v_lshl_add_u64 v[42:43], v[42:43], 0, v[50:51]
	global_store_dwordx4 v[42:43], v[28:31], off
	global_store_dwordx4 v[42:43], v[24:27], off offset:16
	v_mov_b32_dpp v42, v28 quad_perm:[0,0,0,0] row_mask:0xf bank_mask:0xf bound_ctrl:1
	v_add_f32_e32 v42, 0, v42
	v_cndmask_b32_e64 v42, 0, v42, s[40:41]
	v_readlane_b32 s4, v250, 12
	v_readlane_b32 s16, v250, 24
	v_add_f32_dpp v43, v28, v42 quad_perm:[1,1,1,1] row_mask:0xf bank_mask:0xf bound_ctrl:1
	v_cndmask_b32_e64 v42, v42, v43, s[44:45]
	v_readlane_b32 s17, v250, 25
	v_readlane_b32 s5, v250, 13
	v_add_f32_dpp v43, v28, v42 quad_perm:[2,2,2,2] row_mask:0xf bank_mask:0xf bound_ctrl:1
	v_cndmask_b32_e64 v42, v42, v43, s[42:43]
	v_lshl_add_u64 v[50:51], s[16:17], 0, v[50:51]
	v_lshl_add_u64 v[50:51], v[50:51], 0, v[34:35]
	v_add_f32_dpp v43, v28, v42 quad_perm:[3,3,3,3] row_mask:0xf bank_mask:0xf bound_ctrl:1
	v_cndmask_b32_e64 v42, v42, v43, s[0:1]
	v_readlane_b32 s6, v250, 14
	v_mov_b32_dpp v43, v29 quad_perm:[0,0,0,0] row_mask:0xf bank_mask:0xf bound_ctrl:1
	v_add_f32_e32 v43, 0, v43
	v_cndmask_b32_e64 v43, 0, v43, s[40:41]
	v_readlane_b32 s7, v250, 15
	v_readlane_b32 s8, v250, 16
	v_add_f32_dpp v44, v29, v43 quad_perm:[1,1,1,1] row_mask:0xf bank_mask:0xf bound_ctrl:1
	v_cndmask_b32_e64 v43, v43, v44, s[44:45]
	v_readlane_b32 s9, v250, 17
	v_readlane_b32 s10, v250, 18
	v_add_f32_dpp v44, v29, v43 quad_perm:[2,2,2,2] row_mask:0xf bank_mask:0xf bound_ctrl:1
	v_cndmask_b32_e64 v43, v43, v44, s[42:43]
	v_readlane_b32 s11, v250, 19
	v_readlane_b32 s12, v250, 20
	v_add_f32_dpp v44, v29, v43 quad_perm:[3,3,3,3] row_mask:0xf bank_mask:0xf bound_ctrl:1
	v_cndmask_b32_e64 v43, v43, v44, s[0:1]
	v_readlane_b32 s13, v250, 21
	v_mov_b32_dpp v44, v30 quad_perm:[0,0,0,0] row_mask:0xf bank_mask:0xf bound_ctrl:1
	v_add_f32_e32 v44, 0, v44
	v_cndmask_b32_e64 v44, 0, v44, s[40:41]
	v_readlane_b32 s14, v250, 22
	v_readlane_b32 s15, v250, 23
	v_add_f32_dpp v45, v30, v44 quad_perm:[1,1,1,1] row_mask:0xf bank_mask:0xf bound_ctrl:1
	v_cndmask_b32_e64 v44, v44, v45, s[44:45]
	v_readlane_b32 s18, v250, 26
	v_readlane_b32 s19, v250, 27
	v_add_f32_dpp v45, v30, v44 quad_perm:[2,2,2,2] row_mask:0xf bank_mask:0xf bound_ctrl:1
	v_cndmask_b32_e64 v44, v44, v45, s[42:43]
	s_nop 1
	v_add_f32_dpp v45, v30, v44 quad_perm:[3,3,3,3] row_mask:0xf bank_mask:0xf bound_ctrl:1
	v_cndmask_b32_e64 v44, v44, v45, s[0:1]
	s_nop 0
	v_mov_b32_dpp v45, v31 quad_perm:[0,0,0,0] row_mask:0xf bank_mask:0xf bound_ctrl:1
	v_add_f32_e32 v45, 0, v45
	v_cndmask_b32_e64 v45, 0, v45, s[40:41]
	s_nop 1
	v_add_f32_dpp v46, v31, v45 quad_perm:[1,1,1,1] row_mask:0xf bank_mask:0xf bound_ctrl:1
	v_cndmask_b32_e64 v45, v45, v46, s[44:45]
	s_nop 1
	v_add_f32_dpp v46, v31, v45 quad_perm:[2,2,2,2] row_mask:0xf bank_mask:0xf bound_ctrl:1
	v_cndmask_b32_e64 v45, v45, v46, s[42:43]
	s_nop 1
	v_add_f32_dpp v46, v31, v45 quad_perm:[3,3,3,3] row_mask:0xf bank_mask:0xf bound_ctrl:1
	v_cndmask_b32_e64 v45, v45, v46, s[0:1]
	s_nop 0
	v_mov_b32_dpp v46, v24 quad_perm:[0,0,0,0] row_mask:0xf bank_mask:0xf bound_ctrl:1
	v_add_f32_e32 v46, 0, v46
	v_cndmask_b32_e64 v46, 0, v46, s[40:41]
	s_nop 1
	v_add_f32_dpp v47, v24, v46 quad_perm:[1,1,1,1] row_mask:0xf bank_mask:0xf bound_ctrl:1
	v_cndmask_b32_e64 v46, v46, v47, s[44:45]
	s_nop 1
	v_add_f32_dpp v47, v24, v46 quad_perm:[2,2,2,2] row_mask:0xf bank_mask:0xf bound_ctrl:1
	v_cndmask_b32_e64 v46, v46, v47, s[42:43]
	s_nop 1
	v_add_f32_dpp v47, v24, v46 quad_perm:[3,3,3,3] row_mask:0xf bank_mask:0xf bound_ctrl:1
	v_cndmask_b32_e64 v46, v46, v47, s[0:1]
	s_nop 0
	v_mov_b32_dpp v47, v25 quad_perm:[0,0,0,0] row_mask:0xf bank_mask:0xf bound_ctrl:1
	v_add_f32_e32 v47, 0, v47
	v_cndmask_b32_e64 v47, 0, v47, s[40:41]
	s_nop 1
	v_add_f32_dpp v48, v25, v47 quad_perm:[1,1,1,1] row_mask:0xf bank_mask:0xf bound_ctrl:1
	v_cndmask_b32_e64 v47, v47, v48, s[44:45]
	s_nop 1
	v_add_f32_dpp v48, v25, v47 quad_perm:[2,2,2,2] row_mask:0xf bank_mask:0xf bound_ctrl:1
	v_cndmask_b32_e64 v47, v47, v48, s[42:43]
	s_nop 1
	v_add_f32_dpp v48, v25, v47 quad_perm:[3,3,3,3] row_mask:0xf bank_mask:0xf bound_ctrl:1
	v_cndmask_b32_e64 v47, v47, v48, s[0:1]
	s_nop 0
	v_mov_b32_dpp v48, v26 quad_perm:[0,0,0,0] row_mask:0xf bank_mask:0xf bound_ctrl:1
	v_add_f32_e32 v48, 0, v48
	v_cndmask_b32_e64 v48, 0, v48, s[40:41]
	s_nop 1
	v_add_f32_dpp v49, v26, v48 quad_perm:[1,1,1,1] row_mask:0xf bank_mask:0xf bound_ctrl:1
	v_cndmask_b32_e64 v48, v48, v49, s[44:45]
	s_nop 1
	v_add_f32_dpp v49, v26, v48 quad_perm:[2,2,2,2] row_mask:0xf bank_mask:0xf bound_ctrl:1
	v_cndmask_b32_e64 v48, v48, v49, s[42:43]
	s_nop 1
	v_add_f32_dpp v49, v26, v48 quad_perm:[3,3,3,3] row_mask:0xf bank_mask:0xf bound_ctrl:1
	v_cndmask_b32_e64 v48, v48, v49, s[0:1]
	s_nop 0
	v_mov_b32_dpp v49, v27 quad_perm:[0,0,0,0] row_mask:0xf bank_mask:0xf bound_ctrl:1
	v_add_f32_e32 v49, 0, v49
	v_cndmask_b32_e64 v49, 0, v49, s[40:41]
	s_nop 1
	v_add_f32_dpp v52, v27, v49 quad_perm:[1,1,1,1] row_mask:0xf bank_mask:0xf bound_ctrl:1
	v_cndmask_b32_e64 v49, v49, v52, s[44:45]
	s_nop 1
	v_add_f32_dpp v52, v27, v49 quad_perm:[2,2,2,2] row_mask:0xf bank_mask:0xf bound_ctrl:1
	v_cndmask_b32_e64 v49, v49, v52, s[42:43]
	s_nop 1
	v_add_f32_dpp v52, v27, v49 quad_perm:[3,3,3,3] row_mask:0xf bank_mask:0xf bound_ctrl:1
	v_cndmask_b32_e64 v49, v49, v52, s[0:1]
	s_and_saveexec_b64 s[74:75], s[38:39]
	s_cbranch_execz .LBB0_2572
	global_load_dwordx4 v[52:55], v[50:51], off offset:16
	global_load_dwordx4 v[56:59], v[50:51], off
	s_waitcnt vmcnt(0)
	v_pk_add_f32 v[46:47], v[46:47], v[52:53]
	v_pk_add_f32 v[48:49], v[48:49], v[54:55]
	v_pk_add_f32 v[44:45], v[44:45], v[58:59]
	v_pk_add_f32 v[42:43], v[42:43], v[56:57]
	s_or_b64 exec, exec, s[74:75]
	s_and_saveexec_b64 s[74:75], s[36:37]
	s_cbranch_execnz .LBB0_2573

; __device__ __forceinline__ unsigned pk2(float lo, float hi) { return f2bf(lo) | (f2bf(hi) << 16); }
; __device__ __forceinline__ float sigmoidf_(float x) { return __builtin_amdgcn_rcpf(1.0f + __expf(-x)); }
; __device__ __forceinline__ void st8bf(bf16_t* p, f32x4 a, f32x4 b) { u32x4 w; w.x = pk2(a[0], a[1]); w.y = pk2(a[2], a[3]); w.z = pk2(b[0], b[1]); w.w = pk2(b[2], b[3]); st16(p, w); }
; __device__ __forceinline__ void stnt8(float* o, f32x4 a, f32x4 b) { __builtin_nontemporal_store(a, (f32x4*)o); __builtin_nontemporal_store(b, (f32x4*)(o + 4)); }
; __device__ __forceinline__ f32x4 sig4(f32x4 v) { f32x4 r; r[0] = sigmoidf_(v[0]); r[1] = sigmoidf_(v[1]); r[2] = sigmoidf_(v[2]); r[3] = sigmoidf_(v[3]); return r; }
;     __device__ __forceinline__ void st(int pn, int row, int c, f32x4 v0, f32x4 v1) const {
;     ...
;         else st8bf(GT + (size_t)row * 1024 + (pn - 4) * 256 + c, v0 * sig4(v0), v1 * sig4(v1));
.LBB0_2357:
	s_nop 0
	v_add_u32_e32 v16, 0xb0, v150
	v_ashrrev_i32_e32 v17, 31, v16
	v_cmp_lt_i32_e64 s[48:49], s89, v16
	v_lshlrev_b64 v[22:23], 11, v[16:17]
	s_and_b64 vcc, exec, s[46:47]
	s_mov_b64 s[72:73], -1
	s_cbranch_vccnz .LBB0_2359
	v_lshl_add_u64 v[18:19], s[54:55], 0, v[22:23]
	v_mul_f32_e32 v20, 0xbfb8aa3b, v12
	v_exp_f32_e32 v20, v20
	v_lshl_add_u64 v[18:19], s[60:61], 1, v[18:19]
	v_lshlrev_b32_e32 v138, 1, v140
	v_lshl_add_u64 v[24:25], v[18:19], 0, v[138:139]
	v_mul_f32_e32 v19, 0xbfb8aa3b, v13
	v_exp_f32_e32 v19, v19
	v_add_f32_e32 v18, 1.0, v20
	v_mul_f32_e32 v20, 0xbfb8aa3b, v14
	v_mul_f32_e32 v21, 0xbfb8aa3b, v15
	v_exp_f32_e32 v20, v20
	v_exp_f32_e32 v21, v21
	v_add_f32_e32 v19, 1.0, v19
	v_rcp_f32_e32 v18, v18
	v_rcp_f32_e32 v19, v19
	v_mul_f32_e32 v26, 0xbfb8aa3b, v8
	v_mul_f32_e32 v27, 0xbfb8aa3b, v9
	v_exp_f32_e32 v26, v26
	v_exp_f32_e32 v27, v27
	v_add_f32_e32 v20, 1.0, v20
	v_add_f32_e32 v21, 1.0, v21
	v_rcp_f32_e32 v20, v20
	v_rcp_f32_e32 v21, v21
	v_mul_f32_e32 v28, 0xbfb8aa3b, v10
	v_mul_f32_e32 v29, 0xbfb8aa3b, v11
	v_exp_f32_e32 v28, v28
	v_exp_f32_e32 v29, v29
	v_pk_mul_f32 v[18:19], v[12:13], v[18:19]
	v_add_f32_e32 v26, 1.0, v26
	v_add_f32_e32 v27, 1.0, v27
	v_rcp_f32_e32 v26, v26
	v_rcp_f32_e32 v27, v27
	v_pk_mul_f32 v[20:21], v[14:15], v[20:21]
	v_add_f32_e32 v28, 1.0, v28
	v_add_f32_e32 v29, 1.0, v29
	v_cvt_pk_bf16_f32 v18, v18, v19
	v_rcp_f32_e32 v28, v28
	v_rcp_f32_e32 v29, v29
	v_pk_mul_f32 v[26:27], v[8:9], v[26:27]
	v_cvt_pk_bf16_f32 v19, v20, v21
	v_pk_mul_f32 v[28:29], v[10:11], v[28:29]
	v_cvt_pk_bf16_f32 v20, v26, v27
	v_cvt_pk_bf16_f32 v21, v28, v29
	s_mov_b64 s[72:73], 0
	global_store_dwordx4 v[24:25], v[18:21], off
; __device__ __forceinline__ void st16f(float* p, f32x4 v) { st16(p, __builtin_bit_cast(u32x4, v)); }
; __device__ __forceinline__ void st8bf(bf16_t* p, f32x4 a, f32x4 b) { u32x4 w; w.x = pk2(a[0], a[1]); w.y = pk2(a[2], a[3]); w.z = pk2(b[0], b[1]); w.w = pk2(b[2], b[3]); st16(p, w); }
;     __device__ __forceinline__ void st(int pn, int row, int c, f32x4 v0, f32x4 v1) const {
;         const bool smp = row >= MP; const int b = smp ? (row - MP) >> 2 : row >> 13, t = smp ? (row - MP) & 3 : row & (SEQ - 1);
;         if (pn < 4) { const int col = pn * 256 + c; float* o = nullptr;
;             if (smp) o = out + O_POOLS + ((size_t)b * 15 + 11 + t) * 1024 + col;
;             st8bf(V + (size_t)row * 1024 + col, v0, v1); if (o) { st16f(o, v0); st16f(o + 4, v1); }
;             if (smp) {
;                 const int w = 2 << pn;
;                 float x[8] = {v0[0], v0[1], v0[2], v0[3], v1[0], v1[1], v1[2], v1[3]}, s[8];
; #pragma unroll
;                 for (int e = 0; e < 8; ++e) { s[e] = 0.f;
; #pragma unroll
;                     for (int tp = 0; tp < 4; ++tp) { const float xo = quad_bcast(x[e], tp); if (tp <= t && t - tp < w) s[e] += xo; } }
;                 const int e_lo = 15 + t - w + 1;
; #pragma unroll
;                 for (int e2 = 0; e2 < 15; ++e2) if (e2 >= e_lo) { const float* sp = state_pool + ((size_t)b * 15 + e2) * 1024 + col; const f32x4 a = *(const f32x4*)sp, d = *(const f32x4*)(sp + 4);
;                     s[0] += a[0]; s[1] += a[1]; s[2] += a[2]; s[3] += a[3]; s[4] += d[0]; s[5] += d[1]; s[6] += d[2]; s[7] += d[3]; }
;                 const float inv = 1.f / (float)w;
;                 st8bf(DMs + (size_t)row * 1024 + col, (f32x4){s[0] * inv - x[0], s[1] * inv - x[1], s[2] * inv - x[2], s[3] * inv - x[3]}, (f32x4){s[4] * inv - x[4], s[5] * inv - x[5], s[6] * inv - x[6], s[7] * inv - x[7]});
;             } }
.LBB0_2359:
	s_nop 1
	v_add_u32_e32 v18, 0xffff80b0, v150
	v_lshrrev_b32_e32 v24, 2, v18
	v_mad_u64_u32 v[18:19], s[74:75], v24, 15, v[128:129]
	v_lshlrev_b64 v[20:21], 12, v[18:19]
	v_lshlrev_b64 v[16:17], 10, v[16:17]
	s_andn2_b64 vcc, exec, s[72:73]
	v_mad_u64_u32 v[18:19], s[72:73], v24, s90, 0
	s_cbranch_vccnz .LBB0_2380
	v_or_b32_e32 v24, s70, v140
	v_ashrrev_i32_e32 v25, 31, v24
	v_lshl_add_u64 v[26:27], v[16:17], 1, s[52:53]
	v_lshl_add_u64 v[30:31], v[24:25], 1, v[26:27]
	v_cvt_pk_bf16_f32 v26, v12, v13
	v_cvt_pk_bf16_f32 v27, v14, v15
	v_cvt_pk_bf16_f32 v28, v8, v9
	v_cvt_pk_bf16_f32 v29, v10, v11
	global_store_dwordx4 v[30:31], v[26:29], off
	s_and_saveexec_b64 s[72:73], s[48:49]
	s_cbranch_execz .LBB0_2378
	v_readlane_b32 s4, v250, 58
	v_readlane_b32 s5, v250, 59
	v_lshlrev_b64 v[34:35], 2, v[24:25]
	s_nop 0
	v_lshl_add_u64 v[26:27], s[4:5], 0, v[20:21]
	v_lshl_add_u64 v[26:27], v[26:27], 0, v[34:35]
	global_store_dwordx4 v[26:27], v[12:15], off
	global_store_dwordx4 v[26:27], v[8:11], off offset:16
	v_mov_b32_dpp v26, v12 quad_perm:[0,0,0,0] row_mask:0xf bank_mask:0xf bound_ctrl:1
	v_add_f32_e32 v26, 0, v26
	v_cndmask_b32_e64 v26, 0, v26, s[40:41]
	v_readlane_b32 s4, v250, 12
	v_readlane_b32 s16, v250, 24
	v_add_f32_dpp v27, v12, v26 quad_perm:[1,1,1,1] row_mask:0xf bank_mask:0xf bound_ctrl:1
	v_cndmask_b32_e64 v26, v26, v27, s[44:45]
	v_readlane_b32 s17, v250, 25
	v_readlane_b32 s5, v250, 13
	v_add_f32_dpp v27, v12, v26 quad_perm:[2,2,2,2] row_mask:0xf bank_mask:0xf bound_ctrl:1
	v_cndmask_b32_e64 v26, v26, v27, s[42:43]
	v_lshl_add_u64 v[34:35], s[16:17], 0, v[34:35]
	v_lshl_add_u64 v[34:35], v[34:35], 0, v[18:19]
	v_add_f32_dpp v27, v12, v26 quad_perm:[3,3,3,3] row_mask:0xf bank_mask:0xf bound_ctrl:1
	v_cndmask_b32_e64 v26, v26, v27, s[0:1]
	v_readlane_b32 s6, v250, 14
	v_mov_b32_dpp v27, v13 quad_perm:[0,0,0,0] row_mask:0xf bank_mask:0xf bound_ctrl:1
	v_add_f32_e32 v27, 0, v27
	v_cndmask_b32_e64 v27, 0, v27, s[40:41]
	v_readlane_b32 s7, v250, 15
	v_readlane_b32 s8, v250, 16
	v_add_f32_dpp v28, v13, v27 quad_perm:[1,1,1,1] row_mask:0xf bank_mask:0xf bound_ctrl:1
	v_cndmask_b32_e64 v27, v27, v28, s[44:45]
	v_readlane_b32 s9, v250, 17
	v_readlane_b32 s10, v250, 18
	v_add_f32_dpp v28, v13, v27 quad_perm:[2,2,2,2] row_mask:0xf bank_mask:0xf bound_ctrl:1
	v_cndmask_b32_e64 v27, v27, v28, s[42:43]
	v_readlane_b32 s11, v250, 19
	v_readlane_b32 s12, v250, 20
	v_add_f32_dpp v28, v13, v27 quad_perm:[3,3,3,3] row_mask:0xf bank_mask:0xf bound_ctrl:1
	v_cndmask_b32_e64 v27, v27, v28, s[0:1]
	v_readlane_b32 s13, v250, 21
	v_mov_b32_dpp v28, v14 quad_perm:[0,0,0,0] row_mask:0xf bank_mask:0xf bound_ctrl:1
	v_add_f32_e32 v28, 0, v28
	v_cndmask_b32_e64 v28, 0, v28, s[40:41]
	v_readlane_b32 s14, v250, 22
	v_readlane_b32 s15, v250, 23
	v_add_f32_dpp v29, v14, v28 quad_perm:[1,1,1,1] row_mask:0xf bank_mask:0xf bound_ctrl:1
	v_cndmask_b32_e64 v28, v28, v29, s[44:45]
	v_readlane_b32 s18, v250, 26
	v_readlane_b32 s19, v250, 27
	v_add_f32_dpp v29, v14, v28 quad_perm:[2,2,2,2] row_mask:0xf bank_mask:0xf bound_ctrl:1
	v_cndmask_b32_e64 v28, v28, v29, s[42:43]
	s_nop 1
	v_add_f32_dpp v29, v14, v28 quad_perm:[3,3,3,3] row_mask:0xf bank_mask:0xf bound_ctrl:1
	v_cndmask_b32_e64 v28, v28, v29, s[0:1]
	s_nop 0
	v_mov_b32_dpp v29, v15 quad_perm:[0,0,0,0] row_mask:0xf bank_mask:0xf bound_ctrl:1
	v_add_f32_e32 v29, 0, v29
	v_cndmask_b32_e64 v29, 0, v29, s[40:41]
	s_nop 1
	v_add_f32_dpp v30, v15, v29 quad_perm:[1,1,1,1] row_mask:0xf bank_mask:0xf bound_ctrl:1
	v_cndmask_b32_e64 v29, v29, v30, s[44:45]
	s_nop 1
	v_add_f32_dpp v30, v15, v29 quad_perm:[2,2,2,2] row_mask:0xf bank_mask:0xf bound_ctrl:1
	v_cndmask_b32_e64 v29, v29, v30, s[42:43]
	s_nop 1
	v_add_f32_dpp v30, v15, v29 quad_perm:[3,3,3,3] row_mask:0xf bank_mask:0xf bound_ctrl:1
	v_cndmask_b32_e64 v29, v29, v30, s[0:1]
	s_nop 0
	v_mov_b32_dpp v30, v8 quad_perm:[0,0,0,0] row_mask:0xf bank_mask:0xf bound_ctrl:1
	v_add_f32_e32 v30, 0, v30
	v_cndmask_b32_e64 v30, 0, v30, s[40:41]
	s_nop 1
	v_add_f32_dpp v31, v8, v30 quad_perm:[1,1,1,1] row_mask:0xf bank_mask:0xf bound_ctrl:1
	v_cndmask_b32_e64 v30, v30, v31, s[44:45]
	s_nop 1
	v_add_f32_dpp v31, v8, v30 quad_perm:[2,2,2,2] row_mask:0xf bank_mask:0xf bound_ctrl:1
	v_cndmask_b32_e64 v30, v30, v31, s[42:43]
	s_nop 1
	v_add_f32_dpp v31, v8, v30 quad_perm:[3,3,3,3] row_mask:0xf bank_mask:0xf bound_ctrl:1
	v_cndmask_b32_e64 v30, v30, v31, s[0:1]
	s_nop 0
	v_mov_b32_dpp v31, v9 quad_perm:[0,0,0,0] row_mask:0xf bank_mask:0xf bound_ctrl:1
	v_add_f32_e32 v31, 0, v31
	v_cndmask_b32_e64 v31, 0, v31, s[40:41]
	s_nop 1
	v_add_f32_dpp v32, v9, v31 quad_perm:[1,1,1,1] row_mask:0xf bank_mask:0xf bound_ctrl:1
	v_cndmask_b32_e64 v31, v31, v32, s[44:45]
	s_nop 1
	v_add_f32_dpp v32, v9, v31 quad_perm:[2,2,2,2] row_mask:0xf bank_mask:0xf bound_ctrl:1
	v_cndmask_b32_e64 v31, v31, v32, s[42:43]
	s_nop 1
	v_add_f32_dpp v32, v9, v31 quad_perm:[3,3,3,3] row_mask:0xf bank_mask:0xf bound_ctrl:1
	v_cndmask_b32_e64 v31, v31, v32, s[0:1]
	s_nop 0
	v_mov_b32_dpp v32, v10 quad_perm:[0,0,0,0] row_mask:0xf bank_mask:0xf bound_ctrl:1
	v_add_f32_e32 v32, 0, v32
	v_cndmask_b32_e64 v32, 0, v32, s[40:41]
	s_nop 1
	v_add_f32_dpp v33, v10, v32 quad_perm:[1,1,1,1] row_mask:0xf bank_mask:0xf bound_ctrl:1
	v_cndmask_b32_e64 v32, v32, v33, s[44:45]
	s_nop 1
	v_add_f32_dpp v33, v10, v32 quad_perm:[2,2,2,2] row_mask:0xf bank_mask:0xf bound_ctrl:1
	v_cndmask_b32_e64 v32, v32, v33, s[42:43]
	s_nop 1
	v_add_f32_dpp v33, v10, v32 quad_perm:[3,3,3,3] row_mask:0xf bank_mask:0xf bound_ctrl:1
	v_cndmask_b32_e64 v32, v32, v33, s[0:1]
	s_nop 0
	v_mov_b32_dpp v33, v11 quad_perm:[0,0,0,0] row_mask:0xf bank_mask:0xf bound_ctrl:1
	v_add_f32_e32 v33, 0, v33
	v_cndmask_b32_e64 v33, 0, v33, s[40:41]
	s_nop 1
	v_add_f32_dpp v36, v11, v33 quad_perm:[1,1,1,1] row_mask:0xf bank_mask:0xf bound_ctrl:1
	v_cndmask_b32_e64 v33, v33, v36, s[44:45]
	s_nop 1
	v_add_f32_dpp v36, v11, v33 quad_perm:[2,2,2,2] row_mask:0xf bank_mask:0xf bound_ctrl:1
	v_cndmask_b32_e64 v33, v33, v36, s[42:43]
	s_nop 1
	v_add_f32_dpp v36, v11, v33 quad_perm:[3,3,3,3] row_mask:0xf bank_mask:0xf bound_ctrl:1
	v_cndmask_b32_e64 v33, v33, v36, s[0:1]
	s_and_saveexec_b64 s[74:75], s[38:39]
	s_cbranch_execz .LBB0_2600
	global_load_dwordx4 v[36:39], v[34:35], off offset:16
	global_load_dwordx4 v[40:43], v[34:35], off
	s_waitcnt vmcnt(0)
	v_pk_add_f32 v[30:31], v[30:31], v[36:37]
	v_pk_add_f32 v[32:33], v[32:33], v[38:39]
	v_pk_add_f32 v[28:29], v[28:29], v[42:43]
	v_pk_add_f32 v[26:27], v[26:27], v[40:41]
	s_or_b64 exec, exec, s[74:75]
	s_and_saveexec_b64 s[74:75], s[36:37]
	s_cbranch_execnz .LBB0_2601

; __device__ __forceinline__ void st8bf(bf16_t* p, f32x4 a, f32x4 b) { u32x4 w; w.x = pk2(a[0], a[1]); w.y = pk2(a[2], a[3]); w.z = pk2(b[0], b[1]); w.w = pk2(b[2], b[3]); st16(p, w); }
;     __device__ __forceinline__ void st(int pn, int row, int c, f32x4 a, f32x4 d) const {
;         const int col = pn * 256 + c;
;         const u32x4 gw = *(const u32x4*)(GT + (size_t)row * 1024 + col);
;         a = a * *(const f32x4*)(scale + col); d = d * *(const f32x4*)(scale + col + 4);
;         a[0] *= bflo(gw.x); a[1] *= bfhi(gw.x); a[2] *= bflo(gw.y); a[3] *= bfhi(gw.y);
;         d[0] *= bflo(gw.z); d[1] *= bfhi(gw.z); d[2] *= bflo(gw.w); d[3] *= bfhi(gw.w);
;         st8bf(MX + (size_t)row * 1024 + col, a, d);
;     }
;     ...
;         if (kh == 0 && act) {
; #pragma unroll
;             for (int q = 0; q < KS - 1; ++q)
; #pragma unroll
;                 for (int j = 0; j < NACC; ++j) acc[j] += red[((pw * (KS - 1) + q) * NACC + j) * 64 + lane];
;             const int row = row_base + mt * mt_stride + r, c = 32 * sub + 8 * fq;
;             if (glu) epi.st_glu(pn, row, c, acc[0], acc[1], acc[2], acc[3]); else epi.st(pn, row, c, acc[0], acc[1]);
.LBB0_2688:
	s_and_b64 s[16:17], s[12:13], s[16:17]
	s_andn2_b64 vcc, exec, s[16:17]
	s_waitcnt vmcnt(0) lgkmcnt(0)
	s_barrier
	s_cbranch_vccnz .LBB0_2683
	s_lshl_b32 s15, s24, 5
	s_lshl_b32 s14, s14, 8
	s_or_b32 s14, s14, s15
	v_add_u32_e32 v30, s14, v8
	v_readlane_b32 s24, v250, 0
	v_lshl_add_u32 v12, s23, 14, v21
	v_ashrrev_i32_e32 v31, 31, v30
	v_readlane_b32 s26, v250, 2
	v_readlane_b32 s27, v250, 3
	v_lshlrev_b64 v[90:91], 1, v[12:13]
	v_lshlrev_b64 v[92:93], 1, v[30:31]
	v_lshl_add_u64 v[32:33], v[30:31], 2, s[26:27]
	global_load_dwordx4 v[22:25], v[32:33], off offset:16
	global_load_dwordx4 v[26:29], v[32:33], off
	v_lshl_add_u64 v[32:33], s[4:5], 0, v[90:91]
	v_lshl_add_u64 v[30:31], v[32:33], 0, v[92:93]
	global_load_dwordx4 v[30:33], v[30:31], off
	v_add_u32_e32 v12, s18, v18
	ds_read_b128 v[34:37], v12
	ds_read_b128 v[38:41], v12 offset:1024
	ds_read_b128 v[42:45], v12 offset:2048
	ds_read_b128 v[46:49], v12 offset:3072
	ds_read_b128 v[50:53], v12 offset:4096
	ds_read_b128 v[54:57], v12 offset:5120
	ds_read_b128 v[58:61], v12 offset:6144
	ds_read_b128 v[62:65], v12 offset:7168
	ds_read_b128 v[66:69], v12 offset:8192
	ds_read_b128 v[70:73], v12 offset:9216
	ds_read_b128 v[74:77], v12 offset:10240
	ds_read_b128 v[78:81], v12 offset:11264
	ds_read_b128 v[82:85], v12 offset:12288
	ds_read_b128 v[86:89], v12 offset:13312
	s_waitcnt lgkmcnt(13)
	v_pk_add_f32 v[6:7], v[6:7], v[36:37]
	v_pk_add_f32 v[4:5], v[4:5], v[34:35]
	s_waitcnt lgkmcnt(12)
	v_pk_add_f32 v[2:3], v[2:3], v[40:41]
	v_pk_add_f32 v[0:1], v[0:1], v[38:39]
	s_waitcnt lgkmcnt(11)
	v_pk_add_f32 v[6:7], v[6:7], v[44:45]
	v_pk_add_f32 v[4:5], v[4:5], v[42:43]
	s_waitcnt lgkmcnt(10)
	v_pk_add_f32 v[2:3], v[2:3], v[48:49]
	v_pk_add_f32 v[0:1], v[0:1], v[46:47]
	s_waitcnt lgkmcnt(9)
	v_pk_add_f32 v[6:7], v[6:7], v[52:53]
	v_pk_add_f32 v[4:5], v[4:5], v[50:51]
	s_waitcnt lgkmcnt(8)
	v_pk_add_f32 v[2:3], v[2:3], v[56:57]
	v_pk_add_f32 v[0:1], v[0:1], v[54:55]
	s_waitcnt lgkmcnt(7)
	v_pk_add_f32 v[6:7], v[6:7], v[60:61]
	v_pk_add_f32 v[4:5], v[4:5], v[58:59]
	s_waitcnt lgkmcnt(6)
	v_pk_add_f32 v[2:3], v[2:3], v[64:65]
	v_pk_add_f32 v[0:1], v[0:1], v[62:63]
	s_waitcnt lgkmcnt(5)
	v_pk_add_f32 v[6:7], v[6:7], v[68:69]
	v_pk_add_f32 v[4:5], v[4:5], v[66:67]
	s_waitcnt lgkmcnt(4)
	v_pk_add_f32 v[2:3], v[2:3], v[72:73]
	v_pk_add_f32 v[0:1], v[0:1], v[70:71]
	s_waitcnt lgkmcnt(3)
	v_pk_add_f32 v[6:7], v[6:7], v[76:77]
	v_pk_add_f32 v[4:5], v[4:5], v[74:75]
	s_waitcnt lgkmcnt(2)
	v_pk_add_f32 v[2:3], v[2:3], v[80:81]
	v_pk_add_f32 v[0:1], v[0:1], v[78:79]
	s_waitcnt lgkmcnt(1)
	v_pk_add_f32 v[6:7], v[6:7], v[84:85]
	v_pk_add_f32 v[4:5], v[4:5], v[82:83]
	s_waitcnt lgkmcnt(0)
	v_pk_add_f32 v[2:3], v[2:3], v[88:89]
	v_pk_add_f32 v[0:1], v[0:1], v[86:87]
	v_lshl_add_u64 v[90:91], s[6:7], 0, v[90:91]
	v_lshl_add_u64 v[90:91], v[90:91], 0, v[92:93]
	v_readlane_b32 s25, v250, 1
	v_readlane_b32 s28, v250, 4
	v_readlane_b32 s29, v250, 5
	v_readlane_b32 s30, v250, 6
	v_readlane_b32 s31, v250, 7
	s_waitcnt vmcnt(2)
	v_pk_mul_f32 v[2:3], v[2:3], v[24:25]
	s_waitcnt vmcnt(1)
	v_pk_mul_f32 v[6:7], v[6:7], v[28:29]
	v_pk_mul_f32 v[4:5], v[4:5], v[26:27]
	v_pk_mul_f32 v[0:1], v[0:1], v[22:23]
	s_waitcnt vmcnt(0)
	v_lshlrev_b32_e32 v23, 16, v31
	v_lshlrev_b32_e32 v22, 16, v30
	v_mov_b32_e32 v25, v6
	v_and_b32_e32 v27, 0xffff0000, v31
	v_and_b32_e32 v26, 0xffff0000, v30
	v_mov_b32_e32 v6, v5
	v_mov_b32_e32 v29, v2
	v_and_b32_e32 v31, 0xffff0000, v33
	v_and_b32_e32 v30, 0xffff0000, v32
	v_mov_b32_e32 v2, v1
	v_mov_b32_e32 v24, v4
	v_lshlrev_b32_e32 v5, 16, v33
	v_lshlrev_b32_e32 v4, 16, v32
	v_mov_b32_e32 v28, v0
	v_pk_mul_f32 v[6:7], v[6:7], v[26:27]
	v_pk_mul_f32 v[2:3], v[2:3], v[30:31]
	v_pk_mul_f32 v[0:1], v[24:25], v[22:23]
	v_pk_mul_f32 v[4:5], v[28:29], v[4:5]
	v_cvt_pk_bf16_f32 v3, v5, v3
	v_cvt_pk_bf16_f32 v2, v4, v2
	v_cvt_pk_bf16_f32 v1, v1, v7
	v_cvt_pk_bf16_f32 v0, v0, v6
	global_store_dwordx4 v[90:91], v[0:3], off
	s_branch .LBB0_2683

; __device__ __forceinline__ unsigned pk2(float lo, float hi) { return f2bf(lo) | (f2bf(hi) << 16); }
; __device__ __forceinline__ void fir_tile(const Prm& P, Ctx& C, int pm, int gi) {
;     ...
;     for (int j = 0; j < RUN; ++j) {
;         const int t = t0 + j;
;         const u32x4 g = *(const u32x4*)(GT + (size_t)(row0 + j) * 1024 + c0);
;         acc8(s, x[15 + j], 1.f);
;         const float inv = 1.f / (float)(t + 1 < w ? t + 1 : w);
;         const u32x4 xc = x[15 + j];
;         u32x4 o;
;         o.x = pk2((s[0] * inv - bflo(xc.x)) * sc0[0] * bflo(g.x), (s[1] * inv - bfhi(xc.x)) * sc0[1] * bfhi(g.x));
;         o.y = pk2((s[2] * inv - bflo(xc.y)) * sc0[2] * bflo(g.y), (s[3] * inv - bfhi(xc.y)) * sc0[3] * bfhi(g.y));
;         o.z = pk2((s[4] * inv - bflo(xc.z)) * sc1[0] * bflo(g.z), (s[5] * inv - bfhi(xc.z)) * sc1[1] * bfhi(g.z));
;         o.w = pk2((s[6] * inv - bflo(xc.w)) * sc1[2] * bflo(g.w), (s[7] * inv - bfhi(xc.w)) * sc1[3] * bfhi(g.w));
;         *(u32x4*)(MX + (size_t)(row0 + j) * 1024 + c0) = o;
;         if (w == 2) acc8(s, x[15 + j - 1], -1.f); else if (w == 4) acc8(s, x[15 + j - 3], -1.f); else if (w == 8) acc8(s, x[15 + j - 7], -1.f); else acc8(s, x[j], -1.f);
;     }
.LBB0_2851:
	v_or_b32_e32 v174, 7, v132
	v_ashrrev_i32_e32 v175, 31, v174
	v_lshlrev_b64 v[198:199], 11, v[174:175]
	v_lshl_add_u64 v[174:175], v[98:99], 0, v[198:199]
	global_load_dwordx4 v[194:197], v[174:175], off
	v_or_b32_e32 v133, 8, v226
	v_min_i32_e32 v133, s16, v133
	v_cvt_f32_i32_e32 v133, v133
	v_pk_add_f32 v[178:179], v[182:183], v[190:191] neg_lo:[0,1] neg_hi:[0,1]
	v_pk_add_f32 v[180:181], v[184:185], v[192:193] neg_lo:[0,1] neg_hi:[0,1]
	v_pk_add_f32 v[174:175], v[44:45], v[186:187] neg_lo:[0,1] neg_hi:[0,1]
	v_div_scale_f32 v182, s[0:1], v133, v133, 1.0
	v_rcp_f32_e32 v183, v182
	v_div_scale_f32 v184, vcc, 1.0, v133, 1.0
	v_pk_add_f32 v[176:177], v[46:47], v[188:189] neg_lo:[0,1] neg_hi:[0,1]
	v_fma_f32 v185, -v182, v183, 1.0
	v_fmac_f32_e32 v183, v185, v183
	v_mul_f32_e32 v185, v184, v183
	v_fma_f32 v186, -v182, v185, v184
	v_fmac_f32_e32 v185, v186, v183
	v_fma_f32 v182, -v182, v185, v184
	v_lshlrev_b32_e32 v45, 16, v41
	v_lshlrev_b32_e32 v44, 16, v40
	v_and_b32_e32 v41, 0xffff0000, v41
	v_and_b32_e32 v40, 0xffff0000, v40
	v_lshlrev_b32_e32 v47, 16, v43
	v_lshlrev_b32_e32 v46, 16, v42
	v_and_b32_e32 v43, 0xffff0000, v43
	v_and_b32_e32 v42, 0xffff0000, v42
	v_div_fmas_f32 v182, v182, v183, v185
	v_pk_add_f32 v[174:175], v[174:175], v[44:45]
	v_pk_add_f32 v[176:177], v[176:177], v[40:41]
	v_pk_add_f32 v[178:179], v[178:179], v[46:47]
	v_pk_add_f32 v[180:181], v[180:181], v[42:43]
	v_div_fixup_f32 v182, v182, v133, 1.0
	v_pk_fma_f32 v[184:185], v[182:183], v[174:175], v[44:45] op_sel_hi:[0,1,1] neg_lo:[0,0,1] neg_hi:[0,0,1]
	v_pk_fma_f32 v[186:187], v[182:183], v[176:177], v[40:41] op_sel_hi:[0,1,1] neg_lo:[0,0,1] neg_hi:[0,0,1]
	v_pk_fma_f32 v[188:189], v[182:183], v[178:179], v[46:47] op_sel_hi:[0,1,1] neg_lo:[0,0,1] neg_hi:[0,0,1]
	v_pk_fma_f32 v[182:183], v[182:183], v[180:181], v[42:43] op_sel_hi:[0,1,1] neg_lo:[0,0,1] neg_hi:[0,0,1]
	v_pk_mul_f32 v[184:185], v[64:65], v[184:185]
	v_pk_mul_f32 v[188:189], v[4:5], v[188:189]
	v_pk_mul_f32 v[182:183], v[2:3], v[182:183]
	v_pk_mul_f32 v[186:187], v[6:7], v[186:187]
	s_movk_i32 s11, 0x7fff
	s_mov_b32 s10, 0xffff0000
	s_cmp_lt_i32 s14, 1
	s_mov_b64 s[0:1], 0
	s_waitcnt vmcnt(0)
	v_lshlrev_b32_e32 v191, 16, v195
	v_lshlrev_b32_e32 v190, 16, v194
	v_and_b32_e32 v193, 0xffff0000, v195
	v_and_b32_e32 v192, 0xffff0000, v194
	v_lshlrev_b32_e32 v195, 16, v197
	v_lshlrev_b32_e32 v194, 16, v196
	v_and_b32_e32 v197, 0xffff0000, v197
	v_and_b32_e32 v196, 0xffff0000, v196
	v_pk_mul_f32 v[184:185], v[184:185], v[190:191]
	v_pk_mul_f32 v[188:189], v[188:189], v[194:195]
	v_pk_mul_f32 v[182:183], v[182:183], v[196:197]
	v_pk_mul_f32 v[186:187], v[186:187], v[192:193]
	v_bfe_u32 v133, v183, 16, 1
	v_bfe_u32 v193, v184, 16, 1
	v_bfe_u32 v194, v185, 16, 1
	v_bfe_u32 v196, v189, 16, 1
	v_bfe_u32 v191, v187, 16, 1
	v_bfe_u32 v192, v186, 16, 1
	v_add3_u32 v133, v183, v133, s11
	v_add3_u32 v183, v189, v196, s11
	v_add3_u32 v185, v185, v194, s11
	v_add3_u32 v184, v184, v193, s11
	v_add3_u32 v186, v186, v192, s11
	v_add3_u32 v187, v187, v191, s11
	v_lshrrev_b32_e32 v189, 16, v184
	v_lshrrev_b32_e32 v190, 16, v185
	v_lshrrev_b32_e32 v183, 16, v183
	v_and_or_b32 v185, v133, s10, v183
	v_cvt_pk_bf16_f32 v184, v188, v182
	v_and_or_b32 v183, v187, s10, v190
	v_and_or_b32 v182, v186, s10, v189
	v_lshl_add_u64 v[186:187], v[96:97], 0, v[198:199]
	global_store_dwordx4 v[186:187], v[182:185], off
	s_cbranch_scc1 .LBB0_2854
	s_cmp_gt_i32 s14, 1
	s_cbranch_scc0 .LBB0_2855
	s_cmp_lg_u32 s14, 2
	s_cselect_b64 s[10:11], -1, 0
	s_cbranch_execz .LBB0_2856
	s_branch .LBB0_2857

; __device__ __forceinline__ unsigned pk2(float lo, float hi) { return f2bf(lo) | (f2bf(hi) << 16); }
; __device__ __forceinline__ void fir_tile(const Prm& P, Ctx& C, int pm, int gi) {
;     ...
;     for (int j = 0; j < RUN; ++j) {
;         const int t = t0 + j;
;         const u32x4 g = *(const u32x4*)(GT + (size_t)(row0 + j) * 1024 + c0);
;         acc8(s, x[15 + j], 1.f);
;         const float inv = 1.f / (float)(t + 1 < w ? t + 1 : w);
;         const u32x4 xc = x[15 + j];
;         u32x4 o;
;         o.x = pk2((s[0] * inv - bflo(xc.x)) * sc0[0] * bflo(g.x), (s[1] * inv - bfhi(xc.x)) * sc0[1] * bfhi(g.x));
;         o.y = pk2((s[2] * inv - bflo(xc.y)) * sc0[2] * bflo(g.y), (s[3] * inv - bfhi(xc.y)) * sc0[3] * bfhi(g.y));
;         o.z = pk2((s[4] * inv - bflo(xc.z)) * sc1[0] * bflo(g.z), (s[5] * inv - bfhi(xc.z)) * sc1[1] * bfhi(g.z));
;         o.w = pk2((s[6] * inv - bflo(xc.w)) * sc1[2] * bflo(g.w), (s[7] * inv - bfhi(xc.w)) * sc1[3] * bfhi(g.w));
;         *(u32x4*)(MX + (size_t)(row0 + j) * 1024 + c0) = o;
;         if (w == 2) acc8(s, x[15 + j - 1], -1.f); else if (w == 4) acc8(s, x[15 + j - 3], -1.f); else if (w == 8) acc8(s, x[15 + j - 7], -1.f); else acc8(s, x[j], -1.f);
;     }
.LBB0_2863:
	v_or_b32_e32 v72, 8, v132
	v_ashrrev_i32_e32 v73, 31, v72
	v_lshlrev_b64 v[186:187], 11, v[72:73]
	v_lshl_add_u64 v[72:73], v[98:99], 0, v[186:187]
	global_load_dwordx4 v[182:185], v[72:73], off
	v_pk_add_f32 v[128:129], v[176:177], v[76:77] neg_lo:[0,1] neg_hi:[0,1]
	v_lshlrev_b32_e32 v76, 16, v38
	v_and_b32_e32 v80, 0xffff0000, v38
	v_or_b32_e32 v38, 9, v226
	v_min_i32_e32 v38, s16, v38
	v_cvt_f32_i32_e32 v133, v38
	v_pk_add_f32 v[122:123], v[174:175], v[122:123] neg_lo:[0,1] neg_hi:[0,1]
	v_pk_add_f32 v[172:173], v[178:179], v[68:69] neg_lo:[0,1] neg_hi:[0,1]
	v_lshlrev_b32_e32 v69, 16, v37
	v_lshlrev_b32_e32 v68, 16, v36
	v_lshlrev_b32_e32 v77, 16, v39
	v_and_b32_e32 v73, 0xffff0000, v37
	v_and_b32_e32 v72, 0xffff0000, v36
	v_pk_add_f32 v[36:37], v[122:123], v[68:69]
	v_pk_add_f32 v[122:123], v[172:173], v[76:77]
	v_div_scale_f32 v172, s[0:1], v133, v133, 1.0
	v_rcp_f32_e32 v173, v172
	v_pk_add_f32 v[170:171], v[180:181], v[170:171] neg_lo:[0,1] neg_hi:[0,1]
	v_and_b32_e32 v81, 0xffff0000, v39
	v_pk_add_f32 v[38:39], v[128:129], v[72:73]
	v_pk_add_f32 v[128:129], v[170:171], v[80:81]
	v_fma_f32 v171, -v172, v173, 1.0
	v_div_scale_f32 v170, vcc, 1.0, v133, 1.0
	v_fmac_f32_e32 v173, v171, v173
	v_mul_f32_e32 v171, v170, v173
	v_fma_f32 v174, -v172, v171, v170
	v_fmac_f32_e32 v171, v174, v173
	v_fma_f32 v170, -v172, v171, v170
	v_div_fmas_f32 v170, v170, v173, v171
	v_div_fixup_f32 v170, v170, v133, 1.0
	v_pk_fma_f32 v[172:173], v[170:171], v[36:37], v[68:69] op_sel_hi:[0,1,1] neg_lo:[0,0,1] neg_hi:[0,0,1]
	v_pk_fma_f32 v[174:175], v[170:171], v[38:39], v[72:73] op_sel_hi:[0,1,1] neg_lo:[0,0,1] neg_hi:[0,0,1]
	v_pk_fma_f32 v[176:177], v[170:171], v[122:123], v[76:77] op_sel_hi:[0,1,1] neg_lo:[0,0,1] neg_hi:[0,0,1]
	v_pk_fma_f32 v[170:171], v[170:171], v[128:129], v[80:81] op_sel_hi:[0,1,1] neg_lo:[0,0,1] neg_hi:[0,0,1]
	v_pk_mul_f32 v[172:173], v[64:65], v[172:173]
	v_pk_mul_f32 v[176:177], v[4:5], v[176:177]
	v_pk_mul_f32 v[170:171], v[2:3], v[170:171]
	v_pk_mul_f32 v[174:175], v[6:7], v[174:175]
	s_movk_i32 s11, 0x7fff
	s_mov_b32 s10, 0xffff0000
	s_cmp_lt_i32 s14, 1
	s_mov_b64 s[0:1], 0
	s_waitcnt vmcnt(0)
	v_lshlrev_b32_e32 v179, 16, v183
	v_lshlrev_b32_e32 v178, 16, v182
	v_and_b32_e32 v181, 0xffff0000, v183
	v_and_b32_e32 v180, 0xffff0000, v182
	v_lshlrev_b32_e32 v183, 16, v185
	v_lshlrev_b32_e32 v182, 16, v184
	v_and_b32_e32 v185, 0xffff0000, v185
	v_and_b32_e32 v184, 0xffff0000, v184
	v_pk_mul_f32 v[172:173], v[172:173], v[178:179]
	v_pk_mul_f32 v[176:177], v[176:177], v[182:183]
	v_pk_mul_f32 v[170:171], v[170:171], v[184:185]
	v_pk_mul_f32 v[174:175], v[174:175], v[180:181]
	v_bfe_u32 v133, v171, 16, 1
	v_bfe_u32 v181, v172, 16, 1
	v_bfe_u32 v182, v173, 16, 1
	v_bfe_u32 v184, v177, 16, 1
	v_bfe_u32 v179, v175, 16, 1
	v_bfe_u32 v180, v174, 16, 1
	v_add3_u32 v133, v171, v133, s11
	v_add3_u32 v171, v177, v184, s11
	v_add3_u32 v173, v173, v182, s11
	v_add3_u32 v172, v172, v181, s11
	v_add3_u32 v174, v174, v180, s11
	v_add3_u32 v175, v175, v179, s11
	v_lshrrev_b32_e32 v177, 16, v172
	v_lshrrev_b32_e32 v178, 16, v173
	v_lshrrev_b32_e32 v171, 16, v171
	v_and_or_b32 v173, v133, s10, v171
	v_cvt_pk_bf16_f32 v172, v176, v170
	v_and_or_b32 v171, v175, s10, v178
	v_and_or_b32 v170, v174, s10, v177
	v_lshl_add_u64 v[174:175], v[96:97], 0, v[186:187]
	global_store_dwordx4 v[174:175], v[170:173], off
	s_cbranch_scc1 .LBB0_2866
	s_cmp_gt_i32 s14, 1
	s_cbranch_scc0 .LBB0_2867
	s_cmp_lg_u32 s14, 2
	s_cselect_b64 s[10:11], -1, 0
	s_cbranch_execz .LBB0_2868
	s_branch .LBB0_2869

; __device__ __forceinline__ unsigned pk2(float lo, float hi) { return f2bf(lo) | (f2bf(hi) << 16); }
; __device__ __forceinline__ void fir_tile(const Prm& P, Ctx& C, int pm, int gi) {
;     ...
;     for (int j = 0; j < RUN; ++j) {
;         const int t = t0 + j;
;         const u32x4 g = *(const u32x4*)(GT + (size_t)(row0 + j) * 1024 + c0);
;         acc8(s, x[15 + j], 1.f);
;         const float inv = 1.f / (float)(t + 1 < w ? t + 1 : w);
;         const u32x4 xc = x[15 + j];
;         u32x4 o;
;         o.x = pk2((s[0] * inv - bflo(xc.x)) * sc0[0] * bflo(g.x), (s[1] * inv - bfhi(xc.x)) * sc0[1] * bfhi(g.x));
;         o.y = pk2((s[2] * inv - bflo(xc.y)) * sc0[2] * bflo(g.y), (s[3] * inv - bfhi(xc.y)) * sc0[3] * bfhi(g.y));
;         o.z = pk2((s[4] * inv - bflo(xc.z)) * sc1[0] * bflo(g.z), (s[5] * inv - bfhi(xc.z)) * sc1[1] * bfhi(g.z));
;         o.w = pk2((s[6] * inv - bflo(xc.w)) * sc1[2] * bflo(g.w), (s[7] * inv - bfhi(xc.w)) * sc1[3] * bfhi(g.w));
;         *(u32x4*)(MX + (size_t)(row0 + j) * 1024 + c0) = o;
;         if (w == 2) acc8(s, x[15 + j - 1], -1.f); else if (w == 4) acc8(s, x[15 + j - 3], -1.f); else if (w == 8) acc8(s, x[15 + j - 7], -1.f); else acc8(s, x[j], -1.f);
;     }
.LBB0_2887:
	v_or_b32_e32 v122, 10, v132
	v_ashrrev_i32_e32 v123, 31, v122
	v_lshlrev_b64 v[122:123], 11, v[122:123]
	v_lshl_add_u64 v[128:129], v[98:99], 0, v[122:123]
	global_load_dwordx4 v[152:155], v[128:129], off
	v_pk_add_f32 v[156:157], v[66:67], v[70:71] neg_lo:[0,1] neg_hi:[0,1]
	v_lshlrev_b32_e32 v66, 16, v30
	v_and_b32_e32 v70, 0xffff0000, v30
	v_or_b32_e32 v30, 11, v226
	v_min_i32_e32 v30, s16, v30
	v_pk_add_f32 v[78:79], v[78:79], v[82:83] neg_lo:[0,1] neg_hi:[0,1]
	v_pk_add_f32 v[82:83], v[92:93], v[94:95] neg_lo:[0,1] neg_hi:[0,1]
	v_cvt_f32_i32_e32 v92, v30
	v_pk_add_f32 v[128:129], v[34:35], v[0:1] neg_lo:[0,1] neg_hi:[0,1]
	v_lshlrev_b32_e32 v1, 16, v29
	v_lshlrev_b32_e32 v0, 16, v28
	v_div_scale_f32 v93, s[0:1], v92, v92, 1.0
	v_rcp_f32_e32 v94, v93
	v_and_b32_e32 v35, 0xffff0000, v29
	v_and_b32_e32 v34, 0xffff0000, v28
	v_pk_add_f32 v[28:29], v[128:129], v[0:1]
	v_fma_f32 v128, -v93, v94, 1.0
	v_div_scale_f32 v95, vcc, 1.0, v92, 1.0
	v_fmac_f32_e32 v94, v128, v94
	v_mul_f32_e32 v128, v95, v94
	v_fma_f32 v129, -v93, v128, v95
	v_fmac_f32_e32 v128, v129, v94
	v_fma_f32 v93, -v93, v128, v95
	v_lshlrev_b32_e32 v67, 16, v31
	v_and_b32_e32 v71, 0xffff0000, v31
	v_div_fmas_f32 v93, v93, v94, v128
	v_pk_add_f32 v[30:31], v[156:157], v[34:35]
	v_pk_add_f32 v[78:79], v[78:79], v[66:67]
	v_pk_add_f32 v[82:83], v[82:83], v[70:71]
	v_div_fixup_f32 v92, v93, v92, 1.0
	v_pk_fma_f32 v[94:95], v[92:93], v[28:29], v[0:1] op_sel_hi:[0,1,1] neg_lo:[0,0,1] neg_hi:[0,0,1]
	v_pk_fma_f32 v[128:129], v[92:93], v[30:31], v[34:35] op_sel_hi:[0,1,1] neg_lo:[0,0,1] neg_hi:[0,0,1]
	v_pk_fma_f32 v[156:157], v[92:93], v[78:79], v[66:67] op_sel_hi:[0,1,1] neg_lo:[0,0,1] neg_hi:[0,0,1]
	v_pk_fma_f32 v[92:93], v[92:93], v[82:83], v[70:71] op_sel_hi:[0,1,1] neg_lo:[0,0,1] neg_hi:[0,0,1]
	v_pk_mul_f32 v[94:95], v[64:65], v[94:95]
	v_pk_mul_f32 v[128:129], v[6:7], v[128:129]
	v_pk_mul_f32 v[156:157], v[4:5], v[156:157]
	v_pk_mul_f32 v[92:93], v[2:3], v[92:93]
	s_movk_i32 s11, 0x7fff
	s_mov_b32 s10, 0xffff0000
	v_lshl_add_u64 v[122:123], v[96:97], 0, v[122:123]
	s_cmp_lt_i32 s14, 1
	s_mov_b64 s[0:1], 0
	s_waitcnt vmcnt(0)
	v_lshlrev_b32_e32 v159, 16, v153
	v_lshlrev_b32_e32 v158, 16, v152
	v_and_b32_e32 v153, 0xffff0000, v153
	v_and_b32_e32 v152, 0xffff0000, v152
	v_lshlrev_b32_e32 v161, 16, v155
	v_lshlrev_b32_e32 v160, 16, v154
	v_and_b32_e32 v155, 0xffff0000, v155
	v_and_b32_e32 v154, 0xffff0000, v154
	v_pk_mul_f32 v[94:95], v[94:95], v[158:159]
	v_pk_mul_f32 v[128:129], v[128:129], v[152:153]
	v_pk_mul_f32 v[152:153], v[156:157], v[160:161]
	v_pk_mul_f32 v[92:93], v[92:93], v[154:155]
	v_bfe_u32 v157, v94, 16, 1
	v_bfe_u32 v133, v93, 16, 1
	v_bfe_u32 v158, v95, 16, 1
	v_bfe_u32 v160, v153, 16, 1
	v_bfe_u32 v155, v129, 16, 1
	v_bfe_u32 v156, v128, 16, 1
	v_add3_u32 v93, v93, v133, s11
	v_add3_u32 v133, v153, v160, s11
	v_add3_u32 v95, v95, v158, s11
	v_add3_u32 v94, v94, v157, s11
	v_add3_u32 v128, v128, v156, s11
	v_add3_u32 v129, v129, v155, s11
	v_lshrrev_b32_e32 v153, 16, v94
	v_lshrrev_b32_e32 v154, 16, v95
	v_lshrrev_b32_e32 v95, 16, v133
	v_and_or_b32 v95, v93, s10, v95
	v_cvt_pk_bf16_f32 v94, v152, v92
	v_and_or_b32 v93, v129, s10, v154
	v_and_or_b32 v92, v128, s10, v153
	global_store_dwordx4 v[122:123], v[92:95], off
	s_cbranch_scc1 .LBB0_2890
	s_cmp_gt_i32 s14, 1
	s_cbranch_scc0 .LBB0_2891
	s_cmp_lg_u32 s14, 2
	s_cselect_b64 s[10:11], -1, 0
	s_cbranch_execz .LBB0_2892
	s_branch .LBB0_2893

; __device__ __forceinline__ unsigned pk2(float lo, float hi) { return f2bf(lo) | (f2bf(hi) << 16); }
; __device__ __forceinline__ void fir_tile(const Prm& P, Ctx& C, int pm, int gi) {
;     ...
;     for (int j = 0; j < RUN; ++j) {
;         const int t = t0 + j;
;         const u32x4 g = *(const u32x4*)(GT + (size_t)(row0 + j) * 1024 + c0);
;         acc8(s, x[15 + j], 1.f);
;         const float inv = 1.f / (float)(t + 1 < w ? t + 1 : w);
;         const u32x4 xc = x[15 + j];
;         u32x4 o;
;         o.x = pk2((s[0] * inv - bflo(xc.x)) * sc0[0] * bflo(g.x), (s[1] * inv - bfhi(xc.x)) * sc0[1] * bfhi(g.x));
;         o.y = pk2((s[2] * inv - bflo(xc.y)) * sc0[2] * bflo(g.y), (s[3] * inv - bfhi(xc.y)) * sc0[3] * bfhi(g.y));
;         o.z = pk2((s[4] * inv - bflo(xc.z)) * sc1[0] * bflo(g.z), (s[5] * inv - bfhi(xc.z)) * sc1[1] * bfhi(g.z));
;         o.w = pk2((s[6] * inv - bflo(xc.w)) * sc1[2] * bflo(g.w), (s[7] * inv - bfhi(xc.w)) * sc1[3] * bfhi(g.w));
;         *(u32x4*)(MX + (size_t)(row0 + j) * 1024 + c0) = o;
;         if (w == 2) acc8(s, x[15 + j - 1], -1.f); else if (w == 4) acc8(s, x[15 + j - 3], -1.f); else if (w == 8) acc8(s, x[15 + j - 7], -1.f); else acc8(s, x[j], -1.f);
;     }
.LBB0_2899:
	v_or_b32_e32 v92, 11, v132
	v_ashrrev_i32_e32 v93, 31, v92
	v_lshlrev_b64 v[122:123], 11, v[92:93]
	v_lshl_add_u64 v[92:93], v[98:99], 0, v[122:123]
	global_load_dwordx4 v[92:95], v[92:93], off
	v_pk_add_f32 v[78:79], v[78:79], v[84:85] neg_lo:[0,1] neg_hi:[0,1]
	v_or_b32_e32 v84, 12, v226
	v_min_i32_e32 v84, s16, v84
	v_cvt_f32_i32_e32 v84, v84
	v_pk_add_f32 v[82:83], v[82:83], v[100:101] neg_lo:[0,1] neg_hi:[0,1]
	v_pk_add_f32 v[60:61], v[28:29], v[60:61] neg_lo:[0,1] neg_hi:[0,1]
	v_pk_add_f32 v[62:63], v[30:31], v[62:63] neg_lo:[0,1] neg_hi:[0,1]
	v_div_scale_f32 v85, s[0:1], v84, v84, 1.0
	v_rcp_f32_e32 v100, v85
	v_div_scale_f32 v101, vcc, 1.0, v84, 1.0
	v_lshlrev_b32_e32 v29, 16, v25
	v_fma_f32 v128, -v85, v100, 1.0
	v_fmac_f32_e32 v100, v128, v100
	v_mul_f32_e32 v128, v101, v100
	v_fma_f32 v129, -v85, v128, v101
	v_fmac_f32_e32 v128, v129, v100
	v_fma_f32 v85, -v85, v128, v101
	v_lshlrev_b32_e32 v28, 16, v24
	v_and_b32_e32 v25, 0xffff0000, v25
	v_and_b32_e32 v24, 0xffff0000, v24
	v_lshlrev_b32_e32 v31, 16, v27
	v_lshlrev_b32_e32 v30, 16, v26
	v_and_b32_e32 v27, 0xffff0000, v27
	v_and_b32_e32 v26, 0xffff0000, v26
	v_div_fmas_f32 v85, v85, v100, v128
	v_pk_add_f32 v[60:61], v[60:61], v[28:29]
	v_pk_add_f32 v[62:63], v[62:63], v[24:25]
	v_pk_add_f32 v[78:79], v[78:79], v[30:31]
	v_pk_add_f32 v[82:83], v[82:83], v[26:27]
	v_div_fixup_f32 v84, v85, v84, 1.0
	v_pk_fma_f32 v[100:101], v[84:85], v[60:61], v[28:29] op_sel_hi:[0,1,1] neg_lo:[0,0,1] neg_hi:[0,0,1]
	v_pk_fma_f32 v[128:129], v[84:85], v[62:63], v[24:25] op_sel_hi:[0,1,1] neg_lo:[0,0,1] neg_hi:[0,0,1]
	v_pk_fma_f32 v[144:145], v[84:85], v[78:79], v[30:31] op_sel_hi:[0,1,1] neg_lo:[0,0,1] neg_hi:[0,0,1]
	v_pk_fma_f32 v[84:85], v[84:85], v[82:83], v[26:27] op_sel_hi:[0,1,1] neg_lo:[0,0,1] neg_hi:[0,0,1]
	v_pk_mul_f32 v[100:101], v[64:65], v[100:101]
	v_pk_mul_f32 v[128:129], v[6:7], v[128:129]
	v_pk_mul_f32 v[144:145], v[4:5], v[144:145]
	v_pk_mul_f32 v[84:85], v[2:3], v[84:85]
	s_movk_i32 s11, 0x7fff
	s_mov_b32 s10, 0xffff0000
	s_cmp_lt_i32 s14, 1
	s_mov_b64 s[0:1], 0
	s_waitcnt vmcnt(0)
	v_lshlrev_b32_e32 v147, 16, v93
	v_lshlrev_b32_e32 v146, 16, v92
	v_and_b32_e32 v93, 0xffff0000, v93
	v_and_b32_e32 v92, 0xffff0000, v92
	v_lshlrev_b32_e32 v149, 16, v95
	v_lshlrev_b32_e32 v148, 16, v94
	v_and_b32_e32 v95, 0xffff0000, v95
	v_and_b32_e32 v94, 0xffff0000, v94
	v_pk_mul_f32 v[100:101], v[100:101], v[146:147]
	v_pk_mul_f32 v[92:93], v[128:129], v[92:93]
	v_pk_mul_f32 v[128:129], v[144:145], v[148:149]
	v_pk_mul_f32 v[84:85], v[84:85], v[94:95]
	v_cvt_pk_bf16_f32 v95, v129, v85
	v_cvt_pk_bf16_f32 v94, v128, v84
	v_cvt_pk_bf16_f32 v93, v101, v93
	v_cvt_pk_bf16_f32 v92, v100, v92
	v_lshl_add_u64 v[84:85], v[96:97], 0, v[122:123]
	global_store_dwordx4 v[84:85], v[92:95], off
	s_cbranch_scc1 .LBB0_2902
	s_cmp_gt_i32 s14, 1
	s_cbranch_scc0 .LBB0_2903
	s_cmp_lg_u32 s14, 2
	s_cselect_b64 s[10:11], -1, 0
	s_cbranch_execz .LBB0_2904
	s_branch .LBB0_2905

; __device__ __forceinline__ unsigned pk2(float lo, float hi) { return f2bf(lo) | (f2bf(hi) << 16); }
; __device__ __forceinline__ void fir_tile(const Prm& P, Ctx& C, int pm, int gi) {
;     ...
;     for (int j = 0; j < RUN; ++j) {
;         const int t = t0 + j;
;         const u32x4 g = *(const u32x4*)(GT + (size_t)(row0 + j) * 1024 + c0);
;         acc8(s, x[15 + j], 1.f);
;         const float inv = 1.f / (float)(t + 1 < w ? t + 1 : w);
;         const u32x4 xc = x[15 + j];
;         u32x4 o;
;         o.x = pk2((s[0] * inv - bflo(xc.x)) * sc0[0] * bflo(g.x), (s[1] * inv - bfhi(xc.x)) * sc0[1] * bfhi(g.x));
;         o.y = pk2((s[2] * inv - bflo(xc.y)) * sc0[2] * bflo(g.y), (s[3] * inv - bfhi(xc.y)) * sc0[3] * bfhi(g.y));
;         o.z = pk2((s[4] * inv - bflo(xc.z)) * sc1[0] * bflo(g.z), (s[5] * inv - bfhi(xc.z)) * sc1[1] * bfhi(g.z));
;         o.w = pk2((s[6] * inv - bflo(xc.w)) * sc1[2] * bflo(g.w), (s[7] * inv - bfhi(xc.w)) * sc1[3] * bfhi(g.w));
;         *(u32x4*)(MX + (size_t)(row0 + j) * 1024 + c0) = o;
;         if (w == 2) acc8(s, x[15 + j - 1], -1.f); else if (w == 4) acc8(s, x[15 + j - 3], -1.f); else if (w == 8) acc8(s, x[15 + j - 7], -1.f); else acc8(s, x[j], -1.f);
;     }
.LBB0_2935:
	v_or_b32_e32 v0, 14, v132
	v_ashrrev_i32_e32 v1, 31, v0
	v_lshlrev_b64 v[58:59], 11, v[0:1]
	v_lshl_add_u64 v[0:1], v[98:99], 0, v[58:59]
	global_load_dwordx4 v[54:57], v[0:1], off
	v_pk_add_f32 v[0:1], v[32:33], v[48:49] neg_lo:[0,1] neg_hi:[0,1]
	v_pk_add_f32 v[34:35], v[38:39], v[90:91] neg_lo:[0,1] neg_hi:[0,1]
	v_lshlrev_b32_e32 v38, 16, v12
	v_and_b32_e32 v48, 0xffff0000, v12
	v_or_b32_e32 v12, 15, v226
	v_min_i32_e32 v12, s16, v12
	v_cvt_f32_i32_e32 v60, v12
	v_pk_add_f32 v[32:33], v[36:37], v[50:51] neg_lo:[0,1] neg_hi:[0,1]
	v_lshlrev_b32_e32 v51, 16, v15
	v_lshlrev_b32_e32 v50, 16, v14
	v_pk_add_f32 v[36:37], v[52:53], v[168:169] neg_lo:[0,1] neg_hi:[0,1]
	v_and_b32_e32 v53, 0xffff0000, v15
	v_and_b32_e32 v52, 0xffff0000, v14
	v_pk_add_f32 v[14:15], v[34:35], v[50:51]
	v_div_scale_f32 v34, s[0:1], v60, v60, 1.0
	v_rcp_f32_e32 v35, v34
	v_and_b32_e32 v49, 0xffff0000, v13
	v_lshlrev_b32_e32 v39, 16, v13
	v_pk_add_f32 v[12:13], v[32:33], v[48:49]
	v_pk_add_f32 v[32:33], v[36:37], v[52:53]
	v_fma_f32 v37, -v34, v35, 1.0
	v_div_scale_f32 v36, vcc, 1.0, v60, 1.0
	v_fmac_f32_e32 v35, v37, v35
	v_mul_f32_e32 v37, v36, v35
	v_fma_f32 v61, -v34, v37, v36
	v_fmac_f32_e32 v37, v61, v35
	v_fma_f32 v34, -v34, v37, v36
	v_div_fmas_f32 v34, v34, v35, v37
	v_pk_add_f32 v[0:1], v[0:1], v[38:39]
	v_div_fixup_f32 v34, v34, v60, 1.0
	v_pk_fma_f32 v[36:37], v[34:35], v[0:1], v[38:39] op_sel_hi:[0,1,1] neg_lo:[0,0,1] neg_hi:[0,0,1]
	v_pk_fma_f32 v[38:39], v[34:35], v[12:13], v[48:49] op_sel_hi:[0,1,1] neg_lo:[0,0,1] neg_hi:[0,0,1]
	v_pk_fma_f32 v[48:49], v[34:35], v[14:15], v[50:51] op_sel_hi:[0,1,1] neg_lo:[0,0,1] neg_hi:[0,0,1]
	v_pk_fma_f32 v[34:35], v[34:35], v[32:33], v[52:53] op_sel_hi:[0,1,1] neg_lo:[0,0,1] neg_hi:[0,0,1]
	v_pk_mul_f32 v[36:37], v[64:65], v[36:37]
	v_pk_mul_f32 v[48:49], v[4:5], v[48:49]
	v_pk_mul_f32 v[38:39], v[6:7], v[38:39]
	v_pk_mul_f32 v[34:35], v[2:3], v[34:35]
	s_movk_i32 s11, 0x7fff
	s_mov_b32 s10, 0xffff0000
	s_cmp_lt_i32 s14, 1
	s_mov_b64 s[0:1], 0
	s_waitcnt vmcnt(0)
	v_lshlrev_b32_e32 v51, 16, v55
	v_lshlrev_b32_e32 v50, 16, v54
	v_and_b32_e32 v53, 0xffff0000, v55
	v_and_b32_e32 v52, 0xffff0000, v54
	v_lshlrev_b32_e32 v55, 16, v57
	v_lshlrev_b32_e32 v54, 16, v56
	v_and_b32_e32 v57, 0xffff0000, v57
	v_and_b32_e32 v56, 0xffff0000, v56
	v_pk_mul_f32 v[36:37], v[36:37], v[50:51]
	v_pk_mul_f32 v[48:49], v[48:49], v[54:55]
	v_pk_mul_f32 v[38:39], v[38:39], v[52:53]
	v_pk_mul_f32 v[34:35], v[34:35], v[56:57]
	v_bfe_u32 v54, v36, 16, 1
	v_bfe_u32 v55, v37, 16, 1
	v_bfe_u32 v52, v39, 16, 1
	v_bfe_u32 v53, v38, 16, 1
	v_add3_u32 v37, v37, v55, s11
	v_add3_u32 v36, v36, v54, s11
	v_add3_u32 v38, v38, v53, s11
	v_add3_u32 v39, v39, v52, s11
	v_lshrrev_b32_e32 v50, 16, v36
	v_lshrrev_b32_e32 v51, 16, v37
	v_cvt_pk_bf16_f32 v37, v49, v35
	v_cvt_pk_bf16_f32 v36, v48, v34
	v_and_or_b32 v35, v39, s10, v51
	v_and_or_b32 v34, v38, s10, v50
	v_lshl_add_u64 v[38:39], v[96:97], 0, v[58:59]
	global_store_dwordx4 v[38:39], v[34:37], off
	s_cbranch_scc1 .LBB0_2938
	s_cmp_gt_i32 s14, 1
	s_cbranch_scc0 .LBB0_2939
	s_cmp_lg_u32 s14, 2
	s_cselect_b64 s[10:11], -1, 0
	s_cbranch_execz .LBB0_2940
	s_branch .LBB0_2941

; __device__ __forceinline__ unsigned pk2(float lo, float hi) { return f2bf(lo) | (f2bf(hi) << 16); }
; __device__ __forceinline__ void fir_tile(const Prm& P, Ctx& C, int pm, int gi) {
;     ...
;     for (int j = 0; j < RUN; ++j) {
;         const int t = t0 + j;
;         const u32x4 g = *(const u32x4*)(GT + (size_t)(row0 + j) * 1024 + c0);
;         acc8(s, x[15 + j], 1.f);
;         const float inv = 1.f / (float)(t + 1 < w ? t + 1 : w);
;         const u32x4 xc = x[15 + j];
;         u32x4 o;
;         o.x = pk2((s[0] * inv - bflo(xc.x)) * sc0[0] * bflo(g.x), (s[1] * inv - bfhi(xc.x)) * sc0[1] * bfhi(g.x));
;         o.y = pk2((s[2] * inv - bflo(xc.y)) * sc0[2] * bflo(g.y), (s[3] * inv - bfhi(xc.y)) * sc0[3] * bfhi(g.y));
;         o.z = pk2((s[4] * inv - bflo(xc.z)) * sc1[0] * bflo(g.z), (s[5] * inv - bfhi(xc.z)) * sc1[1] * bfhi(g.z));
;         o.w = pk2((s[6] * inv - bflo(xc.w)) * sc1[2] * bflo(g.w), (s[7] * inv - bfhi(xc.w)) * sc1[3] * bfhi(g.w));
;         *(u32x4*)(MX + (size_t)(row0 + j) * 1024 + c0) = o;
;         if (w == 2) acc8(s, x[15 + j - 1], -1.f); else if (w == 4) acc8(s, x[15 + j - 3], -1.f); else if (w == 8) acc8(s, x[15 + j - 7], -1.f); else acc8(s, x[j], -1.f);
;     }
.LBB0_2947:
	v_or_b32_e32 v16, 15, v132
	v_ashrrev_i32_e32 v17, 31, v16
	v_lshlrev_b64 v[20:21], 11, v[16:17]
	v_lshl_add_u64 v[16:17], v[98:99], 0, v[20:21]
	global_load_dwordx4 v[16:19], v[16:17], off
	v_add_u32_e32 v28, 16, v226
	v_min_i32_e32 v28, s16, v28
	v_cvt_f32_i32_e32 v28, v28
	v_pk_add_f32 v[22:23], v[32:33], v[42:43] neg_lo:[0,1] neg_hi:[0,1]
	v_pk_add_f32 v[0:1], v[0:1], v[44:45] neg_lo:[0,1] neg_hi:[0,1]
	v_pk_add_f32 v[12:13], v[12:13], v[40:41] neg_lo:[0,1] neg_hi:[0,1]
	v_div_scale_f32 v29, s[0:1], v28, v28, 1.0
	v_rcp_f32_e32 v30, v29
	v_div_scale_f32 v31, vcc, 1.0, v28, 1.0
	v_pk_add_f32 v[14:15], v[14:15], v[46:47] neg_lo:[0,1] neg_hi:[0,1]
	v_fma_f32 v32, -v29, v30, 1.0
	v_fmac_f32_e32 v30, v32, v30
	v_mul_f32_e32 v32, v31, v30
	v_fma_f32 v33, -v29, v32, v31
	v_fmac_f32_e32 v32, v33, v30
	v_fma_f32 v29, -v29, v32, v31
	v_lshlrev_b32_e32 v24, 16, v8
	v_and_b32_e32 v8, 0xffff0000, v8
	v_lshlrev_b32_e32 v25, 16, v9
	v_and_b32_e32 v9, 0xffff0000, v9
	v_lshlrev_b32_e32 v26, 16, v10
	v_lshlrev_b32_e32 v27, 16, v11
	v_div_fmas_f32 v29, v29, v30, v32
	v_and_b32_e32 v10, 0xffff0000, v10
	v_and_b32_e32 v11, 0xffff0000, v11
	v_pk_add_f32 v[0:1], v[0:1], v[24:25]
	v_pk_add_f32 v[12:13], v[12:13], v[8:9]
	v_pk_add_f32 v[14:15], v[14:15], v[26:27]
	v_div_fixup_f32 v28, v29, v28, 1.0
	v_pk_add_f32 v[22:23], v[22:23], v[10:11]
	v_pk_fma_f32 v[0:1], v[28:29], v[0:1], v[24:25] op_sel_hi:[0,1,1] neg_lo:[0,0,1] neg_hi:[0,0,1]
	v_pk_fma_f32 v[8:9], v[28:29], v[12:13], v[8:9] op_sel_hi:[0,1,1] neg_lo:[0,0,1] neg_hi:[0,0,1]
	v_pk_fma_f32 v[12:13], v[28:29], v[14:15], v[26:27] op_sel_hi:[0,1,1] neg_lo:[0,0,1] neg_hi:[0,0,1]
	v_pk_fma_f32 v[10:11], v[28:29], v[22:23], v[10:11] op_sel_hi:[0,1,1] neg_lo:[0,0,1] neg_hi:[0,0,1]
	v_pk_mul_f32 v[0:1], v[64:65], v[0:1]
	v_pk_mul_f32 v[6:7], v[6:7], v[8:9]
	v_pk_mul_f32 v[4:5], v[4:5], v[12:13]
	v_pk_mul_f32 v[2:3], v[2:3], v[10:11]
	s_movk_i32 s11, 0x7fff
	s_mov_b32 s10, 0xffff0000
	s_waitcnt vmcnt(0)
	v_lshlrev_b32_e32 v9, 16, v17
	v_lshlrev_b32_e32 v8, 16, v16
	v_lshlrev_b32_e32 v13, 16, v19
	v_lshlrev_b32_e32 v12, 16, v18
	v_and_b32_e32 v11, 0xffff0000, v17
	v_and_b32_e32 v10, 0xffff0000, v16
	v_and_b32_e32 v15, 0xffff0000, v19
	v_and_b32_e32 v14, 0xffff0000, v18
	v_pk_mul_f32 v[0:1], v[0:1], v[8:9]
	v_pk_mul_f32 v[4:5], v[4:5], v[12:13]
	v_pk_mul_f32 v[6:7], v[6:7], v[10:11]
	v_pk_mul_f32 v[2:3], v[2:3], v[14:15]
	v_cvt_pk_bf16_f32 v3, v5, v3
	v_cvt_pk_bf16_f32 v2, v4, v2
	v_cvt_pk_bf16_f32 v1, v1, v7
	v_cvt_pk_bf16_f32 v0, v0, v6
	v_lshl_add_u64 v[4:5], v[96:97], 0, v[20:21]
	global_store_dwordx4 v[4:5], v[0:3], off

; __device__ __forceinline__ unsigned pk2(float lo, float hi) { return f2bf(lo) | (f2bf(hi) << 16); }
; __device__ __forceinline__ void fir_tile(const Prm& P, Ctx& C, int pm, int gi) {
;     ...
;     for (int j = 0; j < RUN; ++j) {
;         const int t = t0 + j;
;         const u32x4 g = *(const u32x4*)(GT + (size_t)(row0 + j) * 1024 + c0);
;         acc8(s, x[15 + j], 1.f);
;         const float inv = 1.f / (float)(t + 1 < w ? t + 1 : w);
;         const u32x4 xc = x[15 + j];
;         u32x4 o;
;         o.x = pk2((s[0] * inv - bflo(xc.x)) * sc0[0] * bflo(g.x), (s[1] * inv - bfhi(xc.x)) * sc0[1] * bfhi(g.x));
;         o.y = pk2((s[2] * inv - bflo(xc.y)) * sc0[2] * bflo(g.y), (s[3] * inv - bfhi(xc.y)) * sc0[3] * bfhi(g.y));
;         o.z = pk2((s[4] * inv - bflo(xc.z)) * sc1[0] * bflo(g.z), (s[5] * inv - bfhi(xc.z)) * sc1[1] * bfhi(g.z));
;         o.w = pk2((s[6] * inv - bflo(xc.w)) * sc1[2] * bflo(g.w), (s[7] * inv - bfhi(xc.w)) * sc1[3] * bfhi(g.w));
;         *(u32x4*)(MX + (size_t)(row0 + j) * 1024 + c0) = o;
;         if (w == 2) acc8(s, x[15 + j - 1], -1.f); else if (w == 4) acc8(s, x[15 + j - 3], -1.f); else if (w == 8) acc8(s, x[15 + j - 7], -1.f); else acc8(s, x[j], -1.f);
;     }
.LBB0_3109:
	v_or_b32_e32 v174, 7, v132
	v_ashrrev_i32_e32 v175, 31, v174
	v_lshlrev_b64 v[198:199], 11, v[174:175]
	v_lshl_add_u64 v[174:175], v[98:99], 0, v[198:199]
	global_load_dwordx4 v[194:197], v[174:175], off
	v_or_b32_e32 v133, 8, v224
	v_min_i32_e32 v133, s10, v133
	v_cvt_f32_i32_e32 v133, v133
	v_pk_add_f32 v[178:179], v[182:183], v[190:191] neg_lo:[0,1] neg_hi:[0,1]
	v_pk_add_f32 v[180:181], v[184:185], v[192:193] neg_lo:[0,1] neg_hi:[0,1]
	v_pk_add_f32 v[174:175], v[44:45], v[186:187] neg_lo:[0,1] neg_hi:[0,1]
	v_div_scale_f32 v182, s[0:1], v133, v133, 1.0
	v_rcp_f32_e32 v183, v182
	v_div_scale_f32 v184, vcc, 1.0, v133, 1.0
	v_pk_add_f32 v[176:177], v[46:47], v[188:189] neg_lo:[0,1] neg_hi:[0,1]
	v_fma_f32 v185, -v182, v183, 1.0
	v_fmac_f32_e32 v183, v185, v183
	v_mul_f32_e32 v185, v184, v183
	v_fma_f32 v186, -v182, v185, v184
	v_fmac_f32_e32 v185, v186, v183
	v_fma_f32 v182, -v182, v185, v184
	v_lshlrev_b32_e32 v45, 16, v41
	v_lshlrev_b32_e32 v44, 16, v40
	v_and_b32_e32 v41, 0xffff0000, v41
	v_and_b32_e32 v40, 0xffff0000, v40
	v_lshlrev_b32_e32 v47, 16, v43
	v_lshlrev_b32_e32 v46, 16, v42
	v_and_b32_e32 v43, 0xffff0000, v43
	v_and_b32_e32 v42, 0xffff0000, v42
	v_div_fmas_f32 v182, v182, v183, v185
	v_pk_add_f32 v[174:175], v[174:175], v[44:45]
	v_pk_add_f32 v[176:177], v[176:177], v[40:41]
	v_pk_add_f32 v[178:179], v[178:179], v[46:47]
	v_pk_add_f32 v[180:181], v[180:181], v[42:43]
	v_div_fixup_f32 v182, v182, v133, 1.0
	v_pk_fma_f32 v[184:185], v[182:183], v[174:175], v[44:45] op_sel_hi:[0,1,1] neg_lo:[0,0,1] neg_hi:[0,0,1]
	v_pk_fma_f32 v[186:187], v[182:183], v[176:177], v[40:41] op_sel_hi:[0,1,1] neg_lo:[0,0,1] neg_hi:[0,0,1]
	v_pk_fma_f32 v[188:189], v[182:183], v[178:179], v[46:47] op_sel_hi:[0,1,1] neg_lo:[0,0,1] neg_hi:[0,0,1]
	v_pk_fma_f32 v[182:183], v[182:183], v[180:181], v[42:43] op_sel_hi:[0,1,1] neg_lo:[0,0,1] neg_hi:[0,0,1]
	v_pk_mul_f32 v[184:185], v[64:65], v[184:185]
	v_pk_mul_f32 v[188:189], v[4:5], v[188:189]
	v_pk_mul_f32 v[182:183], v[2:3], v[182:183]
	v_pk_mul_f32 v[186:187], v[6:7], v[186:187]
	s_movk_i32 s5, 0x7fff
	s_mov_b32 s4, 0xffff0000
	s_cmp_lt_i32 s14, 1
	s_mov_b64 s[0:1], 0
	s_waitcnt vmcnt(0)
	v_lshlrev_b32_e32 v191, 16, v195
	v_lshlrev_b32_e32 v190, 16, v194
	v_and_b32_e32 v193, 0xffff0000, v195
	v_and_b32_e32 v192, 0xffff0000, v194
	v_lshlrev_b32_e32 v195, 16, v197
	v_lshlrev_b32_e32 v194, 16, v196
	v_and_b32_e32 v197, 0xffff0000, v197
	v_and_b32_e32 v196, 0xffff0000, v196
	v_pk_mul_f32 v[184:185], v[184:185], v[190:191]
	v_pk_mul_f32 v[188:189], v[188:189], v[194:195]
	v_pk_mul_f32 v[182:183], v[182:183], v[196:197]
	v_pk_mul_f32 v[186:187], v[186:187], v[192:193]
	v_bfe_u32 v133, v183, 16, 1
	v_bfe_u32 v193, v184, 16, 1
	v_bfe_u32 v194, v185, 16, 1
	v_bfe_u32 v196, v189, 16, 1
	v_bfe_u32 v191, v187, 16, 1
	v_bfe_u32 v192, v186, 16, 1
	v_add3_u32 v133, v183, v133, s5
	v_add3_u32 v183, v189, v196, s5
	v_add3_u32 v185, v185, v194, s5
	v_add3_u32 v184, v184, v193, s5
	v_add3_u32 v186, v186, v192, s5
	v_add3_u32 v187, v187, v191, s5
	v_lshrrev_b32_e32 v189, 16, v184
	v_lshrrev_b32_e32 v190, 16, v185
	v_lshrrev_b32_e32 v183, 16, v183
	v_and_or_b32 v185, v133, s4, v183
	v_cvt_pk_bf16_f32 v184, v188, v182
	v_and_or_b32 v183, v187, s4, v190
	v_and_or_b32 v182, v186, s4, v189
	v_lshl_add_u64 v[186:187], v[96:97], 0, v[198:199]
	global_store_dwordx4 v[186:187], v[182:185], off
	s_cbranch_scc1 .LBB0_3112
	s_cmp_gt_i32 s14, 1
	s_cbranch_scc0 .LBB0_3113
	s_cmp_lg_u32 s14, 2
	s_cselect_b64 s[4:5], -1, 0
	s_cbranch_execz .LBB0_3114
	s_branch .LBB0_3115

; __device__ __forceinline__ unsigned pk2(float lo, float hi) { return f2bf(lo) | (f2bf(hi) << 16); }
; __device__ __forceinline__ void fir_tile(const Prm& P, Ctx& C, int pm, int gi) {
;     ...
;     for (int j = 0; j < RUN; ++j) {
;         const int t = t0 + j;
;         const u32x4 g = *(const u32x4*)(GT + (size_t)(row0 + j) * 1024 + c0);
;         acc8(s, x[15 + j], 1.f);
;         const float inv = 1.f / (float)(t + 1 < w ? t + 1 : w);
;         const u32x4 xc = x[15 + j];
;         u32x4 o;
;         o.x = pk2((s[0] * inv - bflo(xc.x)) * sc0[0] * bflo(g.x), (s[1] * inv - bfhi(xc.x)) * sc0[1] * bfhi(g.x));
;         o.y = pk2((s[2] * inv - bflo(xc.y)) * sc0[2] * bflo(g.y), (s[3] * inv - bfhi(xc.y)) * sc0[3] * bfhi(g.y));
;         o.z = pk2((s[4] * inv - bflo(xc.z)) * sc1[0] * bflo(g.z), (s[5] * inv - bfhi(xc.z)) * sc1[1] * bfhi(g.z));
;         o.w = pk2((s[6] * inv - bflo(xc.w)) * sc1[2] * bflo(g.w), (s[7] * inv - bfhi(xc.w)) * sc1[3] * bfhi(g.w));
;         *(u32x4*)(MX + (size_t)(row0 + j) * 1024 + c0) = o;
;         if (w == 2) acc8(s, x[15 + j - 1], -1.f); else if (w == 4) acc8(s, x[15 + j - 3], -1.f); else if (w == 8) acc8(s, x[15 + j - 7], -1.f); else acc8(s, x[j], -1.f);
;     }
.LBB0_3121:
	v_or_b32_e32 v72, 8, v132
	v_ashrrev_i32_e32 v73, 31, v72
	v_lshlrev_b64 v[186:187], 11, v[72:73]
	v_lshl_add_u64 v[72:73], v[98:99], 0, v[186:187]
	global_load_dwordx4 v[182:185], v[72:73], off
	v_pk_add_f32 v[128:129], v[176:177], v[76:77] neg_lo:[0,1] neg_hi:[0,1]
	v_lshlrev_b32_e32 v76, 16, v38
	v_and_b32_e32 v80, 0xffff0000, v38
	v_or_b32_e32 v38, 9, v224
	v_min_i32_e32 v38, s10, v38
	v_cvt_f32_i32_e32 v133, v38
	v_pk_add_f32 v[122:123], v[174:175], v[122:123] neg_lo:[0,1] neg_hi:[0,1]
	v_pk_add_f32 v[172:173], v[178:179], v[68:69] neg_lo:[0,1] neg_hi:[0,1]
	v_lshlrev_b32_e32 v69, 16, v37
	v_lshlrev_b32_e32 v68, 16, v36
	v_lshlrev_b32_e32 v77, 16, v39
	v_and_b32_e32 v73, 0xffff0000, v37
	v_and_b32_e32 v72, 0xffff0000, v36
	v_pk_add_f32 v[36:37], v[122:123], v[68:69]
	v_pk_add_f32 v[122:123], v[172:173], v[76:77]
	v_div_scale_f32 v172, s[0:1], v133, v133, 1.0
	v_rcp_f32_e32 v173, v172
	v_pk_add_f32 v[170:171], v[180:181], v[170:171] neg_lo:[0,1] neg_hi:[0,1]
	v_and_b32_e32 v81, 0xffff0000, v39
	v_pk_add_f32 v[38:39], v[128:129], v[72:73]
	v_pk_add_f32 v[128:129], v[170:171], v[80:81]
	v_fma_f32 v171, -v172, v173, 1.0
	v_div_scale_f32 v170, vcc, 1.0, v133, 1.0
	v_fmac_f32_e32 v173, v171, v173
	v_mul_f32_e32 v171, v170, v173
	v_fma_f32 v174, -v172, v171, v170
	v_fmac_f32_e32 v171, v174, v173
	v_fma_f32 v170, -v172, v171, v170
	v_div_fmas_f32 v170, v170, v173, v171
	v_div_fixup_f32 v170, v170, v133, 1.0
	v_pk_fma_f32 v[172:173], v[170:171], v[36:37], v[68:69] op_sel_hi:[0,1,1] neg_lo:[0,0,1] neg_hi:[0,0,1]
	v_pk_fma_f32 v[174:175], v[170:171], v[38:39], v[72:73] op_sel_hi:[0,1,1] neg_lo:[0,0,1] neg_hi:[0,0,1]
	v_pk_fma_f32 v[176:177], v[170:171], v[122:123], v[76:77] op_sel_hi:[0,1,1] neg_lo:[0,0,1] neg_hi:[0,0,1]
	v_pk_fma_f32 v[170:171], v[170:171], v[128:129], v[80:81] op_sel_hi:[0,1,1] neg_lo:[0,0,1] neg_hi:[0,0,1]
	v_pk_mul_f32 v[172:173], v[64:65], v[172:173]
	v_pk_mul_f32 v[176:177], v[4:5], v[176:177]
	v_pk_mul_f32 v[170:171], v[2:3], v[170:171]
	v_pk_mul_f32 v[174:175], v[6:7], v[174:175]
	s_movk_i32 s5, 0x7fff
	s_mov_b32 s4, 0xffff0000
	s_cmp_lt_i32 s14, 1
	s_mov_b64 s[0:1], 0
	s_waitcnt vmcnt(0)
	v_lshlrev_b32_e32 v179, 16, v183
	v_lshlrev_b32_e32 v178, 16, v182
	v_and_b32_e32 v181, 0xffff0000, v183
	v_and_b32_e32 v180, 0xffff0000, v182
	v_lshlrev_b32_e32 v183, 16, v185
	v_lshlrev_b32_e32 v182, 16, v184
	v_and_b32_e32 v185, 0xffff0000, v185
	v_and_b32_e32 v184, 0xffff0000, v184
	v_pk_mul_f32 v[172:173], v[172:173], v[178:179]
	v_pk_mul_f32 v[176:177], v[176:177], v[182:183]
	v_pk_mul_f32 v[170:171], v[170:171], v[184:185]
	v_pk_mul_f32 v[174:175], v[174:175], v[180:181]
	v_bfe_u32 v133, v171, 16, 1
	v_bfe_u32 v181, v172, 16, 1
	v_bfe_u32 v182, v173, 16, 1
	v_bfe_u32 v184, v177, 16, 1
	v_bfe_u32 v179, v175, 16, 1
	v_bfe_u32 v180, v174, 16, 1
	v_add3_u32 v133, v171, v133, s5
	v_add3_u32 v171, v177, v184, s5
	v_add3_u32 v173, v173, v182, s5
	v_add3_u32 v172, v172, v181, s5
	v_add3_u32 v174, v174, v180, s5
	v_add3_u32 v175, v175, v179, s5
	v_lshrrev_b32_e32 v177, 16, v172
	v_lshrrev_b32_e32 v178, 16, v173
	v_lshrrev_b32_e32 v171, 16, v171
	v_and_or_b32 v173, v133, s4, v171
	v_cvt_pk_bf16_f32 v172, v176, v170
	v_and_or_b32 v171, v175, s4, v178
	v_and_or_b32 v170, v174, s4, v177
	v_lshl_add_u64 v[174:175], v[96:97], 0, v[186:187]
	global_store_dwordx4 v[174:175], v[170:173], off
	s_cbranch_scc1 .LBB0_3124
	s_cmp_gt_i32 s14, 1
	s_cbranch_scc0 .LBB0_3125
	s_cmp_lg_u32 s14, 2
	s_cselect_b64 s[4:5], -1, 0
	s_cbranch_execz .LBB0_3126
	s_branch .LBB0_3127

; __device__ __forceinline__ unsigned pk2(float lo, float hi) { return f2bf(lo) | (f2bf(hi) << 16); }
; __device__ __forceinline__ void fir_tile(const Prm& P, Ctx& C, int pm, int gi) {
;     ...
;     for (int j = 0; j < RUN; ++j) {
;         const int t = t0 + j;
;         const u32x4 g = *(const u32x4*)(GT + (size_t)(row0 + j) * 1024 + c0);
;         acc8(s, x[15 + j], 1.f);
;         const float inv = 1.f / (float)(t + 1 < w ? t + 1 : w);
;         const u32x4 xc = x[15 + j];
;         u32x4 o;
;         o.x = pk2((s[0] * inv - bflo(xc.x)) * sc0[0] * bflo(g.x), (s[1] * inv - bfhi(xc.x)) * sc0[1] * bfhi(g.x));
;         o.y = pk2((s[2] * inv - bflo(xc.y)) * sc0[2] * bflo(g.y), (s[3] * inv - bfhi(xc.y)) * sc0[3] * bfhi(g.y));
;         o.z = pk2((s[4] * inv - bflo(xc.z)) * sc1[0] * bflo(g.z), (s[5] * inv - bfhi(xc.z)) * sc1[1] * bfhi(g.z));
;         o.w = pk2((s[6] * inv - bflo(xc.w)) * sc1[2] * bflo(g.w), (s[7] * inv - bfhi(xc.w)) * sc1[3] * bfhi(g.w));
;         *(u32x4*)(MX + (size_t)(row0 + j) * 1024 + c0) = o;
;         if (w == 2) acc8(s, x[15 + j - 1], -1.f); else if (w == 4) acc8(s, x[15 + j - 3], -1.f); else if (w == 8) acc8(s, x[15 + j - 7], -1.f); else acc8(s, x[j], -1.f);
;     }
.LBB0_3145:
	v_or_b32_e32 v122, 10, v132
	v_ashrrev_i32_e32 v123, 31, v122
	v_lshlrev_b64 v[122:123], 11, v[122:123]
	v_lshl_add_u64 v[128:129], v[98:99], 0, v[122:123]
	global_load_dwordx4 v[152:155], v[128:129], off
	v_pk_add_f32 v[156:157], v[66:67], v[70:71] neg_lo:[0,1] neg_hi:[0,1]
	v_lshlrev_b32_e32 v66, 16, v30
	v_and_b32_e32 v70, 0xffff0000, v30
	v_or_b32_e32 v30, 11, v224
	v_min_i32_e32 v30, s10, v30
	v_pk_add_f32 v[78:79], v[78:79], v[82:83] neg_lo:[0,1] neg_hi:[0,1]
	v_pk_add_f32 v[82:83], v[92:93], v[94:95] neg_lo:[0,1] neg_hi:[0,1]
	v_cvt_f32_i32_e32 v92, v30
	v_pk_add_f32 v[128:129], v[34:35], v[0:1] neg_lo:[0,1] neg_hi:[0,1]
	v_lshlrev_b32_e32 v1, 16, v29
	v_lshlrev_b32_e32 v0, 16, v28
	v_div_scale_f32 v93, s[0:1], v92, v92, 1.0
	v_rcp_f32_e32 v94, v93
	v_and_b32_e32 v35, 0xffff0000, v29
	v_and_b32_e32 v34, 0xffff0000, v28
	v_pk_add_f32 v[28:29], v[128:129], v[0:1]
	v_fma_f32 v128, -v93, v94, 1.0
	v_div_scale_f32 v95, vcc, 1.0, v92, 1.0
	v_fmac_f32_e32 v94, v128, v94
	v_mul_f32_e32 v128, v95, v94
	v_fma_f32 v129, -v93, v128, v95
	v_fmac_f32_e32 v128, v129, v94
	v_fma_f32 v93, -v93, v128, v95
	v_lshlrev_b32_e32 v67, 16, v31
	v_and_b32_e32 v71, 0xffff0000, v31
	v_div_fmas_f32 v93, v93, v94, v128
	v_pk_add_f32 v[30:31], v[156:157], v[34:35]
	v_pk_add_f32 v[78:79], v[78:79], v[66:67]
	v_pk_add_f32 v[82:83], v[82:83], v[70:71]
	v_div_fixup_f32 v92, v93, v92, 1.0
	v_pk_fma_f32 v[94:95], v[92:93], v[28:29], v[0:1] op_sel_hi:[0,1,1] neg_lo:[0,0,1] neg_hi:[0,0,1]
	v_pk_fma_f32 v[128:129], v[92:93], v[30:31], v[34:35] op_sel_hi:[0,1,1] neg_lo:[0,0,1] neg_hi:[0,0,1]
	v_pk_fma_f32 v[156:157], v[92:93], v[78:79], v[66:67] op_sel_hi:[0,1,1] neg_lo:[0,0,1] neg_hi:[0,0,1]
	v_pk_fma_f32 v[92:93], v[92:93], v[82:83], v[70:71] op_sel_hi:[0,1,1] neg_lo:[0,0,1] neg_hi:[0,0,1]
	v_pk_mul_f32 v[94:95], v[64:65], v[94:95]
	v_pk_mul_f32 v[128:129], v[6:7], v[128:129]
	v_pk_mul_f32 v[156:157], v[4:5], v[156:157]
	v_pk_mul_f32 v[92:93], v[2:3], v[92:93]
	s_movk_i32 s5, 0x7fff
	s_mov_b32 s4, 0xffff0000
	v_lshl_add_u64 v[122:123], v[96:97], 0, v[122:123]
	s_cmp_lt_i32 s14, 1
	s_mov_b64 s[0:1], 0
	s_waitcnt vmcnt(0)
	v_lshlrev_b32_e32 v159, 16, v153
	v_lshlrev_b32_e32 v158, 16, v152
	v_and_b32_e32 v153, 0xffff0000, v153
	v_and_b32_e32 v152, 0xffff0000, v152
	v_lshlrev_b32_e32 v161, 16, v155
	v_lshlrev_b32_e32 v160, 16, v154
	v_and_b32_e32 v155, 0xffff0000, v155
	v_and_b32_e32 v154, 0xffff0000, v154
	v_pk_mul_f32 v[94:95], v[94:95], v[158:159]
	v_pk_mul_f32 v[128:129], v[128:129], v[152:153]
	v_pk_mul_f32 v[152:153], v[156:157], v[160:161]
	v_pk_mul_f32 v[92:93], v[92:93], v[154:155]
	v_bfe_u32 v157, v94, 16, 1
	v_bfe_u32 v133, v93, 16, 1
	v_bfe_u32 v158, v95, 16, 1
	v_bfe_u32 v160, v153, 16, 1
	v_bfe_u32 v155, v129, 16, 1
	v_bfe_u32 v156, v128, 16, 1
	v_add3_u32 v93, v93, v133, s5
	v_add3_u32 v133, v153, v160, s5
	v_add3_u32 v95, v95, v158, s5
	v_add3_u32 v94, v94, v157, s5
	v_add3_u32 v128, v128, v156, s5
	v_add3_u32 v129, v129, v155, s5
	v_lshrrev_b32_e32 v153, 16, v94
	v_lshrrev_b32_e32 v154, 16, v95
	v_lshrrev_b32_e32 v95, 16, v133
	v_and_or_b32 v95, v93, s4, v95
	v_cvt_pk_bf16_f32 v94, v152, v92
	v_and_or_b32 v93, v129, s4, v154
	v_and_or_b32 v92, v128, s4, v153
	global_store_dwordx4 v[122:123], v[92:95], off
	s_cbranch_scc1 .LBB0_3148
	s_cmp_gt_i32 s14, 1
	s_cbranch_scc0 .LBB0_3149
	s_cmp_lg_u32 s14, 2
	s_cselect_b64 s[4:5], -1, 0
	s_cbranch_execz .LBB0_3150
	s_branch .LBB0_3151

; __device__ __forceinline__ unsigned pk2(float lo, float hi) { return f2bf(lo) | (f2bf(hi) << 16); }
; __device__ __forceinline__ void fir_tile(const Prm& P, Ctx& C, int pm, int gi) {
;     ...
;     for (int j = 0; j < RUN; ++j) {
;         const int t = t0 + j;
;         const u32x4 g = *(const u32x4*)(GT + (size_t)(row0 + j) * 1024 + c0);
;         acc8(s, x[15 + j], 1.f);
;         const float inv = 1.f / (float)(t + 1 < w ? t + 1 : w);
;         const u32x4 xc = x[15 + j];
;         u32x4 o;
;         o.x = pk2((s[0] * inv - bflo(xc.x)) * sc0[0] * bflo(g.x), (s[1] * inv - bfhi(xc.x)) * sc0[1] * bfhi(g.x));
;         o.y = pk2((s[2] * inv - bflo(xc.y)) * sc0[2] * bflo(g.y), (s[3] * inv - bfhi(xc.y)) * sc0[3] * bfhi(g.y));
;         o.z = pk2((s[4] * inv - bflo(xc.z)) * sc1[0] * bflo(g.z), (s[5] * inv - bfhi(xc.z)) * sc1[1] * bfhi(g.z));
;         o.w = pk2((s[6] * inv - bflo(xc.w)) * sc1[2] * bflo(g.w), (s[7] * inv - bfhi(xc.w)) * sc1[3] * bfhi(g.w));
;         *(u32x4*)(MX + (size_t)(row0 + j) * 1024 + c0) = o;
;         if (w == 2) acc8(s, x[15 + j - 1], -1.f); else if (w == 4) acc8(s, x[15 + j - 3], -1.f); else if (w == 8) acc8(s, x[15 + j - 7], -1.f); else acc8(s, x[j], -1.f);
;     }
.LBB0_3157:
	v_or_b32_e32 v92, 11, v132
	v_ashrrev_i32_e32 v93, 31, v92
	v_lshlrev_b64 v[122:123], 11, v[92:93]
	v_lshl_add_u64 v[92:93], v[98:99], 0, v[122:123]
	global_load_dwordx4 v[92:95], v[92:93], off
	v_pk_add_f32 v[78:79], v[78:79], v[84:85] neg_lo:[0,1] neg_hi:[0,1]
	v_or_b32_e32 v84, 12, v224
	v_min_i32_e32 v84, s10, v84
	v_cvt_f32_i32_e32 v84, v84
	v_pk_add_f32 v[82:83], v[82:83], v[100:101] neg_lo:[0,1] neg_hi:[0,1]
	v_pk_add_f32 v[60:61], v[28:29], v[60:61] neg_lo:[0,1] neg_hi:[0,1]
	v_pk_add_f32 v[62:63], v[30:31], v[62:63] neg_lo:[0,1] neg_hi:[0,1]
	v_div_scale_f32 v85, s[0:1], v84, v84, 1.0
	v_rcp_f32_e32 v100, v85
	v_div_scale_f32 v101, vcc, 1.0, v84, 1.0
	v_lshlrev_b32_e32 v29, 16, v25
	v_fma_f32 v128, -v85, v100, 1.0
	v_fmac_f32_e32 v100, v128, v100
	v_mul_f32_e32 v128, v101, v100
	v_fma_f32 v129, -v85, v128, v101
	v_fmac_f32_e32 v128, v129, v100
	v_fma_f32 v85, -v85, v128, v101
	v_lshlrev_b32_e32 v28, 16, v24
	v_and_b32_e32 v25, 0xffff0000, v25
	v_and_b32_e32 v24, 0xffff0000, v24
	v_lshlrev_b32_e32 v31, 16, v27
	v_lshlrev_b32_e32 v30, 16, v26
	v_and_b32_e32 v27, 0xffff0000, v27
	v_and_b32_e32 v26, 0xffff0000, v26
	v_div_fmas_f32 v85, v85, v100, v128
	v_pk_add_f32 v[60:61], v[60:61], v[28:29]
	v_pk_add_f32 v[62:63], v[62:63], v[24:25]
	v_pk_add_f32 v[78:79], v[78:79], v[30:31]
	v_pk_add_f32 v[82:83], v[82:83], v[26:27]
	v_div_fixup_f32 v84, v85, v84, 1.0
	v_pk_fma_f32 v[100:101], v[84:85], v[60:61], v[28:29] op_sel_hi:[0,1,1] neg_lo:[0,0,1] neg_hi:[0,0,1]
	v_pk_fma_f32 v[128:129], v[84:85], v[62:63], v[24:25] op_sel_hi:[0,1,1] neg_lo:[0,0,1] neg_hi:[0,0,1]
	v_pk_fma_f32 v[144:145], v[84:85], v[78:79], v[30:31] op_sel_hi:[0,1,1] neg_lo:[0,0,1] neg_hi:[0,0,1]
	v_pk_fma_f32 v[84:85], v[84:85], v[82:83], v[26:27] op_sel_hi:[0,1,1] neg_lo:[0,0,1] neg_hi:[0,0,1]
	v_pk_mul_f32 v[100:101], v[64:65], v[100:101]
	v_pk_mul_f32 v[128:129], v[6:7], v[128:129]
	v_pk_mul_f32 v[144:145], v[4:5], v[144:145]
	v_pk_mul_f32 v[84:85], v[2:3], v[84:85]
	s_movk_i32 s5, 0x7fff
	s_mov_b32 s4, 0xffff0000
	s_cmp_lt_i32 s14, 1
	s_mov_b64 s[0:1], 0
	s_waitcnt vmcnt(0)
	v_lshlrev_b32_e32 v147, 16, v93
	v_lshlrev_b32_e32 v146, 16, v92
	v_and_b32_e32 v93, 0xffff0000, v93
	v_and_b32_e32 v92, 0xffff0000, v92
	v_lshlrev_b32_e32 v149, 16, v95
	v_lshlrev_b32_e32 v148, 16, v94
	v_and_b32_e32 v95, 0xffff0000, v95
	v_and_b32_e32 v94, 0xffff0000, v94
	v_pk_mul_f32 v[100:101], v[100:101], v[146:147]
	v_pk_mul_f32 v[92:93], v[128:129], v[92:93]
	v_pk_mul_f32 v[128:129], v[144:145], v[148:149]
	v_pk_mul_f32 v[84:85], v[84:85], v[94:95]
	v_cvt_pk_bf16_f32 v95, v129, v85
	v_cvt_pk_bf16_f32 v94, v128, v84
	v_cvt_pk_bf16_f32 v93, v101, v93
	v_cvt_pk_bf16_f32 v92, v100, v92
	v_lshl_add_u64 v[84:85], v[96:97], 0, v[122:123]
	global_store_dwordx4 v[84:85], v[92:95], off
	s_cbranch_scc1 .LBB0_3160
	s_cmp_gt_i32 s14, 1
	s_cbranch_scc0 .LBB0_3161
	s_cmp_lg_u32 s14, 2
	s_cselect_b64 s[4:5], -1, 0
	s_cbranch_execz .LBB0_3162
	s_branch .LBB0_3163

; __device__ __forceinline__ unsigned pk2(float lo, float hi) { return f2bf(lo) | (f2bf(hi) << 16); }
; __device__ __forceinline__ void fir_tile(const Prm& P, Ctx& C, int pm, int gi) {
;     ...
;     for (int j = 0; j < RUN; ++j) {
;         const int t = t0 + j;
;         const u32x4 g = *(const u32x4*)(GT + (size_t)(row0 + j) * 1024 + c0);
;         acc8(s, x[15 + j], 1.f);
;         const float inv = 1.f / (float)(t + 1 < w ? t + 1 : w);
;         const u32x4 xc = x[15 + j];
;         u32x4 o;
;         o.x = pk2((s[0] * inv - bflo(xc.x)) * sc0[0] * bflo(g.x), (s[1] * inv - bfhi(xc.x)) * sc0[1] * bfhi(g.x));
;         o.y = pk2((s[2] * inv - bflo(xc.y)) * sc0[2] * bflo(g.y), (s[3] * inv - bfhi(xc.y)) * sc0[3] * bfhi(g.y));
;         o.z = pk2((s[4] * inv - bflo(xc.z)) * sc1[0] * bflo(g.z), (s[5] * inv - bfhi(xc.z)) * sc1[1] * bfhi(g.z));
;         o.w = pk2((s[6] * inv - bflo(xc.w)) * sc1[2] * bflo(g.w), (s[7] * inv - bfhi(xc.w)) * sc1[3] * bfhi(g.w));
;         *(u32x4*)(MX + (size_t)(row0 + j) * 1024 + c0) = o;
;         if (w == 2) acc8(s, x[15 + j - 1], -1.f); else if (w == 4) acc8(s, x[15 + j - 3], -1.f); else if (w == 8) acc8(s, x[15 + j - 7], -1.f); else acc8(s, x[j], -1.f);
;     }
.LBB0_3181:
	v_or_b32_e32 v32, 13, v132
	v_ashrrev_i32_e32 v33, 31, v32
	v_lshlrev_b64 v[78:79], 11, v[32:33]
	v_lshl_add_u64 v[32:33], v[98:99], 0, v[78:79]
	global_load_dwordx4 v[74:77], v[32:33], off
	v_pk_add_f32 v[36:37], v[22:23], v[54:55] neg_lo:[0,1] neg_hi:[0,1]
	v_or_b32_e32 v54, 14, v224
	v_min_i32_e32 v54, s10, v54
	v_cvt_f32_i32_e32 v54, v54
	v_pk_add_f32 v[38:39], v[68:69], v[88:89] neg_lo:[0,1] neg_hi:[0,1]
	v_pk_add_f32 v[32:33], v[20:21], v[52:53] neg_lo:[0,1] neg_hi:[0,1]
	v_pk_add_f32 v[52:53], v[72:73], v[130:131] neg_lo:[0,1] neg_hi:[0,1]
	v_div_scale_f32 v55, s[0:1], v54, v54, 1.0
	v_rcp_f32_e32 v68, v55
	v_div_scale_f32 v69, vcc, 1.0, v54, 1.0
	v_lshlrev_b32_e32 v21, 16, v17
	v_fma_f32 v72, -v55, v68, 1.0
	v_fmac_f32_e32 v68, v72, v68
	v_mul_f32_e32 v72, v69, v68
	v_fma_f32 v73, -v55, v72, v69
	v_fmac_f32_e32 v72, v73, v68
	v_fma_f32 v55, -v55, v72, v69
	v_lshlrev_b32_e32 v20, 16, v16
	v_and_b32_e32 v17, 0xffff0000, v17
	v_and_b32_e32 v16, 0xffff0000, v16
	v_lshlrev_b32_e32 v23, 16, v19
	v_lshlrev_b32_e32 v22, 16, v18
	v_div_fmas_f32 v55, v55, v68, v72
	v_and_b32_e32 v19, 0xffff0000, v19
	v_and_b32_e32 v18, 0xffff0000, v18
	v_pk_add_f32 v[32:33], v[32:33], v[20:21]
	v_pk_add_f32 v[36:37], v[36:37], v[16:17]
	v_pk_add_f32 v[38:39], v[38:39], v[22:23]
	v_div_fixup_f32 v54, v55, v54, 1.0
	v_pk_add_f32 v[52:53], v[52:53], v[18:19]
	v_pk_fma_f32 v[68:69], v[54:55], v[32:33], v[20:21] op_sel_hi:[0,1,1] neg_lo:[0,0,1] neg_hi:[0,0,1]
	v_pk_fma_f32 v[72:73], v[54:55], v[36:37], v[16:17] op_sel_hi:[0,1,1] neg_lo:[0,0,1] neg_hi:[0,0,1]
	v_pk_fma_f32 v[80:81], v[54:55], v[38:39], v[22:23] op_sel_hi:[0,1,1] neg_lo:[0,0,1] neg_hi:[0,0,1]
	v_pk_fma_f32 v[54:55], v[54:55], v[52:53], v[18:19] op_sel_hi:[0,1,1] neg_lo:[0,0,1] neg_hi:[0,0,1]
	v_pk_mul_f32 v[68:69], v[64:65], v[68:69]
	v_pk_mul_f32 v[72:73], v[6:7], v[72:73]
	v_pk_mul_f32 v[80:81], v[4:5], v[80:81]
	v_pk_mul_f32 v[54:55], v[2:3], v[54:55]
	s_movk_i32 s5, 0x7fff
	s_mov_b32 s4, 0xffff0000
	s_cmp_lt_i32 s14, 1
	s_mov_b64 s[0:1], 0
	s_waitcnt vmcnt(0)
	v_lshlrev_b32_e32 v83, 16, v75
	v_lshlrev_b32_e32 v82, 16, v74
	v_and_b32_e32 v75, 0xffff0000, v75
	v_and_b32_e32 v74, 0xffff0000, v74
	v_lshlrev_b32_e32 v85, 16, v77
	v_lshlrev_b32_e32 v84, 16, v76
	v_and_b32_e32 v77, 0xffff0000, v77
	v_and_b32_e32 v76, 0xffff0000, v76
	v_pk_mul_f32 v[68:69], v[68:69], v[82:83]
	v_pk_mul_f32 v[72:73], v[72:73], v[74:75]
	v_pk_mul_f32 v[74:75], v[80:81], v[84:85]
	v_pk_mul_f32 v[54:55], v[54:55], v[76:77]
	v_cvt_pk_bf16_f32 v75, v75, v55
	v_cvt_pk_bf16_f32 v74, v74, v54
	v_cvt_pk_bf16_f32 v73, v69, v73
	v_cvt_pk_bf16_f32 v72, v68, v72
	v_lshl_add_u64 v[54:55], v[96:97], 0, v[78:79]
	global_store_dwordx4 v[54:55], v[72:75], off
	s_cbranch_scc1 .LBB0_3184
	s_cmp_gt_i32 s14, 1
	s_cbranch_scc0 .LBB0_3185
	s_cmp_lg_u32 s14, 2
	s_cselect_b64 s[4:5], -1, 0
	s_cbranch_execz .LBB0_3186
	s_branch .LBB0_3187

; __device__ __forceinline__ unsigned pk2(float lo, float hi) { return f2bf(lo) | (f2bf(hi) << 16); }
; __device__ __forceinline__ void fir_tile(const Prm& P, Ctx& C, int pm, int gi) {
;     ...
;     for (int j = 0; j < RUN; ++j) {
;         const int t = t0 + j;
;         const u32x4 g = *(const u32x4*)(GT + (size_t)(row0 + j) * 1024 + c0);
;         acc8(s, x[15 + j], 1.f);
;         const float inv = 1.f / (float)(t + 1 < w ? t + 1 : w);
;         const u32x4 xc = x[15 + j];
;         u32x4 o;
;         o.x = pk2((s[0] * inv - bflo(xc.x)) * sc0[0] * bflo(g.x), (s[1] * inv - bfhi(xc.x)) * sc0[1] * bfhi(g.x));
;         o.y = pk2((s[2] * inv - bflo(xc.y)) * sc0[2] * bflo(g.y), (s[3] * inv - bfhi(xc.y)) * sc0[3] * bfhi(g.y));
;         o.z = pk2((s[4] * inv - bflo(xc.z)) * sc1[0] * bflo(g.z), (s[5] * inv - bfhi(xc.z)) * sc1[1] * bfhi(g.z));
;         o.w = pk2((s[6] * inv - bflo(xc.w)) * sc1[2] * bflo(g.w), (s[7] * inv - bfhi(xc.w)) * sc1[3] * bfhi(g.w));
;         *(u32x4*)(MX + (size_t)(row0 + j) * 1024 + c0) = o;
;         if (w == 2) acc8(s, x[15 + j - 1], -1.f); else if (w == 4) acc8(s, x[15 + j - 3], -1.f); else if (w == 8) acc8(s, x[15 + j - 7], -1.f); else acc8(s, x[j], -1.f);
;     }
.LBB0_3193:
	v_or_b32_e32 v0, 14, v132
	v_ashrrev_i32_e32 v1, 31, v0
	v_lshlrev_b64 v[58:59], 11, v[0:1]
	v_lshl_add_u64 v[0:1], v[98:99], 0, v[58:59]
	global_load_dwordx4 v[54:57], v[0:1], off
	v_pk_add_f32 v[0:1], v[32:33], v[48:49] neg_lo:[0,1] neg_hi:[0,1]
	v_pk_add_f32 v[34:35], v[38:39], v[90:91] neg_lo:[0,1] neg_hi:[0,1]
	v_lshlrev_b32_e32 v38, 16, v12
	v_and_b32_e32 v48, 0xffff0000, v12
	v_or_b32_e32 v12, 15, v224
	v_min_i32_e32 v12, s10, v12
	v_cvt_f32_i32_e32 v60, v12
	v_pk_add_f32 v[32:33], v[36:37], v[50:51] neg_lo:[0,1] neg_hi:[0,1]
	v_lshlrev_b32_e32 v51, 16, v15
	v_lshlrev_b32_e32 v50, 16, v14
	v_pk_add_f32 v[36:37], v[52:53], v[168:169] neg_lo:[0,1] neg_hi:[0,1]
	v_and_b32_e32 v53, 0xffff0000, v15
	v_and_b32_e32 v52, 0xffff0000, v14
	v_pk_add_f32 v[14:15], v[34:35], v[50:51]
	v_div_scale_f32 v34, s[0:1], v60, v60, 1.0
	v_rcp_f32_e32 v35, v34
	v_and_b32_e32 v49, 0xffff0000, v13
	v_lshlrev_b32_e32 v39, 16, v13
	v_pk_add_f32 v[12:13], v[32:33], v[48:49]
	v_pk_add_f32 v[32:33], v[36:37], v[52:53]
	v_fma_f32 v37, -v34, v35, 1.0
	v_div_scale_f32 v36, vcc, 1.0, v60, 1.0
	v_fmac_f32_e32 v35, v37, v35
	v_mul_f32_e32 v37, v36, v35
	v_fma_f32 v61, -v34, v37, v36
	v_fmac_f32_e32 v37, v61, v35
	v_fma_f32 v34, -v34, v37, v36
	v_div_fmas_f32 v34, v34, v35, v37
	v_pk_add_f32 v[0:1], v[0:1], v[38:39]
	v_div_fixup_f32 v34, v34, v60, 1.0
	v_pk_fma_f32 v[36:37], v[34:35], v[0:1], v[38:39] op_sel_hi:[0,1,1] neg_lo:[0,0,1] neg_hi:[0,0,1]
	v_pk_fma_f32 v[38:39], v[34:35], v[12:13], v[48:49] op_sel_hi:[0,1,1] neg_lo:[0,0,1] neg_hi:[0,0,1]
	v_pk_fma_f32 v[48:49], v[34:35], v[14:15], v[50:51] op_sel_hi:[0,1,1] neg_lo:[0,0,1] neg_hi:[0,0,1]
	v_pk_fma_f32 v[34:35], v[34:35], v[32:33], v[52:53] op_sel_hi:[0,1,1] neg_lo:[0,0,1] neg_hi:[0,0,1]
	v_pk_mul_f32 v[36:37], v[64:65], v[36:37]
	v_pk_mul_f32 v[48:49], v[4:5], v[48:49]
	v_pk_mul_f32 v[38:39], v[6:7], v[38:39]
	v_pk_mul_f32 v[34:35], v[2:3], v[34:35]
	s_movk_i32 s5, 0x7fff
	s_mov_b32 s4, 0xffff0000
	s_cmp_lt_i32 s14, 1
	s_mov_b64 s[0:1], 0
	s_waitcnt vmcnt(0)
	v_lshlrev_b32_e32 v51, 16, v55
	v_lshlrev_b32_e32 v50, 16, v54
	v_and_b32_e32 v53, 0xffff0000, v55
	v_and_b32_e32 v52, 0xffff0000, v54
	v_lshlrev_b32_e32 v55, 16, v57
	v_lshlrev_b32_e32 v54, 16, v56
	v_and_b32_e32 v57, 0xffff0000, v57
	v_and_b32_e32 v56, 0xffff0000, v56
	v_pk_mul_f32 v[36:37], v[36:37], v[50:51]
	v_pk_mul_f32 v[48:49], v[48:49], v[54:55]
	v_pk_mul_f32 v[38:39], v[38:39], v[52:53]
	v_pk_mul_f32 v[34:35], v[34:35], v[56:57]
	v_bfe_u32 v54, v36, 16, 1
	v_bfe_u32 v55, v37, 16, 1
	v_bfe_u32 v52, v39, 16, 1
	v_bfe_u32 v53, v38, 16, 1
	v_add3_u32 v37, v37, v55, s5
	v_add3_u32 v36, v36, v54, s5
	v_add3_u32 v38, v38, v53, s5
	v_add3_u32 v39, v39, v52, s5
	v_lshrrev_b32_e32 v50, 16, v36
	v_lshrrev_b32_e32 v51, 16, v37
	v_cvt_pk_bf16_f32 v37, v49, v35
	v_cvt_pk_bf16_f32 v36, v48, v34
	v_and_or_b32 v35, v39, s4, v51
	v_and_or_b32 v34, v38, s4, v50
	v_lshl_add_u64 v[38:39], v[96:97], 0, v[58:59]
	global_store_dwordx4 v[38:39], v[34:37], off
	s_cbranch_scc1 .LBB0_3196
	s_cmp_gt_i32 s14, 1
	s_cbranch_scc0 .LBB0_3197
	s_cmp_lg_u32 s14, 2
	s_cselect_b64 s[4:5], -1, 0
	s_cbranch_execz .LBB0_3198
	s_branch .LBB0_3199
